# GEMM K-loops: removed redundant post-barrier lgkmcnt(0) and no-op setprio 0/1 pairs inside MFMA blocks
# speedup vs baseline: 1.0017x; 1.0000x over previous
; #define PG8_STAGE(bufoff, gbase, voff) do { _Pragma("unroll") for (int _i = 0; _i < 2; ++_i) \
;         __builtin_amdgcn_global_load_lds((const unsigned*)((const char*)(gbase) + (voff)[_i]), (PG8_LAS unsigned*)(lds + (bufoff) + ldsw + _i * 8192), 16, 0, 0); } while (0)
; #define PG8_LDA(dst, b, h) do { _Pragma("unroll") for (int m = 0; m < 4; ++m) _Pragma("unroll") for (int k = 0; k < 2; ++k) dst[m][k] = *(const PG8_LAS bf16x8*)(lds + PG8_SA(b, h) + aoff + m * 2048 + k * 1024); } while (0)
; #define PG8_LDB(dst, b, h) do { _Pragma("unroll") for (int n = 0; n < 2; ++n) _Pragma("unroll") for (int k = 0; k < 2; ++k) dst[n][k] = *(const PG8_LAS bf16x8*)(lds + PG8_SB(b, h) + boff + n * 2048 + k * 1024); } while (0)
; #define PG8_MMA(ai, bj, At, Bt) do { __builtin_amdgcn_s_setprio(1); _Pragma("unroll") for (int m = 0; m < 4; ++m) _Pragma("unroll") for (int n = 0; n < 2; ++n) _Pragma("unroll") for (int k = 0; k < 2; ++k) \
;         acc[ai][bj][m][n] = __builtin_amdgcn_mfma_f32_16x16x32_bf16(Bt[n][k], At[m][k], acc[ai][bj][m][n], 0, 0, 0); __builtin_amdgcn_s_setprio(0); } while (0)
; #define PG8_BAR __builtin_amdgcn_s_barrier()
; template <class Epi, class Sched, bool ALIGN_EPI = false, bool SP2 = false>
; __device__ __forceinline__ void gemm_phase(PG8_LAS unsigned char* lds, const Gemm g, const Sched& S, const Epi& E, const int wave_in) {
;     ...
;             PG8_LDB(B0, 0, 0); PG8_LDB(B1, 0, 1); PG8_SCHED; PG8_LDA(At, 0, 0); PG8_STAGE(PG8_SA(1, 1), a1 + hstepA, voffA);
;             PG8_WAIT_V(8); PG8_WAIT_L(0); PG8_BAR; PG8_MMA(0, 0, At, B0); PG8_MMA(0, 1, At, B1); PG8_BAR; PG8_SCHED;
;             PG8_LDA(At, 0, 1); PG8_STAGE(PG8_SB(0, 0), b2, voffB); PG8_STAGE(PG8_SB(0, 1), b2 + hstep, voffB); PG8_STAGE(PG8_SA(0, 0), a2, voffA);
;             PG8_WAIT_V(8); PG8_WAIT_L(0); PG8_BAR; PG8_MMA(1, 0, At, B0); PG8_MMA(1, 1, At, B1); PG8_BAR; PG8_SCHED;
;             PG8_LDB(B0, 1, 0); PG8_LDB(B1, 1, 1); PG8_SCHED; PG8_LDA(At, 1, 0); PG8_STAGE(PG8_SA(0, 1), a2 + hstepA, voffA);
;             PG8_WAIT_V(8); PG8_WAIT_L(0); PG8_BAR; PG8_MMA(0, 0, At, B0); PG8_MMA(0, 1, At, B1); PG8_BAR; PG8_SCHED;
;             PG8_LDA(At, 1, 1); PG8_STAGE(PG8_SB(1, 0), b3, voffB); PG8_STAGE(PG8_SB(1, 1), b3 + hstep, voffB); PG8_STAGE(PG8_SA(1, 0), a3, voffA);
;             PG8_WAIT_V(8); PG8_WAIT_L(0); PG8_BAR; PG8_MMA(1, 0, At, B0); PG8_MMA(1, 1, At, B1); PG8_BAR; PG8_SCHED;
.LBB0_498:
	ds_read_b128 v[144:147], v153
	ds_read_b128 v[158:161], v153 offset:1024
	ds_read_b128 v[162:165], v153 offset:2048
	ds_read_b128 v[166:169], v153 offset:3072
	ds_read_b128 v[170:173], v154
	ds_read_b128 v[174:177], v154 offset:1024
	ds_read_b128 v[178:181], v154 offset:2048
	ds_read_b128 v[182:185], v154 offset:3072
	s_add_u32 s4, s68, 0xfff80080
	s_addc_u32 s5, s69, -1
	s_cmp_eq_u32 s78, 28
	s_cselect_b32 s71, s36, s5
	s_cselect_b32 s70, s37, s4
	s_cselect_b32 s5, s61, s73
	s_cselect_b32 s4, s63, s72
	v_lshl_add_u64 v[148:149], s[68:69], 0, v[136:137]
	s_add_i32 m0, s19, 0xc000
	ds_read_b128 v[186:189], v155
	ds_read_b128 v[190:193], v155 offset:1024
	ds_read_b128 v[194:197], v155 offset:2048
	ds_read_b128 v[198:201], v155 offset:3072
	ds_read_b128 v[202:205], v155 offset:4096
	ds_read_b128 v[206:209], v155 offset:5120
	ds_read_b128 v[210:213], v155 offset:6144
	ds_read_b128 v[214:217], v155 offset:7168
	global_load_lds_dwordx4 v[148:149], off
	v_lshl_add_u64 v[148:149], s[68:69], 0, v[138:139]
	s_add_i32 m0, s19, 0xe000
	s_nop 0
	global_load_lds_dwordx4 v[148:149], off
	s_waitcnt vmcnt(8)
	s_waitcnt lgkmcnt(0)
	s_barrier
	s_setprio 1
	v_mfma_f32_16x16x32_bf16 v[120:123], v[144:147], v[186:189], v[120:123]
	v_mfma_f32_16x16x32_bf16 v[116:119], v[162:165], v[186:189], v[116:119]
	v_mfma_f32_16x16x32_bf16 v[104:107], v[144:147], v[194:197], v[104:107]
	v_mfma_f32_16x16x32_bf16 v[100:103], v[162:165], v[194:197], v[100:103]
	v_mfma_f32_16x16x32_bf16 v[88:91], v[144:147], v[202:205], v[88:91]
	v_mfma_f32_16x16x32_bf16 v[84:87], v[162:165], v[202:205], v[84:87]
	v_mfma_f32_16x16x32_bf16 v[72:75], v[144:147], v[210:213], v[72:75]
	v_mfma_f32_16x16x32_bf16 v[68:71], v[162:165], v[210:213], v[68:71]
	v_mfma_f32_16x16x32_bf16 v[120:123], v[158:161], v[190:193], v[120:123]
	v_mfma_f32_16x16x32_bf16 v[116:119], v[166:169], v[190:193], v[116:119]
	v_mfma_f32_16x16x32_bf16 v[104:107], v[158:161], v[198:201], v[104:107]
	v_mfma_f32_16x16x32_bf16 v[100:103], v[166:169], v[198:201], v[100:103]
	v_mfma_f32_16x16x32_bf16 v[88:91], v[158:161], v[206:209], v[88:91]
	v_mfma_f32_16x16x32_bf16 v[84:87], v[166:169], v[206:209], v[84:87]
	v_mfma_f32_16x16x32_bf16 v[72:75], v[158:161], v[214:217], v[72:75]
	v_mfma_f32_16x16x32_bf16 v[68:71], v[166:169], v[214:217], v[68:71]
	v_mfma_f32_16x16x32_bf16 v[124:127], v[170:173], v[186:189], v[124:127]
	v_mfma_f32_16x16x32_bf16 v[112:115], v[178:181], v[186:189], v[112:115]
	v_mfma_f32_16x16x32_bf16 v[108:111], v[170:173], v[194:197], v[108:111]
	v_mfma_f32_16x16x32_bf16 v[96:99], v[178:181], v[194:197], v[96:99]
	v_mfma_f32_16x16x32_bf16 v[92:95], v[170:173], v[202:205], v[92:95]
	v_mfma_f32_16x16x32_bf16 v[80:83], v[178:181], v[202:205], v[80:83]
	v_mfma_f32_16x16x32_bf16 v[76:79], v[170:173], v[210:213], v[76:79]
	v_mfma_f32_16x16x32_bf16 v[64:67], v[178:181], v[210:213], v[64:67]
	v_mfma_f32_16x16x32_bf16 v[124:127], v[174:177], v[190:193], v[124:127]
	v_mfma_f32_16x16x32_bf16 v[112:115], v[182:185], v[190:193], v[112:115]
	v_mfma_f32_16x16x32_bf16 v[108:111], v[174:177], v[198:201], v[108:111]
	v_mfma_f32_16x16x32_bf16 v[96:99], v[182:185], v[198:201], v[96:99]
	v_mfma_f32_16x16x32_bf16 v[92:95], v[174:177], v[206:209], v[92:95]
	v_mfma_f32_16x16x32_bf16 v[80:83], v[182:185], v[206:209], v[80:83]
	v_mfma_f32_16x16x32_bf16 v[76:79], v[174:177], v[214:217], v[76:79]
	v_mfma_f32_16x16x32_bf16 v[64:67], v[182:185], v[214:217], v[64:67]
	s_setprio 0
	s_barrier
	s_add_i32 s79, s48, s11
	v_lshl_add_u64 v[148:149], s[4:5], 0, v[132:133]
	s_mov_b32 m0, s79
	ds_read_b128 v[186:189], v155 offset:16384
	ds_read_b128 v[190:193], v155 offset:17408
	ds_read_b128 v[194:197], v155 offset:18432
	ds_read_b128 v[198:201], v155 offset:19456
	ds_read_b128 v[202:205], v155 offset:20480
	ds_read_b128 v[206:209], v155 offset:21504
	ds_read_b128 v[210:213], v155 offset:22528
	ds_read_b128 v[214:217], v155 offset:23552
	global_load_lds_dwordx4 v[148:149], off
	s_add_i32 m0, s79, 0x2000
	s_add_u32 s84, s4, 0x80000
	v_lshl_add_u64 v[218:219], s[4:5], 0, v[128:129]
	s_addc_u32 s85, s5, 0
	s_add_i32 s79, s49, s11
	global_load_lds_dwordx4 v[218:219], off
	v_lshl_add_u64 v[220:221], s[84:85], 0, v[132:133]
	s_mov_b32 m0, s79
	v_lshl_add_u64 v[222:223], s[70:71], 0, v[130:131]
	global_load_lds_dwordx4 v[220:221], off
	v_lshl_add_u64 v[220:221], s[84:85], 0, v[128:129]
	s_add_i32 m0, s79, 0x2000
	s_nop 0
	global_load_lds_dwordx4 v[220:221], off
	v_lshl_add_u64 v[220:221], s[70:71], 0, v[134:135]
	s_mov_b32 m0, s19
	s_nop 0
	global_load_lds_dwordx4 v[220:221], off
	s_mov_b32 m0, s38
	s_nop 0
	global_load_lds_dwordx4 v[222:223], off
	s_waitcnt vmcnt(8)
	s_waitcnt lgkmcnt(0)
	s_barrier
; #define PG8_STAGE(bufoff, gbase, voff) do { _Pragma("unroll") for (int _i = 0; _i < 2; ++_i) \
;         __builtin_amdgcn_global_load_lds((const unsigned*)((const char*)(gbase) + (voff)[_i]), (PG8_LAS unsigned*)(lds + (bufoff) + ldsw + _i * 8192), 16, 0, 0); } while (0)
; #define PG8_LDA(dst, b, h) do { _Pragma("unroll") for (int m = 0; m < 4; ++m) _Pragma("unroll") for (int k = 0; k < 2; ++k) dst[m][k] = *(const PG8_LAS bf16x8*)(lds + PG8_SA(b, h) + aoff + m * 2048 + k * 1024); } while (0)
; #define PG8_LDB(dst, b, h) do { _Pragma("unroll") for (int n = 0; n < 2; ++n) _Pragma("unroll") for (int k = 0; k < 2; ++k) dst[n][k] = *(const PG8_LAS bf16x8*)(lds + PG8_SB(b, h) + boff + n * 2048 + k * 1024); } while (0)
; #define PG8_MMA(ai, bj, At, Bt) do { __builtin_amdgcn_s_setprio(1); _Pragma("unroll") for (int m = 0; m < 4; ++m) _Pragma("unroll") for (int n = 0; n < 2; ++n) _Pragma("unroll") for (int k = 0; k < 2; ++k) \
;         acc[ai][bj][m][n] = __builtin_amdgcn_mfma_f32_16x16x32_bf16(Bt[n][k], At[m][k], acc[ai][bj][m][n], 0, 0, 0); __builtin_amdgcn_s_setprio(0); } while (0)
; #define PG8_BAR __builtin_amdgcn_s_barrier()
; template <class Epi, class Sched, bool ALIGN_EPI = false, bool SP2 = false>
; __device__ __forceinline__ void gemm_phase(PG8_LAS unsigned char* lds, const Gemm g, const Sched& S, const Epi& E, const int wave_in) {
;     ...
;             PG8_LDB(B0, 0, 0); PG8_LDB(B1, 0, 1); PG8_SCHED; PG8_LDA(At, 0, 0); PG8_STAGE(PG8_SA(1, 1), a1 + hstepA, voffA);
;             PG8_WAIT_V(8); PG8_WAIT_L(0); PG8_BAR; PG8_MMA(0, 0, At, B0); PG8_MMA(0, 1, At, B1); PG8_BAR; PG8_SCHED;
;             PG8_LDA(At, 0, 1); PG8_STAGE(PG8_SB(0, 0), b2, voffB); PG8_STAGE(PG8_SB(0, 1), b2 + hstep, voffB); PG8_STAGE(PG8_SA(0, 0), a2, voffA);
;             PG8_WAIT_V(8); PG8_WAIT_L(0); PG8_BAR; PG8_MMA(1, 0, At, B0); PG8_MMA(1, 1, At, B1); PG8_BAR; PG8_SCHED;
;             PG8_LDB(B0, 1, 0); PG8_LDB(B1, 1, 1); PG8_SCHED; PG8_LDA(At, 1, 0); PG8_STAGE(PG8_SA(0, 1), a2 + hstepA, voffA);
;             PG8_WAIT_V(8); PG8_WAIT_L(0); PG8_BAR; PG8_MMA(0, 0, At, B0); PG8_MMA(0, 1, At, B1); PG8_BAR; PG8_SCHED;
;             PG8_LDA(At, 1, 1); PG8_STAGE(PG8_SB(1, 0), b3, voffB); PG8_STAGE(PG8_SB(1, 1), b3 + hstep, voffB); PG8_STAGE(PG8_SA(1, 0), a3, voffA);
;             PG8_WAIT_V(8); PG8_WAIT_L(0); PG8_BAR; PG8_MMA(1, 0, At, B0); PG8_MMA(1, 1, At, B1); PG8_BAR; PG8_SCHED;
	s_setprio 1
	v_mfma_f32_16x16x32_bf16 v[56:59], v[144:147], v[186:189], v[56:59]
	v_mfma_f32_16x16x32_bf16 v[52:55], v[162:165], v[186:189], v[52:55]
	v_mfma_f32_16x16x32_bf16 v[40:43], v[144:147], v[194:197], v[40:43]
	v_mfma_f32_16x16x32_bf16 v[36:39], v[162:165], v[194:197], v[36:39]
	v_mfma_f32_16x16x32_bf16 v[24:27], v[144:147], v[202:205], v[24:27]
	v_mfma_f32_16x16x32_bf16 v[20:23], v[162:165], v[202:205], v[20:23]
	v_mfma_f32_16x16x32_bf16 v[8:11], v[144:147], v[210:213], v[8:11]
	v_mfma_f32_16x16x32_bf16 v[4:7], v[162:165], v[210:213], v[4:7]
	v_mfma_f32_16x16x32_bf16 v[56:59], v[158:161], v[190:193], v[56:59]
	v_mfma_f32_16x16x32_bf16 v[52:55], v[166:169], v[190:193], v[52:55]
	v_mfma_f32_16x16x32_bf16 v[40:43], v[158:161], v[198:201], v[40:43]
	v_mfma_f32_16x16x32_bf16 v[36:39], v[166:169], v[198:201], v[36:39]
	v_mfma_f32_16x16x32_bf16 v[24:27], v[158:161], v[206:209], v[24:27]
	v_mfma_f32_16x16x32_bf16 v[20:23], v[166:169], v[206:209], v[20:23]
	v_mfma_f32_16x16x32_bf16 v[8:11], v[158:161], v[214:217], v[8:11]
	v_mfma_f32_16x16x32_bf16 v[4:7], v[166:169], v[214:217], v[4:7]
	v_mfma_f32_16x16x32_bf16 v[60:63], v[170:173], v[186:189], v[60:63]
	v_mfma_f32_16x16x32_bf16 v[48:51], v[178:181], v[186:189], v[48:51]
	v_mfma_f32_16x16x32_bf16 v[44:47], v[170:173], v[194:197], v[44:47]
	v_mfma_f32_16x16x32_bf16 v[32:35], v[178:181], v[194:197], v[32:35]
	v_mfma_f32_16x16x32_bf16 v[28:31], v[170:173], v[202:205], v[28:31]
	v_mfma_f32_16x16x32_bf16 v[16:19], v[178:181], v[202:205], v[16:19]
	v_mfma_f32_16x16x32_bf16 v[12:15], v[170:173], v[210:213], v[12:15]
	v_mfma_f32_16x16x32_bf16 v[0:3], v[178:181], v[210:213], v[0:3]
	v_mfma_f32_16x16x32_bf16 v[60:63], v[174:177], v[190:193], v[60:63]
	v_mfma_f32_16x16x32_bf16 v[48:51], v[182:185], v[190:193], v[48:51]
	v_mfma_f32_16x16x32_bf16 v[44:47], v[174:177], v[198:201], v[44:47]
	v_mfma_f32_16x16x32_bf16 v[32:35], v[182:185], v[198:201], v[32:35]
	v_mfma_f32_16x16x32_bf16 v[28:31], v[174:177], v[206:209], v[28:31]
	v_mfma_f32_16x16x32_bf16 v[16:19], v[182:185], v[206:209], v[16:19]
	v_mfma_f32_16x16x32_bf16 v[12:15], v[174:177], v[214:217], v[12:15]
	v_mfma_f32_16x16x32_bf16 v[0:3], v[182:185], v[214:217], v[0:3]
	s_setprio 0
	s_barrier
	s_add_i32 s79, 0, 0x18000
	v_add_u32_e32 v157, s79, v151
	s_add_i32 s84, 0, 0x1c000
	ds_read_b128 v[144:147], v157
	ds_read_b128 v[158:161], v157 offset:1024
	ds_read_b128 v[162:165], v157 offset:2048
	ds_read_b128 v[166:169], v157 offset:3072
	v_add_u32_e32 v157, s84, v151
	ds_read_b128 v[170:173], v157
	ds_read_b128 v[174:177], v157 offset:1024
	ds_read_b128 v[178:181], v157 offset:2048
	ds_read_b128 v[182:185], v157 offset:3072
	s_add_u32 s70, s70, 0x80000
	s_addc_u32 s71, s71, 0
	s_mov_b32 m0, s39
	v_lshl_add_u64 v[224:225], s[70:71], 0, v[134:135]
	ds_read_b128 v[186:189], v155 offset:32768
	ds_read_b128 v[190:193], v155 offset:33792
	ds_read_b128 v[194:197], v155 offset:34816
	ds_read_b128 v[198:201], v155 offset:35840
	ds_read_b128 v[202:205], v155 offset:36864
	ds_read_b128 v[206:209], v155 offset:37888
	ds_read_b128 v[210:213], v155 offset:38912
	ds_read_b128 v[214:217], v155 offset:39936
	global_load_lds_dwordx4 v[224:225], off
	v_lshl_add_u64 v[224:225], s[70:71], 0, v[130:131]
	s_mov_b32 m0, s40
	s_nop 0
	global_load_lds_dwordx4 v[224:225], off
	s_waitcnt vmcnt(8)
	s_waitcnt lgkmcnt(0)
	s_barrier
	s_setprio 1
	v_mfma_f32_16x16x32_bf16 v[120:123], v[144:147], v[186:189], v[120:123]
	v_mfma_f32_16x16x32_bf16 v[116:119], v[162:165], v[186:189], v[116:119]
	v_mfma_f32_16x16x32_bf16 v[104:107], v[144:147], v[194:197], v[104:107]
	v_mfma_f32_16x16x32_bf16 v[100:103], v[162:165], v[194:197], v[100:103]
	v_mfma_f32_16x16x32_bf16 v[88:91], v[144:147], v[202:205], v[88:91]
	v_mfma_f32_16x16x32_bf16 v[84:87], v[162:165], v[202:205], v[84:87]
	v_mfma_f32_16x16x32_bf16 v[72:75], v[144:147], v[210:213], v[72:75]
	v_mfma_f32_16x16x32_bf16 v[68:71], v[162:165], v[210:213], v[68:71]
	v_mfma_f32_16x16x32_bf16 v[120:123], v[158:161], v[190:193], v[120:123]
	v_mfma_f32_16x16x32_bf16 v[116:119], v[166:169], v[190:193], v[116:119]
	v_mfma_f32_16x16x32_bf16 v[104:107], v[158:161], v[198:201], v[104:107]
	v_mfma_f32_16x16x32_bf16 v[100:103], v[166:169], v[198:201], v[100:103]
	v_mfma_f32_16x16x32_bf16 v[88:91], v[158:161], v[206:209], v[88:91]
	v_mfma_f32_16x16x32_bf16 v[84:87], v[166:169], v[206:209], v[84:87]
	v_mfma_f32_16x16x32_bf16 v[72:75], v[158:161], v[214:217], v[72:75]
	v_mfma_f32_16x16x32_bf16 v[68:71], v[166:169], v[214:217], v[68:71]
	v_mfma_f32_16x16x32_bf16 v[124:127], v[170:173], v[186:189], v[124:127]
	v_mfma_f32_16x16x32_bf16 v[112:115], v[178:181], v[186:189], v[112:115]
	v_mfma_f32_16x16x32_bf16 v[108:111], v[170:173], v[194:197], v[108:111]
	v_mfma_f32_16x16x32_bf16 v[96:99], v[178:181], v[194:197], v[96:99]
	v_mfma_f32_16x16x32_bf16 v[92:95], v[170:173], v[202:205], v[92:95]
	v_mfma_f32_16x16x32_bf16 v[80:83], v[178:181], v[202:205], v[80:83]
	v_mfma_f32_16x16x32_bf16 v[76:79], v[170:173], v[210:213], v[76:79]
	v_mfma_f32_16x16x32_bf16 v[64:67], v[178:181], v[210:213], v[64:67]
	v_mfma_f32_16x16x32_bf16 v[124:127], v[174:177], v[190:193], v[124:127]
	v_mfma_f32_16x16x32_bf16 v[112:115], v[182:185], v[190:193], v[112:115]
	v_mfma_f32_16x16x32_bf16 v[108:111], v[174:177], v[198:201], v[108:111]
	v_mfma_f32_16x16x32_bf16 v[96:99], v[182:185], v[198:201], v[96:99]
	v_mfma_f32_16x16x32_bf16 v[92:95], v[174:177], v[206:209], v[92:95]
	v_mfma_f32_16x16x32_bf16 v[80:83], v[182:185], v[206:209], v[80:83]
	v_mfma_f32_16x16x32_bf16 v[76:79], v[174:177], v[214:217], v[76:79]
	v_mfma_f32_16x16x32_bf16 v[64:67], v[182:185], v[214:217], v[64:67]
	s_setprio 0
	s_barrier
; #define PG8_STAGE(bufoff, gbase, voff) do { _Pragma("unroll") for (int _i = 0; _i < 2; ++_i) \
;         __builtin_amdgcn_global_load_lds((const unsigned*)((const char*)(gbase) + (voff)[_i]), (PG8_LAS unsigned*)(lds + (bufoff) + ldsw + _i * 8192), 16, 0, 0); } while (0)
; #define PG8_LDA(dst, b, h) do { _Pragma("unroll") for (int m = 0; m < 4; ++m) _Pragma("unroll") for (int k = 0; k < 2; ++k) dst[m][k] = *(const PG8_LAS bf16x8*)(lds + PG8_SA(b, h) + aoff + m * 2048 + k * 1024); } while (0)
; #define PG8_LDB(dst, b, h) do { _Pragma("unroll") for (int n = 0; n < 2; ++n) _Pragma("unroll") for (int k = 0; k < 2; ++k) dst[n][k] = *(const PG8_LAS bf16x8*)(lds + PG8_SB(b, h) + boff + n * 2048 + k * 1024); } while (0)
; #define PG8_MMA(ai, bj, At, Bt) do { __builtin_amdgcn_s_setprio(1); _Pragma("unroll") for (int m = 0; m < 4; ++m) _Pragma("unroll") for (int n = 0; n < 2; ++n) _Pragma("unroll") for (int k = 0; k < 2; ++k) \
;         acc[ai][bj][m][n] = __builtin_amdgcn_mfma_f32_16x16x32_bf16(Bt[n][k], At[m][k], acc[ai][bj][m][n], 0, 0, 0); __builtin_amdgcn_s_setprio(0); } while (0)
; #define PG8_BAR __builtin_amdgcn_s_barrier()
; template <class Epi, class Sched, bool ALIGN_EPI = false, bool SP2 = false>
; __device__ __forceinline__ void gemm_phase(PG8_LAS unsigned char* lds, const Gemm g, const Sched& S, const Epi& E, const int wave_in) {
;     ...
;             PG8_LDB(B0, 0, 0); PG8_LDB(B1, 0, 1); PG8_SCHED; PG8_LDA(At, 0, 0); PG8_STAGE(PG8_SA(1, 1), a1 + hstepA, voffA);
;             PG8_WAIT_V(8); PG8_WAIT_L(0); PG8_BAR; PG8_MMA(0, 0, At, B0); PG8_MMA(0, 1, At, B1); PG8_BAR; PG8_SCHED;
;             PG8_LDA(At, 0, 1); PG8_STAGE(PG8_SB(0, 0), b2, voffB); PG8_STAGE(PG8_SB(0, 1), b2 + hstep, voffB); PG8_STAGE(PG8_SA(0, 0), a2, voffA);
;             PG8_WAIT_V(8); PG8_WAIT_L(0); PG8_BAR; PG8_MMA(1, 0, At, B0); PG8_MMA(1, 1, At, B1); PG8_BAR; PG8_SCHED;
;             PG8_LDB(B0, 1, 0); PG8_LDB(B1, 1, 1); PG8_SCHED; PG8_LDA(At, 1, 0); PG8_STAGE(PG8_SA(0, 1), a2 + hstepA, voffA);
;             PG8_WAIT_V(8); PG8_WAIT_L(0); PG8_BAR; PG8_MMA(0, 0, At, B0); PG8_MMA(0, 1, At, B1); PG8_BAR; PG8_SCHED;
;             PG8_LDA(At, 1, 1); PG8_STAGE(PG8_SB(1, 0), b3, voffB); PG8_STAGE(PG8_SB(1, 1), b3 + hstep, voffB); PG8_STAGE(PG8_SA(1, 0), a3, voffA);
;             PG8_WAIT_V(8); PG8_WAIT_L(0); PG8_BAR; PG8_MMA(1, 0, At, B0); PG8_MMA(1, 1, At, B1); PG8_BAR; PG8_SCHED;
	s_add_i32 s70, s79, s11
	v_lshl_add_u64 v[148:149], v[148:149], 0, s[56:57]
	s_mov_b32 m0, s70
	ds_read_b128 v[186:189], v155 offset:49152
	ds_read_b128 v[190:193], v155 offset:50176
	ds_read_b128 v[194:197], v155 offset:51200
	ds_read_b128 v[198:201], v155 offset:52224
	ds_read_b128 v[202:205], v155 offset:53248
	ds_read_b128 v[206:209], v155 offset:54272
	ds_read_b128 v[210:213], v155 offset:55296
	ds_read_b128 v[214:217], v155 offset:56320
	global_load_lds_dwordx4 v[148:149], off
	s_add_i32 m0, s70, 0x2000
	s_add_u32 s4, s4, 0x80080
	v_lshl_add_u64 v[148:149], v[218:219], 0, s[56:57]
	s_addc_u32 s5, s5, 0
	s_add_i32 s70, s84, s11
	global_load_lds_dwordx4 v[148:149], off
	v_lshl_add_u64 v[148:149], s[4:5], 0, v[132:133]
	s_mov_b32 m0, s70
	s_nop 0
	global_load_lds_dwordx4 v[148:149], off
	v_lshl_add_u64 v[148:149], s[4:5], 0, v[128:129]
	s_add_i32 m0, s70, 0x2000
	s_nop 0
	global_load_lds_dwordx4 v[148:149], off
	v_lshl_add_u64 v[148:149], v[220:221], 0, s[56:57]
	s_mov_b32 m0, s42
	s_nop 0
	global_load_lds_dwordx4 v[148:149], off
	v_lshl_add_u64 v[148:149], v[222:223], 0, s[56:57]
	s_mov_b32 m0, s43
	s_nop 0
	global_load_lds_dwordx4 v[148:149], off
	s_waitcnt vmcnt(8)
	s_waitcnt lgkmcnt(0)
	s_barrier
	s_setprio 1
	v_mfma_f32_16x16x32_bf16 v[56:59], v[144:147], v[186:189], v[56:59]
	v_mfma_f32_16x16x32_bf16 v[52:55], v[162:165], v[186:189], v[52:55]
	v_mfma_f32_16x16x32_bf16 v[40:43], v[144:147], v[194:197], v[40:43]
	v_mfma_f32_16x16x32_bf16 v[36:39], v[162:165], v[194:197], v[36:39]
	v_mfma_f32_16x16x32_bf16 v[24:27], v[144:147], v[202:205], v[24:27]
	v_mfma_f32_16x16x32_bf16 v[20:23], v[162:165], v[202:205], v[20:23]
	v_mfma_f32_16x16x32_bf16 v[8:11], v[144:147], v[210:213], v[8:11]
	v_mfma_f32_16x16x32_bf16 v[4:7], v[162:165], v[210:213], v[4:7]
	v_mfma_f32_16x16x32_bf16 v[56:59], v[158:161], v[190:193], v[56:59]
	v_mfma_f32_16x16x32_bf16 v[52:55], v[166:169], v[190:193], v[52:55]
	v_mfma_f32_16x16x32_bf16 v[40:43], v[158:161], v[198:201], v[40:43]
	v_mfma_f32_16x16x32_bf16 v[36:39], v[166:169], v[198:201], v[36:39]
	v_mfma_f32_16x16x32_bf16 v[24:27], v[158:161], v[206:209], v[24:27]
	v_mfma_f32_16x16x32_bf16 v[20:23], v[166:169], v[206:209], v[20:23]
	v_mfma_f32_16x16x32_bf16 v[8:11], v[158:161], v[214:217], v[8:11]
	v_mfma_f32_16x16x32_bf16 v[4:7], v[166:169], v[214:217], v[4:7]
	v_mfma_f32_16x16x32_bf16 v[60:63], v[170:173], v[186:189], v[60:63]
	v_mfma_f32_16x16x32_bf16 v[48:51], v[178:181], v[186:189], v[48:51]
	v_mfma_f32_16x16x32_bf16 v[44:47], v[170:173], v[194:197], v[44:47]
	v_mfma_f32_16x16x32_bf16 v[32:35], v[178:181], v[194:197], v[32:35]
	v_mfma_f32_16x16x32_bf16 v[28:31], v[170:173], v[202:205], v[28:31]
	v_mfma_f32_16x16x32_bf16 v[16:19], v[178:181], v[202:205], v[16:19]
	v_mfma_f32_16x16x32_bf16 v[12:15], v[170:173], v[210:213], v[12:15]
	v_mfma_f32_16x16x32_bf16 v[0:3], v[178:181], v[210:213], v[0:3]
	v_mfma_f32_16x16x32_bf16 v[60:63], v[174:177], v[190:193], v[60:63]
	v_mfma_f32_16x16x32_bf16 v[48:51], v[182:185], v[190:193], v[48:51]
	v_mfma_f32_16x16x32_bf16 v[44:47], v[174:177], v[198:201], v[44:47]
	v_mfma_f32_16x16x32_bf16 v[32:35], v[182:185], v[198:201], v[32:35]
	v_mfma_f32_16x16x32_bf16 v[28:31], v[174:177], v[206:209], v[28:31]
	v_mfma_f32_16x16x32_bf16 v[16:19], v[182:185], v[206:209], v[16:19]
	v_mfma_f32_16x16x32_bf16 v[12:15], v[174:177], v[214:217], v[12:15]
	v_mfma_f32_16x16x32_bf16 v[0:3], v[182:185], v[214:217], v[0:3]
	s_setprio 0
	s_barrier
	s_add_i32 s78, s78, 2
	s_add_u32 s68, s68, 0x100
	s_addc_u32 s69, s69, 0
	s_add_u32 s72, s72, 0x100
	s_addc_u32 s73, s73, 0
	s_cmp_gt_u32 s78, 29
	s_cbranch_scc0 .LBB0_498
	s_and_b64 vcc, exec, s[58:59]
	s_cbranch_vccz .LBB0_501
	s_barrier

; #define PG8_STAGE(bufoff, gbase, voff) do { _Pragma("unroll") for (int _i = 0; _i < 2; ++_i) \
;         __builtin_amdgcn_global_load_lds((const unsigned*)((const char*)(gbase) + (voff)[_i]), (PG8_LAS unsigned*)(lds + (bufoff) + ldsw + _i * 8192), 16, 0, 0); } while (0)
; #define PG8_LDA(dst, b, h) do { _Pragma("unroll") for (int m = 0; m < 4; ++m) _Pragma("unroll") for (int k = 0; k < 2; ++k) dst[m][k] = *(const PG8_LAS bf16x8*)(lds + PG8_SA(b, h) + aoff + m * 2048 + k * 1024); } while (0)
; #define PG8_LDB(dst, b, h) do { _Pragma("unroll") for (int n = 0; n < 2; ++n) _Pragma("unroll") for (int k = 0; k < 2; ++k) dst[n][k] = *(const PG8_LAS bf16x8*)(lds + PG8_SB(b, h) + boff + n * 2048 + k * 1024); } while (0)
; #define PG8_MMA(ai, bj, At, Bt) do { __builtin_amdgcn_s_setprio(1); _Pragma("unroll") for (int m = 0; m < 4; ++m) _Pragma("unroll") for (int n = 0; n < 2; ++n) _Pragma("unroll") for (int k = 0; k < 2; ++k) \
;         acc[ai][bj][m][n] = __builtin_amdgcn_mfma_f32_16x16x32_bf16(Bt[n][k], At[m][k], acc[ai][bj][m][n], 0, 0, 0); __builtin_amdgcn_s_setprio(0); } while (0)
; #define PG8_BAR __builtin_amdgcn_s_barrier()
; template <class Epi, class Sched, bool ALIGN_EPI = false, bool SP2 = false>
; __device__ __forceinline__ void gemm_phase(PG8_LAS unsigned char* lds, const Gemm g, const Sched& S, const Epi& E, const int wave_in) {
;     ...
;             PG8_LDB(B0, 0, 0); PG8_LDB(B1, 0, 1); PG8_SCHED; PG8_LDA(At, 0, 0); PG8_STAGE(PG8_SA(1, 1), a1 + hstepA, voffA);
;             PG8_WAIT_V(8); PG8_WAIT_L(0); PG8_BAR; PG8_MMA(0, 0, At, B0); PG8_MMA(0, 1, At, B1); PG8_BAR; PG8_SCHED;
;             PG8_LDA(At, 0, 1); PG8_STAGE(PG8_SB(0, 0), b2, voffB); PG8_STAGE(PG8_SB(0, 1), b2 + hstep, voffB); PG8_STAGE(PG8_SA(0, 0), a2, voffA);
;             PG8_WAIT_V(8); PG8_WAIT_L(0); PG8_BAR; PG8_MMA(1, 0, At, B0); PG8_MMA(1, 1, At, B1); PG8_BAR; PG8_SCHED;
;             PG8_LDB(B0, 1, 0); PG8_LDB(B1, 1, 1); PG8_SCHED; PG8_LDA(At, 1, 0); PG8_STAGE(PG8_SA(0, 1), a2 + hstepA, voffA);
;             PG8_WAIT_V(8); PG8_WAIT_L(0); PG8_BAR; PG8_MMA(0, 0, At, B0); PG8_MMA(0, 1, At, B1); PG8_BAR; PG8_SCHED;
;             PG8_LDA(At, 1, 1); PG8_STAGE(PG8_SB(1, 0), b3, voffB); PG8_STAGE(PG8_SB(1, 1), b3 + hstep, voffB); PG8_STAGE(PG8_SA(1, 0), a3, voffA);
;             PG8_WAIT_V(8); PG8_WAIT_L(0); PG8_BAR; PG8_MMA(1, 0, At, B0); PG8_MMA(1, 1, At, B1); PG8_BAR; PG8_SCHED;
.LBB0_583:
	ds_read_b128 v[144:147], v151
	ds_read_b128 v[156:159], v151 offset:1024
	ds_read_b128 v[160:163], v151 offset:2048
	ds_read_b128 v[164:167], v151 offset:3072
	ds_read_b128 v[168:171], v152
	ds_read_b128 v[172:175], v152 offset:1024
	ds_read_b128 v[176:179], v152 offset:2048
	ds_read_b128 v[180:183], v152 offset:3072
	s_add_u32 s64, s62, 0x100
	s_addc_u32 s65, s63, 0
	s_cmpk_eq_i32 s72, 0x54
	s_cselect_b32 s69, s7, s65
	s_cselect_b32 s68, s6, s64
	s_cselect_b32 s67, s61, s71
	s_cselect_b32 s66, s60, s70
	v_lshl_add_u64 v[216:217], s[62:63], 0, v[136:137]
	s_add_i32 m0, s33, 0xc000
	ds_read_b128 v[184:187], v153
	ds_read_b128 v[188:191], v153 offset:1024
	ds_read_b128 v[192:195], v153 offset:2048
	ds_read_b128 v[196:199], v153 offset:3072
	ds_read_b128 v[200:203], v153 offset:4096
	ds_read_b128 v[204:207], v153 offset:5120
	ds_read_b128 v[208:211], v153 offset:6144
	ds_read_b128 v[212:215], v153 offset:7168
	global_load_lds_dwordx4 v[216:217], off
	v_lshl_add_u64 v[216:217], s[62:63], 0, v[138:139]
	s_add_i32 m0, s33, 0xe000
	s_nop 0
	global_load_lds_dwordx4 v[216:217], off
	s_waitcnt vmcnt(8)
	s_waitcnt lgkmcnt(0)
	s_barrier
	s_setprio 1
	v_mfma_f32_16x16x32_bf16 v[124:127], v[144:147], v[184:187], v[124:127]
	v_mfma_f32_16x16x32_bf16 v[120:123], v[160:163], v[184:187], v[120:123]
	v_mfma_f32_16x16x32_bf16 v[108:111], v[144:147], v[192:195], v[108:111]
	v_mfma_f32_16x16x32_bf16 v[104:107], v[160:163], v[192:195], v[104:107]
	v_mfma_f32_16x16x32_bf16 v[92:95], v[144:147], v[200:203], v[92:95]
	v_mfma_f32_16x16x32_bf16 v[88:91], v[160:163], v[200:203], v[88:91]
	v_mfma_f32_16x16x32_bf16 v[76:79], v[144:147], v[208:211], v[76:79]
	v_mfma_f32_16x16x32_bf16 v[72:75], v[160:163], v[208:211], v[72:75]
	v_mfma_f32_16x16x32_bf16 v[124:127], v[156:159], v[188:191], v[124:127]
	v_mfma_f32_16x16x32_bf16 v[120:123], v[164:167], v[188:191], v[120:123]
	v_mfma_f32_16x16x32_bf16 v[108:111], v[156:159], v[196:199], v[108:111]
	v_mfma_f32_16x16x32_bf16 v[104:107], v[164:167], v[196:199], v[104:107]
	v_mfma_f32_16x16x32_bf16 v[92:95], v[156:159], v[204:207], v[92:95]
	v_mfma_f32_16x16x32_bf16 v[88:91], v[164:167], v[204:207], v[88:91]
	v_mfma_f32_16x16x32_bf16 v[76:79], v[156:159], v[212:215], v[76:79]
	v_mfma_f32_16x16x32_bf16 v[72:75], v[164:167], v[212:215], v[72:75]
	v_mfma_f32_16x16x32_bf16 v[116:119], v[168:171], v[184:187], v[116:119]
	v_mfma_f32_16x16x32_bf16 v[112:115], v[176:179], v[184:187], v[112:115]
	v_mfma_f32_16x16x32_bf16 v[100:103], v[168:171], v[192:195], v[100:103]
	v_mfma_f32_16x16x32_bf16 v[96:99], v[176:179], v[192:195], v[96:99]
	v_mfma_f32_16x16x32_bf16 v[84:87], v[168:171], v[200:203], v[84:87]
	v_mfma_f32_16x16x32_bf16 v[80:83], v[176:179], v[200:203], v[80:83]
	v_mfma_f32_16x16x32_bf16 v[68:71], v[168:171], v[208:211], v[68:71]
	v_mfma_f32_16x16x32_bf16 v[64:67], v[176:179], v[208:211], v[64:67]
	v_mfma_f32_16x16x32_bf16 v[116:119], v[172:175], v[188:191], v[116:119]
	v_mfma_f32_16x16x32_bf16 v[112:115], v[180:183], v[188:191], v[112:115]
	v_mfma_f32_16x16x32_bf16 v[100:103], v[172:175], v[196:199], v[100:103]
	v_mfma_f32_16x16x32_bf16 v[96:99], v[180:183], v[196:199], v[96:99]
	v_mfma_f32_16x16x32_bf16 v[84:87], v[172:175], v[204:207], v[84:87]
	v_mfma_f32_16x16x32_bf16 v[80:83], v[180:183], v[204:207], v[80:83]
	v_mfma_f32_16x16x32_bf16 v[68:71], v[172:175], v[212:215], v[68:71]
	v_mfma_f32_16x16x32_bf16 v[64:67], v[180:183], v[212:215], v[64:67]
	s_setprio 0
	s_barrier
	s_add_i32 s62, s48, s11
	v_lshl_add_u64 v[216:217], s[66:67], 0, v[130:131]
	s_mov_b32 m0, s62
	ds_read_b128 v[184:187], v153 offset:16384
	ds_read_b128 v[188:191], v153 offset:17408
	ds_read_b128 v[192:195], v153 offset:18432
	ds_read_b128 v[196:199], v153 offset:19456
	ds_read_b128 v[200:203], v153 offset:20480
	ds_read_b128 v[204:207], v153 offset:21504
	ds_read_b128 v[208:211], v153 offset:22528
	ds_read_b128 v[212:215], v153 offset:23552
	global_load_lds_dwordx4 v[216:217], off
	s_add_i32 m0, s62, 0x2000
	s_add_u32 s62, s66, 0x160000
	v_lshl_add_u64 v[218:219], s[66:67], 0, v[134:135]
	s_addc_u32 s63, s67, 0
	s_add_i32 s73, s49, s11
	global_load_lds_dwordx4 v[218:219], off
	v_lshl_add_u64 v[220:221], s[62:63], 0, v[130:131]
	s_mov_b32 m0, s73
	v_lshl_add_u64 v[222:223], s[68:69], 0, v[132:133]
	global_load_lds_dwordx4 v[220:221], off
	v_lshl_add_u64 v[220:221], s[62:63], 0, v[134:135]
	s_add_i32 m0, s73, 0x2000
	s_nop 0
	global_load_lds_dwordx4 v[220:221], off
	v_lshl_add_u64 v[220:221], s[68:69], 0, v[128:129]
	s_mov_b32 m0, s33
	s_nop 0
	global_load_lds_dwordx4 v[220:221], off
	s_mov_b32 m0, s35
	s_nop 0
	global_load_lds_dwordx4 v[222:223], off
	s_waitcnt vmcnt(8)
	s_waitcnt lgkmcnt(0)
	s_barrier
; #define PG8_STAGE(bufoff, gbase, voff) do { _Pragma("unroll") for (int _i = 0; _i < 2; ++_i) \
;         __builtin_amdgcn_global_load_lds((const unsigned*)((const char*)(gbase) + (voff)[_i]), (PG8_LAS unsigned*)(lds + (bufoff) + ldsw + _i * 8192), 16, 0, 0); } while (0)
; #define PG8_LDA(dst, b, h) do { _Pragma("unroll") for (int m = 0; m < 4; ++m) _Pragma("unroll") for (int k = 0; k < 2; ++k) dst[m][k] = *(const PG8_LAS bf16x8*)(lds + PG8_SA(b, h) + aoff + m * 2048 + k * 1024); } while (0)
; #define PG8_LDB(dst, b, h) do { _Pragma("unroll") for (int n = 0; n < 2; ++n) _Pragma("unroll") for (int k = 0; k < 2; ++k) dst[n][k] = *(const PG8_LAS bf16x8*)(lds + PG8_SB(b, h) + boff + n * 2048 + k * 1024); } while (0)
; #define PG8_MMA(ai, bj, At, Bt) do { __builtin_amdgcn_s_setprio(1); _Pragma("unroll") for (int m = 0; m < 4; ++m) _Pragma("unroll") for (int n = 0; n < 2; ++n) _Pragma("unroll") for (int k = 0; k < 2; ++k) \
;         acc[ai][bj][m][n] = __builtin_amdgcn_mfma_f32_16x16x32_bf16(Bt[n][k], At[m][k], acc[ai][bj][m][n], 0, 0, 0); __builtin_amdgcn_s_setprio(0); } while (0)
; #define PG8_BAR __builtin_amdgcn_s_barrier()
; template <class Epi, class Sched, bool ALIGN_EPI = false, bool SP2 = false>
; __device__ __forceinline__ void gemm_phase(PG8_LAS unsigned char* lds, const Gemm g, const Sched& S, const Epi& E, const int wave_in) {
;     ...
;             PG8_LDB(B0, 0, 0); PG8_LDB(B1, 0, 1); PG8_SCHED; PG8_LDA(At, 0, 0); PG8_STAGE(PG8_SA(1, 1), a1 + hstepA, voffA);
;             PG8_WAIT_V(8); PG8_WAIT_L(0); PG8_BAR; PG8_MMA(0, 0, At, B0); PG8_MMA(0, 1, At, B1); PG8_BAR; PG8_SCHED;
;             PG8_LDA(At, 0, 1); PG8_STAGE(PG8_SB(0, 0), b2, voffB); PG8_STAGE(PG8_SB(0, 1), b2 + hstep, voffB); PG8_STAGE(PG8_SA(0, 0), a2, voffA);
;             PG8_WAIT_V(8); PG8_WAIT_L(0); PG8_BAR; PG8_MMA(1, 0, At, B0); PG8_MMA(1, 1, At, B1); PG8_BAR; PG8_SCHED;
;             PG8_LDB(B0, 1, 0); PG8_LDB(B1, 1, 1); PG8_SCHED; PG8_LDA(At, 1, 0); PG8_STAGE(PG8_SA(0, 1), a2 + hstepA, voffA);
;             PG8_WAIT_V(8); PG8_WAIT_L(0); PG8_BAR; PG8_MMA(0, 0, At, B0); PG8_MMA(0, 1, At, B1); PG8_BAR; PG8_SCHED;
;             PG8_LDA(At, 1, 1); PG8_STAGE(PG8_SB(1, 0), b3, voffB); PG8_STAGE(PG8_SB(1, 1), b3 + hstep, voffB); PG8_STAGE(PG8_SA(1, 0), a3, voffA);
;             PG8_WAIT_V(8); PG8_WAIT_L(0); PG8_BAR; PG8_MMA(1, 0, At, B0); PG8_MMA(1, 1, At, B1); PG8_BAR; PG8_SCHED;
	s_setprio 1
	v_mfma_f32_16x16x32_bf16 v[60:63], v[144:147], v[184:187], v[60:63]
	v_mfma_f32_16x16x32_bf16 v[56:59], v[160:163], v[184:187], v[56:59]
	v_mfma_f32_16x16x32_bf16 v[44:47], v[144:147], v[192:195], v[44:47]
	v_mfma_f32_16x16x32_bf16 v[40:43], v[160:163], v[192:195], v[40:43]
	v_mfma_f32_16x16x32_bf16 v[28:31], v[144:147], v[200:203], v[28:31]
	v_mfma_f32_16x16x32_bf16 v[24:27], v[160:163], v[200:203], v[24:27]
	v_mfma_f32_16x16x32_bf16 v[12:15], v[144:147], v[208:211], v[12:15]
	v_mfma_f32_16x16x32_bf16 v[8:11], v[160:163], v[208:211], v[8:11]
	v_mfma_f32_16x16x32_bf16 v[60:63], v[156:159], v[188:191], v[60:63]
	v_mfma_f32_16x16x32_bf16 v[56:59], v[164:167], v[188:191], v[56:59]
	v_mfma_f32_16x16x32_bf16 v[44:47], v[156:159], v[196:199], v[44:47]
	v_mfma_f32_16x16x32_bf16 v[40:43], v[164:167], v[196:199], v[40:43]
	v_mfma_f32_16x16x32_bf16 v[28:31], v[156:159], v[204:207], v[28:31]
	v_mfma_f32_16x16x32_bf16 v[24:27], v[164:167], v[204:207], v[24:27]
	v_mfma_f32_16x16x32_bf16 v[12:15], v[156:159], v[212:215], v[12:15]
	v_mfma_f32_16x16x32_bf16 v[8:11], v[164:167], v[212:215], v[8:11]
	v_mfma_f32_16x16x32_bf16 v[52:55], v[168:171], v[184:187], v[52:55]
	v_mfma_f32_16x16x32_bf16 v[48:51], v[176:179], v[184:187], v[48:51]
	v_mfma_f32_16x16x32_bf16 v[36:39], v[168:171], v[192:195], v[36:39]
	v_mfma_f32_16x16x32_bf16 v[32:35], v[176:179], v[192:195], v[32:35]
	v_mfma_f32_16x16x32_bf16 v[20:23], v[168:171], v[200:203], v[20:23]
	v_mfma_f32_16x16x32_bf16 v[16:19], v[176:179], v[200:203], v[16:19]
	v_mfma_f32_16x16x32_bf16 v[4:7], v[168:171], v[208:211], v[4:7]
	v_mfma_f32_16x16x32_bf16 v[0:3], v[176:179], v[208:211], v[0:3]
	v_mfma_f32_16x16x32_bf16 v[52:55], v[172:175], v[188:191], v[52:55]
	v_mfma_f32_16x16x32_bf16 v[48:51], v[180:183], v[188:191], v[48:51]
	v_mfma_f32_16x16x32_bf16 v[36:39], v[172:175], v[196:199], v[36:39]
	v_mfma_f32_16x16x32_bf16 v[32:35], v[180:183], v[196:199], v[32:35]
	v_mfma_f32_16x16x32_bf16 v[20:23], v[172:175], v[204:207], v[20:23]
	v_mfma_f32_16x16x32_bf16 v[16:19], v[180:183], v[204:207], v[16:19]
	v_mfma_f32_16x16x32_bf16 v[4:7], v[172:175], v[212:215], v[4:7]
	v_mfma_f32_16x16x32_bf16 v[0:3], v[180:183], v[212:215], v[0:3]
	s_setprio 0
	s_barrier
	s_add_i32 s73, 0, 0x18000
	v_add_u32_e32 v155, s73, v149
	s_add_i32 s78, 0, 0x1c000
	ds_read_b128 v[144:147], v155
	ds_read_b128 v[156:159], v155 offset:1024
	ds_read_b128 v[160:163], v155 offset:2048
	ds_read_b128 v[164:167], v155 offset:3072
	v_add_u32_e32 v155, s78, v149
	ds_read_b128 v[168:171], v155
	ds_read_b128 v[172:175], v155 offset:1024
	ds_read_b128 v[176:179], v155 offset:2048
	ds_read_b128 v[180:183], v155 offset:3072
	s_add_u32 s62, s68, 0x160000
	s_addc_u32 s63, s69, 0
	s_mov_b32 m0, s38
	v_lshl_add_u64 v[224:225], s[62:63], 0, v[128:129]
	ds_read_b128 v[184:187], v153 offset:32768
	ds_read_b128 v[188:191], v153 offset:33792
	ds_read_b128 v[192:195], v153 offset:34816
	ds_read_b128 v[196:199], v153 offset:35840
	ds_read_b128 v[200:203], v153 offset:36864
	ds_read_b128 v[204:207], v153 offset:37888
	ds_read_b128 v[208:211], v153 offset:38912
	ds_read_b128 v[212:215], v153 offset:39936
	global_load_lds_dwordx4 v[224:225], off
	v_lshl_add_u64 v[224:225], s[62:63], 0, v[132:133]
	s_mov_b32 m0, s39
	s_nop 0
	global_load_lds_dwordx4 v[224:225], off
	s_waitcnt vmcnt(8)
	s_waitcnt lgkmcnt(0)
	s_barrier
	s_setprio 1
	v_mfma_f32_16x16x32_bf16 v[124:127], v[144:147], v[184:187], v[124:127]
	v_mfma_f32_16x16x32_bf16 v[120:123], v[160:163], v[184:187], v[120:123]
	v_mfma_f32_16x16x32_bf16 v[108:111], v[144:147], v[192:195], v[108:111]
	v_mfma_f32_16x16x32_bf16 v[104:107], v[160:163], v[192:195], v[104:107]
	v_mfma_f32_16x16x32_bf16 v[92:95], v[144:147], v[200:203], v[92:95]
	v_mfma_f32_16x16x32_bf16 v[88:91], v[160:163], v[200:203], v[88:91]
	v_mfma_f32_16x16x32_bf16 v[76:79], v[144:147], v[208:211], v[76:79]
	v_mfma_f32_16x16x32_bf16 v[72:75], v[160:163], v[208:211], v[72:75]
	v_mfma_f32_16x16x32_bf16 v[124:127], v[156:159], v[188:191], v[124:127]
	v_mfma_f32_16x16x32_bf16 v[120:123], v[164:167], v[188:191], v[120:123]
	v_mfma_f32_16x16x32_bf16 v[108:111], v[156:159], v[196:199], v[108:111]
	v_mfma_f32_16x16x32_bf16 v[104:107], v[164:167], v[196:199], v[104:107]
	v_mfma_f32_16x16x32_bf16 v[92:95], v[156:159], v[204:207], v[92:95]
	v_mfma_f32_16x16x32_bf16 v[88:91], v[164:167], v[204:207], v[88:91]
	v_mfma_f32_16x16x32_bf16 v[76:79], v[156:159], v[212:215], v[76:79]
	v_mfma_f32_16x16x32_bf16 v[72:75], v[164:167], v[212:215], v[72:75]
	v_mfma_f32_16x16x32_bf16 v[116:119], v[168:171], v[184:187], v[116:119]
	v_mfma_f32_16x16x32_bf16 v[112:115], v[176:179], v[184:187], v[112:115]
	v_mfma_f32_16x16x32_bf16 v[100:103], v[168:171], v[192:195], v[100:103]
	v_mfma_f32_16x16x32_bf16 v[96:99], v[176:179], v[192:195], v[96:99]
	v_mfma_f32_16x16x32_bf16 v[84:87], v[168:171], v[200:203], v[84:87]
	v_mfma_f32_16x16x32_bf16 v[80:83], v[176:179], v[200:203], v[80:83]
	v_mfma_f32_16x16x32_bf16 v[68:71], v[168:171], v[208:211], v[68:71]
	v_mfma_f32_16x16x32_bf16 v[64:67], v[176:179], v[208:211], v[64:67]
	v_mfma_f32_16x16x32_bf16 v[116:119], v[172:175], v[188:191], v[116:119]
	v_mfma_f32_16x16x32_bf16 v[112:115], v[180:183], v[188:191], v[112:115]
	v_mfma_f32_16x16x32_bf16 v[100:103], v[172:175], v[196:199], v[100:103]
	v_mfma_f32_16x16x32_bf16 v[96:99], v[180:183], v[196:199], v[96:99]
	v_mfma_f32_16x16x32_bf16 v[84:87], v[172:175], v[204:207], v[84:87]
	v_mfma_f32_16x16x32_bf16 v[80:83], v[180:183], v[204:207], v[80:83]
	v_mfma_f32_16x16x32_bf16 v[68:71], v[172:175], v[212:215], v[68:71]
	v_mfma_f32_16x16x32_bf16 v[64:67], v[180:183], v[212:215], v[64:67]
	s_setprio 0
	s_barrier
; #define PG8_STAGE(bufoff, gbase, voff) do { _Pragma("unroll") for (int _i = 0; _i < 2; ++_i) \
;         __builtin_amdgcn_global_load_lds((const unsigned*)((const char*)(gbase) + (voff)[_i]), (PG8_LAS unsigned*)(lds + (bufoff) + ldsw + _i * 8192), 16, 0, 0); } while (0)
; #define PG8_LDA(dst, b, h) do { _Pragma("unroll") for (int m = 0; m < 4; ++m) _Pragma("unroll") for (int k = 0; k < 2; ++k) dst[m][k] = *(const PG8_LAS bf16x8*)(lds + PG8_SA(b, h) + aoff + m * 2048 + k * 1024); } while (0)
; #define PG8_LDB(dst, b, h) do { _Pragma("unroll") for (int n = 0; n < 2; ++n) _Pragma("unroll") for (int k = 0; k < 2; ++k) dst[n][k] = *(const PG8_LAS bf16x8*)(lds + PG8_SB(b, h) + boff + n * 2048 + k * 1024); } while (0)
; #define PG8_MMA(ai, bj, At, Bt) do { __builtin_amdgcn_s_setprio(1); _Pragma("unroll") for (int m = 0; m < 4; ++m) _Pragma("unroll") for (int n = 0; n < 2; ++n) _Pragma("unroll") for (int k = 0; k < 2; ++k) \
;         acc[ai][bj][m][n] = __builtin_amdgcn_mfma_f32_16x16x32_bf16(Bt[n][k], At[m][k], acc[ai][bj][m][n], 0, 0, 0); __builtin_amdgcn_s_setprio(0); } while (0)
; #define PG8_BAR __builtin_amdgcn_s_barrier()
; template <class Epi, class Sched, bool ALIGN_EPI = false, bool SP2 = false>
; __device__ __forceinline__ void gemm_phase(PG8_LAS unsigned char* lds, const Gemm g, const Sched& S, const Epi& E, const int wave_in) {
;     ...
;             PG8_LDB(B0, 0, 0); PG8_LDB(B1, 0, 1); PG8_SCHED; PG8_LDA(At, 0, 0); PG8_STAGE(PG8_SA(1, 1), a1 + hstepA, voffA);
;             PG8_WAIT_V(8); PG8_WAIT_L(0); PG8_BAR; PG8_MMA(0, 0, At, B0); PG8_MMA(0, 1, At, B1); PG8_BAR; PG8_SCHED;
;             PG8_LDA(At, 0, 1); PG8_STAGE(PG8_SB(0, 0), b2, voffB); PG8_STAGE(PG8_SB(0, 1), b2 + hstep, voffB); PG8_STAGE(PG8_SA(0, 0), a2, voffA);
;             PG8_WAIT_V(8); PG8_WAIT_L(0); PG8_BAR; PG8_MMA(1, 0, At, B0); PG8_MMA(1, 1, At, B1); PG8_BAR; PG8_SCHED;
;             PG8_LDB(B0, 1, 0); PG8_LDB(B1, 1, 1); PG8_SCHED; PG8_LDA(At, 1, 0); PG8_STAGE(PG8_SA(0, 1), a2 + hstepA, voffA);
;             PG8_WAIT_V(8); PG8_WAIT_L(0); PG8_BAR; PG8_MMA(0, 0, At, B0); PG8_MMA(0, 1, At, B1); PG8_BAR; PG8_SCHED;
;             PG8_LDA(At, 1, 1); PG8_STAGE(PG8_SB(1, 0), b3, voffB); PG8_STAGE(PG8_SB(1, 1), b3 + hstep, voffB); PG8_STAGE(PG8_SA(1, 0), a3, voffA);
;             PG8_WAIT_V(8); PG8_WAIT_L(0); PG8_BAR; PG8_MMA(1, 0, At, B0); PG8_MMA(1, 1, At, B1); PG8_BAR; PG8_SCHED;
	s_add_i32 s62, s73, s11
	v_lshl_add_u64 v[216:217], v[216:217], 0, s[56:57]
	s_mov_b32 m0, s62
	ds_read_b128 v[184:187], v153 offset:49152
	ds_read_b128 v[188:191], v153 offset:50176
	ds_read_b128 v[192:195], v153 offset:51200
	ds_read_b128 v[196:199], v153 offset:52224
	ds_read_b128 v[200:203], v153 offset:53248
	ds_read_b128 v[204:207], v153 offset:54272
	ds_read_b128 v[208:211], v153 offset:55296
	ds_read_b128 v[212:215], v153 offset:56320
	global_load_lds_dwordx4 v[216:217], off
	s_add_i32 m0, s62, 0x2000
	s_add_u32 s62, s66, 0x160080
	v_lshl_add_u64 v[216:217], v[218:219], 0, s[56:57]
	s_addc_u32 s63, s67, 0
	s_add_i32 s66, s78, s11
	global_load_lds_dwordx4 v[216:217], off
	v_lshl_add_u64 v[216:217], s[62:63], 0, v[130:131]
	s_mov_b32 m0, s66
	s_nop 0
	global_load_lds_dwordx4 v[216:217], off
	v_lshl_add_u64 v[216:217], s[62:63], 0, v[134:135]
	s_add_i32 m0, s66, 0x2000
	s_nop 0
	global_load_lds_dwordx4 v[216:217], off
	v_lshl_add_u64 v[216:217], v[220:221], 0, s[56:57]
	s_mov_b32 m0, s41
	s_nop 0
	global_load_lds_dwordx4 v[216:217], off
	v_lshl_add_u64 v[216:217], v[222:223], 0, s[56:57]
	s_mov_b32 m0, s42
	s_nop 0
	global_load_lds_dwordx4 v[216:217], off
	s_waitcnt vmcnt(8)
	s_waitcnt lgkmcnt(0)
	s_barrier
	s_setprio 1
	v_mfma_f32_16x16x32_bf16 v[60:63], v[144:147], v[184:187], v[60:63]
	v_mfma_f32_16x16x32_bf16 v[56:59], v[160:163], v[184:187], v[56:59]
	v_mfma_f32_16x16x32_bf16 v[44:47], v[144:147], v[192:195], v[44:47]
	v_mfma_f32_16x16x32_bf16 v[40:43], v[160:163], v[192:195], v[40:43]
	v_mfma_f32_16x16x32_bf16 v[28:31], v[144:147], v[200:203], v[28:31]
	v_mfma_f32_16x16x32_bf16 v[24:27], v[160:163], v[200:203], v[24:27]
	v_mfma_f32_16x16x32_bf16 v[12:15], v[144:147], v[208:211], v[12:15]
	v_mfma_f32_16x16x32_bf16 v[8:11], v[160:163], v[208:211], v[8:11]
	v_mfma_f32_16x16x32_bf16 v[60:63], v[156:159], v[188:191], v[60:63]
	v_mfma_f32_16x16x32_bf16 v[56:59], v[164:167], v[188:191], v[56:59]
	v_mfma_f32_16x16x32_bf16 v[44:47], v[156:159], v[196:199], v[44:47]
	v_mfma_f32_16x16x32_bf16 v[40:43], v[164:167], v[196:199], v[40:43]
	v_mfma_f32_16x16x32_bf16 v[28:31], v[156:159], v[204:207], v[28:31]
	v_mfma_f32_16x16x32_bf16 v[24:27], v[164:167], v[204:207], v[24:27]
	v_mfma_f32_16x16x32_bf16 v[12:15], v[156:159], v[212:215], v[12:15]
	v_mfma_f32_16x16x32_bf16 v[8:11], v[164:167], v[212:215], v[8:11]
	v_mfma_f32_16x16x32_bf16 v[52:55], v[168:171], v[184:187], v[52:55]
	v_mfma_f32_16x16x32_bf16 v[48:51], v[176:179], v[184:187], v[48:51]
	v_mfma_f32_16x16x32_bf16 v[36:39], v[168:171], v[192:195], v[36:39]
	v_mfma_f32_16x16x32_bf16 v[32:35], v[176:179], v[192:195], v[32:35]
	v_mfma_f32_16x16x32_bf16 v[20:23], v[168:171], v[200:203], v[20:23]
	v_mfma_f32_16x16x32_bf16 v[16:19], v[176:179], v[200:203], v[16:19]
	v_mfma_f32_16x16x32_bf16 v[4:7], v[168:171], v[208:211], v[4:7]
	v_mfma_f32_16x16x32_bf16 v[0:3], v[176:179], v[208:211], v[0:3]
	v_mfma_f32_16x16x32_bf16 v[52:55], v[172:175], v[188:191], v[52:55]
	v_mfma_f32_16x16x32_bf16 v[48:51], v[180:183], v[188:191], v[48:51]
	v_mfma_f32_16x16x32_bf16 v[36:39], v[172:175], v[196:199], v[36:39]
	v_mfma_f32_16x16x32_bf16 v[32:35], v[180:183], v[196:199], v[32:35]
	v_mfma_f32_16x16x32_bf16 v[20:23], v[172:175], v[204:207], v[20:23]
	v_mfma_f32_16x16x32_bf16 v[16:19], v[180:183], v[204:207], v[16:19]
	v_mfma_f32_16x16x32_bf16 v[4:7], v[172:175], v[212:215], v[4:7]
	v_mfma_f32_16x16x32_bf16 v[0:3], v[180:183], v[212:215], v[0:3]
	s_setprio 0
	s_barrier
	s_add_i32 s72, s72, 2
	s_add_u32 s70, s70, 0x100
	s_addc_u32 s71, s71, 0
	s_cmpk_gt_u32 s72, 0x55
	s_mov_b64 s[62:63], s[64:65]
	s_cbranch_scc0 .LBB0_583
	s_and_b64 vcc, exec, s[58:59]
	s_cbranch_vccz .LBB0_586
	s_barrier

; #define PG8_STAGE(bufoff, gbase, voff) do { _Pragma("unroll") for (int _i = 0; _i < 2; ++_i) \
;         __builtin_amdgcn_global_load_lds((const unsigned*)((const char*)(gbase) + (voff)[_i]), (PG8_LAS unsigned*)(lds + (bufoff) + ldsw + _i * 8192), 16, 0, 0); } while (0)
; #define PG8_LDA(dst, b, h) do { _Pragma("unroll") for (int m = 0; m < 4; ++m) _Pragma("unroll") for (int k = 0; k < 2; ++k) dst[m][k] = *(const PG8_LAS bf16x8*)(lds + PG8_SA(b, h) + aoff + m * 2048 + k * 1024); } while (0)
; #define PG8_LDB(dst, b, h) do { _Pragma("unroll") for (int n = 0; n < 2; ++n) _Pragma("unroll") for (int k = 0; k < 2; ++k) dst[n][k] = *(const PG8_LAS bf16x8*)(lds + PG8_SB(b, h) + boff + n * 2048 + k * 1024); } while (0)
; #define PG8_MMA(ai, bj, At, Bt) do { __builtin_amdgcn_s_setprio(1); _Pragma("unroll") for (int m = 0; m < 4; ++m) _Pragma("unroll") for (int n = 0; n < 2; ++n) _Pragma("unroll") for (int k = 0; k < 2; ++k) \
;         acc[ai][bj][m][n] = __builtin_amdgcn_mfma_f32_16x16x32_bf16(Bt[n][k], At[m][k], acc[ai][bj][m][n], 0, 0, 0); __builtin_amdgcn_s_setprio(0); } while (0)
; #define PG8_BAR __builtin_amdgcn_s_barrier()
; template <class Epi, class Sched, bool ALIGN_EPI = false, bool SP2 = false>
; __device__ __forceinline__ void gemm_phase(PG8_LAS unsigned char* lds, const Gemm g, const Sched& S, const Epi& E, const int wave_in) {
;     ...
;             PG8_LDB(B0, 0, 0); PG8_LDB(B1, 0, 1); PG8_SCHED; PG8_LDA(At, 0, 0); PG8_STAGE(PG8_SA(1, 1), a1 + hstepA, voffA);
;             PG8_WAIT_V(8); PG8_WAIT_L(0); PG8_BAR; PG8_MMA(0, 0, At, B0); PG8_MMA(0, 1, At, B1); PG8_BAR; PG8_SCHED;
;             PG8_LDA(At, 0, 1); PG8_STAGE(PG8_SB(0, 0), b2, voffB); PG8_STAGE(PG8_SB(0, 1), b2 + hstep, voffB); PG8_STAGE(PG8_SA(0, 0), a2, voffA);
;             PG8_WAIT_V(8); PG8_WAIT_L(0); PG8_BAR; PG8_MMA(1, 0, At, B0); PG8_MMA(1, 1, At, B1); PG8_BAR; PG8_SCHED;
;             PG8_LDB(B0, 1, 0); PG8_LDB(B1, 1, 1); PG8_SCHED; PG8_LDA(At, 1, 0); PG8_STAGE(PG8_SA(0, 1), a2 + hstepA, voffA);
;             PG8_WAIT_V(8); PG8_WAIT_L(0); PG8_BAR; PG8_MMA(0, 0, At, B0); PG8_MMA(0, 1, At, B1); PG8_BAR; PG8_SCHED;
;             PG8_LDA(At, 1, 1); PG8_STAGE(PG8_SB(1, 0), b3, voffB); PG8_STAGE(PG8_SB(1, 1), b3 + hstep, voffB); PG8_STAGE(PG8_SA(1, 0), a3, voffA);
;             PG8_WAIT_V(8); PG8_WAIT_L(0); PG8_BAR; PG8_MMA(1, 0, At, B0); PG8_MMA(1, 1, At, B1); PG8_BAR; PG8_SCHED;
.LBB0_672:
	ds_read_b128 v[128:131], v169
	ds_read_b128 v[132:135], v169 offset:1024
	ds_read_b128 v[160:163], v169 offset:2048
	ds_read_b128 v[174:177], v169 offset:3072
	ds_read_b128 v[178:181], v170
	ds_read_b128 v[182:185], v170 offset:1024
	ds_read_b128 v[186:189], v170 offset:2048
	ds_read_b128 v[190:193], v170 offset:3072
	s_add_u32 s73, s18, 0xfff80080
	s_addc_u32 s78, s19, -1
	s_cmp_eq_u32 s71, 28
	s_cselect_b32 s85, s1, s78
	s_cselect_b32 s84, s7, s73
	s_cselect_b32 s79, s36, s57
	s_cselect_b32 s78, s37, s56
	v_lshl_add_u64 v[164:165], s[18:19], 0, v[152:153]
	s_add_i32 m0, s33, 0xc000
	ds_read_b128 v[194:197], v171
	ds_read_b128 v[198:201], v171 offset:1024
	ds_read_b128 v[202:205], v171 offset:2048
	ds_read_b128 v[206:209], v171 offset:3072
	ds_read_b128 v[210:213], v171 offset:4096
	ds_read_b128 v[214:217], v171 offset:5120
	ds_read_b128 v[218:221], v171 offset:6144
	ds_read_b128 v[222:225], v171 offset:7168
	global_load_lds_dwordx4 v[164:165], off
	v_lshl_add_u64 v[164:165], s[18:19], 0, v[154:155]
	s_add_i32 m0, s33, 0xe000
	s_nop 0
	global_load_lds_dwordx4 v[164:165], off
	s_waitcnt vmcnt(8)
	s_waitcnt lgkmcnt(0)
	s_barrier
	s_setprio 1
	v_mfma_f32_16x16x32_bf16 v[124:127], v[128:131], v[194:197], v[124:127]
	v_mfma_f32_16x16x32_bf16 v[120:123], v[160:163], v[194:197], v[120:123]
	v_mfma_f32_16x16x32_bf16 v[108:111], v[128:131], v[202:205], v[108:111]
	v_mfma_f32_16x16x32_bf16 v[104:107], v[160:163], v[202:205], v[104:107]
	v_mfma_f32_16x16x32_bf16 v[92:95], v[128:131], v[210:213], v[92:95]
	v_mfma_f32_16x16x32_bf16 v[88:91], v[160:163], v[210:213], v[88:91]
	v_mfma_f32_16x16x32_bf16 v[76:79], v[128:131], v[218:221], v[76:79]
	v_mfma_f32_16x16x32_bf16 v[72:75], v[160:163], v[218:221], v[72:75]
	v_mfma_f32_16x16x32_bf16 v[124:127], v[132:135], v[198:201], v[124:127]
	v_mfma_f32_16x16x32_bf16 v[120:123], v[174:177], v[198:201], v[120:123]
	v_mfma_f32_16x16x32_bf16 v[108:111], v[132:135], v[206:209], v[108:111]
	v_mfma_f32_16x16x32_bf16 v[104:107], v[174:177], v[206:209], v[104:107]
	v_mfma_f32_16x16x32_bf16 v[92:95], v[132:135], v[214:217], v[92:95]
	v_mfma_f32_16x16x32_bf16 v[88:91], v[174:177], v[214:217], v[88:91]
	v_mfma_f32_16x16x32_bf16 v[76:79], v[132:135], v[222:225], v[76:79]
	v_mfma_f32_16x16x32_bf16 v[72:75], v[174:177], v[222:225], v[72:75]
	v_mfma_f32_16x16x32_bf16 v[116:119], v[178:181], v[194:197], v[116:119]
	v_mfma_f32_16x16x32_bf16 v[112:115], v[186:189], v[194:197], v[112:115]
	v_mfma_f32_16x16x32_bf16 v[100:103], v[178:181], v[202:205], v[100:103]
	v_mfma_f32_16x16x32_bf16 v[96:99], v[186:189], v[202:205], v[96:99]
	v_mfma_f32_16x16x32_bf16 v[84:87], v[178:181], v[210:213], v[84:87]
	v_mfma_f32_16x16x32_bf16 v[80:83], v[186:189], v[210:213], v[80:83]
	v_mfma_f32_16x16x32_bf16 v[68:71], v[178:181], v[218:221], v[68:71]
	v_mfma_f32_16x16x32_bf16 v[64:67], v[186:189], v[218:221], v[64:67]
	v_mfma_f32_16x16x32_bf16 v[116:119], v[182:185], v[198:201], v[116:119]
	v_mfma_f32_16x16x32_bf16 v[112:115], v[190:193], v[198:201], v[112:115]
	v_mfma_f32_16x16x32_bf16 v[100:103], v[182:185], v[206:209], v[100:103]
	v_mfma_f32_16x16x32_bf16 v[96:99], v[190:193], v[206:209], v[96:99]
	v_mfma_f32_16x16x32_bf16 v[84:87], v[182:185], v[214:217], v[84:87]
	v_mfma_f32_16x16x32_bf16 v[80:83], v[190:193], v[214:217], v[80:83]
	v_mfma_f32_16x16x32_bf16 v[68:71], v[182:185], v[222:225], v[68:71]
	v_mfma_f32_16x16x32_bf16 v[64:67], v[190:193], v[222:225], v[64:67]
	s_setprio 0
	s_barrier
	s_add_i32 s73, s92, s11
	v_lshl_add_u64 v[164:165], s[78:79], 0, v[138:139]
	s_mov_b32 m0, s73
	ds_read_b128 v[194:197], v171 offset:16384
	ds_read_b128 v[198:201], v171 offset:17408
	ds_read_b128 v[202:205], v171 offset:18432
	ds_read_b128 v[206:209], v171 offset:19456
	ds_read_b128 v[210:213], v171 offset:20480
	ds_read_b128 v[214:217], v171 offset:21504
	ds_read_b128 v[218:221], v171 offset:22528
	ds_read_b128 v[222:225], v171 offset:23552
	global_load_lds_dwordx4 v[164:165], off
	s_add_i32 m0, s73, 0x2000
	s_add_u32 vcc_lo, s78, 0x80000
	v_lshl_add_u64 v[226:227], s[78:79], 0, v[142:143]
	s_addc_u32 vcc_hi, s79, 0
	s_add_i32 s73, s93, s11
	global_load_lds_dwordx4 v[226:227], off
	v_lshl_add_u64 v[228:229], vcc, 0, v[138:139]
	s_mov_b32 m0, s73
	v_lshl_add_u64 v[230:231], s[84:85], 0, v[140:141]
	global_load_lds_dwordx4 v[228:229], off
	v_lshl_add_u64 v[228:229], vcc, 0, v[142:143]
	s_add_i32 m0, s73, 0x2000
	s_nop 0
	global_load_lds_dwordx4 v[228:229], off
	v_lshl_add_u64 v[228:229], s[84:85], 0, v[136:137]
	s_mov_b32 m0, s33
	s_nop 0
	global_load_lds_dwordx4 v[228:229], off
	s_mov_b32 m0, s35
	s_nop 0
	global_load_lds_dwordx4 v[230:231], off
	s_waitcnt vmcnt(8)
	s_waitcnt lgkmcnt(0)
	s_barrier
; #define PG8_STAGE(bufoff, gbase, voff) do { _Pragma("unroll") for (int _i = 0; _i < 2; ++_i) \
;         __builtin_amdgcn_global_load_lds((const unsigned*)((const char*)(gbase) + (voff)[_i]), (PG8_LAS unsigned*)(lds + (bufoff) + ldsw + _i * 8192), 16, 0, 0); } while (0)
; #define PG8_LDA(dst, b, h) do { _Pragma("unroll") for (int m = 0; m < 4; ++m) _Pragma("unroll") for (int k = 0; k < 2; ++k) dst[m][k] = *(const PG8_LAS bf16x8*)(lds + PG8_SA(b, h) + aoff + m * 2048 + k * 1024); } while (0)
; #define PG8_LDB(dst, b, h) do { _Pragma("unroll") for (int n = 0; n < 2; ++n) _Pragma("unroll") for (int k = 0; k < 2; ++k) dst[n][k] = *(const PG8_LAS bf16x8*)(lds + PG8_SB(b, h) + boff + n * 2048 + k * 1024); } while (0)
; #define PG8_MMA(ai, bj, At, Bt) do { __builtin_amdgcn_s_setprio(1); _Pragma("unroll") for (int m = 0; m < 4; ++m) _Pragma("unroll") for (int n = 0; n < 2; ++n) _Pragma("unroll") for (int k = 0; k < 2; ++k) \
;         acc[ai][bj][m][n] = __builtin_amdgcn_mfma_f32_16x16x32_bf16(Bt[n][k], At[m][k], acc[ai][bj][m][n], 0, 0, 0); __builtin_amdgcn_s_setprio(0); } while (0)
; #define PG8_BAR __builtin_amdgcn_s_barrier()
; template <class Epi, class Sched, bool ALIGN_EPI = false, bool SP2 = false>
; __device__ __forceinline__ void gemm_phase(PG8_LAS unsigned char* lds, const Gemm g, const Sched& S, const Epi& E, const int wave_in) {
;     ...
;             PG8_LDB(B0, 0, 0); PG8_LDB(B1, 0, 1); PG8_SCHED; PG8_LDA(At, 0, 0); PG8_STAGE(PG8_SA(1, 1), a1 + hstepA, voffA);
;             PG8_WAIT_V(8); PG8_WAIT_L(0); PG8_BAR; PG8_MMA(0, 0, At, B0); PG8_MMA(0, 1, At, B1); PG8_BAR; PG8_SCHED;
;             PG8_LDA(At, 0, 1); PG8_STAGE(PG8_SB(0, 0), b2, voffB); PG8_STAGE(PG8_SB(0, 1), b2 + hstep, voffB); PG8_STAGE(PG8_SA(0, 0), a2, voffA);
;             PG8_WAIT_V(8); PG8_WAIT_L(0); PG8_BAR; PG8_MMA(1, 0, At, B0); PG8_MMA(1, 1, At, B1); PG8_BAR; PG8_SCHED;
;             PG8_LDB(B0, 1, 0); PG8_LDB(B1, 1, 1); PG8_SCHED; PG8_LDA(At, 1, 0); PG8_STAGE(PG8_SA(0, 1), a2 + hstepA, voffA);
;             PG8_WAIT_V(8); PG8_WAIT_L(0); PG8_BAR; PG8_MMA(0, 0, At, B0); PG8_MMA(0, 1, At, B1); PG8_BAR; PG8_SCHED;
;             PG8_LDA(At, 1, 1); PG8_STAGE(PG8_SB(1, 0), b3, voffB); PG8_STAGE(PG8_SB(1, 1), b3 + hstep, voffB); PG8_STAGE(PG8_SA(1, 0), a3, voffA);
;             PG8_WAIT_V(8); PG8_WAIT_L(0); PG8_BAR; PG8_MMA(1, 0, At, B0); PG8_MMA(1, 1, At, B1); PG8_BAR; PG8_SCHED;
	s_setprio 1
	v_mfma_f32_16x16x32_bf16 v[60:63], v[128:131], v[194:197], v[60:63]
	v_mfma_f32_16x16x32_bf16 v[56:59], v[160:163], v[194:197], v[56:59]
	v_mfma_f32_16x16x32_bf16 v[44:47], v[128:131], v[202:205], v[44:47]
	v_mfma_f32_16x16x32_bf16 v[40:43], v[160:163], v[202:205], v[40:43]
	v_mfma_f32_16x16x32_bf16 v[28:31], v[128:131], v[210:213], v[28:31]
	v_mfma_f32_16x16x32_bf16 v[24:27], v[160:163], v[210:213], v[24:27]
	v_mfma_f32_16x16x32_bf16 v[12:15], v[128:131], v[218:221], v[12:15]
	v_mfma_f32_16x16x32_bf16 v[8:11], v[160:163], v[218:221], v[8:11]
	v_mfma_f32_16x16x32_bf16 v[60:63], v[132:135], v[198:201], v[60:63]
	v_mfma_f32_16x16x32_bf16 v[56:59], v[174:177], v[198:201], v[56:59]
	v_mfma_f32_16x16x32_bf16 v[44:47], v[132:135], v[206:209], v[44:47]
	v_mfma_f32_16x16x32_bf16 v[40:43], v[174:177], v[206:209], v[40:43]
	v_mfma_f32_16x16x32_bf16 v[28:31], v[132:135], v[214:217], v[28:31]
	v_mfma_f32_16x16x32_bf16 v[24:27], v[174:177], v[214:217], v[24:27]
	v_mfma_f32_16x16x32_bf16 v[12:15], v[132:135], v[222:225], v[12:15]
	v_mfma_f32_16x16x32_bf16 v[8:11], v[174:177], v[222:225], v[8:11]
	v_mfma_f32_16x16x32_bf16 v[52:55], v[178:181], v[194:197], v[52:55]
	v_mfma_f32_16x16x32_bf16 v[48:51], v[186:189], v[194:197], v[48:51]
	v_mfma_f32_16x16x32_bf16 v[36:39], v[178:181], v[202:205], v[36:39]
	v_mfma_f32_16x16x32_bf16 v[32:35], v[186:189], v[202:205], v[32:35]
	v_mfma_f32_16x16x32_bf16 v[20:23], v[178:181], v[210:213], v[20:23]
	v_mfma_f32_16x16x32_bf16 v[16:19], v[186:189], v[210:213], v[16:19]
	v_mfma_f32_16x16x32_bf16 v[4:7], v[178:181], v[218:221], v[4:7]
	v_mfma_f32_16x16x32_bf16 v[0:3], v[186:189], v[218:221], v[0:3]
	v_mfma_f32_16x16x32_bf16 v[52:55], v[182:185], v[198:201], v[52:55]
	v_mfma_f32_16x16x32_bf16 v[48:51], v[190:193], v[198:201], v[48:51]
	v_mfma_f32_16x16x32_bf16 v[36:39], v[182:185], v[206:209], v[36:39]
	v_mfma_f32_16x16x32_bf16 v[32:35], v[190:193], v[206:209], v[32:35]
	v_mfma_f32_16x16x32_bf16 v[20:23], v[182:185], v[214:217], v[20:23]
	v_mfma_f32_16x16x32_bf16 v[16:19], v[190:193], v[214:217], v[16:19]
	v_mfma_f32_16x16x32_bf16 v[4:7], v[182:185], v[222:225], v[4:7]
	v_mfma_f32_16x16x32_bf16 v[0:3], v[190:193], v[222:225], v[0:3]
	s_setprio 0
	s_barrier
	s_add_i32 s73, 0, 0x18000
	s_add_i32 vcc_lo, 0, 0x1c000
	v_add_u32_e32 v174, s73, v167
	v_add_u32_e32 v190, vcc_lo, v167
	ds_read_b128 v[128:131], v174
	ds_read_b128 v[132:135], v174 offset:1024
	ds_read_b128 v[160:163], v174 offset:2048
	ds_read_b128 v[174:177], v174 offset:3072
	ds_read_b128 v[178:181], v190
	ds_read_b128 v[182:185], v190 offset:1024
	ds_read_b128 v[186:189], v190 offset:2048
	ds_read_b128 v[190:193], v190 offset:3072
	s_add_u32 s84, s84, 0x80000
	s_addc_u32 s85, s85, 0
	s_mov_b32 m0, s38
	v_lshl_add_u64 v[232:233], s[84:85], 0, v[136:137]
	ds_read_b128 v[194:197], v171 offset:32768
	ds_read_b128 v[198:201], v171 offset:33792
	ds_read_b128 v[202:205], v171 offset:34816
	ds_read_b128 v[206:209], v171 offset:35840
	ds_read_b128 v[210:213], v171 offset:36864
	ds_read_b128 v[214:217], v171 offset:37888
	ds_read_b128 v[218:221], v171 offset:38912
	ds_read_b128 v[222:225], v171 offset:39936
	global_load_lds_dwordx4 v[232:233], off
	v_lshl_add_u64 v[232:233], s[84:85], 0, v[140:141]
	s_mov_b32 m0, s39
	s_nop 0
	global_load_lds_dwordx4 v[232:233], off
	s_waitcnt vmcnt(8)
	s_waitcnt lgkmcnt(0)
	s_barrier
	s_setprio 1
	v_mfma_f32_16x16x32_bf16 v[124:127], v[128:131], v[194:197], v[124:127]
	v_mfma_f32_16x16x32_bf16 v[120:123], v[160:163], v[194:197], v[120:123]
	v_mfma_f32_16x16x32_bf16 v[108:111], v[128:131], v[202:205], v[108:111]
	v_mfma_f32_16x16x32_bf16 v[104:107], v[160:163], v[202:205], v[104:107]
	v_mfma_f32_16x16x32_bf16 v[92:95], v[128:131], v[210:213], v[92:95]
	v_mfma_f32_16x16x32_bf16 v[88:91], v[160:163], v[210:213], v[88:91]
	v_mfma_f32_16x16x32_bf16 v[76:79], v[128:131], v[218:221], v[76:79]
	v_mfma_f32_16x16x32_bf16 v[72:75], v[160:163], v[218:221], v[72:75]
	v_mfma_f32_16x16x32_bf16 v[124:127], v[132:135], v[198:201], v[124:127]
	v_mfma_f32_16x16x32_bf16 v[120:123], v[174:177], v[198:201], v[120:123]
	v_mfma_f32_16x16x32_bf16 v[108:111], v[132:135], v[206:209], v[108:111]
	v_mfma_f32_16x16x32_bf16 v[104:107], v[174:177], v[206:209], v[104:107]
	v_mfma_f32_16x16x32_bf16 v[92:95], v[132:135], v[214:217], v[92:95]
	v_mfma_f32_16x16x32_bf16 v[88:91], v[174:177], v[214:217], v[88:91]
	v_mfma_f32_16x16x32_bf16 v[76:79], v[132:135], v[222:225], v[76:79]
	v_mfma_f32_16x16x32_bf16 v[72:75], v[174:177], v[222:225], v[72:75]
	v_mfma_f32_16x16x32_bf16 v[116:119], v[178:181], v[194:197], v[116:119]
	v_mfma_f32_16x16x32_bf16 v[112:115], v[186:189], v[194:197], v[112:115]
	v_mfma_f32_16x16x32_bf16 v[100:103], v[178:181], v[202:205], v[100:103]
	v_mfma_f32_16x16x32_bf16 v[96:99], v[186:189], v[202:205], v[96:99]
	v_mfma_f32_16x16x32_bf16 v[84:87], v[178:181], v[210:213], v[84:87]
	v_mfma_f32_16x16x32_bf16 v[80:83], v[186:189], v[210:213], v[80:83]
	v_mfma_f32_16x16x32_bf16 v[68:71], v[178:181], v[218:221], v[68:71]
	v_mfma_f32_16x16x32_bf16 v[64:67], v[186:189], v[218:221], v[64:67]
	v_mfma_f32_16x16x32_bf16 v[116:119], v[182:185], v[198:201], v[116:119]
	v_mfma_f32_16x16x32_bf16 v[112:115], v[190:193], v[198:201], v[112:115]
	v_mfma_f32_16x16x32_bf16 v[100:103], v[182:185], v[206:209], v[100:103]
	v_mfma_f32_16x16x32_bf16 v[96:99], v[190:193], v[206:209], v[96:99]
	v_mfma_f32_16x16x32_bf16 v[84:87], v[182:185], v[214:217], v[84:87]
	v_mfma_f32_16x16x32_bf16 v[80:83], v[190:193], v[214:217], v[80:83]
	v_mfma_f32_16x16x32_bf16 v[68:71], v[182:185], v[222:225], v[68:71]
	v_mfma_f32_16x16x32_bf16 v[64:67], v[190:193], v[222:225], v[64:67]
	s_setprio 0
	s_barrier
; #define PG8_STAGE(bufoff, gbase, voff) do { _Pragma("unroll") for (int _i = 0; _i < 2; ++_i) \
;         __builtin_amdgcn_global_load_lds((const unsigned*)((const char*)(gbase) + (voff)[_i]), (PG8_LAS unsigned*)(lds + (bufoff) + ldsw + _i * 8192), 16, 0, 0); } while (0)
; #define PG8_LDA(dst, b, h) do { _Pragma("unroll") for (int m = 0; m < 4; ++m) _Pragma("unroll") for (int k = 0; k < 2; ++k) dst[m][k] = *(const PG8_LAS bf16x8*)(lds + PG8_SA(b, h) + aoff + m * 2048 + k * 1024); } while (0)
; #define PG8_LDB(dst, b, h) do { _Pragma("unroll") for (int n = 0; n < 2; ++n) _Pragma("unroll") for (int k = 0; k < 2; ++k) dst[n][k] = *(const PG8_LAS bf16x8*)(lds + PG8_SB(b, h) + boff + n * 2048 + k * 1024); } while (0)
; #define PG8_MMA(ai, bj, At, Bt) do { __builtin_amdgcn_s_setprio(1); _Pragma("unroll") for (int m = 0; m < 4; ++m) _Pragma("unroll") for (int n = 0; n < 2; ++n) _Pragma("unroll") for (int k = 0; k < 2; ++k) \
;         acc[ai][bj][m][n] = __builtin_amdgcn_mfma_f32_16x16x32_bf16(Bt[n][k], At[m][k], acc[ai][bj][m][n], 0, 0, 0); __builtin_amdgcn_s_setprio(0); } while (0)
; #define PG8_BAR __builtin_amdgcn_s_barrier()
; template <class Epi, class Sched, bool ALIGN_EPI = false, bool SP2 = false>
; __device__ __forceinline__ void gemm_phase(PG8_LAS unsigned char* lds, const Gemm g, const Sched& S, const Epi& E, const int wave_in) {
;     ...
;             PG8_LDB(B0, 0, 0); PG8_LDB(B1, 0, 1); PG8_SCHED; PG8_LDA(At, 0, 0); PG8_STAGE(PG8_SA(1, 1), a1 + hstepA, voffA);
;             PG8_WAIT_V(8); PG8_WAIT_L(0); PG8_BAR; PG8_MMA(0, 0, At, B0); PG8_MMA(0, 1, At, B1); PG8_BAR; PG8_SCHED;
;             PG8_LDA(At, 0, 1); PG8_STAGE(PG8_SB(0, 0), b2, voffB); PG8_STAGE(PG8_SB(0, 1), b2 + hstep, voffB); PG8_STAGE(PG8_SA(0, 0), a2, voffA);
;             PG8_WAIT_V(8); PG8_WAIT_L(0); PG8_BAR; PG8_MMA(1, 0, At, B0); PG8_MMA(1, 1, At, B1); PG8_BAR; PG8_SCHED;
;             PG8_LDB(B0, 1, 0); PG8_LDB(B1, 1, 1); PG8_SCHED; PG8_LDA(At, 1, 0); PG8_STAGE(PG8_SA(0, 1), a2 + hstepA, voffA);
;             PG8_WAIT_V(8); PG8_WAIT_L(0); PG8_BAR; PG8_MMA(0, 0, At, B0); PG8_MMA(0, 1, At, B1); PG8_BAR; PG8_SCHED;
;             PG8_LDA(At, 1, 1); PG8_STAGE(PG8_SB(1, 0), b3, voffB); PG8_STAGE(PG8_SB(1, 1), b3 + hstep, voffB); PG8_STAGE(PG8_SA(1, 0), a3, voffA);
;             PG8_WAIT_V(8); PG8_WAIT_L(0); PG8_BAR; PG8_MMA(1, 0, At, B0); PG8_MMA(1, 1, At, B1); PG8_BAR; PG8_SCHED;
	s_add_i32 s73, s73, s11
	v_lshl_add_u64 v[164:165], v[164:165], 0, s[62:63]
	s_mov_b32 m0, s73
	ds_read_b128 v[194:197], v171 offset:49152
	ds_read_b128 v[198:201], v171 offset:50176
	ds_read_b128 v[202:205], v171 offset:51200
	ds_read_b128 v[206:209], v171 offset:52224
	ds_read_b128 v[210:213], v171 offset:53248
	ds_read_b128 v[214:217], v171 offset:54272
	ds_read_b128 v[218:221], v171 offset:55296
	ds_read_b128 v[222:225], v171 offset:56320
	global_load_lds_dwordx4 v[164:165], off
	s_add_i32 m0, s73, 0x2000
	s_add_u32 s78, s78, 0x80080
	v_lshl_add_u64 v[164:165], v[226:227], 0, s[62:63]
	s_addc_u32 s79, s79, 0
	s_add_i32 s73, vcc_lo, s11
	global_load_lds_dwordx4 v[164:165], off
	v_lshl_add_u64 v[164:165], s[78:79], 0, v[138:139]
	s_mov_b32 m0, s73
	s_nop 0
	global_load_lds_dwordx4 v[164:165], off
	v_lshl_add_u64 v[164:165], s[78:79], 0, v[142:143]
	s_add_i32 m0, s73, 0x2000
	s_nop 0
	global_load_lds_dwordx4 v[164:165], off
	v_lshl_add_u64 v[164:165], v[228:229], 0, s[62:63]
	s_mov_b32 m0, s49
	s_nop 0
	global_load_lds_dwordx4 v[164:165], off
	v_lshl_add_u64 v[164:165], v[230:231], 0, s[62:63]
	s_mov_b32 m0, s50
	s_nop 0
	global_load_lds_dwordx4 v[164:165], off
	s_waitcnt vmcnt(8)
	s_waitcnt lgkmcnt(0)
	s_barrier
	s_setprio 1
	v_mfma_f32_16x16x32_bf16 v[60:63], v[128:131], v[194:197], v[60:63]
	v_mfma_f32_16x16x32_bf16 v[56:59], v[160:163], v[194:197], v[56:59]
	v_mfma_f32_16x16x32_bf16 v[44:47], v[128:131], v[202:205], v[44:47]
	v_mfma_f32_16x16x32_bf16 v[40:43], v[160:163], v[202:205], v[40:43]
	v_mfma_f32_16x16x32_bf16 v[28:31], v[128:131], v[210:213], v[28:31]
	v_mfma_f32_16x16x32_bf16 v[24:27], v[160:163], v[210:213], v[24:27]
	v_mfma_f32_16x16x32_bf16 v[12:15], v[128:131], v[218:221], v[12:15]
	v_mfma_f32_16x16x32_bf16 v[8:11], v[160:163], v[218:221], v[8:11]
	v_mfma_f32_16x16x32_bf16 v[60:63], v[132:135], v[198:201], v[60:63]
	v_mfma_f32_16x16x32_bf16 v[56:59], v[174:177], v[198:201], v[56:59]
	v_mfma_f32_16x16x32_bf16 v[44:47], v[132:135], v[206:209], v[44:47]
	v_mfma_f32_16x16x32_bf16 v[40:43], v[174:177], v[206:209], v[40:43]
	v_mfma_f32_16x16x32_bf16 v[28:31], v[132:135], v[214:217], v[28:31]
	v_mfma_f32_16x16x32_bf16 v[24:27], v[174:177], v[214:217], v[24:27]
	v_mfma_f32_16x16x32_bf16 v[12:15], v[132:135], v[222:225], v[12:15]
	v_mfma_f32_16x16x32_bf16 v[8:11], v[174:177], v[222:225], v[8:11]
	v_mfma_f32_16x16x32_bf16 v[52:55], v[178:181], v[194:197], v[52:55]
	v_mfma_f32_16x16x32_bf16 v[48:51], v[186:189], v[194:197], v[48:51]
	v_mfma_f32_16x16x32_bf16 v[36:39], v[178:181], v[202:205], v[36:39]
	v_mfma_f32_16x16x32_bf16 v[32:35], v[186:189], v[202:205], v[32:35]
	v_mfma_f32_16x16x32_bf16 v[20:23], v[178:181], v[210:213], v[20:23]
	v_mfma_f32_16x16x32_bf16 v[16:19], v[186:189], v[210:213], v[16:19]
	v_mfma_f32_16x16x32_bf16 v[4:7], v[178:181], v[218:221], v[4:7]
	v_mfma_f32_16x16x32_bf16 v[0:3], v[186:189], v[218:221], v[0:3]
	v_mfma_f32_16x16x32_bf16 v[52:55], v[182:185], v[198:201], v[52:55]
	v_mfma_f32_16x16x32_bf16 v[48:51], v[190:193], v[198:201], v[48:51]
	v_mfma_f32_16x16x32_bf16 v[36:39], v[182:185], v[206:209], v[36:39]
	v_mfma_f32_16x16x32_bf16 v[32:35], v[190:193], v[206:209], v[32:35]
	v_mfma_f32_16x16x32_bf16 v[20:23], v[182:185], v[214:217], v[20:23]
	v_mfma_f32_16x16x32_bf16 v[16:19], v[190:193], v[214:217], v[16:19]
	v_mfma_f32_16x16x32_bf16 v[4:7], v[182:185], v[222:225], v[4:7]
	v_mfma_f32_16x16x32_bf16 v[0:3], v[190:193], v[222:225], v[0:3]
	s_setprio 0
	s_barrier
	s_add_i32 s71, s71, 2
	s_add_u32 s18, s18, 0x100
	s_addc_u32 s19, s19, 0
	s_add_u32 s56, s56, 0x100
	s_addc_u32 s57, s57, 0
	s_cmp_gt_u32 s71, 29
	s_cbranch_scc0 .LBB0_672
	s_and_b64 vcc, exec, s[64:65]
	s_cbranch_vccnz .LBB0_676
	v_lshl_add_u32 v160, s0, 8, v166
	s_cmp_gt_i32 s6, 15
	s_mov_b64 s[0:1], -1
	s_cbranch_scc1 .LBB0_677

; #define PG8_STAGE(bufoff, gbase, voff) do { _Pragma("unroll") for (int _i = 0; _i < 2; ++_i) \
;         __builtin_amdgcn_global_load_lds((const unsigned*)((const char*)(gbase) + (voff)[_i]), (PG8_LAS unsigned*)(lds + (bufoff) + ldsw + _i * 8192), 16, 0, 0); } while (0)
; #define PG8_LDA(dst, b, h) do { _Pragma("unroll") for (int m = 0; m < 4; ++m) _Pragma("unroll") for (int k = 0; k < 2; ++k) dst[m][k] = *(const PG8_LAS bf16x8*)(lds + PG8_SA(b, h) + aoff + m * 2048 + k * 1024); } while (0)
; #define PG8_LDB(dst, b, h) do { _Pragma("unroll") for (int n = 0; n < 2; ++n) _Pragma("unroll") for (int k = 0; k < 2; ++k) dst[n][k] = *(const PG8_LAS bf16x8*)(lds + PG8_SB(b, h) + boff + n * 2048 + k * 1024); } while (0)
; #define PG8_MMA(ai, bj, At, Bt) do { __builtin_amdgcn_s_setprio(1); _Pragma("unroll") for (int m = 0; m < 4; ++m) _Pragma("unroll") for (int n = 0; n < 2; ++n) _Pragma("unroll") for (int k = 0; k < 2; ++k) \
;         acc[ai][bj][m][n] = __builtin_amdgcn_mfma_f32_16x16x32_bf16(Bt[n][k], At[m][k], acc[ai][bj][m][n], 0, 0, 0); __builtin_amdgcn_s_setprio(0); } while (0)
; #define PG8_BAR __builtin_amdgcn_s_barrier()
; template <class Epi, class Sched, bool ALIGN_EPI = false, bool SP2 = false>
; __device__ __forceinline__ void gemm_phase(PG8_LAS unsigned char* lds, const Gemm g, const Sched& S, const Epi& E, const int wave_in) {
;     ...
;             PG8_LDB(B0, 0, 0); PG8_LDB(B1, 0, 1); PG8_SCHED; PG8_LDA(At, 0, 0); PG8_STAGE(PG8_SA(1, 1), a1 + hstepA, voffA);
;             PG8_WAIT_V(8); PG8_WAIT_L(0); PG8_BAR; PG8_MMA(0, 0, At, B0); PG8_MMA(0, 1, At, B1); PG8_BAR; PG8_SCHED;
;             PG8_LDA(At, 0, 1); PG8_STAGE(PG8_SB(0, 0), b2, voffB); PG8_STAGE(PG8_SB(0, 1), b2 + hstep, voffB); PG8_STAGE(PG8_SA(0, 0), a2, voffA);
;             PG8_WAIT_V(8); PG8_WAIT_L(0); PG8_BAR; PG8_MMA(1, 0, At, B0); PG8_MMA(1, 1, At, B1); PG8_BAR; PG8_SCHED;
;             PG8_LDB(B0, 1, 0); PG8_LDB(B1, 1, 1); PG8_SCHED; PG8_LDA(At, 1, 0); PG8_STAGE(PG8_SA(0, 1), a2 + hstepA, voffA);
;             PG8_WAIT_V(8); PG8_WAIT_L(0); PG8_BAR; PG8_MMA(0, 0, At, B0); PG8_MMA(0, 1, At, B1); PG8_BAR; PG8_SCHED;
;             PG8_LDA(At, 1, 1); PG8_STAGE(PG8_SB(1, 0), b3, voffB); PG8_STAGE(PG8_SB(1, 1), b3 + hstep, voffB); PG8_STAGE(PG8_SA(1, 0), a3, voffA);
;             PG8_WAIT_V(8); PG8_WAIT_L(0); PG8_BAR; PG8_MMA(1, 0, At, B0); PG8_MMA(1, 1, At, B1); PG8_BAR; PG8_SCHED;
.LBB0_786:
	ds_read_b128 v[128:131], v160
	ds_read_b128 v[152:155], v160 offset:1024
	ds_read_b128 v[164:167], v160 offset:2048
	ds_read_b128 v[168:171], v160 offset:3072
	ds_read_b128 v[172:175], v161
	ds_read_b128 v[176:179], v161 offset:1024
	ds_read_b128 v[180:183], v161 offset:2048
	ds_read_b128 v[184:187], v161 offset:3072
	s_add_u32 s60, s18, 0xfff00080
	s_addc_u32 s61, s19, -1
	s_cmp_eq_u32 s75, 4
	s_cselect_b32 s85, s1, s61
	s_cselect_b32 s84, s5, s60
	s_cselect_b32 s61, s36, s73
	s_cselect_b32 s60, s37, s62
	v_lshl_add_u64 v[156:157], s[18:19], 0, v[144:145]
	s_add_i32 m0, s42, 0xc000
	ds_read_b128 v[188:191], v162
	ds_read_b128 v[192:195], v162 offset:1024
	ds_read_b128 v[196:199], v162 offset:2048
	ds_read_b128 v[200:203], v162 offset:3072
	ds_read_b128 v[204:207], v162 offset:4096
	ds_read_b128 v[208:211], v162 offset:5120
	ds_read_b128 v[212:215], v162 offset:6144
	ds_read_b128 v[216:219], v162 offset:7168
	global_load_lds_dwordx4 v[156:157], off
	v_lshl_add_u64 v[156:157], s[18:19], 0, v[146:147]
	s_add_i32 m0, s42, 0xe000
	s_nop 0
	global_load_lds_dwordx4 v[156:157], off
	s_waitcnt vmcnt(8)
	s_waitcnt lgkmcnt(0)
	s_barrier
	s_setprio 1
	v_mfma_f32_16x16x32_bf16 v[124:127], v[128:131], v[188:191], v[124:127]
	v_mfma_f32_16x16x32_bf16 v[120:123], v[164:167], v[188:191], v[120:123]
	v_mfma_f32_16x16x32_bf16 v[108:111], v[128:131], v[196:199], v[108:111]
	v_mfma_f32_16x16x32_bf16 v[104:107], v[164:167], v[196:199], v[104:107]
	v_mfma_f32_16x16x32_bf16 v[92:95], v[128:131], v[204:207], v[92:95]
	v_mfma_f32_16x16x32_bf16 v[88:91], v[164:167], v[204:207], v[88:91]
	v_mfma_f32_16x16x32_bf16 v[76:79], v[128:131], v[212:215], v[76:79]
	v_mfma_f32_16x16x32_bf16 v[72:75], v[164:167], v[212:215], v[72:75]
	v_mfma_f32_16x16x32_bf16 v[124:127], v[152:155], v[192:195], v[124:127]
	v_mfma_f32_16x16x32_bf16 v[120:123], v[168:171], v[192:195], v[120:123]
	v_mfma_f32_16x16x32_bf16 v[108:111], v[152:155], v[200:203], v[108:111]
	v_mfma_f32_16x16x32_bf16 v[104:107], v[168:171], v[200:203], v[104:107]
	v_mfma_f32_16x16x32_bf16 v[92:95], v[152:155], v[208:211], v[92:95]
	v_mfma_f32_16x16x32_bf16 v[88:91], v[168:171], v[208:211], v[88:91]
	v_mfma_f32_16x16x32_bf16 v[76:79], v[152:155], v[216:219], v[76:79]
	v_mfma_f32_16x16x32_bf16 v[72:75], v[168:171], v[216:219], v[72:75]
	v_mfma_f32_16x16x32_bf16 v[116:119], v[172:175], v[188:191], v[116:119]
	v_mfma_f32_16x16x32_bf16 v[112:115], v[180:183], v[188:191], v[112:115]
	v_mfma_f32_16x16x32_bf16 v[100:103], v[172:175], v[196:199], v[100:103]
	v_mfma_f32_16x16x32_bf16 v[96:99], v[180:183], v[196:199], v[96:99]
	v_mfma_f32_16x16x32_bf16 v[84:87], v[172:175], v[204:207], v[84:87]
	v_mfma_f32_16x16x32_bf16 v[80:83], v[180:183], v[204:207], v[80:83]
	v_mfma_f32_16x16x32_bf16 v[68:71], v[172:175], v[212:215], v[68:71]
	v_mfma_f32_16x16x32_bf16 v[64:67], v[180:183], v[212:215], v[64:67]
	v_mfma_f32_16x16x32_bf16 v[116:119], v[176:179], v[192:195], v[116:119]
	v_mfma_f32_16x16x32_bf16 v[112:115], v[184:187], v[192:195], v[112:115]
	v_mfma_f32_16x16x32_bf16 v[100:103], v[176:179], v[200:203], v[100:103]
	v_mfma_f32_16x16x32_bf16 v[96:99], v[184:187], v[200:203], v[96:99]
	v_mfma_f32_16x16x32_bf16 v[84:87], v[176:179], v[208:211], v[84:87]
	v_mfma_f32_16x16x32_bf16 v[80:83], v[184:187], v[208:211], v[80:83]
	v_mfma_f32_16x16x32_bf16 v[68:71], v[176:179], v[216:219], v[68:71]
	v_mfma_f32_16x16x32_bf16 v[64:67], v[184:187], v[216:219], v[64:67]
	s_setprio 0
	s_barrier
	s_add_i32 vcc_lo, s93, s41
	v_lshl_add_u64 v[156:157], s[60:61], 0, v[134:135]
	s_mov_b32 m0, vcc_lo
	ds_read_b128 v[188:191], v162 offset:16384
	ds_read_b128 v[192:195], v162 offset:17408
	ds_read_b128 v[196:199], v162 offset:18432
	ds_read_b128 v[200:203], v162 offset:19456
	ds_read_b128 v[204:207], v162 offset:20480
	ds_read_b128 v[208:211], v162 offset:21504
	ds_read_b128 v[212:215], v162 offset:22528
	ds_read_b128 v[216:219], v162 offset:23552
	global_load_lds_dwordx4 v[156:157], off
	s_add_i32 m0, vcc_lo, 0x2000
	s_add_u32 vcc_lo, s60, 0x20000
	v_lshl_add_u64 v[220:221], s[60:61], 0, v[138:139]
	s_addc_u32 vcc_hi, s61, 0
	s_add_i32 s11, s40, s41
	global_load_lds_dwordx4 v[220:221], off
	v_lshl_add_u64 v[222:223], vcc, 0, v[134:135]
	s_mov_b32 m0, s11
	v_lshl_add_u64 v[224:225], s[84:85], 0, v[136:137]
	global_load_lds_dwordx4 v[222:223], off
	v_lshl_add_u64 v[222:223], vcc, 0, v[138:139]
	s_add_i32 m0, s11, 0x2000
	s_nop 0
	global_load_lds_dwordx4 v[222:223], off
	v_lshl_add_u64 v[222:223], s[84:85], 0, v[132:133]
	s_mov_b32 m0, s42
	s_nop 0
	global_load_lds_dwordx4 v[222:223], off
	s_mov_b32 m0, s43
	s_nop 0
	global_load_lds_dwordx4 v[224:225], off
	s_waitcnt vmcnt(8)
	s_waitcnt lgkmcnt(0)
	s_barrier
; #define PG8_STAGE(bufoff, gbase, voff) do { _Pragma("unroll") for (int _i = 0; _i < 2; ++_i) \
;         __builtin_amdgcn_global_load_lds((const unsigned*)((const char*)(gbase) + (voff)[_i]), (PG8_LAS unsigned*)(lds + (bufoff) + ldsw + _i * 8192), 16, 0, 0); } while (0)
; #define PG8_LDA(dst, b, h) do { _Pragma("unroll") for (int m = 0; m < 4; ++m) _Pragma("unroll") for (int k = 0; k < 2; ++k) dst[m][k] = *(const PG8_LAS bf16x8*)(lds + PG8_SA(b, h) + aoff + m * 2048 + k * 1024); } while (0)
; #define PG8_LDB(dst, b, h) do { _Pragma("unroll") for (int n = 0; n < 2; ++n) _Pragma("unroll") for (int k = 0; k < 2; ++k) dst[n][k] = *(const PG8_LAS bf16x8*)(lds + PG8_SB(b, h) + boff + n * 2048 + k * 1024); } while (0)
; #define PG8_MMA(ai, bj, At, Bt) do { __builtin_amdgcn_s_setprio(1); _Pragma("unroll") for (int m = 0; m < 4; ++m) _Pragma("unroll") for (int n = 0; n < 2; ++n) _Pragma("unroll") for (int k = 0; k < 2; ++k) \
;         acc[ai][bj][m][n] = __builtin_amdgcn_mfma_f32_16x16x32_bf16(Bt[n][k], At[m][k], acc[ai][bj][m][n], 0, 0, 0); __builtin_amdgcn_s_setprio(0); } while (0)
; #define PG8_BAR __builtin_amdgcn_s_barrier()
; template <class Epi, class Sched, bool ALIGN_EPI = false, bool SP2 = false>
; __device__ __forceinline__ void gemm_phase(PG8_LAS unsigned char* lds, const Gemm g, const Sched& S, const Epi& E, const int wave_in) {
;     ...
;             PG8_LDB(B0, 0, 0); PG8_LDB(B1, 0, 1); PG8_SCHED; PG8_LDA(At, 0, 0); PG8_STAGE(PG8_SA(1, 1), a1 + hstepA, voffA);
;             PG8_WAIT_V(8); PG8_WAIT_L(0); PG8_BAR; PG8_MMA(0, 0, At, B0); PG8_MMA(0, 1, At, B1); PG8_BAR; PG8_SCHED;
;             PG8_LDA(At, 0, 1); PG8_STAGE(PG8_SB(0, 0), b2, voffB); PG8_STAGE(PG8_SB(0, 1), b2 + hstep, voffB); PG8_STAGE(PG8_SA(0, 0), a2, voffA);
;             PG8_WAIT_V(8); PG8_WAIT_L(0); PG8_BAR; PG8_MMA(1, 0, At, B0); PG8_MMA(1, 1, At, B1); PG8_BAR; PG8_SCHED;
;             PG8_LDB(B0, 1, 0); PG8_LDB(B1, 1, 1); PG8_SCHED; PG8_LDA(At, 1, 0); PG8_STAGE(PG8_SA(0, 1), a2 + hstepA, voffA);
;             PG8_WAIT_V(8); PG8_WAIT_L(0); PG8_BAR; PG8_MMA(0, 0, At, B0); PG8_MMA(0, 1, At, B1); PG8_BAR; PG8_SCHED;
;             PG8_LDA(At, 1, 1); PG8_STAGE(PG8_SB(1, 0), b3, voffB); PG8_STAGE(PG8_SB(1, 1), b3 + hstep, voffB); PG8_STAGE(PG8_SA(1, 0), a3, voffA);
;             PG8_WAIT_V(8); PG8_WAIT_L(0); PG8_BAR; PG8_MMA(1, 0, At, B0); PG8_MMA(1, 1, At, B1); PG8_BAR; PG8_SCHED;
	s_setprio 1
	v_mfma_f32_16x16x32_bf16 v[60:63], v[128:131], v[188:191], v[60:63]
	v_mfma_f32_16x16x32_bf16 v[56:59], v[164:167], v[188:191], v[56:59]
	v_mfma_f32_16x16x32_bf16 v[44:47], v[128:131], v[196:199], v[44:47]
	v_mfma_f32_16x16x32_bf16 v[40:43], v[164:167], v[196:199], v[40:43]
	v_mfma_f32_16x16x32_bf16 v[28:31], v[128:131], v[204:207], v[28:31]
	v_mfma_f32_16x16x32_bf16 v[24:27], v[164:167], v[204:207], v[24:27]
	v_mfma_f32_16x16x32_bf16 v[12:15], v[128:131], v[212:215], v[12:15]
	v_mfma_f32_16x16x32_bf16 v[8:11], v[164:167], v[212:215], v[8:11]
	v_mfma_f32_16x16x32_bf16 v[60:63], v[152:155], v[192:195], v[60:63]
	v_mfma_f32_16x16x32_bf16 v[56:59], v[168:171], v[192:195], v[56:59]
	v_mfma_f32_16x16x32_bf16 v[44:47], v[152:155], v[200:203], v[44:47]
	v_mfma_f32_16x16x32_bf16 v[40:43], v[168:171], v[200:203], v[40:43]
	v_mfma_f32_16x16x32_bf16 v[28:31], v[152:155], v[208:211], v[28:31]
	v_mfma_f32_16x16x32_bf16 v[24:27], v[168:171], v[208:211], v[24:27]
	v_mfma_f32_16x16x32_bf16 v[12:15], v[152:155], v[216:219], v[12:15]
	v_mfma_f32_16x16x32_bf16 v[8:11], v[168:171], v[216:219], v[8:11]
	v_mfma_f32_16x16x32_bf16 v[52:55], v[172:175], v[188:191], v[52:55]
	v_mfma_f32_16x16x32_bf16 v[48:51], v[180:183], v[188:191], v[48:51]
	v_mfma_f32_16x16x32_bf16 v[36:39], v[172:175], v[196:199], v[36:39]
	v_mfma_f32_16x16x32_bf16 v[32:35], v[180:183], v[196:199], v[32:35]
	v_mfma_f32_16x16x32_bf16 v[20:23], v[172:175], v[204:207], v[20:23]
	v_mfma_f32_16x16x32_bf16 v[16:19], v[180:183], v[204:207], v[16:19]
	v_mfma_f32_16x16x32_bf16 v[4:7], v[172:175], v[212:215], v[4:7]
	v_mfma_f32_16x16x32_bf16 v[0:3], v[180:183], v[212:215], v[0:3]
	v_mfma_f32_16x16x32_bf16 v[52:55], v[176:179], v[192:195], v[52:55]
	v_mfma_f32_16x16x32_bf16 v[48:51], v[184:187], v[192:195], v[48:51]
	v_mfma_f32_16x16x32_bf16 v[36:39], v[176:179], v[200:203], v[36:39]
	v_mfma_f32_16x16x32_bf16 v[32:35], v[184:187], v[200:203], v[32:35]
	v_mfma_f32_16x16x32_bf16 v[20:23], v[176:179], v[208:211], v[20:23]
	v_mfma_f32_16x16x32_bf16 v[16:19], v[184:187], v[208:211], v[16:19]
	v_mfma_f32_16x16x32_bf16 v[4:7], v[176:179], v[216:219], v[4:7]
	v_mfma_f32_16x16x32_bf16 v[0:3], v[184:187], v[216:219], v[0:3]
	s_setprio 0
	s_barrier
	s_add_i32 s11, 0, 0x18000
	s_add_i32 vcc_lo, 0, 0x1c000
	v_add_u32_e32 v168, s11, v159
	v_add_u32_e32 v184, vcc_lo, v159
	ds_read_b128 v[128:131], v168
	ds_read_b128 v[152:155], v168 offset:1024
	ds_read_b128 v[164:167], v168 offset:2048
	ds_read_b128 v[168:171], v168 offset:3072
	ds_read_b128 v[172:175], v184
	ds_read_b128 v[176:179], v184 offset:1024
	ds_read_b128 v[180:183], v184 offset:2048
	ds_read_b128 v[184:187], v184 offset:3072
	s_add_u32 s84, s84, 0x100000
	s_addc_u32 s85, s85, 0
	s_mov_b32 m0, s48
	v_lshl_add_u64 v[226:227], s[84:85], 0, v[132:133]
	ds_read_b128 v[188:191], v162 offset:32768
	ds_read_b128 v[192:195], v162 offset:33792
	ds_read_b128 v[196:199], v162 offset:34816
	ds_read_b128 v[200:203], v162 offset:35840
	ds_read_b128 v[204:207], v162 offset:36864
	ds_read_b128 v[208:211], v162 offset:37888
	ds_read_b128 v[212:215], v162 offset:38912
	ds_read_b128 v[216:219], v162 offset:39936
	global_load_lds_dwordx4 v[226:227], off
	v_lshl_add_u64 v[226:227], s[84:85], 0, v[136:137]
	s_mov_b32 m0, s49
	s_nop 0
	global_load_lds_dwordx4 v[226:227], off
	s_waitcnt vmcnt(8)
	s_waitcnt lgkmcnt(0)
	s_barrier
	s_setprio 1
	v_mfma_f32_16x16x32_bf16 v[124:127], v[128:131], v[188:191], v[124:127]
	v_mfma_f32_16x16x32_bf16 v[120:123], v[164:167], v[188:191], v[120:123]
	v_mfma_f32_16x16x32_bf16 v[108:111], v[128:131], v[196:199], v[108:111]
	v_mfma_f32_16x16x32_bf16 v[104:107], v[164:167], v[196:199], v[104:107]
	v_mfma_f32_16x16x32_bf16 v[92:95], v[128:131], v[204:207], v[92:95]
	v_mfma_f32_16x16x32_bf16 v[88:91], v[164:167], v[204:207], v[88:91]
	v_mfma_f32_16x16x32_bf16 v[76:79], v[128:131], v[212:215], v[76:79]
	v_mfma_f32_16x16x32_bf16 v[72:75], v[164:167], v[212:215], v[72:75]
	v_mfma_f32_16x16x32_bf16 v[124:127], v[152:155], v[192:195], v[124:127]
	v_mfma_f32_16x16x32_bf16 v[120:123], v[168:171], v[192:195], v[120:123]
	v_mfma_f32_16x16x32_bf16 v[108:111], v[152:155], v[200:203], v[108:111]
	v_mfma_f32_16x16x32_bf16 v[104:107], v[168:171], v[200:203], v[104:107]
	v_mfma_f32_16x16x32_bf16 v[92:95], v[152:155], v[208:211], v[92:95]
	v_mfma_f32_16x16x32_bf16 v[88:91], v[168:171], v[208:211], v[88:91]
	v_mfma_f32_16x16x32_bf16 v[76:79], v[152:155], v[216:219], v[76:79]
	v_mfma_f32_16x16x32_bf16 v[72:75], v[168:171], v[216:219], v[72:75]
	v_mfma_f32_16x16x32_bf16 v[116:119], v[172:175], v[188:191], v[116:119]
	v_mfma_f32_16x16x32_bf16 v[112:115], v[180:183], v[188:191], v[112:115]
	v_mfma_f32_16x16x32_bf16 v[100:103], v[172:175], v[196:199], v[100:103]
	v_mfma_f32_16x16x32_bf16 v[96:99], v[180:183], v[196:199], v[96:99]
	v_mfma_f32_16x16x32_bf16 v[84:87], v[172:175], v[204:207], v[84:87]
	v_mfma_f32_16x16x32_bf16 v[80:83], v[180:183], v[204:207], v[80:83]
	v_mfma_f32_16x16x32_bf16 v[68:71], v[172:175], v[212:215], v[68:71]
	v_mfma_f32_16x16x32_bf16 v[64:67], v[180:183], v[212:215], v[64:67]
	v_mfma_f32_16x16x32_bf16 v[116:119], v[176:179], v[192:195], v[116:119]
	v_mfma_f32_16x16x32_bf16 v[112:115], v[184:187], v[192:195], v[112:115]
	v_mfma_f32_16x16x32_bf16 v[100:103], v[176:179], v[200:203], v[100:103]
	v_mfma_f32_16x16x32_bf16 v[96:99], v[184:187], v[200:203], v[96:99]
	v_mfma_f32_16x16x32_bf16 v[84:87], v[176:179], v[208:211], v[84:87]
	v_mfma_f32_16x16x32_bf16 v[80:83], v[184:187], v[208:211], v[80:83]
	v_mfma_f32_16x16x32_bf16 v[68:71], v[176:179], v[216:219], v[68:71]
	v_mfma_f32_16x16x32_bf16 v[64:67], v[184:187], v[216:219], v[64:67]
	s_setprio 0
	s_barrier
; #define PG8_STAGE(bufoff, gbase, voff) do { _Pragma("unroll") for (int _i = 0; _i < 2; ++_i) \
;         __builtin_amdgcn_global_load_lds((const unsigned*)((const char*)(gbase) + (voff)[_i]), (PG8_LAS unsigned*)(lds + (bufoff) + ldsw + _i * 8192), 16, 0, 0); } while (0)
; #define PG8_LDA(dst, b, h) do { _Pragma("unroll") for (int m = 0; m < 4; ++m) _Pragma("unroll") for (int k = 0; k < 2; ++k) dst[m][k] = *(const PG8_LAS bf16x8*)(lds + PG8_SA(b, h) + aoff + m * 2048 + k * 1024); } while (0)
; #define PG8_MMA(ai, bj, At, Bt) do { __builtin_amdgcn_s_setprio(1); _Pragma("unroll") for (int m = 0; m < 4; ++m) _Pragma("unroll") for (int n = 0; n < 2; ++n) _Pragma("unroll") for (int k = 0; k < 2; ++k) \
;         acc[ai][bj][m][n] = __builtin_amdgcn_mfma_f32_16x16x32_bf16(Bt[n][k], At[m][k], acc[ai][bj][m][n], 0, 0, 0); __builtin_amdgcn_s_setprio(0); } while (0)
; #define PG8_WAIT_V(n) asm volatile("s_waitcnt vmcnt(" #n ")" ::: "memory")
; #define PG8_WAIT_L(n) asm volatile("s_waitcnt lgkmcnt(" #n ")" ::: "memory")
; #define PG8_BAR __builtin_amdgcn_s_barrier()
; #define PG8_SCHED __builtin_amdgcn_sched_barrier(0)
; template <class Epi, class Sched, bool ALIGN_EPI = false, bool SP2 = false>
; __device__ __forceinline__ void gemm_phase(PG8_LAS unsigned char* lds, const Gemm g, const Sched& S, const Epi& E, const int wave_in) {
;     ...
;         for (int t = 0; t < nt; t += 2) {
;             const bool last = (t == nt - 2);
;             const char* a1 = cA + (size_t)(t + 1) * kstep;
;             const char* a2 = last ? nA : cA + (size_t)(t + 2) * kstep; const char* b2 = last ? nB : cB + (size_t)(t + 2) * kstep;
;             const char* a3 = a2 + kstep; const char* b3 = b2 + kstep;
;             if (last && has_next) S.a_ready(nxt);
;     ...
;             PG8_LDA(At, 1, 1); PG8_STAGE(PG8_SB(1, 0), b3, voffB); PG8_STAGE(PG8_SB(1, 1), b3 + hstep, voffB); PG8_STAGE(PG8_SA(1, 0), a3, voffA);
;             PG8_WAIT_V(8); PG8_WAIT_L(0); PG8_BAR; PG8_MMA(1, 0, At, B0); PG8_MMA(1, 1, At, B1); PG8_BAR; PG8_SCHED;
	s_add_i32 s11, s11, s41
	v_lshl_add_u64 v[156:157], v[156:157], 0, s[68:69]
	s_mov_b32 m0, s11
	ds_read_b128 v[188:191], v162 offset:49152
	ds_read_b128 v[192:195], v162 offset:50176
	ds_read_b128 v[196:199], v162 offset:51200
	ds_read_b128 v[200:203], v162 offset:52224
	ds_read_b128 v[204:207], v162 offset:53248
	ds_read_b128 v[208:211], v162 offset:54272
	ds_read_b128 v[212:215], v162 offset:55296
	ds_read_b128 v[216:219], v162 offset:56320
	global_load_lds_dwordx4 v[156:157], off
	s_add_i32 m0, s11, 0x2000
	s_add_u32 s60, s60, 0x20080
	v_lshl_add_u64 v[156:157], v[220:221], 0, s[68:69]
	s_addc_u32 s61, s61, 0
	s_add_i32 s11, vcc_lo, s41
	global_load_lds_dwordx4 v[156:157], off
	v_lshl_add_u64 v[156:157], s[60:61], 0, v[134:135]
	s_mov_b32 m0, s11
	s_nop 0
	global_load_lds_dwordx4 v[156:157], off
	v_lshl_add_u64 v[156:157], s[60:61], 0, v[138:139]
	s_add_i32 m0, s11, 0x2000
	s_nop 0
	global_load_lds_dwordx4 v[156:157], off
	v_lshl_add_u64 v[156:157], v[222:223], 0, s[68:69]
	s_mov_b32 m0, s51
	s_nop 0
	global_load_lds_dwordx4 v[156:157], off
	v_lshl_add_u64 v[156:157], v[224:225], 0, s[68:69]
	s_mov_b32 m0, s39
	s_nop 0
	global_load_lds_dwordx4 v[156:157], off
	s_waitcnt vmcnt(8)
	s_waitcnt lgkmcnt(0)
	s_barrier
	s_setprio 1
	v_mfma_f32_16x16x32_bf16 v[60:63], v[128:131], v[188:191], v[60:63]
	v_mfma_f32_16x16x32_bf16 v[56:59], v[164:167], v[188:191], v[56:59]
	v_mfma_f32_16x16x32_bf16 v[44:47], v[128:131], v[196:199], v[44:47]
	v_mfma_f32_16x16x32_bf16 v[40:43], v[164:167], v[196:199], v[40:43]
	v_mfma_f32_16x16x32_bf16 v[28:31], v[128:131], v[204:207], v[28:31]
	v_mfma_f32_16x16x32_bf16 v[24:27], v[164:167], v[204:207], v[24:27]
	v_mfma_f32_16x16x32_bf16 v[12:15], v[128:131], v[212:215], v[12:15]
	v_mfma_f32_16x16x32_bf16 v[8:11], v[164:167], v[212:215], v[8:11]
	v_mfma_f32_16x16x32_bf16 v[60:63], v[152:155], v[192:195], v[60:63]
	v_mfma_f32_16x16x32_bf16 v[56:59], v[168:171], v[192:195], v[56:59]
	v_mfma_f32_16x16x32_bf16 v[44:47], v[152:155], v[200:203], v[44:47]
	v_mfma_f32_16x16x32_bf16 v[40:43], v[168:171], v[200:203], v[40:43]
	v_mfma_f32_16x16x32_bf16 v[28:31], v[152:155], v[208:211], v[28:31]
	v_mfma_f32_16x16x32_bf16 v[24:27], v[168:171], v[208:211], v[24:27]
	v_mfma_f32_16x16x32_bf16 v[12:15], v[152:155], v[216:219], v[12:15]
	v_mfma_f32_16x16x32_bf16 v[8:11], v[168:171], v[216:219], v[8:11]
	v_mfma_f32_16x16x32_bf16 v[52:55], v[172:175], v[188:191], v[52:55]
	v_mfma_f32_16x16x32_bf16 v[48:51], v[180:183], v[188:191], v[48:51]
	v_mfma_f32_16x16x32_bf16 v[36:39], v[172:175], v[196:199], v[36:39]
	v_mfma_f32_16x16x32_bf16 v[32:35], v[180:183], v[196:199], v[32:35]
	v_mfma_f32_16x16x32_bf16 v[20:23], v[172:175], v[204:207], v[20:23]
	v_mfma_f32_16x16x32_bf16 v[16:19], v[180:183], v[204:207], v[16:19]
	v_mfma_f32_16x16x32_bf16 v[4:7], v[172:175], v[212:215], v[4:7]
	v_mfma_f32_16x16x32_bf16 v[0:3], v[180:183], v[212:215], v[0:3]
	v_mfma_f32_16x16x32_bf16 v[52:55], v[176:179], v[192:195], v[52:55]
	v_mfma_f32_16x16x32_bf16 v[48:51], v[184:187], v[192:195], v[48:51]
	v_mfma_f32_16x16x32_bf16 v[36:39], v[176:179], v[200:203], v[36:39]
	v_mfma_f32_16x16x32_bf16 v[32:35], v[184:187], v[200:203], v[32:35]
	v_mfma_f32_16x16x32_bf16 v[20:23], v[176:179], v[208:211], v[20:23]
	v_mfma_f32_16x16x32_bf16 v[16:19], v[184:187], v[208:211], v[16:19]
	v_mfma_f32_16x16x32_bf16 v[4:7], v[176:179], v[216:219], v[4:7]
	v_mfma_f32_16x16x32_bf16 v[0:3], v[184:187], v[216:219], v[0:3]
	s_setprio 0
	s_barrier
	s_add_i32 s75, s75, 2
	s_add_u32 s18, s18, 0x100
	s_addc_u32 s19, s19, 0
	s_add_u32 s62, s62, 0x100
	s_addc_u32 s73, s73, 0
	s_cmp_gt_u32 s75, 5
	s_cbranch_scc0 .LBB0_786
	s_and_b64 vcc, exec, s[70:71]
	s_cbranch_vccz .LBB0_789
	s_barrier

; #define PG8_STAGE(bufoff, gbase, voff) do { _Pragma("unroll") for (int _i = 0; _i < 2; ++_i) \
;         __builtin_amdgcn_global_load_lds((const unsigned*)((const char*)(gbase) + (voff)[_i]), (PG8_LAS unsigned*)(lds + (bufoff) + ldsw + _i * 8192), 16, 0, 0); } while (0)
; #define PG8_LDA(dst, b, h) do { _Pragma("unroll") for (int m = 0; m < 4; ++m) _Pragma("unroll") for (int k = 0; k < 2; ++k) dst[m][k] = *(const PG8_LAS bf16x8*)(lds + PG8_SA(b, h) + aoff + m * 2048 + k * 1024); } while (0)
; #define PG8_LDB(dst, b, h) do { _Pragma("unroll") for (int n = 0; n < 2; ++n) _Pragma("unroll") for (int k = 0; k < 2; ++k) dst[n][k] = *(const PG8_LAS bf16x8*)(lds + PG8_SB(b, h) + boff + n * 2048 + k * 1024); } while (0)
; #define PG8_MMA(ai, bj, At, Bt) do { __builtin_amdgcn_s_setprio(1); _Pragma("unroll") for (int m = 0; m < 4; ++m) _Pragma("unroll") for (int n = 0; n < 2; ++n) _Pragma("unroll") for (int k = 0; k < 2; ++k) \
;         acc[ai][bj][m][n] = __builtin_amdgcn_mfma_f32_16x16x32_bf16(Bt[n][k], At[m][k], acc[ai][bj][m][n], 0, 0, 0); __builtin_amdgcn_s_setprio(0); } while (0)
; #define PG8_WAIT_V(n) asm volatile("s_waitcnt vmcnt(" #n ")" ::: "memory")
; #define PG8_WAIT_L(n) asm volatile("s_waitcnt lgkmcnt(" #n ")" ::: "memory")
; #define PG8_BAR __builtin_amdgcn_s_barrier()
; #define PG8_SCHED __builtin_amdgcn_sched_barrier(0)
; template <class Epi, class Sched, bool ALIGN_EPI = false, bool SP2 = false>
; __device__ __forceinline__ void gemm_phase(PG8_LAS unsigned char* lds, const Gemm g, const Sched& S, const Epi& E, const int wave_in) {
;     ...
;             const char* a2 = last ? nA : cA + (size_t)(t + 2) * kstep; const char* b2 = last ? nB : cB + (size_t)(t + 2) * kstep;
;     ...
;             PG8_LDB(B0, 0, 0); PG8_LDB(B1, 0, 1); PG8_SCHED; PG8_LDA(At, 0, 0); PG8_STAGE(PG8_SA(1, 1), a1 + hstepA, voffA);
;             PG8_WAIT_V(8); PG8_WAIT_L(0); PG8_BAR; PG8_MMA(0, 0, At, B0); PG8_MMA(0, 1, At, B1); PG8_BAR; PG8_SCHED;
;             PG8_LDA(At, 0, 1); PG8_STAGE(PG8_SB(0, 0), b2, voffB); PG8_STAGE(PG8_SB(0, 1), b2 + hstep, voffB); PG8_STAGE(PG8_SA(0, 0), a2, voffA);
;             PG8_WAIT_V(8); PG8_WAIT_L(0); PG8_BAR; PG8_MMA(1, 0, At, B0); PG8_MMA(1, 1, At, B1); PG8_BAR; PG8_SCHED;
.LBB0_838:
	ds_read_b128 v[146:149], v152
	ds_read_b128 v[156:159], v152 offset:1024
	ds_read_b128 v[160:163], v152 offset:2048
	ds_read_b128 v[164:167], v152 offset:3072
	ds_read_b128 v[168:171], v153
	ds_read_b128 v[172:175], v153 offset:1024
	ds_read_b128 v[176:179], v153 offset:2048
	ds_read_b128 v[180:183], v153 offset:3072
	s_add_u32 s11, s18, 0xfff00080
	s_addc_u32 s78, s19, -1
	s_cmp_eq_u32 s94, 4
	s_cselect_b32 s85, s1, s78
	s_cselect_b32 s84, s36, s11
	s_cselect_b32 s79, s37, s93
	s_cselect_b32 s78, s69, s71
	v_lshl_add_u64 v[216:217], s[18:19], 0, v[136:137]
	s_add_i32 m0, s42, 0xc000
	ds_read_b128 v[184:187], v154
	ds_read_b128 v[188:191], v154 offset:1024
	ds_read_b128 v[192:195], v154 offset:2048
	ds_read_b128 v[196:199], v154 offset:3072
	ds_read_b128 v[200:203], v154 offset:4096
	ds_read_b128 v[204:207], v154 offset:5120
	ds_read_b128 v[208:211], v154 offset:6144
	ds_read_b128 v[212:215], v154 offset:7168
	global_load_lds_dwordx4 v[216:217], off
	v_lshl_add_u64 v[216:217], s[18:19], 0, v[138:139]
	s_add_i32 m0, s42, 0xe000
	s_nop 0
	global_load_lds_dwordx4 v[216:217], off
	s_waitcnt vmcnt(8)
	s_waitcnt lgkmcnt(0)
	s_barrier
	s_setprio 1
	v_mfma_f32_16x16x32_bf16 v[124:127], v[146:149], v[184:187], v[124:127]
	v_mfma_f32_16x16x32_bf16 v[120:123], v[160:163], v[184:187], v[120:123]
	v_mfma_f32_16x16x32_bf16 v[108:111], v[146:149], v[192:195], v[108:111]
	v_mfma_f32_16x16x32_bf16 v[104:107], v[160:163], v[192:195], v[104:107]
	v_mfma_f32_16x16x32_bf16 v[92:95], v[146:149], v[200:203], v[92:95]
	v_mfma_f32_16x16x32_bf16 v[88:91], v[160:163], v[200:203], v[88:91]
	v_mfma_f32_16x16x32_bf16 v[76:79], v[146:149], v[208:211], v[76:79]
	v_mfma_f32_16x16x32_bf16 v[72:75], v[160:163], v[208:211], v[72:75]
	v_mfma_f32_16x16x32_bf16 v[124:127], v[156:159], v[188:191], v[124:127]
	v_mfma_f32_16x16x32_bf16 v[120:123], v[164:167], v[188:191], v[120:123]
	v_mfma_f32_16x16x32_bf16 v[108:111], v[156:159], v[196:199], v[108:111]
	v_mfma_f32_16x16x32_bf16 v[104:107], v[164:167], v[196:199], v[104:107]
	v_mfma_f32_16x16x32_bf16 v[92:95], v[156:159], v[204:207], v[92:95]
	v_mfma_f32_16x16x32_bf16 v[88:91], v[164:167], v[204:207], v[88:91]
	v_mfma_f32_16x16x32_bf16 v[76:79], v[156:159], v[212:215], v[76:79]
	v_mfma_f32_16x16x32_bf16 v[72:75], v[164:167], v[212:215], v[72:75]
	v_mfma_f32_16x16x32_bf16 v[116:119], v[168:171], v[184:187], v[116:119]
	v_mfma_f32_16x16x32_bf16 v[112:115], v[176:179], v[184:187], v[112:115]
	v_mfma_f32_16x16x32_bf16 v[100:103], v[168:171], v[192:195], v[100:103]
	v_mfma_f32_16x16x32_bf16 v[96:99], v[176:179], v[192:195], v[96:99]
	v_mfma_f32_16x16x32_bf16 v[84:87], v[168:171], v[200:203], v[84:87]
	v_mfma_f32_16x16x32_bf16 v[80:83], v[176:179], v[200:203], v[80:83]
	v_mfma_f32_16x16x32_bf16 v[68:71], v[168:171], v[208:211], v[68:71]
	v_mfma_f32_16x16x32_bf16 v[64:67], v[176:179], v[208:211], v[64:67]
	v_mfma_f32_16x16x32_bf16 v[116:119], v[172:175], v[188:191], v[116:119]
	v_mfma_f32_16x16x32_bf16 v[112:115], v[180:183], v[188:191], v[112:115]
	v_mfma_f32_16x16x32_bf16 v[100:103], v[172:175], v[196:199], v[100:103]
	v_mfma_f32_16x16x32_bf16 v[96:99], v[180:183], v[196:199], v[96:99]
	v_mfma_f32_16x16x32_bf16 v[84:87], v[172:175], v[204:207], v[84:87]
	v_mfma_f32_16x16x32_bf16 v[80:83], v[180:183], v[204:207], v[80:83]
	v_mfma_f32_16x16x32_bf16 v[68:71], v[172:175], v[212:215], v[68:71]
	v_mfma_f32_16x16x32_bf16 v[64:67], v[180:183], v[212:215], v[64:67]
	s_setprio 0
	s_barrier
	s_add_i32 s11, s56, s39
	v_lshl_add_u64 v[216:217], s[78:79], 0, v[132:133]
	s_mov_b32 m0, s11
	ds_read_b128 v[184:187], v154 offset:16384
	ds_read_b128 v[188:191], v154 offset:17408
	ds_read_b128 v[192:195], v154 offset:18432
	ds_read_b128 v[196:199], v154 offset:19456
	ds_read_b128 v[200:203], v154 offset:20480
	ds_read_b128 v[204:207], v154 offset:21504
	ds_read_b128 v[208:211], v154 offset:22528
	ds_read_b128 v[212:215], v154 offset:23552
	global_load_lds_dwordx4 v[216:217], off
	s_add_i32 m0, s11, 0x2000
	s_add_u32 vcc_lo, s78, 0x20000
	v_lshl_add_u64 v[218:219], s[78:79], 0, v[128:129]
	s_addc_u32 vcc_hi, s79, 0
	s_add_i32 s11, s57, s39
	global_load_lds_dwordx4 v[218:219], off
	v_lshl_add_u64 v[220:221], vcc, 0, v[132:133]
	s_mov_b32 m0, s11
	v_lshl_add_u64 v[222:223], s[84:85], 0, v[130:131]
	global_load_lds_dwordx4 v[220:221], off
	v_lshl_add_u64 v[220:221], vcc, 0, v[128:129]
	s_add_i32 m0, s11, 0x2000
	s_nop 0
	global_load_lds_dwordx4 v[220:221], off
	v_lshl_add_u64 v[220:221], s[84:85], 0, v[134:135]
	s_mov_b32 m0, s42
	s_nop 0
	global_load_lds_dwordx4 v[220:221], off
	s_mov_b32 m0, s43
	s_nop 0
	global_load_lds_dwordx4 v[222:223], off
	s_waitcnt vmcnt(8)
	s_waitcnt lgkmcnt(0)
	s_barrier
; #define PG8_STAGE(bufoff, gbase, voff) do { _Pragma("unroll") for (int _i = 0; _i < 2; ++_i) \
;         __builtin_amdgcn_global_load_lds((const unsigned*)((const char*)(gbase) + (voff)[_i]), (PG8_LAS unsigned*)(lds + (bufoff) + ldsw + _i * 8192), 16, 0, 0); } while (0)
; #define PG8_LDA(dst, b, h) do { _Pragma("unroll") for (int m = 0; m < 4; ++m) _Pragma("unroll") for (int k = 0; k < 2; ++k) dst[m][k] = *(const PG8_LAS bf16x8*)(lds + PG8_SA(b, h) + aoff + m * 2048 + k * 1024); } while (0)
; #define PG8_LDB(dst, b, h) do { _Pragma("unroll") for (int n = 0; n < 2; ++n) _Pragma("unroll") for (int k = 0; k < 2; ++k) dst[n][k] = *(const PG8_LAS bf16x8*)(lds + PG8_SB(b, h) + boff + n * 2048 + k * 1024); } while (0)
; #define PG8_MMA(ai, bj, At, Bt) do { __builtin_amdgcn_s_setprio(1); _Pragma("unroll") for (int m = 0; m < 4; ++m) _Pragma("unroll") for (int n = 0; n < 2; ++n) _Pragma("unroll") for (int k = 0; k < 2; ++k) \
;         acc[ai][bj][m][n] = __builtin_amdgcn_mfma_f32_16x16x32_bf16(Bt[n][k], At[m][k], acc[ai][bj][m][n], 0, 0, 0); __builtin_amdgcn_s_setprio(0); } while (0)
; #define PG8_WAIT_V(n) asm volatile("s_waitcnt vmcnt(" #n ")" ::: "memory")
; #define PG8_WAIT_L(n) asm volatile("s_waitcnt lgkmcnt(" #n ")" ::: "memory")
; #define PG8_BAR __builtin_amdgcn_s_barrier()
; #define PG8_SCHED __builtin_amdgcn_sched_barrier(0)
; template <class Epi, class Sched, bool ALIGN_EPI = false, bool SP2 = false>
; __device__ __forceinline__ void gemm_phase(PG8_LAS unsigned char* lds, const Gemm g, const Sched& S, const Epi& E, const int wave_in) {
;     ...
;             PG8_WAIT_V(8); PG8_WAIT_L(0); PG8_BAR; PG8_MMA(1, 0, At, B0); PG8_MMA(1, 1, At, B1); PG8_BAR; PG8_SCHED;
;             PG8_LDB(B0, 1, 0); PG8_LDB(B1, 1, 1); PG8_SCHED; PG8_LDA(At, 1, 0); PG8_STAGE(PG8_SA(0, 1), a2 + hstepA, voffA);
;             PG8_WAIT_V(8); PG8_WAIT_L(0); PG8_BAR; PG8_MMA(0, 0, At, B0); PG8_MMA(0, 1, At, B1); PG8_BAR; PG8_SCHED;
	s_setprio 1
	v_mfma_f32_16x16x32_bf16 v[60:63], v[146:149], v[184:187], v[60:63]
	v_mfma_f32_16x16x32_bf16 v[56:59], v[160:163], v[184:187], v[56:59]
	v_mfma_f32_16x16x32_bf16 v[44:47], v[146:149], v[192:195], v[44:47]
	v_mfma_f32_16x16x32_bf16 v[40:43], v[160:163], v[192:195], v[40:43]
	v_mfma_f32_16x16x32_bf16 v[28:31], v[146:149], v[200:203], v[28:31]
	v_mfma_f32_16x16x32_bf16 v[24:27], v[160:163], v[200:203], v[24:27]
	v_mfma_f32_16x16x32_bf16 v[12:15], v[146:149], v[208:211], v[12:15]
	v_mfma_f32_16x16x32_bf16 v[8:11], v[160:163], v[208:211], v[8:11]
	v_mfma_f32_16x16x32_bf16 v[60:63], v[156:159], v[188:191], v[60:63]
	v_mfma_f32_16x16x32_bf16 v[56:59], v[164:167], v[188:191], v[56:59]
	v_mfma_f32_16x16x32_bf16 v[44:47], v[156:159], v[196:199], v[44:47]
	v_mfma_f32_16x16x32_bf16 v[40:43], v[164:167], v[196:199], v[40:43]
	v_mfma_f32_16x16x32_bf16 v[28:31], v[156:159], v[204:207], v[28:31]
	v_mfma_f32_16x16x32_bf16 v[24:27], v[164:167], v[204:207], v[24:27]
	v_mfma_f32_16x16x32_bf16 v[12:15], v[156:159], v[212:215], v[12:15]
	v_mfma_f32_16x16x32_bf16 v[8:11], v[164:167], v[212:215], v[8:11]
	v_mfma_f32_16x16x32_bf16 v[52:55], v[168:171], v[184:187], v[52:55]
	v_mfma_f32_16x16x32_bf16 v[48:51], v[176:179], v[184:187], v[48:51]
	v_mfma_f32_16x16x32_bf16 v[36:39], v[168:171], v[192:195], v[36:39]
	v_mfma_f32_16x16x32_bf16 v[32:35], v[176:179], v[192:195], v[32:35]
	v_mfma_f32_16x16x32_bf16 v[20:23], v[168:171], v[200:203], v[20:23]
	v_mfma_f32_16x16x32_bf16 v[16:19], v[176:179], v[200:203], v[16:19]
	v_mfma_f32_16x16x32_bf16 v[4:7], v[168:171], v[208:211], v[4:7]
	v_mfma_f32_16x16x32_bf16 v[0:3], v[176:179], v[208:211], v[0:3]
	v_mfma_f32_16x16x32_bf16 v[52:55], v[172:175], v[188:191], v[52:55]
	v_mfma_f32_16x16x32_bf16 v[48:51], v[180:183], v[188:191], v[48:51]
	v_mfma_f32_16x16x32_bf16 v[36:39], v[172:175], v[196:199], v[36:39]
	v_mfma_f32_16x16x32_bf16 v[32:35], v[180:183], v[196:199], v[32:35]
	v_mfma_f32_16x16x32_bf16 v[20:23], v[172:175], v[204:207], v[20:23]
	v_mfma_f32_16x16x32_bf16 v[16:19], v[180:183], v[204:207], v[16:19]
	v_mfma_f32_16x16x32_bf16 v[4:7], v[172:175], v[212:215], v[4:7]
	v_mfma_f32_16x16x32_bf16 v[0:3], v[180:183], v[212:215], v[0:3]
	s_setprio 0
	s_barrier
	s_add_i32 s11, 0, 0x18000
	s_add_i32 s95, 0, 0x1c000
	v_add_u32_e32 v164, s11, v151
	v_add_u32_e32 v180, s95, v151
	ds_read_b128 v[146:149], v164
	ds_read_b128 v[156:159], v164 offset:1024
	ds_read_b128 v[160:163], v164 offset:2048
	ds_read_b128 v[164:167], v164 offset:3072
	ds_read_b128 v[168:171], v180
	ds_read_b128 v[172:175], v180 offset:1024
	ds_read_b128 v[176:179], v180 offset:2048
	ds_read_b128 v[180:183], v180 offset:3072
	s_add_u32 s84, s84, 0x100000
	s_addc_u32 s85, s85, 0
	s_mov_b32 m0, s48
	v_lshl_add_u64 v[224:225], s[84:85], 0, v[134:135]
	ds_read_b128 v[184:187], v154 offset:32768
	ds_read_b128 v[188:191], v154 offset:33792
	ds_read_b128 v[192:195], v154 offset:34816
	ds_read_b128 v[196:199], v154 offset:35840
	ds_read_b128 v[200:203], v154 offset:36864
	ds_read_b128 v[204:207], v154 offset:37888
	ds_read_b128 v[208:211], v154 offset:38912
	ds_read_b128 v[212:215], v154 offset:39936
	global_load_lds_dwordx4 v[224:225], off
	v_lshl_add_u64 v[224:225], s[84:85], 0, v[130:131]
	s_mov_b32 m0, s49
	s_nop 0
	global_load_lds_dwordx4 v[224:225], off
	s_waitcnt vmcnt(8)
	s_waitcnt lgkmcnt(0)
	s_barrier
	s_setprio 1
	v_mfma_f32_16x16x32_bf16 v[124:127], v[146:149], v[184:187], v[124:127]
	v_mfma_f32_16x16x32_bf16 v[120:123], v[160:163], v[184:187], v[120:123]
	v_mfma_f32_16x16x32_bf16 v[108:111], v[146:149], v[192:195], v[108:111]
	v_mfma_f32_16x16x32_bf16 v[104:107], v[160:163], v[192:195], v[104:107]
	v_mfma_f32_16x16x32_bf16 v[92:95], v[146:149], v[200:203], v[92:95]
	v_mfma_f32_16x16x32_bf16 v[88:91], v[160:163], v[200:203], v[88:91]
	v_mfma_f32_16x16x32_bf16 v[76:79], v[146:149], v[208:211], v[76:79]
	v_mfma_f32_16x16x32_bf16 v[72:75], v[160:163], v[208:211], v[72:75]
	v_mfma_f32_16x16x32_bf16 v[124:127], v[156:159], v[188:191], v[124:127]
	v_mfma_f32_16x16x32_bf16 v[120:123], v[164:167], v[188:191], v[120:123]
	v_mfma_f32_16x16x32_bf16 v[108:111], v[156:159], v[196:199], v[108:111]
	v_mfma_f32_16x16x32_bf16 v[104:107], v[164:167], v[196:199], v[104:107]
	v_mfma_f32_16x16x32_bf16 v[92:95], v[156:159], v[204:207], v[92:95]
	v_mfma_f32_16x16x32_bf16 v[88:91], v[164:167], v[204:207], v[88:91]
	v_mfma_f32_16x16x32_bf16 v[76:79], v[156:159], v[212:215], v[76:79]
	v_mfma_f32_16x16x32_bf16 v[72:75], v[164:167], v[212:215], v[72:75]
	v_mfma_f32_16x16x32_bf16 v[116:119], v[168:171], v[184:187], v[116:119]
	v_mfma_f32_16x16x32_bf16 v[112:115], v[176:179], v[184:187], v[112:115]
	v_mfma_f32_16x16x32_bf16 v[100:103], v[168:171], v[192:195], v[100:103]
	v_mfma_f32_16x16x32_bf16 v[96:99], v[176:179], v[192:195], v[96:99]
	v_mfma_f32_16x16x32_bf16 v[84:87], v[168:171], v[200:203], v[84:87]
	v_mfma_f32_16x16x32_bf16 v[80:83], v[176:179], v[200:203], v[80:83]
	v_mfma_f32_16x16x32_bf16 v[68:71], v[168:171], v[208:211], v[68:71]
	v_mfma_f32_16x16x32_bf16 v[64:67], v[176:179], v[208:211], v[64:67]
	v_mfma_f32_16x16x32_bf16 v[116:119], v[172:175], v[188:191], v[116:119]
	v_mfma_f32_16x16x32_bf16 v[112:115], v[180:183], v[188:191], v[112:115]
	v_mfma_f32_16x16x32_bf16 v[100:103], v[172:175], v[196:199], v[100:103]
	v_mfma_f32_16x16x32_bf16 v[96:99], v[180:183], v[196:199], v[96:99]
	v_mfma_f32_16x16x32_bf16 v[84:87], v[172:175], v[204:207], v[84:87]
	v_mfma_f32_16x16x32_bf16 v[80:83], v[180:183], v[204:207], v[80:83]
	v_mfma_f32_16x16x32_bf16 v[68:71], v[172:175], v[212:215], v[68:71]
	v_mfma_f32_16x16x32_bf16 v[64:67], v[180:183], v[212:215], v[64:67]
	s_setprio 0
	s_barrier
; #define PG8_STAGE(bufoff, gbase, voff) do { _Pragma("unroll") for (int _i = 0; _i < 2; ++_i) \
;         __builtin_amdgcn_global_load_lds((const unsigned*)((const char*)(gbase) + (voff)[_i]), (PG8_LAS unsigned*)(lds + (bufoff) + ldsw + _i * 8192), 16, 0, 0); } while (0)
; #define PG8_LDA(dst, b, h) do { _Pragma("unroll") for (int m = 0; m < 4; ++m) _Pragma("unroll") for (int k = 0; k < 2; ++k) dst[m][k] = *(const PG8_LAS bf16x8*)(lds + PG8_SA(b, h) + aoff + m * 2048 + k * 1024); } while (0)
; #define PG8_MMA(ai, bj, At, Bt) do { __builtin_amdgcn_s_setprio(1); _Pragma("unroll") for (int m = 0; m < 4; ++m) _Pragma("unroll") for (int n = 0; n < 2; ++n) _Pragma("unroll") for (int k = 0; k < 2; ++k) \
;         acc[ai][bj][m][n] = __builtin_amdgcn_mfma_f32_16x16x32_bf16(Bt[n][k], At[m][k], acc[ai][bj][m][n], 0, 0, 0); __builtin_amdgcn_s_setprio(0); } while (0)
; #define PG8_WAIT_V(n) asm volatile("s_waitcnt vmcnt(" #n ")" ::: "memory")
; #define PG8_WAIT_L(n) asm volatile("s_waitcnt lgkmcnt(" #n ")" ::: "memory")
; #define PG8_BAR __builtin_amdgcn_s_barrier()
; #define PG8_SCHED __builtin_amdgcn_sched_barrier(0)
; template <class Epi, class Sched, bool ALIGN_EPI = false, bool SP2 = false>
; __device__ __forceinline__ void gemm_phase(PG8_LAS unsigned char* lds, const Gemm g, const Sched& S, const Epi& E, const int wave_in) {
;     ...
;         for (int t = 0; t < nt; t += 2) {
;             const bool last = (t == nt - 2);
;             const char* a1 = cA + (size_t)(t + 1) * kstep;
;             const char* a2 = last ? nA : cA + (size_t)(t + 2) * kstep; const char* b2 = last ? nB : cB + (size_t)(t + 2) * kstep;
;             const char* a3 = a2 + kstep; const char* b3 = b2 + kstep;
;             if (last && has_next) S.a_ready(nxt);
;     ...
;             PG8_LDA(At, 1, 1); PG8_STAGE(PG8_SB(1, 0), b3, voffB); PG8_STAGE(PG8_SB(1, 1), b3 + hstep, voffB); PG8_STAGE(PG8_SA(1, 0), a3, voffA);
;             PG8_WAIT_V(8); PG8_WAIT_L(0); PG8_BAR; PG8_MMA(1, 0, At, B0); PG8_MMA(1, 1, At, B1); PG8_BAR; PG8_SCHED;
	s_add_i32 s11, s11, s39
	v_lshl_add_u64 v[216:217], v[216:217], 0, s[64:65]
	s_mov_b32 m0, s11
	ds_read_b128 v[184:187], v154 offset:49152
	ds_read_b128 v[188:191], v154 offset:50176
	ds_read_b128 v[192:195], v154 offset:51200
	ds_read_b128 v[196:199], v154 offset:52224
	ds_read_b128 v[200:203], v154 offset:53248
	ds_read_b128 v[204:207], v154 offset:54272
	ds_read_b128 v[208:211], v154 offset:55296
	ds_read_b128 v[212:215], v154 offset:56320
	global_load_lds_dwordx4 v[216:217], off
	s_add_i32 m0, s11, 0x2000
	s_add_u32 s78, s78, 0x20080
	v_lshl_add_u64 v[216:217], v[218:219], 0, s[64:65]
	s_addc_u32 s79, s79, 0
	s_add_i32 s11, s95, s39
	global_load_lds_dwordx4 v[216:217], off
	v_lshl_add_u64 v[216:217], s[78:79], 0, v[132:133]
	s_mov_b32 m0, s11
	s_nop 0
	global_load_lds_dwordx4 v[216:217], off
	v_lshl_add_u64 v[216:217], s[78:79], 0, v[128:129]
	s_add_i32 m0, s11, 0x2000
	s_nop 0
	global_load_lds_dwordx4 v[216:217], off
	v_lshl_add_u64 v[216:217], v[220:221], 0, s[64:65]
	s_mov_b32 m0, s50
	s_nop 0
	global_load_lds_dwordx4 v[216:217], off
	v_lshl_add_u64 v[216:217], v[222:223], 0, s[64:65]
	s_mov_b32 m0, s51
	s_nop 0
	global_load_lds_dwordx4 v[216:217], off
	s_waitcnt vmcnt(8)
	s_waitcnt lgkmcnt(0)
	s_barrier
	s_setprio 1
	v_mfma_f32_16x16x32_bf16 v[60:63], v[146:149], v[184:187], v[60:63]
	v_mfma_f32_16x16x32_bf16 v[56:59], v[160:163], v[184:187], v[56:59]
	v_mfma_f32_16x16x32_bf16 v[44:47], v[146:149], v[192:195], v[44:47]
	v_mfma_f32_16x16x32_bf16 v[40:43], v[160:163], v[192:195], v[40:43]
	v_mfma_f32_16x16x32_bf16 v[28:31], v[146:149], v[200:203], v[28:31]
	v_mfma_f32_16x16x32_bf16 v[24:27], v[160:163], v[200:203], v[24:27]
	v_mfma_f32_16x16x32_bf16 v[12:15], v[146:149], v[208:211], v[12:15]
	v_mfma_f32_16x16x32_bf16 v[8:11], v[160:163], v[208:211], v[8:11]
	v_mfma_f32_16x16x32_bf16 v[60:63], v[156:159], v[188:191], v[60:63]
	v_mfma_f32_16x16x32_bf16 v[56:59], v[164:167], v[188:191], v[56:59]
	v_mfma_f32_16x16x32_bf16 v[44:47], v[156:159], v[196:199], v[44:47]
	v_mfma_f32_16x16x32_bf16 v[40:43], v[164:167], v[196:199], v[40:43]
	v_mfma_f32_16x16x32_bf16 v[28:31], v[156:159], v[204:207], v[28:31]
	v_mfma_f32_16x16x32_bf16 v[24:27], v[164:167], v[204:207], v[24:27]
	v_mfma_f32_16x16x32_bf16 v[12:15], v[156:159], v[212:215], v[12:15]
	v_mfma_f32_16x16x32_bf16 v[8:11], v[164:167], v[212:215], v[8:11]
	v_mfma_f32_16x16x32_bf16 v[52:55], v[168:171], v[184:187], v[52:55]
	v_mfma_f32_16x16x32_bf16 v[48:51], v[176:179], v[184:187], v[48:51]
	v_mfma_f32_16x16x32_bf16 v[36:39], v[168:171], v[192:195], v[36:39]
	v_mfma_f32_16x16x32_bf16 v[32:35], v[176:179], v[192:195], v[32:35]
	v_mfma_f32_16x16x32_bf16 v[20:23], v[168:171], v[200:203], v[20:23]
	v_mfma_f32_16x16x32_bf16 v[16:19], v[176:179], v[200:203], v[16:19]
	v_mfma_f32_16x16x32_bf16 v[4:7], v[168:171], v[208:211], v[4:7]
	v_mfma_f32_16x16x32_bf16 v[0:3], v[176:179], v[208:211], v[0:3]
	v_mfma_f32_16x16x32_bf16 v[52:55], v[172:175], v[188:191], v[52:55]
	v_mfma_f32_16x16x32_bf16 v[48:51], v[180:183], v[188:191], v[48:51]
	v_mfma_f32_16x16x32_bf16 v[36:39], v[172:175], v[196:199], v[36:39]
	v_mfma_f32_16x16x32_bf16 v[32:35], v[180:183], v[196:199], v[32:35]
	v_mfma_f32_16x16x32_bf16 v[20:23], v[172:175], v[204:207], v[20:23]
	v_mfma_f32_16x16x32_bf16 v[16:19], v[180:183], v[204:207], v[16:19]
	v_mfma_f32_16x16x32_bf16 v[4:7], v[172:175], v[212:215], v[4:7]
	v_mfma_f32_16x16x32_bf16 v[0:3], v[180:183], v[212:215], v[0:3]
	s_setprio 0
	s_barrier
	s_add_i32 s94, s94, 2
	s_add_u32 s18, s18, 0x100
	s_addc_u32 s19, s19, 0
	s_add_u32 s71, s71, 0x100
	s_addc_u32 s93, s93, 0
	s_cmp_gt_u32 s94, 5
	s_cbranch_scc0 .LBB0_838
	s_and_b64 vcc, exec, s[66:67]
	s_cbranch_vccz .LBB0_841
	s_barrier

; #define PG8_STAGE(bufoff, gbase, voff) do { _Pragma("unroll") for (int _i = 0; _i < 2; ++_i) \
;         __builtin_amdgcn_global_load_lds((const unsigned*)((const char*)(gbase) + (voff)[_i]), (PG8_LAS unsigned*)(lds + (bufoff) + ldsw + _i * 8192), 16, 0, 0); } while (0)
; #define PG8_LDA(dst, b, h) do { _Pragma("unroll") for (int m = 0; m < 4; ++m) _Pragma("unroll") for (int k = 0; k < 2; ++k) dst[m][k] = *(const PG8_LAS bf16x8*)(lds + PG8_SA(b, h) + aoff + m * 2048 + k * 1024); } while (0)
; #define PG8_LDB(dst, b, h) do { _Pragma("unroll") for (int n = 0; n < 2; ++n) _Pragma("unroll") for (int k = 0; k < 2; ++k) dst[n][k] = *(const PG8_LAS bf16x8*)(lds + PG8_SB(b, h) + boff + n * 2048 + k * 1024); } while (0)
; #define PG8_MMA(ai, bj, At, Bt) do { __builtin_amdgcn_s_setprio(1); _Pragma("unroll") for (int m = 0; m < 4; ++m) _Pragma("unroll") for (int n = 0; n < 2; ++n) _Pragma("unroll") for (int k = 0; k < 2; ++k) \
;         acc[ai][bj][m][n] = __builtin_amdgcn_mfma_f32_16x16x32_bf16(Bt[n][k], At[m][k], acc[ai][bj][m][n], 0, 0, 0); __builtin_amdgcn_s_setprio(0); } while (0)
; #define PG8_WAIT_V(n) asm volatile("s_waitcnt vmcnt(" #n ")" ::: "memory")
; #define PG8_WAIT_L(n) asm volatile("s_waitcnt lgkmcnt(" #n ")" ::: "memory")
; #define PG8_BAR __builtin_amdgcn_s_barrier()
; #define PG8_SCHED __builtin_amdgcn_sched_barrier(0)
; template <class Epi, class Sched, bool ALIGN_EPI = false, bool SP2 = false>
; __device__ __forceinline__ void gemm_phase(PG8_LAS unsigned char* lds, const Gemm g, const Sched& S, const Epi& E, const int wave_in) {
;     ...
;             const char* a2 = last ? nA : cA + (size_t)(t + 2) * kstep; const char* b2 = last ? nB : cB + (size_t)(t + 2) * kstep;
;     ...
;             PG8_LDB(B0, 0, 0); PG8_LDB(B1, 0, 1); PG8_SCHED; PG8_LDA(At, 0, 0); PG8_STAGE(PG8_SA(1, 1), a1 + hstepA, voffA);
;             PG8_WAIT_V(8); PG8_WAIT_L(0); PG8_BAR; PG8_MMA(0, 0, At, B0); PG8_MMA(0, 1, At, B1); PG8_BAR; PG8_SCHED;
;             PG8_LDA(At, 0, 1); PG8_STAGE(PG8_SB(0, 0), b2, voffB); PG8_STAGE(PG8_SB(0, 1), b2 + hstep, voffB); PG8_STAGE(PG8_SA(0, 0), a2, voffA);
;             PG8_WAIT_V(8); PG8_WAIT_L(0); PG8_BAR; PG8_MMA(1, 0, At, B0); PG8_MMA(1, 1, At, B1); PG8_BAR; PG8_SCHED;
.LBB0_1303:
	ds_read_b128 v[144:147], v151
	ds_read_b128 v[156:159], v151 offset:1024
	ds_read_b128 v[160:163], v151 offset:2048
	ds_read_b128 v[164:167], v151 offset:3072
	ds_read_b128 v[168:171], v152
	ds_read_b128 v[172:175], v152 offset:1024
	ds_read_b128 v[176:179], v152 offset:2048
	ds_read_b128 v[180:183], v152 offset:3072
	s_add_u32 s68, s66, 0xfff80080
	s_addc_u32 s69, s67, -1
	s_cmp_eq_u32 s78, 28
	s_cselect_b32 s71, s43, s69
	s_cselect_b32 s70, s48, s68
	s_cselect_b32 s69, s41, s77
	s_cselect_b32 s68, s49, s76
	v_lshl_add_u64 v[216:217], s[66:67], 0, v[136:137]
	s_add_i32 m0, s33, 0xc000
	ds_read_b128 v[184:187], v153
	ds_read_b128 v[188:191], v153 offset:1024
	ds_read_b128 v[192:195], v153 offset:2048
	ds_read_b128 v[196:199], v153 offset:3072
	ds_read_b128 v[200:203], v153 offset:4096
	ds_read_b128 v[204:207], v153 offset:5120
	ds_read_b128 v[208:211], v153 offset:6144
	ds_read_b128 v[212:215], v153 offset:7168
	global_load_lds_dwordx4 v[216:217], off
	v_lshl_add_u64 v[216:217], s[66:67], 0, v[138:139]
	s_add_i32 m0, s33, 0xe000
	s_nop 0
	global_load_lds_dwordx4 v[216:217], off
	s_waitcnt vmcnt(8)
	s_waitcnt lgkmcnt(0)
	s_barrier
	s_setprio 1
	v_mfma_f32_16x16x32_bf16 v[124:127], v[144:147], v[184:187], v[124:127]
	v_mfma_f32_16x16x32_bf16 v[120:123], v[160:163], v[184:187], v[120:123]
	v_mfma_f32_16x16x32_bf16 v[108:111], v[144:147], v[192:195], v[108:111]
	v_mfma_f32_16x16x32_bf16 v[104:107], v[160:163], v[192:195], v[104:107]
	v_mfma_f32_16x16x32_bf16 v[92:95], v[144:147], v[200:203], v[92:95]
	v_mfma_f32_16x16x32_bf16 v[88:91], v[160:163], v[200:203], v[88:91]
	v_mfma_f32_16x16x32_bf16 v[76:79], v[144:147], v[208:211], v[76:79]
	v_mfma_f32_16x16x32_bf16 v[72:75], v[160:163], v[208:211], v[72:75]
	v_mfma_f32_16x16x32_bf16 v[124:127], v[156:159], v[188:191], v[124:127]
	v_mfma_f32_16x16x32_bf16 v[120:123], v[164:167], v[188:191], v[120:123]
	v_mfma_f32_16x16x32_bf16 v[108:111], v[156:159], v[196:199], v[108:111]
	v_mfma_f32_16x16x32_bf16 v[104:107], v[164:167], v[196:199], v[104:107]
	v_mfma_f32_16x16x32_bf16 v[92:95], v[156:159], v[204:207], v[92:95]
	v_mfma_f32_16x16x32_bf16 v[88:91], v[164:167], v[204:207], v[88:91]
	v_mfma_f32_16x16x32_bf16 v[76:79], v[156:159], v[212:215], v[76:79]
	v_mfma_f32_16x16x32_bf16 v[72:75], v[164:167], v[212:215], v[72:75]
	v_mfma_f32_16x16x32_bf16 v[116:119], v[168:171], v[184:187], v[116:119]
	v_mfma_f32_16x16x32_bf16 v[112:115], v[176:179], v[184:187], v[112:115]
	v_mfma_f32_16x16x32_bf16 v[100:103], v[168:171], v[192:195], v[100:103]
	v_mfma_f32_16x16x32_bf16 v[96:99], v[176:179], v[192:195], v[96:99]
	v_mfma_f32_16x16x32_bf16 v[84:87], v[168:171], v[200:203], v[84:87]
	v_mfma_f32_16x16x32_bf16 v[80:83], v[176:179], v[200:203], v[80:83]
	v_mfma_f32_16x16x32_bf16 v[68:71], v[168:171], v[208:211], v[68:71]
	v_mfma_f32_16x16x32_bf16 v[64:67], v[176:179], v[208:211], v[64:67]
	v_mfma_f32_16x16x32_bf16 v[116:119], v[172:175], v[188:191], v[116:119]
	v_mfma_f32_16x16x32_bf16 v[112:115], v[180:183], v[188:191], v[112:115]
	v_mfma_f32_16x16x32_bf16 v[100:103], v[172:175], v[196:199], v[100:103]
	v_mfma_f32_16x16x32_bf16 v[96:99], v[180:183], v[196:199], v[96:99]
	v_mfma_f32_16x16x32_bf16 v[84:87], v[172:175], v[204:207], v[84:87]
	v_mfma_f32_16x16x32_bf16 v[80:83], v[180:183], v[204:207], v[80:83]
	v_mfma_f32_16x16x32_bf16 v[68:71], v[172:175], v[212:215], v[68:71]
	v_mfma_f32_16x16x32_bf16 v[64:67], v[180:183], v[212:215], v[64:67]
	s_setprio 0
	s_barrier
	s_add_i32 s79, s74, s11
	v_lshl_add_u64 v[216:217], s[68:69], 0, v[130:131]
	s_mov_b32 m0, s79
	ds_read_b128 v[184:187], v153 offset:16384
	ds_read_b128 v[188:191], v153 offset:17408
	ds_read_b128 v[192:195], v153 offset:18432
	ds_read_b128 v[196:199], v153 offset:19456
	ds_read_b128 v[200:203], v153 offset:20480
	ds_read_b128 v[204:207], v153 offset:21504
	ds_read_b128 v[208:211], v153 offset:22528
	ds_read_b128 v[212:215], v153 offset:23552
	global_load_lds_dwordx4 v[216:217], off
	s_add_i32 m0, s79, 0x2000
	s_add_u32 s82, s68, 0x80000
	v_lshl_add_u64 v[218:219], s[68:69], 0, v[134:135]
	s_addc_u32 s83, s69, 0
	s_add_i32 s79, s75, s11
	global_load_lds_dwordx4 v[218:219], off
	v_lshl_add_u64 v[220:221], s[82:83], 0, v[130:131]
	s_mov_b32 m0, s79
	v_lshl_add_u64 v[222:223], s[70:71], 0, v[132:133]
	global_load_lds_dwordx4 v[220:221], off
	v_lshl_add_u64 v[220:221], s[82:83], 0, v[134:135]
	s_add_i32 m0, s79, 0x2000
	s_nop 0
	global_load_lds_dwordx4 v[220:221], off
	v_lshl_add_u64 v[220:221], s[70:71], 0, v[128:129]
	s_mov_b32 m0, s33
	s_nop 0
	global_load_lds_dwordx4 v[220:221], off
	s_mov_b32 m0, s35
	s_nop 0
	global_load_lds_dwordx4 v[222:223], off
	s_waitcnt vmcnt(8)
	s_waitcnt lgkmcnt(0)
	s_barrier
; #define PG8_STAGE(bufoff, gbase, voff) do { _Pragma("unroll") for (int _i = 0; _i < 2; ++_i) \
;         __builtin_amdgcn_global_load_lds((const unsigned*)((const char*)(gbase) + (voff)[_i]), (PG8_LAS unsigned*)(lds + (bufoff) + ldsw + _i * 8192), 16, 0, 0); } while (0)
; #define PG8_LDA(dst, b, h) do { _Pragma("unroll") for (int m = 0; m < 4; ++m) _Pragma("unroll") for (int k = 0; k < 2; ++k) dst[m][k] = *(const PG8_LAS bf16x8*)(lds + PG8_SA(b, h) + aoff + m * 2048 + k * 1024); } while (0)
; #define PG8_LDB(dst, b, h) do { _Pragma("unroll") for (int n = 0; n < 2; ++n) _Pragma("unroll") for (int k = 0; k < 2; ++k) dst[n][k] = *(const PG8_LAS bf16x8*)(lds + PG8_SB(b, h) + boff + n * 2048 + k * 1024); } while (0)
; #define PG8_MMA(ai, bj, At, Bt) do { __builtin_amdgcn_s_setprio(1); _Pragma("unroll") for (int m = 0; m < 4; ++m) _Pragma("unroll") for (int n = 0; n < 2; ++n) _Pragma("unroll") for (int k = 0; k < 2; ++k) \
;         acc[ai][bj][m][n] = __builtin_amdgcn_mfma_f32_16x16x32_bf16(Bt[n][k], At[m][k], acc[ai][bj][m][n], 0, 0, 0); __builtin_amdgcn_s_setprio(0); } while (0)
; #define PG8_WAIT_V(n) asm volatile("s_waitcnt vmcnt(" #n ")" ::: "memory")
; #define PG8_WAIT_L(n) asm volatile("s_waitcnt lgkmcnt(" #n ")" ::: "memory")
; #define PG8_BAR __builtin_amdgcn_s_barrier()
; #define PG8_SCHED __builtin_amdgcn_sched_barrier(0)
; template <class Epi, class Sched, bool ALIGN_EPI = false, bool SP2 = false>
; __device__ __forceinline__ void gemm_phase(PG8_LAS unsigned char* lds, const Gemm g, const Sched& S, const Epi& E, const int wave_in) {
;     ...
;             PG8_WAIT_V(8); PG8_WAIT_L(0); PG8_BAR; PG8_MMA(1, 0, At, B0); PG8_MMA(1, 1, At, B1); PG8_BAR; PG8_SCHED;
;             PG8_LDB(B0, 1, 0); PG8_LDB(B1, 1, 1); PG8_SCHED; PG8_LDA(At, 1, 0); PG8_STAGE(PG8_SA(0, 1), a2 + hstepA, voffA);
;             PG8_WAIT_V(8); PG8_WAIT_L(0); PG8_BAR; PG8_MMA(0, 0, At, B0); PG8_MMA(0, 1, At, B1); PG8_BAR; PG8_SCHED;
	s_setprio 1
	v_mfma_f32_16x16x32_bf16 v[60:63], v[144:147], v[184:187], v[60:63]
	v_mfma_f32_16x16x32_bf16 v[56:59], v[160:163], v[184:187], v[56:59]
	v_mfma_f32_16x16x32_bf16 v[44:47], v[144:147], v[192:195], v[44:47]
	v_mfma_f32_16x16x32_bf16 v[40:43], v[160:163], v[192:195], v[40:43]
	v_mfma_f32_16x16x32_bf16 v[28:31], v[144:147], v[200:203], v[28:31]
	v_mfma_f32_16x16x32_bf16 v[24:27], v[160:163], v[200:203], v[24:27]
	v_mfma_f32_16x16x32_bf16 v[12:15], v[144:147], v[208:211], v[12:15]
	v_mfma_f32_16x16x32_bf16 v[8:11], v[160:163], v[208:211], v[8:11]
	v_mfma_f32_16x16x32_bf16 v[60:63], v[156:159], v[188:191], v[60:63]
	v_mfma_f32_16x16x32_bf16 v[56:59], v[164:167], v[188:191], v[56:59]
	v_mfma_f32_16x16x32_bf16 v[44:47], v[156:159], v[196:199], v[44:47]
	v_mfma_f32_16x16x32_bf16 v[40:43], v[164:167], v[196:199], v[40:43]
	v_mfma_f32_16x16x32_bf16 v[28:31], v[156:159], v[204:207], v[28:31]
	v_mfma_f32_16x16x32_bf16 v[24:27], v[164:167], v[204:207], v[24:27]
	v_mfma_f32_16x16x32_bf16 v[12:15], v[156:159], v[212:215], v[12:15]
	v_mfma_f32_16x16x32_bf16 v[8:11], v[164:167], v[212:215], v[8:11]
	v_mfma_f32_16x16x32_bf16 v[52:55], v[168:171], v[184:187], v[52:55]
	v_mfma_f32_16x16x32_bf16 v[48:51], v[176:179], v[184:187], v[48:51]
	v_mfma_f32_16x16x32_bf16 v[36:39], v[168:171], v[192:195], v[36:39]
	v_mfma_f32_16x16x32_bf16 v[32:35], v[176:179], v[192:195], v[32:35]
	v_mfma_f32_16x16x32_bf16 v[20:23], v[168:171], v[200:203], v[20:23]
	v_mfma_f32_16x16x32_bf16 v[16:19], v[176:179], v[200:203], v[16:19]
	v_mfma_f32_16x16x32_bf16 v[4:7], v[168:171], v[208:211], v[4:7]
	v_mfma_f32_16x16x32_bf16 v[0:3], v[176:179], v[208:211], v[0:3]
	v_mfma_f32_16x16x32_bf16 v[52:55], v[172:175], v[188:191], v[52:55]
	v_mfma_f32_16x16x32_bf16 v[48:51], v[180:183], v[188:191], v[48:51]
	v_mfma_f32_16x16x32_bf16 v[36:39], v[172:175], v[196:199], v[36:39]
	v_mfma_f32_16x16x32_bf16 v[32:35], v[180:183], v[196:199], v[32:35]
	v_mfma_f32_16x16x32_bf16 v[20:23], v[172:175], v[204:207], v[20:23]
	v_mfma_f32_16x16x32_bf16 v[16:19], v[180:183], v[204:207], v[16:19]
	v_mfma_f32_16x16x32_bf16 v[4:7], v[172:175], v[212:215], v[4:7]
	v_mfma_f32_16x16x32_bf16 v[0:3], v[180:183], v[212:215], v[0:3]
	s_setprio 0
	s_barrier
	s_add_i32 s79, 0, 0x18000
	v_add_u32_e32 v155, s79, v149
	s_add_i32 s82, 0, 0x1c000
	ds_read_b128 v[144:147], v155
	ds_read_b128 v[156:159], v155 offset:1024
	ds_read_b128 v[160:163], v155 offset:2048
	ds_read_b128 v[164:167], v155 offset:3072
	v_add_u32_e32 v155, s82, v149
	ds_read_b128 v[168:171], v155
	ds_read_b128 v[172:175], v155 offset:1024
	ds_read_b128 v[176:179], v155 offset:2048
	ds_read_b128 v[180:183], v155 offset:3072
	s_add_u32 s70, s70, 0x80000
	s_addc_u32 s71, s71, 0
	s_mov_b32 m0, s50
	v_lshl_add_u64 v[224:225], s[70:71], 0, v[128:129]
	ds_read_b128 v[184:187], v153 offset:32768
	ds_read_b128 v[188:191], v153 offset:33792
	ds_read_b128 v[192:195], v153 offset:34816
	ds_read_b128 v[196:199], v153 offset:35840
	ds_read_b128 v[200:203], v153 offset:36864
	ds_read_b128 v[204:207], v153 offset:37888
	ds_read_b128 v[208:211], v153 offset:38912
	ds_read_b128 v[212:215], v153 offset:39936
	global_load_lds_dwordx4 v[224:225], off
	v_lshl_add_u64 v[224:225], s[70:71], 0, v[132:133]
	s_mov_b32 m0, s51
	s_nop 0
	global_load_lds_dwordx4 v[224:225], off
	s_waitcnt vmcnt(8)
	s_waitcnt lgkmcnt(0)
	s_barrier
	s_setprio 1
	v_mfma_f32_16x16x32_bf16 v[124:127], v[144:147], v[184:187], v[124:127]
	v_mfma_f32_16x16x32_bf16 v[120:123], v[160:163], v[184:187], v[120:123]
	v_mfma_f32_16x16x32_bf16 v[108:111], v[144:147], v[192:195], v[108:111]
	v_mfma_f32_16x16x32_bf16 v[104:107], v[160:163], v[192:195], v[104:107]
	v_mfma_f32_16x16x32_bf16 v[92:95], v[144:147], v[200:203], v[92:95]
	v_mfma_f32_16x16x32_bf16 v[88:91], v[160:163], v[200:203], v[88:91]
	v_mfma_f32_16x16x32_bf16 v[76:79], v[144:147], v[208:211], v[76:79]
	v_mfma_f32_16x16x32_bf16 v[72:75], v[160:163], v[208:211], v[72:75]
	v_mfma_f32_16x16x32_bf16 v[124:127], v[156:159], v[188:191], v[124:127]
	v_mfma_f32_16x16x32_bf16 v[120:123], v[164:167], v[188:191], v[120:123]
	v_mfma_f32_16x16x32_bf16 v[108:111], v[156:159], v[196:199], v[108:111]
	v_mfma_f32_16x16x32_bf16 v[104:107], v[164:167], v[196:199], v[104:107]
	v_mfma_f32_16x16x32_bf16 v[92:95], v[156:159], v[204:207], v[92:95]
	v_mfma_f32_16x16x32_bf16 v[88:91], v[164:167], v[204:207], v[88:91]
	v_mfma_f32_16x16x32_bf16 v[76:79], v[156:159], v[212:215], v[76:79]
	v_mfma_f32_16x16x32_bf16 v[72:75], v[164:167], v[212:215], v[72:75]
	v_mfma_f32_16x16x32_bf16 v[116:119], v[168:171], v[184:187], v[116:119]
	v_mfma_f32_16x16x32_bf16 v[112:115], v[176:179], v[184:187], v[112:115]
	v_mfma_f32_16x16x32_bf16 v[100:103], v[168:171], v[192:195], v[100:103]
	v_mfma_f32_16x16x32_bf16 v[96:99], v[176:179], v[192:195], v[96:99]
	v_mfma_f32_16x16x32_bf16 v[84:87], v[168:171], v[200:203], v[84:87]
	v_mfma_f32_16x16x32_bf16 v[80:83], v[176:179], v[200:203], v[80:83]
	v_mfma_f32_16x16x32_bf16 v[68:71], v[168:171], v[208:211], v[68:71]
	v_mfma_f32_16x16x32_bf16 v[64:67], v[176:179], v[208:211], v[64:67]
	v_mfma_f32_16x16x32_bf16 v[116:119], v[172:175], v[188:191], v[116:119]
	v_mfma_f32_16x16x32_bf16 v[112:115], v[180:183], v[188:191], v[112:115]
	v_mfma_f32_16x16x32_bf16 v[100:103], v[172:175], v[196:199], v[100:103]
	v_mfma_f32_16x16x32_bf16 v[96:99], v[180:183], v[196:199], v[96:99]
	v_mfma_f32_16x16x32_bf16 v[84:87], v[172:175], v[204:207], v[84:87]
	v_mfma_f32_16x16x32_bf16 v[80:83], v[180:183], v[204:207], v[80:83]
	v_mfma_f32_16x16x32_bf16 v[68:71], v[172:175], v[212:215], v[68:71]
	v_mfma_f32_16x16x32_bf16 v[64:67], v[180:183], v[212:215], v[64:67]
	s_setprio 0
	s_barrier
; #define PG8_STAGE(bufoff, gbase, voff) do { _Pragma("unroll") for (int _i = 0; _i < 2; ++_i) \
;         __builtin_amdgcn_global_load_lds((const unsigned*)((const char*)(gbase) + (voff)[_i]), (PG8_LAS unsigned*)(lds + (bufoff) + ldsw + _i * 8192), 16, 0, 0); } while (0)
; #define PG8_LDA(dst, b, h) do { _Pragma("unroll") for (int m = 0; m < 4; ++m) _Pragma("unroll") for (int k = 0; k < 2; ++k) dst[m][k] = *(const PG8_LAS bf16x8*)(lds + PG8_SA(b, h) + aoff + m * 2048 + k * 1024); } while (0)
; #define PG8_MMA(ai, bj, At, Bt) do { __builtin_amdgcn_s_setprio(1); _Pragma("unroll") for (int m = 0; m < 4; ++m) _Pragma("unroll") for (int n = 0; n < 2; ++n) _Pragma("unroll") for (int k = 0; k < 2; ++k) \
;         acc[ai][bj][m][n] = __builtin_amdgcn_mfma_f32_16x16x32_bf16(Bt[n][k], At[m][k], acc[ai][bj][m][n], 0, 0, 0); __builtin_amdgcn_s_setprio(0); } while (0)
; #define PG8_WAIT_V(n) asm volatile("s_waitcnt vmcnt(" #n ")" ::: "memory")
; #define PG8_WAIT_L(n) asm volatile("s_waitcnt lgkmcnt(" #n ")" ::: "memory")
; #define PG8_BAR __builtin_amdgcn_s_barrier()
; #define PG8_SCHED __builtin_amdgcn_sched_barrier(0)
; template <class Epi, class Sched, bool ALIGN_EPI = false, bool SP2 = false>
; __device__ __forceinline__ void gemm_phase(PG8_LAS unsigned char* lds, const Gemm g, const Sched& S, const Epi& E, const int wave_in) {
;     ...
;         for (int t = 0; t < nt; t += 2) {
;             const bool last = (t == nt - 2);
;             const char* a1 = cA + (size_t)(t + 1) * kstep;
;             const char* a2 = last ? nA : cA + (size_t)(t + 2) * kstep; const char* b2 = last ? nB : cB + (size_t)(t + 2) * kstep;
;             const char* a3 = a2 + kstep; const char* b3 = b2 + kstep;
;             if (last && has_next) S.a_ready(nxt);
;     ...
;             PG8_LDA(At, 1, 1); PG8_STAGE(PG8_SB(1, 0), b3, voffB); PG8_STAGE(PG8_SB(1, 1), b3 + hstep, voffB); PG8_STAGE(PG8_SA(1, 0), a3, voffA);
;             PG8_WAIT_V(8); PG8_WAIT_L(0); PG8_BAR; PG8_MMA(1, 0, At, B0); PG8_MMA(1, 1, At, B1); PG8_BAR; PG8_SCHED;
	s_add_i32 s70, s79, s11
	v_lshl_add_u64 v[216:217], v[216:217], 0, s[18:19]
	s_mov_b32 m0, s70
	ds_read_b128 v[184:187], v153 offset:49152
	ds_read_b128 v[188:191], v153 offset:50176
	ds_read_b128 v[192:195], v153 offset:51200
	ds_read_b128 v[196:199], v153 offset:52224
	ds_read_b128 v[200:203], v153 offset:53248
	ds_read_b128 v[204:207], v153 offset:54272
	ds_read_b128 v[208:211], v153 offset:55296
	ds_read_b128 v[212:215], v153 offset:56320
	global_load_lds_dwordx4 v[216:217], off
	s_add_i32 m0, s70, 0x2000
	s_add_u32 s68, s68, 0x80080
	v_lshl_add_u64 v[216:217], v[218:219], 0, s[18:19]
	s_addc_u32 s69, s69, 0
	s_add_i32 s70, s82, s11
	global_load_lds_dwordx4 v[216:217], off
	v_lshl_add_u64 v[216:217], s[68:69], 0, v[130:131]
	s_mov_b32 m0, s70
	s_nop 0
	global_load_lds_dwordx4 v[216:217], off
	v_lshl_add_u64 v[216:217], s[68:69], 0, v[134:135]
	s_add_i32 m0, s70, 0x2000
	s_nop 0
	global_load_lds_dwordx4 v[216:217], off
	v_lshl_add_u64 v[216:217], v[220:221], 0, s[18:19]
	s_mov_b32 m0, s65
	s_nop 0
	global_load_lds_dwordx4 v[216:217], off
	v_lshl_add_u64 v[216:217], v[222:223], 0, s[18:19]
	s_mov_b32 m0, s72
	s_nop 0
	global_load_lds_dwordx4 v[216:217], off
	s_waitcnt vmcnt(8)
	s_waitcnt lgkmcnt(0)
	s_barrier
	s_setprio 1
	v_mfma_f32_16x16x32_bf16 v[60:63], v[144:147], v[184:187], v[60:63]
	v_mfma_f32_16x16x32_bf16 v[56:59], v[160:163], v[184:187], v[56:59]
	v_mfma_f32_16x16x32_bf16 v[44:47], v[144:147], v[192:195], v[44:47]
	v_mfma_f32_16x16x32_bf16 v[40:43], v[160:163], v[192:195], v[40:43]
	v_mfma_f32_16x16x32_bf16 v[28:31], v[144:147], v[200:203], v[28:31]
	v_mfma_f32_16x16x32_bf16 v[24:27], v[160:163], v[200:203], v[24:27]
	v_mfma_f32_16x16x32_bf16 v[12:15], v[144:147], v[208:211], v[12:15]
	v_mfma_f32_16x16x32_bf16 v[8:11], v[160:163], v[208:211], v[8:11]
	v_mfma_f32_16x16x32_bf16 v[60:63], v[156:159], v[188:191], v[60:63]
	v_mfma_f32_16x16x32_bf16 v[56:59], v[164:167], v[188:191], v[56:59]
	v_mfma_f32_16x16x32_bf16 v[44:47], v[156:159], v[196:199], v[44:47]
	v_mfma_f32_16x16x32_bf16 v[40:43], v[164:167], v[196:199], v[40:43]
	v_mfma_f32_16x16x32_bf16 v[28:31], v[156:159], v[204:207], v[28:31]
	v_mfma_f32_16x16x32_bf16 v[24:27], v[164:167], v[204:207], v[24:27]
	v_mfma_f32_16x16x32_bf16 v[12:15], v[156:159], v[212:215], v[12:15]
	v_mfma_f32_16x16x32_bf16 v[8:11], v[164:167], v[212:215], v[8:11]
	v_mfma_f32_16x16x32_bf16 v[52:55], v[168:171], v[184:187], v[52:55]
	v_mfma_f32_16x16x32_bf16 v[48:51], v[176:179], v[184:187], v[48:51]
	v_mfma_f32_16x16x32_bf16 v[36:39], v[168:171], v[192:195], v[36:39]
	v_mfma_f32_16x16x32_bf16 v[32:35], v[176:179], v[192:195], v[32:35]
	v_mfma_f32_16x16x32_bf16 v[20:23], v[168:171], v[200:203], v[20:23]
	v_mfma_f32_16x16x32_bf16 v[16:19], v[176:179], v[200:203], v[16:19]
	v_mfma_f32_16x16x32_bf16 v[4:7], v[168:171], v[208:211], v[4:7]
	v_mfma_f32_16x16x32_bf16 v[0:3], v[176:179], v[208:211], v[0:3]
	v_mfma_f32_16x16x32_bf16 v[52:55], v[172:175], v[188:191], v[52:55]
	v_mfma_f32_16x16x32_bf16 v[48:51], v[180:183], v[188:191], v[48:51]
	v_mfma_f32_16x16x32_bf16 v[36:39], v[172:175], v[196:199], v[36:39]
	v_mfma_f32_16x16x32_bf16 v[32:35], v[180:183], v[196:199], v[32:35]
	v_mfma_f32_16x16x32_bf16 v[20:23], v[172:175], v[204:207], v[20:23]
	v_mfma_f32_16x16x32_bf16 v[16:19], v[180:183], v[204:207], v[16:19]
	v_mfma_f32_16x16x32_bf16 v[4:7], v[172:175], v[212:215], v[4:7]
	v_mfma_f32_16x16x32_bf16 v[0:3], v[180:183], v[212:215], v[0:3]
	s_setprio 0
	s_barrier
	s_add_i32 s78, s78, 2
	s_add_u32 s66, s66, 0x100
	s_addc_u32 s67, s67, 0
	s_add_u32 s76, s76, 0x100
	s_addc_u32 s77, s77, 0
	s_cmp_gt_u32 s78, 29
	s_cbranch_scc0 .LBB0_1303
	s_and_b64 vcc, exec, s[38:39]
	s_cbranch_vccz .LBB0_1306
	s_barrier

; #define PG8_STAGE(bufoff, gbase, voff) do { _Pragma("unroll") for (int _i = 0; _i < 2; ++_i) \
;         __builtin_amdgcn_global_load_lds((const unsigned*)((const char*)(gbase) + (voff)[_i]), (PG8_LAS unsigned*)(lds + (bufoff) + ldsw + _i * 8192), 16, 0, 0); } while (0)
; #define PG8_LDA(dst, b, h) do { _Pragma("unroll") for (int m = 0; m < 4; ++m) _Pragma("unroll") for (int k = 0; k < 2; ++k) dst[m][k] = *(const PG8_LAS bf16x8*)(lds + PG8_SA(b, h) + aoff + m * 2048 + k * 1024); } while (0)
; #define PG8_LDB(dst, b, h) do { _Pragma("unroll") for (int n = 0; n < 2; ++n) _Pragma("unroll") for (int k = 0; k < 2; ++k) dst[n][k] = *(const PG8_LAS bf16x8*)(lds + PG8_SB(b, h) + boff + n * 2048 + k * 1024); } while (0)
; #define PG8_MMA(ai, bj, At, Bt) do { __builtin_amdgcn_s_setprio(1); _Pragma("unroll") for (int m = 0; m < 4; ++m) _Pragma("unroll") for (int n = 0; n < 2; ++n) _Pragma("unroll") for (int k = 0; k < 2; ++k) \
;         acc[ai][bj][m][n] = __builtin_amdgcn_mfma_f32_16x16x32_bf16(Bt[n][k], At[m][k], acc[ai][bj][m][n], 0, 0, 0); __builtin_amdgcn_s_setprio(0); } while (0)
; #define PG8_WAIT_V(n) asm volatile("s_waitcnt vmcnt(" #n ")" ::: "memory")
; #define PG8_WAIT_L(n) asm volatile("s_waitcnt lgkmcnt(" #n ")" ::: "memory")
; #define PG8_BAR __builtin_amdgcn_s_barrier()
; #define PG8_SCHED __builtin_amdgcn_sched_barrier(0)
; template <class Epi, class Sched, bool ALIGN_EPI = false, bool SP2 = false>
; __device__ __forceinline__ void gemm_phase(PG8_LAS unsigned char* lds, const Gemm g, const Sched& S, const Epi& E, const int wave_in) {
;     ...
;             const char* a2 = last ? nA : cA + (size_t)(t + 2) * kstep; const char* b2 = last ? nB : cB + (size_t)(t + 2) * kstep;
;     ...
;             PG8_LDB(B0, 0, 0); PG8_LDB(B1, 0, 1); PG8_SCHED; PG8_LDA(At, 0, 0); PG8_STAGE(PG8_SA(1, 1), a1 + hstepA, voffA);
;             PG8_WAIT_V(8); PG8_WAIT_L(0); PG8_BAR; PG8_MMA(0, 0, At, B0); PG8_MMA(0, 1, At, B1); PG8_BAR; PG8_SCHED;
;             PG8_LDA(At, 0, 1); PG8_STAGE(PG8_SB(0, 0), b2, voffB); PG8_STAGE(PG8_SB(0, 1), b2 + hstep, voffB); PG8_STAGE(PG8_SA(0, 0), a2, voffA);
;             PG8_WAIT_V(8); PG8_WAIT_L(0); PG8_BAR; PG8_MMA(1, 0, At, B0); PG8_MMA(1, 1, At, B1); PG8_BAR; PG8_SCHED;
.LBB0_1390:
	ds_read_b128 v[144:147], v151
	ds_read_b128 v[156:159], v151 offset:1024
	ds_read_b128 v[160:163], v151 offset:2048
	ds_read_b128 v[164:167], v151 offset:3072
	ds_read_b128 v[168:171], v152
	ds_read_b128 v[172:175], v152 offset:1024
	ds_read_b128 v[176:179], v152 offset:2048
	ds_read_b128 v[180:183], v152 offset:3072
	s_add_u32 s64, s62, 0xfff80080
	s_addc_u32 s65, s63, -1
	s_cmp_eq_u32 s78, 28
	s_cselect_b32 s67, s41, s65
	s_cselect_b32 s66, s74, s64
	s_cselect_b32 s65, s39, s77
	s_cselect_b32 s64, s75, s76
	v_lshl_add_u64 v[216:217], s[62:63], 0, v[136:137]
	s_add_i32 m0, s48, 0xc000
	ds_read_b128 v[184:187], v153
	ds_read_b128 v[188:191], v153 offset:1024
	ds_read_b128 v[192:195], v153 offset:2048
	ds_read_b128 v[196:199], v153 offset:3072
	ds_read_b128 v[200:203], v153 offset:4096
	ds_read_b128 v[204:207], v153 offset:5120
	ds_read_b128 v[208:211], v153 offset:6144
	ds_read_b128 v[212:215], v153 offset:7168
	global_load_lds_dwordx4 v[216:217], off
	v_lshl_add_u64 v[216:217], s[62:63], 0, v[138:139]
	s_add_i32 m0, s48, 0xe000
	s_nop 0
	global_load_lds_dwordx4 v[216:217], off
	s_waitcnt vmcnt(8)
	s_waitcnt lgkmcnt(0)
	s_barrier
	s_setprio 1
	v_mfma_f32_16x16x32_bf16 v[116:119], v[144:147], v[184:187], v[116:119]
	v_mfma_f32_16x16x32_bf16 v[112:115], v[160:163], v[184:187], v[112:115]
	v_mfma_f32_16x16x32_bf16 v[100:103], v[144:147], v[192:195], v[100:103]
	v_mfma_f32_16x16x32_bf16 v[96:99], v[160:163], v[192:195], v[96:99]
	v_mfma_f32_16x16x32_bf16 v[84:87], v[144:147], v[200:203], v[84:87]
	v_mfma_f32_16x16x32_bf16 v[80:83], v[160:163], v[200:203], v[80:83]
	v_mfma_f32_16x16x32_bf16 v[68:71], v[144:147], v[208:211], v[68:71]
	v_mfma_f32_16x16x32_bf16 v[64:67], v[160:163], v[208:211], v[64:67]
	v_mfma_f32_16x16x32_bf16 v[116:119], v[156:159], v[188:191], v[116:119]
	v_mfma_f32_16x16x32_bf16 v[112:115], v[164:167], v[188:191], v[112:115]
	v_mfma_f32_16x16x32_bf16 v[100:103], v[156:159], v[196:199], v[100:103]
	v_mfma_f32_16x16x32_bf16 v[96:99], v[164:167], v[196:199], v[96:99]
	v_mfma_f32_16x16x32_bf16 v[84:87], v[156:159], v[204:207], v[84:87]
	v_mfma_f32_16x16x32_bf16 v[80:83], v[164:167], v[204:207], v[80:83]
	v_mfma_f32_16x16x32_bf16 v[68:71], v[156:159], v[212:215], v[68:71]
	v_mfma_f32_16x16x32_bf16 v[64:67], v[164:167], v[212:215], v[64:67]
	v_mfma_f32_16x16x32_bf16 v[124:127], v[168:171], v[184:187], v[124:127]
	v_mfma_f32_16x16x32_bf16 v[120:123], v[176:179], v[184:187], v[120:123]
	v_mfma_f32_16x16x32_bf16 v[108:111], v[168:171], v[192:195], v[108:111]
	v_mfma_f32_16x16x32_bf16 v[104:107], v[176:179], v[192:195], v[104:107]
	v_mfma_f32_16x16x32_bf16 v[92:95], v[168:171], v[200:203], v[92:95]
	v_mfma_f32_16x16x32_bf16 v[88:91], v[176:179], v[200:203], v[88:91]
	v_mfma_f32_16x16x32_bf16 v[76:79], v[168:171], v[208:211], v[76:79]
	v_mfma_f32_16x16x32_bf16 v[72:75], v[176:179], v[208:211], v[72:75]
	v_mfma_f32_16x16x32_bf16 v[124:127], v[172:175], v[188:191], v[124:127]
	v_mfma_f32_16x16x32_bf16 v[120:123], v[180:183], v[188:191], v[120:123]
	v_mfma_f32_16x16x32_bf16 v[108:111], v[172:175], v[196:199], v[108:111]
	v_mfma_f32_16x16x32_bf16 v[104:107], v[180:183], v[196:199], v[104:107]
	v_mfma_f32_16x16x32_bf16 v[92:95], v[172:175], v[204:207], v[92:95]
	v_mfma_f32_16x16x32_bf16 v[88:91], v[180:183], v[204:207], v[88:91]
	v_mfma_f32_16x16x32_bf16 v[76:79], v[172:175], v[212:215], v[76:79]
	v_mfma_f32_16x16x32_bf16 v[72:75], v[180:183], v[212:215], v[72:75]
	s_setprio 0
	s_barrier
	s_add_i32 s79, s70, s11
	v_lshl_add_u64 v[216:217], s[64:65], 0, v[132:133]
	s_mov_b32 m0, s79
	ds_read_b128 v[184:187], v153 offset:16384
	ds_read_b128 v[188:191], v153 offset:17408
	ds_read_b128 v[192:195], v153 offset:18432
	ds_read_b128 v[196:199], v153 offset:19456
	ds_read_b128 v[200:203], v153 offset:20480
	ds_read_b128 v[204:207], v153 offset:21504
	ds_read_b128 v[208:211], v153 offset:22528
	ds_read_b128 v[212:215], v153 offset:23552
	global_load_lds_dwordx4 v[216:217], off
	s_add_i32 m0, s79, 0x2000
	s_add_u32 s80, s64, 0x80000
	v_lshl_add_u64 v[218:219], s[64:65], 0, v[128:129]
	s_addc_u32 s81, s65, 0
	s_add_i32 s79, s71, s11
	global_load_lds_dwordx4 v[218:219], off
	v_lshl_add_u64 v[220:221], s[80:81], 0, v[132:133]
	s_mov_b32 m0, s79
	v_lshl_add_u64 v[222:223], s[66:67], 0, v[130:131]
	global_load_lds_dwordx4 v[220:221], off
	v_lshl_add_u64 v[220:221], s[80:81], 0, v[128:129]
	s_add_i32 m0, s79, 0x2000
	s_nop 0
	global_load_lds_dwordx4 v[220:221], off
	v_lshl_add_u64 v[220:221], s[66:67], 0, v[134:135]
	s_mov_b32 m0, s48
	s_nop 0
	global_load_lds_dwordx4 v[220:221], off
	s_mov_b32 m0, s49
	s_nop 0
	global_load_lds_dwordx4 v[222:223], off
	s_waitcnt vmcnt(8)
	s_waitcnt lgkmcnt(0)
	s_barrier
; #define PG8_STAGE(bufoff, gbase, voff) do { _Pragma("unroll") for (int _i = 0; _i < 2; ++_i) \
;         __builtin_amdgcn_global_load_lds((const unsigned*)((const char*)(gbase) + (voff)[_i]), (PG8_LAS unsigned*)(lds + (bufoff) + ldsw + _i * 8192), 16, 0, 0); } while (0)
; #define PG8_LDA(dst, b, h) do { _Pragma("unroll") for (int m = 0; m < 4; ++m) _Pragma("unroll") for (int k = 0; k < 2; ++k) dst[m][k] = *(const PG8_LAS bf16x8*)(lds + PG8_SA(b, h) + aoff + m * 2048 + k * 1024); } while (0)
; #define PG8_LDB(dst, b, h) do { _Pragma("unroll") for (int n = 0; n < 2; ++n) _Pragma("unroll") for (int k = 0; k < 2; ++k) dst[n][k] = *(const PG8_LAS bf16x8*)(lds + PG8_SB(b, h) + boff + n * 2048 + k * 1024); } while (0)
; #define PG8_MMA(ai, bj, At, Bt) do { __builtin_amdgcn_s_setprio(1); _Pragma("unroll") for (int m = 0; m < 4; ++m) _Pragma("unroll") for (int n = 0; n < 2; ++n) _Pragma("unroll") for (int k = 0; k < 2; ++k) \
;         acc[ai][bj][m][n] = __builtin_amdgcn_mfma_f32_16x16x32_bf16(Bt[n][k], At[m][k], acc[ai][bj][m][n], 0, 0, 0); __builtin_amdgcn_s_setprio(0); } while (0)
; #define PG8_WAIT_V(n) asm volatile("s_waitcnt vmcnt(" #n ")" ::: "memory")
; #define PG8_WAIT_L(n) asm volatile("s_waitcnt lgkmcnt(" #n ")" ::: "memory")
; #define PG8_BAR __builtin_amdgcn_s_barrier()
; #define PG8_SCHED __builtin_amdgcn_sched_barrier(0)
; template <class Epi, class Sched, bool ALIGN_EPI = false, bool SP2 = false>
; __device__ __forceinline__ void gemm_phase(PG8_LAS unsigned char* lds, const Gemm g, const Sched& S, const Epi& E, const int wave_in) {
;     ...
;             PG8_WAIT_V(8); PG8_WAIT_L(0); PG8_BAR; PG8_MMA(1, 0, At, B0); PG8_MMA(1, 1, At, B1); PG8_BAR; PG8_SCHED;
;             PG8_LDB(B0, 1, 0); PG8_LDB(B1, 1, 1); PG8_SCHED; PG8_LDA(At, 1, 0); PG8_STAGE(PG8_SA(0, 1), a2 + hstepA, voffA);
;             PG8_WAIT_V(8); PG8_WAIT_L(0); PG8_BAR; PG8_MMA(0, 0, At, B0); PG8_MMA(0, 1, At, B1); PG8_BAR; PG8_SCHED;
	s_setprio 1
	v_mfma_f32_16x16x32_bf16 v[52:55], v[144:147], v[184:187], v[52:55]
	v_mfma_f32_16x16x32_bf16 v[48:51], v[160:163], v[184:187], v[48:51]
	v_mfma_f32_16x16x32_bf16 v[36:39], v[144:147], v[192:195], v[36:39]
	v_mfma_f32_16x16x32_bf16 v[32:35], v[160:163], v[192:195], v[32:35]
	v_mfma_f32_16x16x32_bf16 v[20:23], v[144:147], v[200:203], v[20:23]
	v_mfma_f32_16x16x32_bf16 v[16:19], v[160:163], v[200:203], v[16:19]
	v_mfma_f32_16x16x32_bf16 v[4:7], v[144:147], v[208:211], v[4:7]
	v_mfma_f32_16x16x32_bf16 v[0:3], v[160:163], v[208:211], v[0:3]
	v_mfma_f32_16x16x32_bf16 v[52:55], v[156:159], v[188:191], v[52:55]
	v_mfma_f32_16x16x32_bf16 v[48:51], v[164:167], v[188:191], v[48:51]
	v_mfma_f32_16x16x32_bf16 v[36:39], v[156:159], v[196:199], v[36:39]
	v_mfma_f32_16x16x32_bf16 v[32:35], v[164:167], v[196:199], v[32:35]
	v_mfma_f32_16x16x32_bf16 v[20:23], v[156:159], v[204:207], v[20:23]
	v_mfma_f32_16x16x32_bf16 v[16:19], v[164:167], v[204:207], v[16:19]
	v_mfma_f32_16x16x32_bf16 v[4:7], v[156:159], v[212:215], v[4:7]
	v_mfma_f32_16x16x32_bf16 v[0:3], v[164:167], v[212:215], v[0:3]
	v_mfma_f32_16x16x32_bf16 v[60:63], v[168:171], v[184:187], v[60:63]
	v_mfma_f32_16x16x32_bf16 v[56:59], v[176:179], v[184:187], v[56:59]
	v_mfma_f32_16x16x32_bf16 v[44:47], v[168:171], v[192:195], v[44:47]
	v_mfma_f32_16x16x32_bf16 v[40:43], v[176:179], v[192:195], v[40:43]
	v_mfma_f32_16x16x32_bf16 v[28:31], v[168:171], v[200:203], v[28:31]
	v_mfma_f32_16x16x32_bf16 v[24:27], v[176:179], v[200:203], v[24:27]
	v_mfma_f32_16x16x32_bf16 v[12:15], v[168:171], v[208:211], v[12:15]
	v_mfma_f32_16x16x32_bf16 v[8:11], v[176:179], v[208:211], v[8:11]
	v_mfma_f32_16x16x32_bf16 v[60:63], v[172:175], v[188:191], v[60:63]
	v_mfma_f32_16x16x32_bf16 v[56:59], v[180:183], v[188:191], v[56:59]
	v_mfma_f32_16x16x32_bf16 v[44:47], v[172:175], v[196:199], v[44:47]
	v_mfma_f32_16x16x32_bf16 v[40:43], v[180:183], v[196:199], v[40:43]
	v_mfma_f32_16x16x32_bf16 v[28:31], v[172:175], v[204:207], v[28:31]
	v_mfma_f32_16x16x32_bf16 v[24:27], v[180:183], v[204:207], v[24:27]
	v_mfma_f32_16x16x32_bf16 v[12:15], v[172:175], v[212:215], v[12:15]
	v_mfma_f32_16x16x32_bf16 v[8:11], v[180:183], v[212:215], v[8:11]
	s_setprio 0
	s_barrier
	s_add_i32 s79, 0, 0x18000
	v_add_u32_e32 v155, s79, v149
	s_add_i32 s80, 0, 0x1c000
	ds_read_b128 v[144:147], v155
	ds_read_b128 v[156:159], v155 offset:1024
	ds_read_b128 v[160:163], v155 offset:2048
	ds_read_b128 v[164:167], v155 offset:3072
	v_add_u32_e32 v155, s80, v149
	ds_read_b128 v[168:171], v155
	ds_read_b128 v[172:175], v155 offset:1024
	ds_read_b128 v[176:179], v155 offset:2048
	ds_read_b128 v[180:183], v155 offset:3072
	s_add_u32 s66, s66, 0x80000
	s_addc_u32 s67, s67, 0
	s_mov_b32 m0, s50
	v_lshl_add_u64 v[224:225], s[66:67], 0, v[134:135]
	ds_read_b128 v[184:187], v153 offset:32768
	ds_read_b128 v[188:191], v153 offset:33792
	ds_read_b128 v[192:195], v153 offset:34816
	ds_read_b128 v[196:199], v153 offset:35840
	ds_read_b128 v[200:203], v153 offset:36864
	ds_read_b128 v[204:207], v153 offset:37888
	ds_read_b128 v[208:211], v153 offset:38912
	ds_read_b128 v[212:215], v153 offset:39936
	global_load_lds_dwordx4 v[224:225], off
	v_lshl_add_u64 v[224:225], s[66:67], 0, v[130:131]
	s_mov_b32 m0, s51
	s_nop 0
	global_load_lds_dwordx4 v[224:225], off
	s_waitcnt vmcnt(8)
	s_waitcnt lgkmcnt(0)
	s_barrier
	s_setprio 1
	v_mfma_f32_16x16x32_bf16 v[116:119], v[144:147], v[184:187], v[116:119]
	v_mfma_f32_16x16x32_bf16 v[112:115], v[160:163], v[184:187], v[112:115]
	v_mfma_f32_16x16x32_bf16 v[100:103], v[144:147], v[192:195], v[100:103]
	v_mfma_f32_16x16x32_bf16 v[96:99], v[160:163], v[192:195], v[96:99]
	v_mfma_f32_16x16x32_bf16 v[84:87], v[144:147], v[200:203], v[84:87]
	v_mfma_f32_16x16x32_bf16 v[80:83], v[160:163], v[200:203], v[80:83]
	v_mfma_f32_16x16x32_bf16 v[68:71], v[144:147], v[208:211], v[68:71]
	v_mfma_f32_16x16x32_bf16 v[64:67], v[160:163], v[208:211], v[64:67]
	v_mfma_f32_16x16x32_bf16 v[116:119], v[156:159], v[188:191], v[116:119]
	v_mfma_f32_16x16x32_bf16 v[112:115], v[164:167], v[188:191], v[112:115]
	v_mfma_f32_16x16x32_bf16 v[100:103], v[156:159], v[196:199], v[100:103]
	v_mfma_f32_16x16x32_bf16 v[96:99], v[164:167], v[196:199], v[96:99]
	v_mfma_f32_16x16x32_bf16 v[84:87], v[156:159], v[204:207], v[84:87]
	v_mfma_f32_16x16x32_bf16 v[80:83], v[164:167], v[204:207], v[80:83]
	v_mfma_f32_16x16x32_bf16 v[68:71], v[156:159], v[212:215], v[68:71]
	v_mfma_f32_16x16x32_bf16 v[64:67], v[164:167], v[212:215], v[64:67]
	v_mfma_f32_16x16x32_bf16 v[124:127], v[168:171], v[184:187], v[124:127]
	v_mfma_f32_16x16x32_bf16 v[120:123], v[176:179], v[184:187], v[120:123]
	v_mfma_f32_16x16x32_bf16 v[108:111], v[168:171], v[192:195], v[108:111]
	v_mfma_f32_16x16x32_bf16 v[104:107], v[176:179], v[192:195], v[104:107]
	v_mfma_f32_16x16x32_bf16 v[92:95], v[168:171], v[200:203], v[92:95]
	v_mfma_f32_16x16x32_bf16 v[88:91], v[176:179], v[200:203], v[88:91]
	v_mfma_f32_16x16x32_bf16 v[76:79], v[168:171], v[208:211], v[76:79]
	v_mfma_f32_16x16x32_bf16 v[72:75], v[176:179], v[208:211], v[72:75]
	v_mfma_f32_16x16x32_bf16 v[124:127], v[172:175], v[188:191], v[124:127]
	v_mfma_f32_16x16x32_bf16 v[120:123], v[180:183], v[188:191], v[120:123]
	v_mfma_f32_16x16x32_bf16 v[108:111], v[172:175], v[196:199], v[108:111]
	v_mfma_f32_16x16x32_bf16 v[104:107], v[180:183], v[196:199], v[104:107]
	v_mfma_f32_16x16x32_bf16 v[92:95], v[172:175], v[204:207], v[92:95]
	v_mfma_f32_16x16x32_bf16 v[88:91], v[180:183], v[204:207], v[88:91]
	v_mfma_f32_16x16x32_bf16 v[76:79], v[172:175], v[212:215], v[76:79]
	v_mfma_f32_16x16x32_bf16 v[72:75], v[180:183], v[212:215], v[72:75]
	s_setprio 0
	s_barrier
; #define PG8_STAGE(bufoff, gbase, voff) do { _Pragma("unroll") for (int _i = 0; _i < 2; ++_i) \
;         __builtin_amdgcn_global_load_lds((const unsigned*)((const char*)(gbase) + (voff)[_i]), (PG8_LAS unsigned*)(lds + (bufoff) + ldsw + _i * 8192), 16, 0, 0); } while (0)
; #define PG8_LDA(dst, b, h) do { _Pragma("unroll") for (int m = 0; m < 4; ++m) _Pragma("unroll") for (int k = 0; k < 2; ++k) dst[m][k] = *(const PG8_LAS bf16x8*)(lds + PG8_SA(b, h) + aoff + m * 2048 + k * 1024); } while (0)
; #define PG8_MMA(ai, bj, At, Bt) do { __builtin_amdgcn_s_setprio(1); _Pragma("unroll") for (int m = 0; m < 4; ++m) _Pragma("unroll") for (int n = 0; n < 2; ++n) _Pragma("unroll") for (int k = 0; k < 2; ++k) \
;         acc[ai][bj][m][n] = __builtin_amdgcn_mfma_f32_16x16x32_bf16(Bt[n][k], At[m][k], acc[ai][bj][m][n], 0, 0, 0); __builtin_amdgcn_s_setprio(0); } while (0)
; #define PG8_WAIT_V(n) asm volatile("s_waitcnt vmcnt(" #n ")" ::: "memory")
; #define PG8_WAIT_L(n) asm volatile("s_waitcnt lgkmcnt(" #n ")" ::: "memory")
; #define PG8_BAR __builtin_amdgcn_s_barrier()
; #define PG8_SCHED __builtin_amdgcn_sched_barrier(0)
; template <class Epi, class Sched, bool ALIGN_EPI = false, bool SP2 = false>
; __device__ __forceinline__ void gemm_phase(PG8_LAS unsigned char* lds, const Gemm g, const Sched& S, const Epi& E, const int wave_in) {
;     ...
;         for (int t = 0; t < nt; t += 2) {
;             const bool last = (t == nt - 2);
;             const char* a1 = cA + (size_t)(t + 1) * kstep;
;             const char* a2 = last ? nA : cA + (size_t)(t + 2) * kstep; const char* b2 = last ? nB : cB + (size_t)(t + 2) * kstep;
;             const char* a3 = a2 + kstep; const char* b3 = b2 + kstep;
;             if (last && has_next) S.a_ready(nxt);
;     ...
;             PG8_LDA(At, 1, 1); PG8_STAGE(PG8_SB(1, 0), b3, voffB); PG8_STAGE(PG8_SB(1, 1), b3 + hstep, voffB); PG8_STAGE(PG8_SA(1, 0), a3, voffA);
;             PG8_WAIT_V(8); PG8_WAIT_L(0); PG8_BAR; PG8_MMA(1, 0, At, B0); PG8_MMA(1, 1, At, B1); PG8_BAR; PG8_SCHED;
	s_add_i32 s66, s79, s11
	v_lshl_add_u64 v[216:217], v[216:217], 0, s[6:7]
	s_mov_b32 m0, s66
	ds_read_b128 v[184:187], v153 offset:49152
	ds_read_b128 v[188:191], v153 offset:50176
	ds_read_b128 v[192:195], v153 offset:51200
	ds_read_b128 v[196:199], v153 offset:52224
	ds_read_b128 v[200:203], v153 offset:53248
	ds_read_b128 v[204:207], v153 offset:54272
	ds_read_b128 v[208:211], v153 offset:55296
	ds_read_b128 v[212:215], v153 offset:56320
	global_load_lds_dwordx4 v[216:217], off
	s_add_i32 m0, s66, 0x2000
	s_add_u32 s64, s64, 0x80080
	v_lshl_add_u64 v[216:217], v[218:219], 0, s[6:7]
	s_addc_u32 s65, s65, 0
	s_add_i32 s66, s80, s11
	global_load_lds_dwordx4 v[216:217], off
	v_lshl_add_u64 v[216:217], s[64:65], 0, v[132:133]
	s_mov_b32 m0, s66
	s_nop 0
	global_load_lds_dwordx4 v[216:217], off
	v_lshl_add_u64 v[216:217], s[64:65], 0, v[128:129]
	s_add_i32 m0, s66, 0x2000
	s_nop 0
	global_load_lds_dwordx4 v[216:217], off
	v_lshl_add_u64 v[216:217], v[220:221], 0, s[6:7]
	s_mov_b32 m0, s68
	s_nop 0
	global_load_lds_dwordx4 v[216:217], off
	v_lshl_add_u64 v[216:217], v[222:223], 0, s[6:7]
	s_mov_b32 m0, s69
	s_nop 0
	global_load_lds_dwordx4 v[216:217], off
	s_waitcnt vmcnt(8)
	s_waitcnt lgkmcnt(0)
	s_barrier
	s_setprio 1
	v_mfma_f32_16x16x32_bf16 v[52:55], v[144:147], v[184:187], v[52:55]
	v_mfma_f32_16x16x32_bf16 v[48:51], v[160:163], v[184:187], v[48:51]
	v_mfma_f32_16x16x32_bf16 v[36:39], v[144:147], v[192:195], v[36:39]
	v_mfma_f32_16x16x32_bf16 v[32:35], v[160:163], v[192:195], v[32:35]
	v_mfma_f32_16x16x32_bf16 v[20:23], v[144:147], v[200:203], v[20:23]
	v_mfma_f32_16x16x32_bf16 v[16:19], v[160:163], v[200:203], v[16:19]
	v_mfma_f32_16x16x32_bf16 v[4:7], v[144:147], v[208:211], v[4:7]
	v_mfma_f32_16x16x32_bf16 v[0:3], v[160:163], v[208:211], v[0:3]
	v_mfma_f32_16x16x32_bf16 v[52:55], v[156:159], v[188:191], v[52:55]
	v_mfma_f32_16x16x32_bf16 v[48:51], v[164:167], v[188:191], v[48:51]
	v_mfma_f32_16x16x32_bf16 v[36:39], v[156:159], v[196:199], v[36:39]
	v_mfma_f32_16x16x32_bf16 v[32:35], v[164:167], v[196:199], v[32:35]
	v_mfma_f32_16x16x32_bf16 v[20:23], v[156:159], v[204:207], v[20:23]
	v_mfma_f32_16x16x32_bf16 v[16:19], v[164:167], v[204:207], v[16:19]
	v_mfma_f32_16x16x32_bf16 v[4:7], v[156:159], v[212:215], v[4:7]
	v_mfma_f32_16x16x32_bf16 v[0:3], v[164:167], v[212:215], v[0:3]
	v_mfma_f32_16x16x32_bf16 v[60:63], v[168:171], v[184:187], v[60:63]
	v_mfma_f32_16x16x32_bf16 v[56:59], v[176:179], v[184:187], v[56:59]
	v_mfma_f32_16x16x32_bf16 v[44:47], v[168:171], v[192:195], v[44:47]
	v_mfma_f32_16x16x32_bf16 v[40:43], v[176:179], v[192:195], v[40:43]
	v_mfma_f32_16x16x32_bf16 v[28:31], v[168:171], v[200:203], v[28:31]
	v_mfma_f32_16x16x32_bf16 v[24:27], v[176:179], v[200:203], v[24:27]
	v_mfma_f32_16x16x32_bf16 v[12:15], v[168:171], v[208:211], v[12:15]
	v_mfma_f32_16x16x32_bf16 v[8:11], v[176:179], v[208:211], v[8:11]
	v_mfma_f32_16x16x32_bf16 v[60:63], v[172:175], v[188:191], v[60:63]
	v_mfma_f32_16x16x32_bf16 v[56:59], v[180:183], v[188:191], v[56:59]
	v_mfma_f32_16x16x32_bf16 v[44:47], v[172:175], v[196:199], v[44:47]
	v_mfma_f32_16x16x32_bf16 v[40:43], v[180:183], v[196:199], v[40:43]
	v_mfma_f32_16x16x32_bf16 v[28:31], v[172:175], v[204:207], v[28:31]
	v_mfma_f32_16x16x32_bf16 v[24:27], v[180:183], v[204:207], v[24:27]
	v_mfma_f32_16x16x32_bf16 v[12:15], v[172:175], v[212:215], v[12:15]
	v_mfma_f32_16x16x32_bf16 v[8:11], v[180:183], v[212:215], v[8:11]
	s_setprio 0
	s_barrier
	s_add_i32 s78, s78, 2
	s_add_u32 s62, s62, 0x100
	s_addc_u32 s63, s63, 0
	s_add_u32 s76, s76, 0x100
	s_addc_u32 s77, s77, 0
	s_cmp_gt_u32 s78, 29
	s_cbranch_scc0 .LBB0_1390
	s_and_b64 vcc, exec, s[18:19]
	s_cbranch_vccz .LBB0_1393
	s_barrier

; #define PG8_STAGE(bufoff, gbase, voff) do { _Pragma("unroll") for (int _i = 0; _i < 2; ++_i) \
;         __builtin_amdgcn_global_load_lds((const unsigned*)((const char*)(gbase) + (voff)[_i]), (PG8_LAS unsigned*)(lds + (bufoff) + ldsw + _i * 8192), 16, 0, 0); } while (0)
; #define PG8_LDA(dst, b, h) do { _Pragma("unroll") for (int m = 0; m < 4; ++m) _Pragma("unroll") for (int k = 0; k < 2; ++k) dst[m][k] = *(const PG8_LAS bf16x8*)(lds + PG8_SA(b, h) + aoff + m * 2048 + k * 1024); } while (0)
; #define PG8_LDB(dst, b, h) do { _Pragma("unroll") for (int n = 0; n < 2; ++n) _Pragma("unroll") for (int k = 0; k < 2; ++k) dst[n][k] = *(const PG8_LAS bf16x8*)(lds + PG8_SB(b, h) + boff + n * 2048 + k * 1024); } while (0)
; #define PG8_MMA(ai, bj, At, Bt) do { __builtin_amdgcn_s_setprio(1); _Pragma("unroll") for (int m = 0; m < 4; ++m) _Pragma("unroll") for (int n = 0; n < 2; ++n) _Pragma("unroll") for (int k = 0; k < 2; ++k) \
;         acc[ai][bj][m][n] = __builtin_amdgcn_mfma_f32_16x16x32_bf16(Bt[n][k], At[m][k], acc[ai][bj][m][n], 0, 0, 0); __builtin_amdgcn_s_setprio(0); } while (0)
; #define PG8_WAIT_V(n) asm volatile("s_waitcnt vmcnt(" #n ")" ::: "memory")
; #define PG8_WAIT_L(n) asm volatile("s_waitcnt lgkmcnt(" #n ")" ::: "memory")
; #define PG8_BAR __builtin_amdgcn_s_barrier()
; #define PG8_SCHED __builtin_amdgcn_sched_barrier(0)
; template <class Epi, class Sched, bool ALIGN_EPI = false, bool SP2 = false>
; __device__ __forceinline__ void gemm_phase(PG8_LAS unsigned char* lds, const Gemm g, const Sched& S, const Epi& E, const int wave_in) {
;     ...
;             const char* a2 = last ? nA : cA + (size_t)(t + 2) * kstep; const char* b2 = last ? nB : cB + (size_t)(t + 2) * kstep;
;     ...
;             PG8_LDB(B0, 0, 0); PG8_LDB(B1, 0, 1); PG8_SCHED; PG8_LDA(At, 0, 0); PG8_STAGE(PG8_SA(1, 1), a1 + hstepA, voffA);
;             PG8_WAIT_V(8); PG8_WAIT_L(0); PG8_BAR; PG8_MMA(0, 0, At, B0); PG8_MMA(0, 1, At, B1); PG8_BAR; PG8_SCHED;
;             PG8_LDA(At, 0, 1); PG8_STAGE(PG8_SB(0, 0), b2, voffB); PG8_STAGE(PG8_SB(0, 1), b2 + hstep, voffB); PG8_STAGE(PG8_SA(0, 0), a2, voffA);
;             PG8_WAIT_V(8); PG8_WAIT_L(0); PG8_BAR; PG8_MMA(1, 0, At, B0); PG8_MMA(1, 1, At, B1); PG8_BAR; PG8_SCHED;
.LBB0_1475:
	ds_read_b128 v[144:147], v151
	ds_read_b128 v[156:159], v151 offset:1024
	ds_read_b128 v[160:163], v151 offset:2048
	ds_read_b128 v[164:167], v151 offset:3072
	ds_read_b128 v[168:171], v152
	ds_read_b128 v[172:175], v152 offset:1024
	ds_read_b128 v[176:179], v152 offset:2048
	ds_read_b128 v[180:183], v152 offset:3072
	s_add_u32 s60, s58, 0x100
	s_addc_u32 s61, s59, 0
	s_cmpk_eq_i32 s76, 0x54
	s_cselect_b32 s65, s7, s61
	s_cselect_b32 s64, s6, s60
	s_cselect_b32 s63, s43, s75
	s_cselect_b32 s62, s42, s74
	v_lshl_add_u64 v[216:217], s[58:59], 0, v[136:137]
	s_add_i32 m0, s33, 0xc000
	ds_read_b128 v[184:187], v153
	ds_read_b128 v[188:191], v153 offset:1024
	ds_read_b128 v[192:195], v153 offset:2048
	ds_read_b128 v[196:199], v153 offset:3072
	ds_read_b128 v[200:203], v153 offset:4096
	ds_read_b128 v[204:207], v153 offset:5120
	ds_read_b128 v[208:211], v153 offset:6144
	ds_read_b128 v[212:215], v153 offset:7168
	global_load_lds_dwordx4 v[216:217], off
	v_lshl_add_u64 v[216:217], s[58:59], 0, v[138:139]
	s_add_i32 m0, s33, 0xe000
	s_nop 0
	global_load_lds_dwordx4 v[216:217], off
	s_waitcnt vmcnt(8)
	s_waitcnt lgkmcnt(0)
	s_barrier
	s_setprio 1
	v_mfma_f32_16x16x32_bf16 v[124:127], v[144:147], v[184:187], v[124:127]
	v_mfma_f32_16x16x32_bf16 v[120:123], v[160:163], v[184:187], v[120:123]
	v_mfma_f32_16x16x32_bf16 v[108:111], v[144:147], v[192:195], v[108:111]
	v_mfma_f32_16x16x32_bf16 v[104:107], v[160:163], v[192:195], v[104:107]
	v_mfma_f32_16x16x32_bf16 v[92:95], v[144:147], v[200:203], v[92:95]
	v_mfma_f32_16x16x32_bf16 v[88:91], v[160:163], v[200:203], v[88:91]
	v_mfma_f32_16x16x32_bf16 v[76:79], v[144:147], v[208:211], v[76:79]
	v_mfma_f32_16x16x32_bf16 v[72:75], v[160:163], v[208:211], v[72:75]
	v_mfma_f32_16x16x32_bf16 v[124:127], v[156:159], v[188:191], v[124:127]
	v_mfma_f32_16x16x32_bf16 v[120:123], v[164:167], v[188:191], v[120:123]
	v_mfma_f32_16x16x32_bf16 v[108:111], v[156:159], v[196:199], v[108:111]
	v_mfma_f32_16x16x32_bf16 v[104:107], v[164:167], v[196:199], v[104:107]
	v_mfma_f32_16x16x32_bf16 v[92:95], v[156:159], v[204:207], v[92:95]
	v_mfma_f32_16x16x32_bf16 v[88:91], v[164:167], v[204:207], v[88:91]
	v_mfma_f32_16x16x32_bf16 v[76:79], v[156:159], v[212:215], v[76:79]
	v_mfma_f32_16x16x32_bf16 v[72:75], v[164:167], v[212:215], v[72:75]
	v_mfma_f32_16x16x32_bf16 v[116:119], v[168:171], v[184:187], v[116:119]
	v_mfma_f32_16x16x32_bf16 v[112:115], v[176:179], v[184:187], v[112:115]
	v_mfma_f32_16x16x32_bf16 v[100:103], v[168:171], v[192:195], v[100:103]
	v_mfma_f32_16x16x32_bf16 v[96:99], v[176:179], v[192:195], v[96:99]
	v_mfma_f32_16x16x32_bf16 v[84:87], v[168:171], v[200:203], v[84:87]
	v_mfma_f32_16x16x32_bf16 v[80:83], v[176:179], v[200:203], v[80:83]
	v_mfma_f32_16x16x32_bf16 v[68:71], v[168:171], v[208:211], v[68:71]
	v_mfma_f32_16x16x32_bf16 v[64:67], v[176:179], v[208:211], v[64:67]
	v_mfma_f32_16x16x32_bf16 v[116:119], v[172:175], v[188:191], v[116:119]
	v_mfma_f32_16x16x32_bf16 v[112:115], v[180:183], v[188:191], v[112:115]
	v_mfma_f32_16x16x32_bf16 v[100:103], v[172:175], v[196:199], v[100:103]
	v_mfma_f32_16x16x32_bf16 v[96:99], v[180:183], v[196:199], v[96:99]
	v_mfma_f32_16x16x32_bf16 v[84:87], v[172:175], v[204:207], v[84:87]
	v_mfma_f32_16x16x32_bf16 v[80:83], v[180:183], v[204:207], v[80:83]
	v_mfma_f32_16x16x32_bf16 v[68:71], v[172:175], v[212:215], v[68:71]
	v_mfma_f32_16x16x32_bf16 v[64:67], v[180:183], v[212:215], v[64:67]
	s_setprio 0
	s_barrier
	s_add_i32 s58, s70, s11
	v_lshl_add_u64 v[216:217], s[62:63], 0, v[130:131]
	s_mov_b32 m0, s58
	ds_read_b128 v[184:187], v153 offset:16384
	ds_read_b128 v[188:191], v153 offset:17408
	ds_read_b128 v[192:195], v153 offset:18432
	ds_read_b128 v[196:199], v153 offset:19456
	ds_read_b128 v[200:203], v153 offset:20480
	ds_read_b128 v[204:207], v153 offset:21504
	ds_read_b128 v[208:211], v153 offset:22528
	ds_read_b128 v[212:215], v153 offset:23552
	global_load_lds_dwordx4 v[216:217], off
	s_add_i32 m0, s58, 0x2000
	s_add_u32 s58, s62, 0x160000
	v_lshl_add_u64 v[218:219], s[62:63], 0, v[134:135]
	s_addc_u32 s59, s63, 0
	s_add_i32 s77, s71, s11
	global_load_lds_dwordx4 v[218:219], off
	v_lshl_add_u64 v[220:221], s[58:59], 0, v[130:131]
	s_mov_b32 m0, s77
	v_lshl_add_u64 v[222:223], s[64:65], 0, v[132:133]
	global_load_lds_dwordx4 v[220:221], off
	v_lshl_add_u64 v[220:221], s[58:59], 0, v[134:135]
	s_add_i32 m0, s77, 0x2000
	s_nop 0
	global_load_lds_dwordx4 v[220:221], off
	v_lshl_add_u64 v[220:221], s[64:65], 0, v[128:129]
	s_mov_b32 m0, s33
	s_nop 0
	global_load_lds_dwordx4 v[220:221], off
	s_mov_b32 m0, s35
	s_nop 0
	global_load_lds_dwordx4 v[222:223], off
	s_waitcnt vmcnt(8)
	s_waitcnt lgkmcnt(0)
	s_barrier
; #define PG8_STAGE(bufoff, gbase, voff) do { _Pragma("unroll") for (int _i = 0; _i < 2; ++_i) \
;         __builtin_amdgcn_global_load_lds((const unsigned*)((const char*)(gbase) + (voff)[_i]), (PG8_LAS unsigned*)(lds + (bufoff) + ldsw + _i * 8192), 16, 0, 0); } while (0)
; #define PG8_LDA(dst, b, h) do { _Pragma("unroll") for (int m = 0; m < 4; ++m) _Pragma("unroll") for (int k = 0; k < 2; ++k) dst[m][k] = *(const PG8_LAS bf16x8*)(lds + PG8_SA(b, h) + aoff + m * 2048 + k * 1024); } while (0)
; #define PG8_LDB(dst, b, h) do { _Pragma("unroll") for (int n = 0; n < 2; ++n) _Pragma("unroll") for (int k = 0; k < 2; ++k) dst[n][k] = *(const PG8_LAS bf16x8*)(lds + PG8_SB(b, h) + boff + n * 2048 + k * 1024); } while (0)
; #define PG8_MMA(ai, bj, At, Bt) do { __builtin_amdgcn_s_setprio(1); _Pragma("unroll") for (int m = 0; m < 4; ++m) _Pragma("unroll") for (int n = 0; n < 2; ++n) _Pragma("unroll") for (int k = 0; k < 2; ++k) \
;         acc[ai][bj][m][n] = __builtin_amdgcn_mfma_f32_16x16x32_bf16(Bt[n][k], At[m][k], acc[ai][bj][m][n], 0, 0, 0); __builtin_amdgcn_s_setprio(0); } while (0)
; #define PG8_WAIT_V(n) asm volatile("s_waitcnt vmcnt(" #n ")" ::: "memory")
; #define PG8_WAIT_L(n) asm volatile("s_waitcnt lgkmcnt(" #n ")" ::: "memory")
; #define PG8_BAR __builtin_amdgcn_s_barrier()
; #define PG8_SCHED __builtin_amdgcn_sched_barrier(0)
; template <class Epi, class Sched, bool ALIGN_EPI = false, bool SP2 = false>
; __device__ __forceinline__ void gemm_phase(PG8_LAS unsigned char* lds, const Gemm g, const Sched& S, const Epi& E, const int wave_in) {
;     ...
;             PG8_WAIT_V(8); PG8_WAIT_L(0); PG8_BAR; PG8_MMA(1, 0, At, B0); PG8_MMA(1, 1, At, B1); PG8_BAR; PG8_SCHED;
;             PG8_LDB(B0, 1, 0); PG8_LDB(B1, 1, 1); PG8_SCHED; PG8_LDA(At, 1, 0); PG8_STAGE(PG8_SA(0, 1), a2 + hstepA, voffA);
;             PG8_WAIT_V(8); PG8_WAIT_L(0); PG8_BAR; PG8_MMA(0, 0, At, B0); PG8_MMA(0, 1, At, B1); PG8_BAR; PG8_SCHED;
	s_setprio 1
	v_mfma_f32_16x16x32_bf16 v[60:63], v[144:147], v[184:187], v[60:63]
	v_mfma_f32_16x16x32_bf16 v[56:59], v[160:163], v[184:187], v[56:59]
	v_mfma_f32_16x16x32_bf16 v[44:47], v[144:147], v[192:195], v[44:47]
	v_mfma_f32_16x16x32_bf16 v[40:43], v[160:163], v[192:195], v[40:43]
	v_mfma_f32_16x16x32_bf16 v[28:31], v[144:147], v[200:203], v[28:31]
	v_mfma_f32_16x16x32_bf16 v[24:27], v[160:163], v[200:203], v[24:27]
	v_mfma_f32_16x16x32_bf16 v[12:15], v[144:147], v[208:211], v[12:15]
	v_mfma_f32_16x16x32_bf16 v[8:11], v[160:163], v[208:211], v[8:11]
	v_mfma_f32_16x16x32_bf16 v[60:63], v[156:159], v[188:191], v[60:63]
	v_mfma_f32_16x16x32_bf16 v[56:59], v[164:167], v[188:191], v[56:59]
	v_mfma_f32_16x16x32_bf16 v[44:47], v[156:159], v[196:199], v[44:47]
	v_mfma_f32_16x16x32_bf16 v[40:43], v[164:167], v[196:199], v[40:43]
	v_mfma_f32_16x16x32_bf16 v[28:31], v[156:159], v[204:207], v[28:31]
	v_mfma_f32_16x16x32_bf16 v[24:27], v[164:167], v[204:207], v[24:27]
	v_mfma_f32_16x16x32_bf16 v[12:15], v[156:159], v[212:215], v[12:15]
	v_mfma_f32_16x16x32_bf16 v[8:11], v[164:167], v[212:215], v[8:11]
	v_mfma_f32_16x16x32_bf16 v[52:55], v[168:171], v[184:187], v[52:55]
	v_mfma_f32_16x16x32_bf16 v[48:51], v[176:179], v[184:187], v[48:51]
	v_mfma_f32_16x16x32_bf16 v[36:39], v[168:171], v[192:195], v[36:39]
	v_mfma_f32_16x16x32_bf16 v[32:35], v[176:179], v[192:195], v[32:35]
	v_mfma_f32_16x16x32_bf16 v[20:23], v[168:171], v[200:203], v[20:23]
	v_mfma_f32_16x16x32_bf16 v[16:19], v[176:179], v[200:203], v[16:19]
	v_mfma_f32_16x16x32_bf16 v[4:7], v[168:171], v[208:211], v[4:7]
	v_mfma_f32_16x16x32_bf16 v[0:3], v[176:179], v[208:211], v[0:3]
	v_mfma_f32_16x16x32_bf16 v[52:55], v[172:175], v[188:191], v[52:55]
	v_mfma_f32_16x16x32_bf16 v[48:51], v[180:183], v[188:191], v[48:51]
	v_mfma_f32_16x16x32_bf16 v[36:39], v[172:175], v[196:199], v[36:39]
	v_mfma_f32_16x16x32_bf16 v[32:35], v[180:183], v[196:199], v[32:35]
	v_mfma_f32_16x16x32_bf16 v[20:23], v[172:175], v[204:207], v[20:23]
	v_mfma_f32_16x16x32_bf16 v[16:19], v[180:183], v[204:207], v[16:19]
	v_mfma_f32_16x16x32_bf16 v[4:7], v[172:175], v[212:215], v[4:7]
	v_mfma_f32_16x16x32_bf16 v[0:3], v[180:183], v[212:215], v[0:3]
	s_setprio 0
	s_barrier
	s_add_i32 s77, 0, 0x18000
	v_add_u32_e32 v155, s77, v149
	s_add_i32 s78, 0, 0x1c000
	ds_read_b128 v[144:147], v155
	ds_read_b128 v[156:159], v155 offset:1024
	ds_read_b128 v[160:163], v155 offset:2048
	ds_read_b128 v[164:167], v155 offset:3072
	v_add_u32_e32 v155, s78, v149
	ds_read_b128 v[168:171], v155
	ds_read_b128 v[172:175], v155 offset:1024
	ds_read_b128 v[176:179], v155 offset:2048
	ds_read_b128 v[180:183], v155 offset:3072
	s_add_u32 s58, s64, 0x160000
	s_addc_u32 s59, s65, 0
	s_mov_b32 m0, s50
	v_lshl_add_u64 v[224:225], s[58:59], 0, v[128:129]
	ds_read_b128 v[184:187], v153 offset:32768
	ds_read_b128 v[188:191], v153 offset:33792
	ds_read_b128 v[192:195], v153 offset:34816
	ds_read_b128 v[196:199], v153 offset:35840
	ds_read_b128 v[200:203], v153 offset:36864
	ds_read_b128 v[204:207], v153 offset:37888
	ds_read_b128 v[208:211], v153 offset:38912
	ds_read_b128 v[212:215], v153 offset:39936
	global_load_lds_dwordx4 v[224:225], off
	v_lshl_add_u64 v[224:225], s[58:59], 0, v[132:133]
	s_mov_b32 m0, s51
	s_nop 0
	global_load_lds_dwordx4 v[224:225], off
	s_waitcnt vmcnt(8)
	s_waitcnt lgkmcnt(0)
	s_barrier
	s_setprio 1
	v_mfma_f32_16x16x32_bf16 v[124:127], v[144:147], v[184:187], v[124:127]
	v_mfma_f32_16x16x32_bf16 v[120:123], v[160:163], v[184:187], v[120:123]
	v_mfma_f32_16x16x32_bf16 v[108:111], v[144:147], v[192:195], v[108:111]
	v_mfma_f32_16x16x32_bf16 v[104:107], v[160:163], v[192:195], v[104:107]
	v_mfma_f32_16x16x32_bf16 v[92:95], v[144:147], v[200:203], v[92:95]
	v_mfma_f32_16x16x32_bf16 v[88:91], v[160:163], v[200:203], v[88:91]
	v_mfma_f32_16x16x32_bf16 v[76:79], v[144:147], v[208:211], v[76:79]
	v_mfma_f32_16x16x32_bf16 v[72:75], v[160:163], v[208:211], v[72:75]
	v_mfma_f32_16x16x32_bf16 v[124:127], v[156:159], v[188:191], v[124:127]
	v_mfma_f32_16x16x32_bf16 v[120:123], v[164:167], v[188:191], v[120:123]
	v_mfma_f32_16x16x32_bf16 v[108:111], v[156:159], v[196:199], v[108:111]
	v_mfma_f32_16x16x32_bf16 v[104:107], v[164:167], v[196:199], v[104:107]
	v_mfma_f32_16x16x32_bf16 v[92:95], v[156:159], v[204:207], v[92:95]
	v_mfma_f32_16x16x32_bf16 v[88:91], v[164:167], v[204:207], v[88:91]
	v_mfma_f32_16x16x32_bf16 v[76:79], v[156:159], v[212:215], v[76:79]
	v_mfma_f32_16x16x32_bf16 v[72:75], v[164:167], v[212:215], v[72:75]
	v_mfma_f32_16x16x32_bf16 v[116:119], v[168:171], v[184:187], v[116:119]
	v_mfma_f32_16x16x32_bf16 v[112:115], v[176:179], v[184:187], v[112:115]
	v_mfma_f32_16x16x32_bf16 v[100:103], v[168:171], v[192:195], v[100:103]
	v_mfma_f32_16x16x32_bf16 v[96:99], v[176:179], v[192:195], v[96:99]
	v_mfma_f32_16x16x32_bf16 v[84:87], v[168:171], v[200:203], v[84:87]
	v_mfma_f32_16x16x32_bf16 v[80:83], v[176:179], v[200:203], v[80:83]
	v_mfma_f32_16x16x32_bf16 v[68:71], v[168:171], v[208:211], v[68:71]
	v_mfma_f32_16x16x32_bf16 v[64:67], v[176:179], v[208:211], v[64:67]
	v_mfma_f32_16x16x32_bf16 v[116:119], v[172:175], v[188:191], v[116:119]
	v_mfma_f32_16x16x32_bf16 v[112:115], v[180:183], v[188:191], v[112:115]
	v_mfma_f32_16x16x32_bf16 v[100:103], v[172:175], v[196:199], v[100:103]
	v_mfma_f32_16x16x32_bf16 v[96:99], v[180:183], v[196:199], v[96:99]
	v_mfma_f32_16x16x32_bf16 v[84:87], v[172:175], v[204:207], v[84:87]
	v_mfma_f32_16x16x32_bf16 v[80:83], v[180:183], v[204:207], v[80:83]
	v_mfma_f32_16x16x32_bf16 v[68:71], v[172:175], v[212:215], v[68:71]
	v_mfma_f32_16x16x32_bf16 v[64:67], v[180:183], v[212:215], v[64:67]
	s_setprio 0
	s_barrier
; #define PG8_STAGE(bufoff, gbase, voff) do { _Pragma("unroll") for (int _i = 0; _i < 2; ++_i) \
;         __builtin_amdgcn_global_load_lds((const unsigned*)((const char*)(gbase) + (voff)[_i]), (PG8_LAS unsigned*)(lds + (bufoff) + ldsw + _i * 8192), 16, 0, 0); } while (0)
; #define PG8_LDA(dst, b, h) do { _Pragma("unroll") for (int m = 0; m < 4; ++m) _Pragma("unroll") for (int k = 0; k < 2; ++k) dst[m][k] = *(const PG8_LAS bf16x8*)(lds + PG8_SA(b, h) + aoff + m * 2048 + k * 1024); } while (0)
; #define PG8_MMA(ai, bj, At, Bt) do { __builtin_amdgcn_s_setprio(1); _Pragma("unroll") for (int m = 0; m < 4; ++m) _Pragma("unroll") for (int n = 0; n < 2; ++n) _Pragma("unroll") for (int k = 0; k < 2; ++k) \
;         acc[ai][bj][m][n] = __builtin_amdgcn_mfma_f32_16x16x32_bf16(Bt[n][k], At[m][k], acc[ai][bj][m][n], 0, 0, 0); __builtin_amdgcn_s_setprio(0); } while (0)
; #define PG8_WAIT_V(n) asm volatile("s_waitcnt vmcnt(" #n ")" ::: "memory")
; #define PG8_WAIT_L(n) asm volatile("s_waitcnt lgkmcnt(" #n ")" ::: "memory")
; #define PG8_BAR __builtin_amdgcn_s_barrier()
; #define PG8_SCHED __builtin_amdgcn_sched_barrier(0)
; template <class Epi, class Sched, bool ALIGN_EPI = false, bool SP2 = false>
; __device__ __forceinline__ void gemm_phase(PG8_LAS unsigned char* lds, const Gemm g, const Sched& S, const Epi& E, const int wave_in) {
;     ...
;         for (int t = 0; t < nt; t += 2) {
;             const bool last = (t == nt - 2);
;             const char* a1 = cA + (size_t)(t + 1) * kstep;
;             const char* a2 = last ? nA : cA + (size_t)(t + 2) * kstep; const char* b2 = last ? nB : cB + (size_t)(t + 2) * kstep;
;             const char* a3 = a2 + kstep; const char* b3 = b2 + kstep;
;             if (last && has_next) S.a_ready(nxt);
;     ...
;             PG8_LDA(At, 1, 1); PG8_STAGE(PG8_SB(1, 0), b3, voffB); PG8_STAGE(PG8_SB(1, 1), b3 + hstep, voffB); PG8_STAGE(PG8_SA(1, 0), a3, voffA);
;             PG8_WAIT_V(8); PG8_WAIT_L(0); PG8_BAR; PG8_MMA(1, 0, At, B0); PG8_MMA(1, 1, At, B1); PG8_BAR; PG8_SCHED;
	s_add_i32 s58, s77, s11
	v_lshl_add_u64 v[216:217], v[216:217], 0, s[38:39]
	s_mov_b32 m0, s58
	ds_read_b128 v[184:187], v153 offset:49152
	ds_read_b128 v[188:191], v153 offset:50176
	ds_read_b128 v[192:195], v153 offset:51200
	ds_read_b128 v[196:199], v153 offset:52224
	ds_read_b128 v[200:203], v153 offset:53248
	ds_read_b128 v[204:207], v153 offset:54272
	ds_read_b128 v[208:211], v153 offset:55296
	ds_read_b128 v[212:215], v153 offset:56320
	global_load_lds_dwordx4 v[216:217], off
	s_add_i32 m0, s58, 0x2000
	s_add_u32 s58, s62, 0x160080
	v_lshl_add_u64 v[216:217], v[218:219], 0, s[38:39]
	s_addc_u32 s59, s63, 0
	s_add_i32 s62, s78, s11
	global_load_lds_dwordx4 v[216:217], off
	v_lshl_add_u64 v[216:217], s[58:59], 0, v[130:131]
	s_mov_b32 m0, s62
	s_nop 0
	global_load_lds_dwordx4 v[216:217], off
	v_lshl_add_u64 v[216:217], s[58:59], 0, v[134:135]
	s_add_i32 m0, s62, 0x2000
	s_nop 0
	global_load_lds_dwordx4 v[216:217], off
	v_lshl_add_u64 v[216:217], v[220:221], 0, s[38:39]
	s_mov_b32 m0, s67
	s_nop 0
	global_load_lds_dwordx4 v[216:217], off
	v_lshl_add_u64 v[216:217], v[222:223], 0, s[38:39]
	s_mov_b32 m0, s68
	s_nop 0
	global_load_lds_dwordx4 v[216:217], off
	s_waitcnt vmcnt(8)
	s_waitcnt lgkmcnt(0)
	s_barrier
	s_setprio 1
	v_mfma_f32_16x16x32_bf16 v[60:63], v[144:147], v[184:187], v[60:63]
	v_mfma_f32_16x16x32_bf16 v[56:59], v[160:163], v[184:187], v[56:59]
	v_mfma_f32_16x16x32_bf16 v[44:47], v[144:147], v[192:195], v[44:47]
	v_mfma_f32_16x16x32_bf16 v[40:43], v[160:163], v[192:195], v[40:43]
	v_mfma_f32_16x16x32_bf16 v[28:31], v[144:147], v[200:203], v[28:31]
	v_mfma_f32_16x16x32_bf16 v[24:27], v[160:163], v[200:203], v[24:27]
	v_mfma_f32_16x16x32_bf16 v[12:15], v[144:147], v[208:211], v[12:15]
	v_mfma_f32_16x16x32_bf16 v[8:11], v[160:163], v[208:211], v[8:11]
	v_mfma_f32_16x16x32_bf16 v[60:63], v[156:159], v[188:191], v[60:63]
	v_mfma_f32_16x16x32_bf16 v[56:59], v[164:167], v[188:191], v[56:59]
	v_mfma_f32_16x16x32_bf16 v[44:47], v[156:159], v[196:199], v[44:47]
	v_mfma_f32_16x16x32_bf16 v[40:43], v[164:167], v[196:199], v[40:43]
	v_mfma_f32_16x16x32_bf16 v[28:31], v[156:159], v[204:207], v[28:31]
	v_mfma_f32_16x16x32_bf16 v[24:27], v[164:167], v[204:207], v[24:27]
	v_mfma_f32_16x16x32_bf16 v[12:15], v[156:159], v[212:215], v[12:15]
	v_mfma_f32_16x16x32_bf16 v[8:11], v[164:167], v[212:215], v[8:11]
	v_mfma_f32_16x16x32_bf16 v[52:55], v[168:171], v[184:187], v[52:55]
	v_mfma_f32_16x16x32_bf16 v[48:51], v[176:179], v[184:187], v[48:51]
	v_mfma_f32_16x16x32_bf16 v[36:39], v[168:171], v[192:195], v[36:39]
	v_mfma_f32_16x16x32_bf16 v[32:35], v[176:179], v[192:195], v[32:35]
	v_mfma_f32_16x16x32_bf16 v[20:23], v[168:171], v[200:203], v[20:23]
	v_mfma_f32_16x16x32_bf16 v[16:19], v[176:179], v[200:203], v[16:19]
	v_mfma_f32_16x16x32_bf16 v[4:7], v[168:171], v[208:211], v[4:7]
	v_mfma_f32_16x16x32_bf16 v[0:3], v[176:179], v[208:211], v[0:3]
	v_mfma_f32_16x16x32_bf16 v[52:55], v[172:175], v[188:191], v[52:55]
	v_mfma_f32_16x16x32_bf16 v[48:51], v[180:183], v[188:191], v[48:51]
	v_mfma_f32_16x16x32_bf16 v[36:39], v[172:175], v[196:199], v[36:39]
	v_mfma_f32_16x16x32_bf16 v[32:35], v[180:183], v[196:199], v[32:35]
	v_mfma_f32_16x16x32_bf16 v[20:23], v[172:175], v[204:207], v[20:23]
	v_mfma_f32_16x16x32_bf16 v[16:19], v[180:183], v[204:207], v[16:19]
	v_mfma_f32_16x16x32_bf16 v[4:7], v[172:175], v[212:215], v[4:7]
	v_mfma_f32_16x16x32_bf16 v[0:3], v[180:183], v[212:215], v[0:3]
	s_setprio 0
	s_barrier
	s_add_i32 s76, s76, 2
	s_add_u32 s74, s74, 0x100
	s_addc_u32 s75, s75, 0
	s_cmpk_gt_u32 s76, 0x55
	s_mov_b64 s[58:59], s[60:61]
	s_cbranch_scc0 .LBB0_1475
	s_and_b64 vcc, exec, s[40:41]
	s_cbranch_vccz .LBB0_1478
	s_barrier

; #define PG8_STAGE(bufoff, gbase, voff) do { _Pragma("unroll") for (int _i = 0; _i < 2; ++_i) \
;         __builtin_amdgcn_global_load_lds((const unsigned*)((const char*)(gbase) + (voff)[_i]), (PG8_LAS unsigned*)(lds + (bufoff) + ldsw + _i * 8192), 16, 0, 0); } while (0)
; #define PG8_LDA(dst, b, h) do { _Pragma("unroll") for (int m = 0; m < 4; ++m) _Pragma("unroll") for (int k = 0; k < 2; ++k) dst[m][k] = *(const PG8_LAS bf16x8*)(lds + PG8_SA(b, h) + aoff + m * 2048 + k * 1024); } while (0)
; #define PG8_LDB(dst, b, h) do { _Pragma("unroll") for (int n = 0; n < 2; ++n) _Pragma("unroll") for (int k = 0; k < 2; ++k) dst[n][k] = *(const PG8_LAS bf16x8*)(lds + PG8_SB(b, h) + boff + n * 2048 + k * 1024); } while (0)
; #define PG8_MMA(ai, bj, At, Bt) do { __builtin_amdgcn_s_setprio(1); _Pragma("unroll") for (int m = 0; m < 4; ++m) _Pragma("unroll") for (int n = 0; n < 2; ++n) _Pragma("unroll") for (int k = 0; k < 2; ++k) \
;         acc[ai][bj][m][n] = __builtin_amdgcn_mfma_f32_16x16x32_bf16(Bt[n][k], At[m][k], acc[ai][bj][m][n], 0, 0, 0); __builtin_amdgcn_s_setprio(0); } while (0)
; #define PG8_WAIT_V(n) asm volatile("s_waitcnt vmcnt(" #n ")" ::: "memory")
; #define PG8_WAIT_L(n) asm volatile("s_waitcnt lgkmcnt(" #n ")" ::: "memory")
; #define PG8_BAR __builtin_amdgcn_s_barrier()
; #define PG8_SCHED __builtin_amdgcn_sched_barrier(0)
; template <class Epi, class Sched, bool ALIGN_EPI = false, bool SP2 = false>
; __device__ __forceinline__ void gemm_phase(PG8_LAS unsigned char* lds, const Gemm g, const Sched& S, const Epi& E, const int wave_in) {
;     ...
;             const char* a2 = last ? nA : cA + (size_t)(t + 2) * kstep; const char* b2 = last ? nB : cB + (size_t)(t + 2) * kstep;
;     ...
;             PG8_LDB(B0, 0, 0); PG8_LDB(B1, 0, 1); PG8_SCHED; PG8_LDA(At, 0, 0); PG8_STAGE(PG8_SA(1, 1), a1 + hstepA, voffA);
;             PG8_WAIT_V(8); PG8_WAIT_L(0); PG8_BAR; PG8_MMA(0, 0, At, B0); PG8_MMA(0, 1, At, B1); PG8_BAR; PG8_SCHED;
;             PG8_LDA(At, 0, 1); PG8_STAGE(PG8_SB(0, 0), b2, voffB); PG8_STAGE(PG8_SB(0, 1), b2 + hstep, voffB); PG8_STAGE(PG8_SA(0, 0), a2, voffA);
;             PG8_WAIT_V(8); PG8_WAIT_L(0); PG8_BAR; PG8_MMA(1, 0, At, B0); PG8_MMA(1, 1, At, B1); PG8_BAR; PG8_SCHED;
.LBB0_1647:
	ds_read_b128 v[144:147], v151
	ds_read_b128 v[156:159], v151 offset:1024
	ds_read_b128 v[160:163], v151 offset:2048
	ds_read_b128 v[164:167], v151 offset:3072
	ds_read_b128 v[168:171], v152
	ds_read_b128 v[172:175], v152 offset:1024
	ds_read_b128 v[176:179], v152 offset:2048
	ds_read_b128 v[180:183], v152 offset:3072
	s_add_u32 s58, s56, 0x100
	s_addc_u32 s59, s57, 0
	s_cmpk_eq_i32 s74, 0x54
	s_cselect_b32 s63, s7, s59
	s_cselect_b32 s62, s6, s58
	s_cselect_b32 s61, s43, s73
	s_cselect_b32 s60, s42, s72
	v_lshl_add_u64 v[216:217], s[56:57], 0, v[136:137]
	s_add_i32 m0, s33, 0xc000
	ds_read_b128 v[184:187], v153
	ds_read_b128 v[188:191], v153 offset:1024
	ds_read_b128 v[192:195], v153 offset:2048
	ds_read_b128 v[196:199], v153 offset:3072
	ds_read_b128 v[200:203], v153 offset:4096
	ds_read_b128 v[204:207], v153 offset:5120
	ds_read_b128 v[208:211], v153 offset:6144
	ds_read_b128 v[212:215], v153 offset:7168
	global_load_lds_dwordx4 v[216:217], off
	v_lshl_add_u64 v[216:217], s[56:57], 0, v[138:139]
	s_add_i32 m0, s33, 0xe000
	s_nop 0
	global_load_lds_dwordx4 v[216:217], off
	s_waitcnt vmcnt(8)
	s_waitcnt lgkmcnt(0)
	s_barrier
	s_setprio 1
	v_mfma_f32_16x16x32_bf16 v[124:127], v[144:147], v[184:187], v[124:127]
	v_mfma_f32_16x16x32_bf16 v[120:123], v[160:163], v[184:187], v[120:123]
	v_mfma_f32_16x16x32_bf16 v[108:111], v[144:147], v[192:195], v[108:111]
	v_mfma_f32_16x16x32_bf16 v[104:107], v[160:163], v[192:195], v[104:107]
	v_mfma_f32_16x16x32_bf16 v[92:95], v[144:147], v[200:203], v[92:95]
	v_mfma_f32_16x16x32_bf16 v[88:91], v[160:163], v[200:203], v[88:91]
	v_mfma_f32_16x16x32_bf16 v[76:79], v[144:147], v[208:211], v[76:79]
	v_mfma_f32_16x16x32_bf16 v[72:75], v[160:163], v[208:211], v[72:75]
	v_mfma_f32_16x16x32_bf16 v[124:127], v[156:159], v[188:191], v[124:127]
	v_mfma_f32_16x16x32_bf16 v[120:123], v[164:167], v[188:191], v[120:123]
	v_mfma_f32_16x16x32_bf16 v[108:111], v[156:159], v[196:199], v[108:111]
	v_mfma_f32_16x16x32_bf16 v[104:107], v[164:167], v[196:199], v[104:107]
	v_mfma_f32_16x16x32_bf16 v[92:95], v[156:159], v[204:207], v[92:95]
	v_mfma_f32_16x16x32_bf16 v[88:91], v[164:167], v[204:207], v[88:91]
	v_mfma_f32_16x16x32_bf16 v[76:79], v[156:159], v[212:215], v[76:79]
	v_mfma_f32_16x16x32_bf16 v[72:75], v[164:167], v[212:215], v[72:75]
	v_mfma_f32_16x16x32_bf16 v[116:119], v[168:171], v[184:187], v[116:119]
	v_mfma_f32_16x16x32_bf16 v[112:115], v[176:179], v[184:187], v[112:115]
	v_mfma_f32_16x16x32_bf16 v[100:103], v[168:171], v[192:195], v[100:103]
	v_mfma_f32_16x16x32_bf16 v[96:99], v[176:179], v[192:195], v[96:99]
	v_mfma_f32_16x16x32_bf16 v[84:87], v[168:171], v[200:203], v[84:87]
	v_mfma_f32_16x16x32_bf16 v[80:83], v[176:179], v[200:203], v[80:83]
	v_mfma_f32_16x16x32_bf16 v[68:71], v[168:171], v[208:211], v[68:71]
	v_mfma_f32_16x16x32_bf16 v[64:67], v[176:179], v[208:211], v[64:67]
	v_mfma_f32_16x16x32_bf16 v[116:119], v[172:175], v[188:191], v[116:119]
	v_mfma_f32_16x16x32_bf16 v[112:115], v[180:183], v[188:191], v[112:115]
	v_mfma_f32_16x16x32_bf16 v[100:103], v[172:175], v[196:199], v[100:103]
	v_mfma_f32_16x16x32_bf16 v[96:99], v[180:183], v[196:199], v[96:99]
	v_mfma_f32_16x16x32_bf16 v[84:87], v[172:175], v[204:207], v[84:87]
	v_mfma_f32_16x16x32_bf16 v[80:83], v[180:183], v[204:207], v[80:83]
	v_mfma_f32_16x16x32_bf16 v[68:71], v[172:175], v[212:215], v[68:71]
	v_mfma_f32_16x16x32_bf16 v[64:67], v[180:183], v[212:215], v[64:67]
	s_setprio 0
	s_barrier
	s_add_i32 s56, s68, s11
	v_lshl_add_u64 v[216:217], s[60:61], 0, v[130:131]
	s_mov_b32 m0, s56
	ds_read_b128 v[184:187], v153 offset:16384
	ds_read_b128 v[188:191], v153 offset:17408
	ds_read_b128 v[192:195], v153 offset:18432
	ds_read_b128 v[196:199], v153 offset:19456
	ds_read_b128 v[200:203], v153 offset:20480
	ds_read_b128 v[204:207], v153 offset:21504
	ds_read_b128 v[208:211], v153 offset:22528
	ds_read_b128 v[212:215], v153 offset:23552
	global_load_lds_dwordx4 v[216:217], off
	s_add_i32 m0, s56, 0x2000
	s_add_u32 s56, s60, 0x160000
	v_lshl_add_u64 v[218:219], s[60:61], 0, v[134:135]
	s_addc_u32 s57, s61, 0
	s_add_i32 s75, s69, s11
	global_load_lds_dwordx4 v[218:219], off
	v_lshl_add_u64 v[220:221], s[56:57], 0, v[130:131]
	s_mov_b32 m0, s75
	v_lshl_add_u64 v[222:223], s[62:63], 0, v[132:133]
	global_load_lds_dwordx4 v[220:221], off
	v_lshl_add_u64 v[220:221], s[56:57], 0, v[134:135]
	s_add_i32 m0, s75, 0x2000
	s_nop 0
	global_load_lds_dwordx4 v[220:221], off
	v_lshl_add_u64 v[220:221], s[62:63], 0, v[128:129]
	s_mov_b32 m0, s33
	s_nop 0
	global_load_lds_dwordx4 v[220:221], off
	s_mov_b32 m0, s35
	s_nop 0
	global_load_lds_dwordx4 v[222:223], off
	s_waitcnt vmcnt(8)
	s_waitcnt lgkmcnt(0)
	s_barrier
; #define PG8_STAGE(bufoff, gbase, voff) do { _Pragma("unroll") for (int _i = 0; _i < 2; ++_i) \
;         __builtin_amdgcn_global_load_lds((const unsigned*)((const char*)(gbase) + (voff)[_i]), (PG8_LAS unsigned*)(lds + (bufoff) + ldsw + _i * 8192), 16, 0, 0); } while (0)
; #define PG8_LDA(dst, b, h) do { _Pragma("unroll") for (int m = 0; m < 4; ++m) _Pragma("unroll") for (int k = 0; k < 2; ++k) dst[m][k] = *(const PG8_LAS bf16x8*)(lds + PG8_SA(b, h) + aoff + m * 2048 + k * 1024); } while (0)
; #define PG8_LDB(dst, b, h) do { _Pragma("unroll") for (int n = 0; n < 2; ++n) _Pragma("unroll") for (int k = 0; k < 2; ++k) dst[n][k] = *(const PG8_LAS bf16x8*)(lds + PG8_SB(b, h) + boff + n * 2048 + k * 1024); } while (0)
; #define PG8_MMA(ai, bj, At, Bt) do { __builtin_amdgcn_s_setprio(1); _Pragma("unroll") for (int m = 0; m < 4; ++m) _Pragma("unroll") for (int n = 0; n < 2; ++n) _Pragma("unroll") for (int k = 0; k < 2; ++k) \
;         acc[ai][bj][m][n] = __builtin_amdgcn_mfma_f32_16x16x32_bf16(Bt[n][k], At[m][k], acc[ai][bj][m][n], 0, 0, 0); __builtin_amdgcn_s_setprio(0); } while (0)
; #define PG8_WAIT_V(n) asm volatile("s_waitcnt vmcnt(" #n ")" ::: "memory")
; #define PG8_WAIT_L(n) asm volatile("s_waitcnt lgkmcnt(" #n ")" ::: "memory")
; #define PG8_BAR __builtin_amdgcn_s_barrier()
; #define PG8_SCHED __builtin_amdgcn_sched_barrier(0)
; template <class Epi, class Sched, bool ALIGN_EPI = false, bool SP2 = false>
; __device__ __forceinline__ void gemm_phase(PG8_LAS unsigned char* lds, const Gemm g, const Sched& S, const Epi& E, const int wave_in) {
;     ...
;             PG8_WAIT_V(8); PG8_WAIT_L(0); PG8_BAR; PG8_MMA(1, 0, At, B0); PG8_MMA(1, 1, At, B1); PG8_BAR; PG8_SCHED;
;             PG8_LDB(B0, 1, 0); PG8_LDB(B1, 1, 1); PG8_SCHED; PG8_LDA(At, 1, 0); PG8_STAGE(PG8_SA(0, 1), a2 + hstepA, voffA);
;             PG8_WAIT_V(8); PG8_WAIT_L(0); PG8_BAR; PG8_MMA(0, 0, At, B0); PG8_MMA(0, 1, At, B1); PG8_BAR; PG8_SCHED;
	s_setprio 1
	v_mfma_f32_16x16x32_bf16 v[60:63], v[144:147], v[184:187], v[60:63]
	v_mfma_f32_16x16x32_bf16 v[56:59], v[160:163], v[184:187], v[56:59]
	v_mfma_f32_16x16x32_bf16 v[44:47], v[144:147], v[192:195], v[44:47]
	v_mfma_f32_16x16x32_bf16 v[40:43], v[160:163], v[192:195], v[40:43]
	v_mfma_f32_16x16x32_bf16 v[28:31], v[144:147], v[200:203], v[28:31]
	v_mfma_f32_16x16x32_bf16 v[24:27], v[160:163], v[200:203], v[24:27]
	v_mfma_f32_16x16x32_bf16 v[12:15], v[144:147], v[208:211], v[12:15]
	v_mfma_f32_16x16x32_bf16 v[8:11], v[160:163], v[208:211], v[8:11]
	v_mfma_f32_16x16x32_bf16 v[60:63], v[156:159], v[188:191], v[60:63]
	v_mfma_f32_16x16x32_bf16 v[56:59], v[164:167], v[188:191], v[56:59]
	v_mfma_f32_16x16x32_bf16 v[44:47], v[156:159], v[196:199], v[44:47]
	v_mfma_f32_16x16x32_bf16 v[40:43], v[164:167], v[196:199], v[40:43]
	v_mfma_f32_16x16x32_bf16 v[28:31], v[156:159], v[204:207], v[28:31]
	v_mfma_f32_16x16x32_bf16 v[24:27], v[164:167], v[204:207], v[24:27]
	v_mfma_f32_16x16x32_bf16 v[12:15], v[156:159], v[212:215], v[12:15]
	v_mfma_f32_16x16x32_bf16 v[8:11], v[164:167], v[212:215], v[8:11]
	v_mfma_f32_16x16x32_bf16 v[52:55], v[168:171], v[184:187], v[52:55]
	v_mfma_f32_16x16x32_bf16 v[48:51], v[176:179], v[184:187], v[48:51]
	v_mfma_f32_16x16x32_bf16 v[36:39], v[168:171], v[192:195], v[36:39]
	v_mfma_f32_16x16x32_bf16 v[32:35], v[176:179], v[192:195], v[32:35]
	v_mfma_f32_16x16x32_bf16 v[20:23], v[168:171], v[200:203], v[20:23]
	v_mfma_f32_16x16x32_bf16 v[16:19], v[176:179], v[200:203], v[16:19]
	v_mfma_f32_16x16x32_bf16 v[4:7], v[168:171], v[208:211], v[4:7]
	v_mfma_f32_16x16x32_bf16 v[0:3], v[176:179], v[208:211], v[0:3]
	v_mfma_f32_16x16x32_bf16 v[52:55], v[172:175], v[188:191], v[52:55]
	v_mfma_f32_16x16x32_bf16 v[48:51], v[180:183], v[188:191], v[48:51]
	v_mfma_f32_16x16x32_bf16 v[36:39], v[172:175], v[196:199], v[36:39]
	v_mfma_f32_16x16x32_bf16 v[32:35], v[180:183], v[196:199], v[32:35]
	v_mfma_f32_16x16x32_bf16 v[20:23], v[172:175], v[204:207], v[20:23]
	v_mfma_f32_16x16x32_bf16 v[16:19], v[180:183], v[204:207], v[16:19]
	v_mfma_f32_16x16x32_bf16 v[4:7], v[172:175], v[212:215], v[4:7]
	v_mfma_f32_16x16x32_bf16 v[0:3], v[180:183], v[212:215], v[0:3]
	s_setprio 0
	s_barrier
	s_add_i32 s75, 0, 0x18000
	v_add_u32_e32 v155, s75, v149
	s_add_i32 s76, 0, 0x1c000
	ds_read_b128 v[144:147], v155
	ds_read_b128 v[156:159], v155 offset:1024
	ds_read_b128 v[160:163], v155 offset:2048
	ds_read_b128 v[164:167], v155 offset:3072
	v_add_u32_e32 v155, s76, v149
	ds_read_b128 v[168:171], v155
	ds_read_b128 v[172:175], v155 offset:1024
	ds_read_b128 v[176:179], v155 offset:2048
	ds_read_b128 v[180:183], v155 offset:3072
	s_add_u32 s56, s62, 0x160000
	s_addc_u32 s57, s63, 0
	s_mov_b32 m0, s50
	v_lshl_add_u64 v[224:225], s[56:57], 0, v[128:129]
	ds_read_b128 v[184:187], v153 offset:32768
	ds_read_b128 v[188:191], v153 offset:33792
	ds_read_b128 v[192:195], v153 offset:34816
	ds_read_b128 v[196:199], v153 offset:35840
	ds_read_b128 v[200:203], v153 offset:36864
	ds_read_b128 v[204:207], v153 offset:37888
	ds_read_b128 v[208:211], v153 offset:38912
	ds_read_b128 v[212:215], v153 offset:39936
	global_load_lds_dwordx4 v[224:225], off
	v_lshl_add_u64 v[224:225], s[56:57], 0, v[132:133]
	s_mov_b32 m0, s51
	s_nop 0
	global_load_lds_dwordx4 v[224:225], off
	s_waitcnt vmcnt(8)
	s_waitcnt lgkmcnt(0)
	s_barrier
	s_setprio 1
	v_mfma_f32_16x16x32_bf16 v[124:127], v[144:147], v[184:187], v[124:127]
	v_mfma_f32_16x16x32_bf16 v[120:123], v[160:163], v[184:187], v[120:123]
	v_mfma_f32_16x16x32_bf16 v[108:111], v[144:147], v[192:195], v[108:111]
	v_mfma_f32_16x16x32_bf16 v[104:107], v[160:163], v[192:195], v[104:107]
	v_mfma_f32_16x16x32_bf16 v[92:95], v[144:147], v[200:203], v[92:95]
	v_mfma_f32_16x16x32_bf16 v[88:91], v[160:163], v[200:203], v[88:91]
	v_mfma_f32_16x16x32_bf16 v[76:79], v[144:147], v[208:211], v[76:79]
	v_mfma_f32_16x16x32_bf16 v[72:75], v[160:163], v[208:211], v[72:75]
	v_mfma_f32_16x16x32_bf16 v[124:127], v[156:159], v[188:191], v[124:127]
	v_mfma_f32_16x16x32_bf16 v[120:123], v[164:167], v[188:191], v[120:123]
	v_mfma_f32_16x16x32_bf16 v[108:111], v[156:159], v[196:199], v[108:111]
	v_mfma_f32_16x16x32_bf16 v[104:107], v[164:167], v[196:199], v[104:107]
	v_mfma_f32_16x16x32_bf16 v[92:95], v[156:159], v[204:207], v[92:95]
	v_mfma_f32_16x16x32_bf16 v[88:91], v[164:167], v[204:207], v[88:91]
	v_mfma_f32_16x16x32_bf16 v[76:79], v[156:159], v[212:215], v[76:79]
	v_mfma_f32_16x16x32_bf16 v[72:75], v[164:167], v[212:215], v[72:75]
	v_mfma_f32_16x16x32_bf16 v[116:119], v[168:171], v[184:187], v[116:119]
	v_mfma_f32_16x16x32_bf16 v[112:115], v[176:179], v[184:187], v[112:115]
	v_mfma_f32_16x16x32_bf16 v[100:103], v[168:171], v[192:195], v[100:103]
	v_mfma_f32_16x16x32_bf16 v[96:99], v[176:179], v[192:195], v[96:99]
	v_mfma_f32_16x16x32_bf16 v[84:87], v[168:171], v[200:203], v[84:87]
	v_mfma_f32_16x16x32_bf16 v[80:83], v[176:179], v[200:203], v[80:83]
	v_mfma_f32_16x16x32_bf16 v[68:71], v[168:171], v[208:211], v[68:71]
	v_mfma_f32_16x16x32_bf16 v[64:67], v[176:179], v[208:211], v[64:67]
	v_mfma_f32_16x16x32_bf16 v[116:119], v[172:175], v[188:191], v[116:119]
	v_mfma_f32_16x16x32_bf16 v[112:115], v[180:183], v[188:191], v[112:115]
	v_mfma_f32_16x16x32_bf16 v[100:103], v[172:175], v[196:199], v[100:103]
	v_mfma_f32_16x16x32_bf16 v[96:99], v[180:183], v[196:199], v[96:99]
	v_mfma_f32_16x16x32_bf16 v[84:87], v[172:175], v[204:207], v[84:87]
	v_mfma_f32_16x16x32_bf16 v[80:83], v[180:183], v[204:207], v[80:83]
	v_mfma_f32_16x16x32_bf16 v[68:71], v[172:175], v[212:215], v[68:71]
	v_mfma_f32_16x16x32_bf16 v[64:67], v[180:183], v[212:215], v[64:67]
	s_setprio 0
	s_barrier
; #define PG8_STAGE(bufoff, gbase, voff) do { _Pragma("unroll") for (int _i = 0; _i < 2; ++_i) \
;         __builtin_amdgcn_global_load_lds((const unsigned*)((const char*)(gbase) + (voff)[_i]), (PG8_LAS unsigned*)(lds + (bufoff) + ldsw + _i * 8192), 16, 0, 0); } while (0)
; #define PG8_LDA(dst, b, h) do { _Pragma("unroll") for (int m = 0; m < 4; ++m) _Pragma("unroll") for (int k = 0; k < 2; ++k) dst[m][k] = *(const PG8_LAS bf16x8*)(lds + PG8_SA(b, h) + aoff + m * 2048 + k * 1024); } while (0)
; #define PG8_MMA(ai, bj, At, Bt) do { __builtin_amdgcn_s_setprio(1); _Pragma("unroll") for (int m = 0; m < 4; ++m) _Pragma("unroll") for (int n = 0; n < 2; ++n) _Pragma("unroll") for (int k = 0; k < 2; ++k) \
;         acc[ai][bj][m][n] = __builtin_amdgcn_mfma_f32_16x16x32_bf16(Bt[n][k], At[m][k], acc[ai][bj][m][n], 0, 0, 0); __builtin_amdgcn_s_setprio(0); } while (0)
; #define PG8_WAIT_V(n) asm volatile("s_waitcnt vmcnt(" #n ")" ::: "memory")
; #define PG8_WAIT_L(n) asm volatile("s_waitcnt lgkmcnt(" #n ")" ::: "memory")
; #define PG8_BAR __builtin_amdgcn_s_barrier()
; #define PG8_SCHED __builtin_amdgcn_sched_barrier(0)
; template <class Epi, class Sched, bool ALIGN_EPI = false, bool SP2 = false>
; __device__ __forceinline__ void gemm_phase(PG8_LAS unsigned char* lds, const Gemm g, const Sched& S, const Epi& E, const int wave_in) {
;     ...
;         for (int t = 0; t < nt; t += 2) {
;             const bool last = (t == nt - 2);
;             const char* a1 = cA + (size_t)(t + 1) * kstep;
;             const char* a2 = last ? nA : cA + (size_t)(t + 2) * kstep; const char* b2 = last ? nB : cB + (size_t)(t + 2) * kstep;
;             const char* a3 = a2 + kstep; const char* b3 = b2 + kstep;
;             if (last && has_next) S.a_ready(nxt);
;     ...
;             PG8_LDA(At, 1, 1); PG8_STAGE(PG8_SB(1, 0), b3, voffB); PG8_STAGE(PG8_SB(1, 1), b3 + hstep, voffB); PG8_STAGE(PG8_SA(1, 0), a3, voffA);
;             PG8_WAIT_V(8); PG8_WAIT_L(0); PG8_BAR; PG8_MMA(1, 0, At, B0); PG8_MMA(1, 1, At, B1); PG8_BAR; PG8_SCHED;
	s_add_i32 s56, s75, s11
	v_lshl_add_u64 v[216:217], v[216:217], 0, s[38:39]
	s_mov_b32 m0, s56
	ds_read_b128 v[184:187], v153 offset:49152
	ds_read_b128 v[188:191], v153 offset:50176
	ds_read_b128 v[192:195], v153 offset:51200
	ds_read_b128 v[196:199], v153 offset:52224
	ds_read_b128 v[200:203], v153 offset:53248
	ds_read_b128 v[204:207], v153 offset:54272
	ds_read_b128 v[208:211], v153 offset:55296
	ds_read_b128 v[212:215], v153 offset:56320
	global_load_lds_dwordx4 v[216:217], off
	s_add_i32 m0, s56, 0x2000
	s_add_u32 s56, s60, 0x160080
	v_lshl_add_u64 v[216:217], v[218:219], 0, s[38:39]
	s_addc_u32 s57, s61, 0
	s_add_i32 s60, s76, s11
	global_load_lds_dwordx4 v[216:217], off
	v_lshl_add_u64 v[216:217], s[56:57], 0, v[130:131]
	s_mov_b32 m0, s60
	s_nop 0
	global_load_lds_dwordx4 v[216:217], off
	v_lshl_add_u64 v[216:217], s[56:57], 0, v[134:135]
	s_add_i32 m0, s60, 0x2000
	s_nop 0
	global_load_lds_dwordx4 v[216:217], off
	v_lshl_add_u64 v[216:217], v[220:221], 0, s[38:39]
	s_mov_b32 m0, s65
	s_nop 0
	global_load_lds_dwordx4 v[216:217], off
	v_lshl_add_u64 v[216:217], v[222:223], 0, s[38:39]
	s_mov_b32 m0, s66
	s_nop 0
	global_load_lds_dwordx4 v[216:217], off
	s_waitcnt vmcnt(8)
	s_waitcnt lgkmcnt(0)
	s_barrier
	s_setprio 1
	v_mfma_f32_16x16x32_bf16 v[60:63], v[144:147], v[184:187], v[60:63]
	v_mfma_f32_16x16x32_bf16 v[56:59], v[160:163], v[184:187], v[56:59]
	v_mfma_f32_16x16x32_bf16 v[44:47], v[144:147], v[192:195], v[44:47]
	v_mfma_f32_16x16x32_bf16 v[40:43], v[160:163], v[192:195], v[40:43]
	v_mfma_f32_16x16x32_bf16 v[28:31], v[144:147], v[200:203], v[28:31]
	v_mfma_f32_16x16x32_bf16 v[24:27], v[160:163], v[200:203], v[24:27]
	v_mfma_f32_16x16x32_bf16 v[12:15], v[144:147], v[208:211], v[12:15]
	v_mfma_f32_16x16x32_bf16 v[8:11], v[160:163], v[208:211], v[8:11]
	v_mfma_f32_16x16x32_bf16 v[60:63], v[156:159], v[188:191], v[60:63]
	v_mfma_f32_16x16x32_bf16 v[56:59], v[164:167], v[188:191], v[56:59]
	v_mfma_f32_16x16x32_bf16 v[44:47], v[156:159], v[196:199], v[44:47]
	v_mfma_f32_16x16x32_bf16 v[40:43], v[164:167], v[196:199], v[40:43]
	v_mfma_f32_16x16x32_bf16 v[28:31], v[156:159], v[204:207], v[28:31]
	v_mfma_f32_16x16x32_bf16 v[24:27], v[164:167], v[204:207], v[24:27]
	v_mfma_f32_16x16x32_bf16 v[12:15], v[156:159], v[212:215], v[12:15]
	v_mfma_f32_16x16x32_bf16 v[8:11], v[164:167], v[212:215], v[8:11]
	v_mfma_f32_16x16x32_bf16 v[52:55], v[168:171], v[184:187], v[52:55]
	v_mfma_f32_16x16x32_bf16 v[48:51], v[176:179], v[184:187], v[48:51]
	v_mfma_f32_16x16x32_bf16 v[36:39], v[168:171], v[192:195], v[36:39]
	v_mfma_f32_16x16x32_bf16 v[32:35], v[176:179], v[192:195], v[32:35]
	v_mfma_f32_16x16x32_bf16 v[20:23], v[168:171], v[200:203], v[20:23]
	v_mfma_f32_16x16x32_bf16 v[16:19], v[176:179], v[200:203], v[16:19]
	v_mfma_f32_16x16x32_bf16 v[4:7], v[168:171], v[208:211], v[4:7]
	v_mfma_f32_16x16x32_bf16 v[0:3], v[176:179], v[208:211], v[0:3]
	v_mfma_f32_16x16x32_bf16 v[52:55], v[172:175], v[188:191], v[52:55]
	v_mfma_f32_16x16x32_bf16 v[48:51], v[180:183], v[188:191], v[48:51]
	v_mfma_f32_16x16x32_bf16 v[36:39], v[172:175], v[196:199], v[36:39]
	v_mfma_f32_16x16x32_bf16 v[32:35], v[180:183], v[196:199], v[32:35]
	v_mfma_f32_16x16x32_bf16 v[20:23], v[172:175], v[204:207], v[20:23]
	v_mfma_f32_16x16x32_bf16 v[16:19], v[180:183], v[204:207], v[16:19]
	v_mfma_f32_16x16x32_bf16 v[4:7], v[172:175], v[212:215], v[4:7]
	v_mfma_f32_16x16x32_bf16 v[0:3], v[180:183], v[212:215], v[0:3]
	s_setprio 0
	s_barrier
	s_add_i32 s74, s74, 2
	s_add_u32 s72, s72, 0x100
	s_addc_u32 s73, s73, 0
	s_cmpk_gt_u32 s74, 0x55
	s_mov_b64 s[56:57], s[58:59]
	s_cbranch_scc0 .LBB0_1647
	s_and_b64 vcc, exec, s[40:41]
	s_cbranch_vccz .LBB0_1650
	s_barrier

; #define PG8_STAGE(bufoff, gbase, voff) do { _Pragma("unroll") for (int _i = 0; _i < 2; ++_i) \
;         __builtin_amdgcn_global_load_lds((const unsigned*)((const char*)(gbase) + (voff)[_i]), (PG8_LAS unsigned*)(lds + (bufoff) + ldsw + _i * 8192), 16, 0, 0); } while (0)
; #define PG8_LDA(dst, b, h) do { _Pragma("unroll") for (int m = 0; m < 4; ++m) _Pragma("unroll") for (int k = 0; k < 2; ++k) dst[m][k] = *(const PG8_LAS bf16x8*)(lds + PG8_SA(b, h) + aoff + m * 2048 + k * 1024); } while (0)
; #define PG8_LDB(dst, b, h) do { _Pragma("unroll") for (int n = 0; n < 2; ++n) _Pragma("unroll") for (int k = 0; k < 2; ++k) dst[n][k] = *(const PG8_LAS bf16x8*)(lds + PG8_SB(b, h) + boff + n * 2048 + k * 1024); } while (0)
; #define PG8_MMA(ai, bj, At, Bt) do { __builtin_amdgcn_s_setprio(1); _Pragma("unroll") for (int m = 0; m < 4; ++m) _Pragma("unroll") for (int n = 0; n < 2; ++n) _Pragma("unroll") for (int k = 0; k < 2; ++k) \
;         acc[ai][bj][m][n] = __builtin_amdgcn_mfma_f32_16x16x32_bf16(Bt[n][k], At[m][k], acc[ai][bj][m][n], 0, 0, 0); __builtin_amdgcn_s_setprio(0); } while (0)
; #define PG8_WAIT_V(n) asm volatile("s_waitcnt vmcnt(" #n ")" ::: "memory")
; #define PG8_WAIT_L(n) asm volatile("s_waitcnt lgkmcnt(" #n ")" ::: "memory")
; #define PG8_BAR __builtin_amdgcn_s_barrier()
; #define PG8_SCHED __builtin_amdgcn_sched_barrier(0)
; template <class Epi, class Sched, bool ALIGN_EPI = false, bool SP2 = false>
; __device__ __forceinline__ void gemm_phase(PG8_LAS unsigned char* lds, const Gemm g, const Sched& S, const Epi& E, const int wave_in) {
;     ...
;             const char* a2 = last ? nA : cA + (size_t)(t + 2) * kstep; const char* b2 = last ? nB : cB + (size_t)(t + 2) * kstep;
;     ...
;             PG8_LDB(B0, 0, 0); PG8_LDB(B1, 0, 1); PG8_SCHED; PG8_LDA(At, 0, 0); PG8_STAGE(PG8_SA(1, 1), a1 + hstepA, voffA);
;             PG8_WAIT_V(8); PG8_WAIT_L(0); PG8_BAR; PG8_MMA(0, 0, At, B0); PG8_MMA(0, 1, At, B1); PG8_BAR; PG8_SCHED;
;             PG8_LDA(At, 0, 1); PG8_STAGE(PG8_SB(0, 0), b2, voffB); PG8_STAGE(PG8_SB(0, 1), b2 + hstep, voffB); PG8_STAGE(PG8_SA(0, 0), a2, voffA);
;             PG8_WAIT_V(8); PG8_WAIT_L(0); PG8_BAR; PG8_MMA(1, 0, At, B0); PG8_MMA(1, 1, At, B1); PG8_BAR; PG8_SCHED;
.LBB0_1734:
	ds_read_b128 v[144:147], v155
	ds_read_b128 v[148:151], v155 offset:1024
	ds_read_b128 v[160:163], v155 offset:2048
	ds_read_b128 v[164:167], v155 offset:3072
	ds_read_b128 v[168:171], v156
	ds_read_b128 v[172:175], v156 offset:1024
	ds_read_b128 v[176:179], v156 offset:2048
	ds_read_b128 v[180:183], v156 offset:3072
	s_add_u32 s60, s58, 0xfff80080
	s_addc_u32 s61, s59, -1
	s_cmp_eq_u32 s74, 28
	s_cselect_b32 s63, s39, s61
	s_cselect_b32 s62, s70, s60
	s_cselect_b32 s61, s37, s73
	s_cselect_b32 s60, s71, s72
	v_lshl_add_u64 v[216:217], s[58:59], 0, v[136:137]
	s_add_i32 m0, s48, 0xc000
	ds_read_b128 v[184:187], v157
	ds_read_b128 v[188:191], v157 offset:1024
	ds_read_b128 v[192:195], v157 offset:2048
	ds_read_b128 v[196:199], v157 offset:3072
	ds_read_b128 v[200:203], v157 offset:4096
	ds_read_b128 v[204:207], v157 offset:5120
	ds_read_b128 v[208:211], v157 offset:6144
	ds_read_b128 v[212:215], v157 offset:7168
	global_load_lds_dwordx4 v[216:217], off
	v_lshl_add_u64 v[216:217], s[58:59], 0, v[138:139]
	s_add_i32 m0, s48, 0xe000
	s_nop 0
	global_load_lds_dwordx4 v[216:217], off
	s_waitcnt vmcnt(8)
	s_waitcnt lgkmcnt(0)
	s_barrier
	s_setprio 1
	v_mfma_f32_16x16x32_bf16 v[124:127], v[144:147], v[184:187], v[124:127]
	v_mfma_f32_16x16x32_bf16 v[120:123], v[160:163], v[184:187], v[120:123]
	v_mfma_f32_16x16x32_bf16 v[108:111], v[144:147], v[192:195], v[108:111]
	v_mfma_f32_16x16x32_bf16 v[104:107], v[160:163], v[192:195], v[104:107]
	v_mfma_f32_16x16x32_bf16 v[92:95], v[144:147], v[200:203], v[92:95]
	v_mfma_f32_16x16x32_bf16 v[88:91], v[160:163], v[200:203], v[88:91]
	v_mfma_f32_16x16x32_bf16 v[76:79], v[144:147], v[208:211], v[76:79]
	v_mfma_f32_16x16x32_bf16 v[72:75], v[160:163], v[208:211], v[72:75]
	v_mfma_f32_16x16x32_bf16 v[124:127], v[148:151], v[188:191], v[124:127]
	v_mfma_f32_16x16x32_bf16 v[120:123], v[164:167], v[188:191], v[120:123]
	v_mfma_f32_16x16x32_bf16 v[108:111], v[148:151], v[196:199], v[108:111]
	v_mfma_f32_16x16x32_bf16 v[104:107], v[164:167], v[196:199], v[104:107]
	v_mfma_f32_16x16x32_bf16 v[92:95], v[148:151], v[204:207], v[92:95]
	v_mfma_f32_16x16x32_bf16 v[88:91], v[164:167], v[204:207], v[88:91]
	v_mfma_f32_16x16x32_bf16 v[76:79], v[148:151], v[212:215], v[76:79]
	v_mfma_f32_16x16x32_bf16 v[72:75], v[164:167], v[212:215], v[72:75]
	v_mfma_f32_16x16x32_bf16 v[116:119], v[168:171], v[184:187], v[116:119]
	v_mfma_f32_16x16x32_bf16 v[112:115], v[176:179], v[184:187], v[112:115]
	v_mfma_f32_16x16x32_bf16 v[100:103], v[168:171], v[192:195], v[100:103]
	v_mfma_f32_16x16x32_bf16 v[96:99], v[176:179], v[192:195], v[96:99]
	v_mfma_f32_16x16x32_bf16 v[84:87], v[168:171], v[200:203], v[84:87]
	v_mfma_f32_16x16x32_bf16 v[80:83], v[176:179], v[200:203], v[80:83]
	v_mfma_f32_16x16x32_bf16 v[68:71], v[168:171], v[208:211], v[68:71]
	v_mfma_f32_16x16x32_bf16 v[64:67], v[176:179], v[208:211], v[64:67]
	v_mfma_f32_16x16x32_bf16 v[116:119], v[172:175], v[188:191], v[116:119]
	v_mfma_f32_16x16x32_bf16 v[112:115], v[180:183], v[188:191], v[112:115]
	v_mfma_f32_16x16x32_bf16 v[100:103], v[172:175], v[196:199], v[100:103]
	v_mfma_f32_16x16x32_bf16 v[96:99], v[180:183], v[196:199], v[96:99]
	v_mfma_f32_16x16x32_bf16 v[84:87], v[172:175], v[204:207], v[84:87]
	v_mfma_f32_16x16x32_bf16 v[80:83], v[180:183], v[204:207], v[80:83]
	v_mfma_f32_16x16x32_bf16 v[68:71], v[172:175], v[212:215], v[68:71]
	v_mfma_f32_16x16x32_bf16 v[64:67], v[180:183], v[212:215], v[64:67]
	s_setprio 0
	s_barrier
	s_add_i32 s75, s66, s11
	v_lshl_add_u64 v[216:217], s[60:61], 0, v[132:133]
	s_mov_b32 m0, s75
	ds_read_b128 v[184:187], v157 offset:16384
	ds_read_b128 v[188:191], v157 offset:17408
	ds_read_b128 v[192:195], v157 offset:18432
	ds_read_b128 v[196:199], v157 offset:19456
	ds_read_b128 v[200:203], v157 offset:20480
	ds_read_b128 v[204:207], v157 offset:21504
	ds_read_b128 v[208:211], v157 offset:22528
	ds_read_b128 v[212:215], v157 offset:23552
	global_load_lds_dwordx4 v[216:217], off
	s_add_i32 m0, s75, 0x2000
	s_add_u32 s76, s60, 0x80000
	v_lshl_add_u64 v[218:219], s[60:61], 0, v[128:129]
	s_addc_u32 s77, s61, 0
	s_add_i32 s75, s67, s11
	global_load_lds_dwordx4 v[218:219], off
	v_lshl_add_u64 v[220:221], s[76:77], 0, v[132:133]
	s_mov_b32 m0, s75
	v_lshl_add_u64 v[222:223], s[62:63], 0, v[130:131]
	global_load_lds_dwordx4 v[220:221], off
	v_lshl_add_u64 v[220:221], s[76:77], 0, v[128:129]
	s_add_i32 m0, s75, 0x2000
	s_nop 0
	global_load_lds_dwordx4 v[220:221], off
	v_lshl_add_u64 v[220:221], s[62:63], 0, v[134:135]
	s_mov_b32 m0, s48
	s_nop 0
	global_load_lds_dwordx4 v[220:221], off
	s_mov_b32 m0, s49
	s_nop 0
	global_load_lds_dwordx4 v[222:223], off
	s_waitcnt vmcnt(8)
	s_waitcnt lgkmcnt(0)
	s_barrier
; #define PG8_STAGE(bufoff, gbase, voff) do { _Pragma("unroll") for (int _i = 0; _i < 2; ++_i) \
;         __builtin_amdgcn_global_load_lds((const unsigned*)((const char*)(gbase) + (voff)[_i]), (PG8_LAS unsigned*)(lds + (bufoff) + ldsw + _i * 8192), 16, 0, 0); } while (0)
; #define PG8_LDA(dst, b, h) do { _Pragma("unroll") for (int m = 0; m < 4; ++m) _Pragma("unroll") for (int k = 0; k < 2; ++k) dst[m][k] = *(const PG8_LAS bf16x8*)(lds + PG8_SA(b, h) + aoff + m * 2048 + k * 1024); } while (0)
; #define PG8_LDB(dst, b, h) do { _Pragma("unroll") for (int n = 0; n < 2; ++n) _Pragma("unroll") for (int k = 0; k < 2; ++k) dst[n][k] = *(const PG8_LAS bf16x8*)(lds + PG8_SB(b, h) + boff + n * 2048 + k * 1024); } while (0)
; #define PG8_MMA(ai, bj, At, Bt) do { __builtin_amdgcn_s_setprio(1); _Pragma("unroll") for (int m = 0; m < 4; ++m) _Pragma("unroll") for (int n = 0; n < 2; ++n) _Pragma("unroll") for (int k = 0; k < 2; ++k) \
;         acc[ai][bj][m][n] = __builtin_amdgcn_mfma_f32_16x16x32_bf16(Bt[n][k], At[m][k], acc[ai][bj][m][n], 0, 0, 0); __builtin_amdgcn_s_setprio(0); } while (0)
; #define PG8_WAIT_V(n) asm volatile("s_waitcnt vmcnt(" #n ")" ::: "memory")
; #define PG8_WAIT_L(n) asm volatile("s_waitcnt lgkmcnt(" #n ")" ::: "memory")
; #define PG8_BAR __builtin_amdgcn_s_barrier()
; #define PG8_SCHED __builtin_amdgcn_sched_barrier(0)
; template <class Epi, class Sched, bool ALIGN_EPI = false, bool SP2 = false>
; __device__ __forceinline__ void gemm_phase(PG8_LAS unsigned char* lds, const Gemm g, const Sched& S, const Epi& E, const int wave_in) {
;     ...
;             PG8_WAIT_V(8); PG8_WAIT_L(0); PG8_BAR; PG8_MMA(1, 0, At, B0); PG8_MMA(1, 1, At, B1); PG8_BAR; PG8_SCHED;
;             PG8_LDB(B0, 1, 0); PG8_LDB(B1, 1, 1); PG8_SCHED; PG8_LDA(At, 1, 0); PG8_STAGE(PG8_SA(0, 1), a2 + hstepA, voffA);
;             PG8_WAIT_V(8); PG8_WAIT_L(0); PG8_BAR; PG8_MMA(0, 0, At, B0); PG8_MMA(0, 1, At, B1); PG8_BAR; PG8_SCHED;
	s_setprio 1
	v_mfma_f32_16x16x32_bf16 v[60:63], v[144:147], v[184:187], v[60:63]
	v_mfma_f32_16x16x32_bf16 v[56:59], v[160:163], v[184:187], v[56:59]
	v_mfma_f32_16x16x32_bf16 v[44:47], v[144:147], v[192:195], v[44:47]
	v_mfma_f32_16x16x32_bf16 v[40:43], v[160:163], v[192:195], v[40:43]
	v_mfma_f32_16x16x32_bf16 v[28:31], v[144:147], v[200:203], v[28:31]
	v_mfma_f32_16x16x32_bf16 v[24:27], v[160:163], v[200:203], v[24:27]
	v_mfma_f32_16x16x32_bf16 v[12:15], v[144:147], v[208:211], v[12:15]
	v_mfma_f32_16x16x32_bf16 v[8:11], v[160:163], v[208:211], v[8:11]
	v_mfma_f32_16x16x32_bf16 v[60:63], v[148:151], v[188:191], v[60:63]
	v_mfma_f32_16x16x32_bf16 v[56:59], v[164:167], v[188:191], v[56:59]
	v_mfma_f32_16x16x32_bf16 v[44:47], v[148:151], v[196:199], v[44:47]
	v_mfma_f32_16x16x32_bf16 v[40:43], v[164:167], v[196:199], v[40:43]
	v_mfma_f32_16x16x32_bf16 v[28:31], v[148:151], v[204:207], v[28:31]
	v_mfma_f32_16x16x32_bf16 v[24:27], v[164:167], v[204:207], v[24:27]
	v_mfma_f32_16x16x32_bf16 v[12:15], v[148:151], v[212:215], v[12:15]
	v_mfma_f32_16x16x32_bf16 v[8:11], v[164:167], v[212:215], v[8:11]
	v_mfma_f32_16x16x32_bf16 v[52:55], v[168:171], v[184:187], v[52:55]
	v_mfma_f32_16x16x32_bf16 v[48:51], v[176:179], v[184:187], v[48:51]
	v_mfma_f32_16x16x32_bf16 v[36:39], v[168:171], v[192:195], v[36:39]
	v_mfma_f32_16x16x32_bf16 v[32:35], v[176:179], v[192:195], v[32:35]
	v_mfma_f32_16x16x32_bf16 v[20:23], v[168:171], v[200:203], v[20:23]
	v_mfma_f32_16x16x32_bf16 v[16:19], v[176:179], v[200:203], v[16:19]
	v_mfma_f32_16x16x32_bf16 v[4:7], v[168:171], v[208:211], v[4:7]
	v_mfma_f32_16x16x32_bf16 v[0:3], v[176:179], v[208:211], v[0:3]
	v_mfma_f32_16x16x32_bf16 v[52:55], v[172:175], v[188:191], v[52:55]
	v_mfma_f32_16x16x32_bf16 v[48:51], v[180:183], v[188:191], v[48:51]
	v_mfma_f32_16x16x32_bf16 v[36:39], v[172:175], v[196:199], v[36:39]
	v_mfma_f32_16x16x32_bf16 v[32:35], v[180:183], v[196:199], v[32:35]
	v_mfma_f32_16x16x32_bf16 v[20:23], v[172:175], v[204:207], v[20:23]
	v_mfma_f32_16x16x32_bf16 v[16:19], v[180:183], v[204:207], v[16:19]
	v_mfma_f32_16x16x32_bf16 v[4:7], v[172:175], v[212:215], v[4:7]
	v_mfma_f32_16x16x32_bf16 v[0:3], v[180:183], v[212:215], v[0:3]
	s_setprio 0
	s_barrier
	s_add_i32 s75, 0, 0x18000
	v_add_u32_e32 v159, s75, v153
	s_add_i32 s76, 0, 0x1c000
	ds_read_b128 v[144:147], v159
	ds_read_b128 v[148:151], v159 offset:1024
	ds_read_b128 v[160:163], v159 offset:2048
	ds_read_b128 v[164:167], v159 offset:3072
	v_add_u32_e32 v159, s76, v153
	ds_read_b128 v[168:171], v159
	ds_read_b128 v[172:175], v159 offset:1024
	ds_read_b128 v[176:179], v159 offset:2048
	ds_read_b128 v[180:183], v159 offset:3072
	s_add_u32 s62, s62, 0x80000
	s_addc_u32 s63, s63, 0
	s_mov_b32 m0, s50
	v_lshl_add_u64 v[224:225], s[62:63], 0, v[134:135]
	ds_read_b128 v[184:187], v157 offset:32768
	ds_read_b128 v[188:191], v157 offset:33792
	ds_read_b128 v[192:195], v157 offset:34816
	ds_read_b128 v[196:199], v157 offset:35840
	ds_read_b128 v[200:203], v157 offset:36864
	ds_read_b128 v[204:207], v157 offset:37888
	ds_read_b128 v[208:211], v157 offset:38912
	ds_read_b128 v[212:215], v157 offset:39936
	global_load_lds_dwordx4 v[224:225], off
	v_lshl_add_u64 v[224:225], s[62:63], 0, v[130:131]
	s_mov_b32 m0, s51
	s_nop 0
	global_load_lds_dwordx4 v[224:225], off
	s_waitcnt vmcnt(8)
	s_waitcnt lgkmcnt(0)
	s_barrier
	s_setprio 1
	v_mfma_f32_16x16x32_bf16 v[124:127], v[144:147], v[184:187], v[124:127]
	v_mfma_f32_16x16x32_bf16 v[120:123], v[160:163], v[184:187], v[120:123]
	v_mfma_f32_16x16x32_bf16 v[108:111], v[144:147], v[192:195], v[108:111]
	v_mfma_f32_16x16x32_bf16 v[104:107], v[160:163], v[192:195], v[104:107]
	v_mfma_f32_16x16x32_bf16 v[92:95], v[144:147], v[200:203], v[92:95]
	v_mfma_f32_16x16x32_bf16 v[88:91], v[160:163], v[200:203], v[88:91]
	v_mfma_f32_16x16x32_bf16 v[76:79], v[144:147], v[208:211], v[76:79]
	v_mfma_f32_16x16x32_bf16 v[72:75], v[160:163], v[208:211], v[72:75]
	v_mfma_f32_16x16x32_bf16 v[124:127], v[148:151], v[188:191], v[124:127]
	v_mfma_f32_16x16x32_bf16 v[120:123], v[164:167], v[188:191], v[120:123]
	v_mfma_f32_16x16x32_bf16 v[108:111], v[148:151], v[196:199], v[108:111]
	v_mfma_f32_16x16x32_bf16 v[104:107], v[164:167], v[196:199], v[104:107]
	v_mfma_f32_16x16x32_bf16 v[92:95], v[148:151], v[204:207], v[92:95]
	v_mfma_f32_16x16x32_bf16 v[88:91], v[164:167], v[204:207], v[88:91]
	v_mfma_f32_16x16x32_bf16 v[76:79], v[148:151], v[212:215], v[76:79]
	v_mfma_f32_16x16x32_bf16 v[72:75], v[164:167], v[212:215], v[72:75]
	v_mfma_f32_16x16x32_bf16 v[116:119], v[168:171], v[184:187], v[116:119]
	v_mfma_f32_16x16x32_bf16 v[112:115], v[176:179], v[184:187], v[112:115]
	v_mfma_f32_16x16x32_bf16 v[100:103], v[168:171], v[192:195], v[100:103]
	v_mfma_f32_16x16x32_bf16 v[96:99], v[176:179], v[192:195], v[96:99]
	v_mfma_f32_16x16x32_bf16 v[84:87], v[168:171], v[200:203], v[84:87]
	v_mfma_f32_16x16x32_bf16 v[80:83], v[176:179], v[200:203], v[80:83]
	v_mfma_f32_16x16x32_bf16 v[68:71], v[168:171], v[208:211], v[68:71]
	v_mfma_f32_16x16x32_bf16 v[64:67], v[176:179], v[208:211], v[64:67]
	v_mfma_f32_16x16x32_bf16 v[116:119], v[172:175], v[188:191], v[116:119]
	v_mfma_f32_16x16x32_bf16 v[112:115], v[180:183], v[188:191], v[112:115]
	v_mfma_f32_16x16x32_bf16 v[100:103], v[172:175], v[196:199], v[100:103]
	v_mfma_f32_16x16x32_bf16 v[96:99], v[180:183], v[196:199], v[96:99]
	v_mfma_f32_16x16x32_bf16 v[84:87], v[172:175], v[204:207], v[84:87]
	v_mfma_f32_16x16x32_bf16 v[80:83], v[180:183], v[204:207], v[80:83]
	v_mfma_f32_16x16x32_bf16 v[68:71], v[172:175], v[212:215], v[68:71]
	v_mfma_f32_16x16x32_bf16 v[64:67], v[180:183], v[212:215], v[64:67]
	s_setprio 0
	s_barrier
; #define PG8_STAGE(bufoff, gbase, voff) do { _Pragma("unroll") for (int _i = 0; _i < 2; ++_i) \
;         __builtin_amdgcn_global_load_lds((const unsigned*)((const char*)(gbase) + (voff)[_i]), (PG8_LAS unsigned*)(lds + (bufoff) + ldsw + _i * 8192), 16, 0, 0); } while (0)
; #define PG8_LDA(dst, b, h) do { _Pragma("unroll") for (int m = 0; m < 4; ++m) _Pragma("unroll") for (int k = 0; k < 2; ++k) dst[m][k] = *(const PG8_LAS bf16x8*)(lds + PG8_SA(b, h) + aoff + m * 2048 + k * 1024); } while (0)
; #define PG8_MMA(ai, bj, At, Bt) do { __builtin_amdgcn_s_setprio(1); _Pragma("unroll") for (int m = 0; m < 4; ++m) _Pragma("unroll") for (int n = 0; n < 2; ++n) _Pragma("unroll") for (int k = 0; k < 2; ++k) \
;         acc[ai][bj][m][n] = __builtin_amdgcn_mfma_f32_16x16x32_bf16(Bt[n][k], At[m][k], acc[ai][bj][m][n], 0, 0, 0); __builtin_amdgcn_s_setprio(0); } while (0)
; #define PG8_WAIT_V(n) asm volatile("s_waitcnt vmcnt(" #n ")" ::: "memory")
; #define PG8_WAIT_L(n) asm volatile("s_waitcnt lgkmcnt(" #n ")" ::: "memory")
; #define PG8_BAR __builtin_amdgcn_s_barrier()
; #define PG8_SCHED __builtin_amdgcn_sched_barrier(0)
; template <class Epi, class Sched, bool ALIGN_EPI = false, bool SP2 = false>
; __device__ __forceinline__ void gemm_phase(PG8_LAS unsigned char* lds, const Gemm g, const Sched& S, const Epi& E, const int wave_in) {
;     ...
;         for (int t = 0; t < nt; t += 2) {
;             const bool last = (t == nt - 2);
;             const char* a1 = cA + (size_t)(t + 1) * kstep;
;             const char* a2 = last ? nA : cA + (size_t)(t + 2) * kstep; const char* b2 = last ? nB : cB + (size_t)(t + 2) * kstep;
;             const char* a3 = a2 + kstep; const char* b3 = b2 + kstep;
;             if (last && has_next) S.a_ready(nxt);
;     ...
;             PG8_LDA(At, 1, 1); PG8_STAGE(PG8_SB(1, 0), b3, voffB); PG8_STAGE(PG8_SB(1, 1), b3 + hstep, voffB); PG8_STAGE(PG8_SA(1, 0), a3, voffA);
;             PG8_WAIT_V(8); PG8_WAIT_L(0); PG8_BAR; PG8_MMA(1, 0, At, B0); PG8_MMA(1, 1, At, B1); PG8_BAR; PG8_SCHED;
	s_add_i32 s62, s75, s11
	v_lshl_add_u64 v[216:217], v[216:217], 0, s[6:7]
	s_mov_b32 m0, s62
	ds_read_b128 v[184:187], v157 offset:49152
	ds_read_b128 v[188:191], v157 offset:50176
	ds_read_b128 v[192:195], v157 offset:51200
	ds_read_b128 v[196:199], v157 offset:52224
	ds_read_b128 v[200:203], v157 offset:53248
	ds_read_b128 v[204:207], v157 offset:54272
	ds_read_b128 v[208:211], v157 offset:55296
	ds_read_b128 v[212:215], v157 offset:56320
	global_load_lds_dwordx4 v[216:217], off
	s_add_i32 m0, s62, 0x2000
	s_add_u32 s60, s60, 0x80080
	v_lshl_add_u64 v[216:217], v[218:219], 0, s[6:7]
	s_addc_u32 s61, s61, 0
	s_add_i32 s62, s76, s11
	global_load_lds_dwordx4 v[216:217], off
	v_lshl_add_u64 v[216:217], s[60:61], 0, v[132:133]
	s_mov_b32 m0, s62
	s_nop 0
	global_load_lds_dwordx4 v[216:217], off
	v_lshl_add_u64 v[216:217], s[60:61], 0, v[128:129]
	s_add_i32 m0, s62, 0x2000
	s_nop 0
	global_load_lds_dwordx4 v[216:217], off
	v_lshl_add_u64 v[216:217], v[220:221], 0, s[6:7]
	s_mov_b32 m0, s64
	s_nop 0
	global_load_lds_dwordx4 v[216:217], off
	v_lshl_add_u64 v[216:217], v[222:223], 0, s[6:7]
	s_mov_b32 m0, s65
	s_nop 0
	global_load_lds_dwordx4 v[216:217], off
	s_waitcnt vmcnt(8)
	s_waitcnt lgkmcnt(0)
	s_barrier
	s_setprio 1
	v_mfma_f32_16x16x32_bf16 v[60:63], v[144:147], v[184:187], v[60:63]
	v_mfma_f32_16x16x32_bf16 v[56:59], v[160:163], v[184:187], v[56:59]
	v_mfma_f32_16x16x32_bf16 v[44:47], v[144:147], v[192:195], v[44:47]
	v_mfma_f32_16x16x32_bf16 v[40:43], v[160:163], v[192:195], v[40:43]
	v_mfma_f32_16x16x32_bf16 v[28:31], v[144:147], v[200:203], v[28:31]
	v_mfma_f32_16x16x32_bf16 v[24:27], v[160:163], v[200:203], v[24:27]
	v_mfma_f32_16x16x32_bf16 v[12:15], v[144:147], v[208:211], v[12:15]
	v_mfma_f32_16x16x32_bf16 v[8:11], v[160:163], v[208:211], v[8:11]
	v_mfma_f32_16x16x32_bf16 v[60:63], v[148:151], v[188:191], v[60:63]
	v_mfma_f32_16x16x32_bf16 v[56:59], v[164:167], v[188:191], v[56:59]
	v_mfma_f32_16x16x32_bf16 v[44:47], v[148:151], v[196:199], v[44:47]
	v_mfma_f32_16x16x32_bf16 v[40:43], v[164:167], v[196:199], v[40:43]
	v_mfma_f32_16x16x32_bf16 v[28:31], v[148:151], v[204:207], v[28:31]
	v_mfma_f32_16x16x32_bf16 v[24:27], v[164:167], v[204:207], v[24:27]
	v_mfma_f32_16x16x32_bf16 v[12:15], v[148:151], v[212:215], v[12:15]
	v_mfma_f32_16x16x32_bf16 v[8:11], v[164:167], v[212:215], v[8:11]
	v_mfma_f32_16x16x32_bf16 v[52:55], v[168:171], v[184:187], v[52:55]
	v_mfma_f32_16x16x32_bf16 v[48:51], v[176:179], v[184:187], v[48:51]
	v_mfma_f32_16x16x32_bf16 v[36:39], v[168:171], v[192:195], v[36:39]
	v_mfma_f32_16x16x32_bf16 v[32:35], v[176:179], v[192:195], v[32:35]
	v_mfma_f32_16x16x32_bf16 v[20:23], v[168:171], v[200:203], v[20:23]
	v_mfma_f32_16x16x32_bf16 v[16:19], v[176:179], v[200:203], v[16:19]
	v_mfma_f32_16x16x32_bf16 v[4:7], v[168:171], v[208:211], v[4:7]
	v_mfma_f32_16x16x32_bf16 v[0:3], v[176:179], v[208:211], v[0:3]
	v_mfma_f32_16x16x32_bf16 v[52:55], v[172:175], v[188:191], v[52:55]
	v_mfma_f32_16x16x32_bf16 v[48:51], v[180:183], v[188:191], v[48:51]
	v_mfma_f32_16x16x32_bf16 v[36:39], v[172:175], v[196:199], v[36:39]
	v_mfma_f32_16x16x32_bf16 v[32:35], v[180:183], v[196:199], v[32:35]
	v_mfma_f32_16x16x32_bf16 v[20:23], v[172:175], v[204:207], v[20:23]
	v_mfma_f32_16x16x32_bf16 v[16:19], v[180:183], v[204:207], v[16:19]
	v_mfma_f32_16x16x32_bf16 v[4:7], v[172:175], v[212:215], v[4:7]
	v_mfma_f32_16x16x32_bf16 v[0:3], v[180:183], v[212:215], v[0:3]
	s_setprio 0
	s_barrier
	s_add_i32 s74, s74, 2
	s_add_u32 s58, s58, 0x100
	s_addc_u32 s59, s59, 0
	s_add_u32 s72, s72, 0x100
	s_addc_u32 s73, s73, 0
	s_cmp_gt_u32 s74, 29
	s_cbranch_scc0 .LBB0_1734
	s_and_b64 vcc, exec, s[18:19]
	s_cbranch_vccz .LBB0_1737
	s_barrier

; #define PG8_STAGE(bufoff, gbase, voff) do { _Pragma("unroll") for (int _i = 0; _i < 2; ++_i) \
;         __builtin_amdgcn_global_load_lds((const unsigned*)((const char*)(gbase) + (voff)[_i]), (PG8_LAS unsigned*)(lds + (bufoff) + ldsw + _i * 8192), 16, 0, 0); } while (0)
; #define PG8_LDA(dst, b, h) do { _Pragma("unroll") for (int m = 0; m < 4; ++m) _Pragma("unroll") for (int k = 0; k < 2; ++k) dst[m][k] = *(const PG8_LAS bf16x8*)(lds + PG8_SA(b, h) + aoff + m * 2048 + k * 1024); } while (0)
; #define PG8_LDB(dst, b, h) do { _Pragma("unroll") for (int n = 0; n < 2; ++n) _Pragma("unroll") for (int k = 0; k < 2; ++k) dst[n][k] = *(const PG8_LAS bf16x8*)(lds + PG8_SB(b, h) + boff + n * 2048 + k * 1024); } while (0)
; #define PG8_MMA(ai, bj, At, Bt) do { __builtin_amdgcn_s_setprio(1); _Pragma("unroll") for (int m = 0; m < 4; ++m) _Pragma("unroll") for (int n = 0; n < 2; ++n) _Pragma("unroll") for (int k = 0; k < 2; ++k) \
;         acc[ai][bj][m][n] = __builtin_amdgcn_mfma_f32_16x16x32_bf16(Bt[n][k], At[m][k], acc[ai][bj][m][n], 0, 0, 0); __builtin_amdgcn_s_setprio(0); } while (0)
; #define PG8_WAIT_V(n) asm volatile("s_waitcnt vmcnt(" #n ")" ::: "memory")
; #define PG8_WAIT_L(n) asm volatile("s_waitcnt lgkmcnt(" #n ")" ::: "memory")
; #define PG8_BAR __builtin_amdgcn_s_barrier()
; #define PG8_SCHED __builtin_amdgcn_sched_barrier(0)
; template <class Epi, class Sched, bool ALIGN_EPI = false, bool SP2 = false>
; __device__ __forceinline__ void gemm_phase(PG8_LAS unsigned char* lds, const Gemm g, const Sched& S, const Epi& E, const int wave_in) {
;     ...
;             const char* a2 = last ? nA : cA + (size_t)(t + 2) * kstep; const char* b2 = last ? nB : cB + (size_t)(t + 2) * kstep;
;     ...
;             PG8_LDB(B0, 0, 0); PG8_LDB(B1, 0, 1); PG8_SCHED; PG8_LDA(At, 0, 0); PG8_STAGE(PG8_SA(1, 1), a1 + hstepA, voffA);
;             PG8_WAIT_V(8); PG8_WAIT_L(0); PG8_BAR; PG8_MMA(0, 0, At, B0); PG8_MMA(0, 1, At, B1); PG8_BAR; PG8_SCHED;
;             PG8_LDA(At, 0, 1); PG8_STAGE(PG8_SB(0, 0), b2, voffB); PG8_STAGE(PG8_SB(0, 1), b2 + hstep, voffB); PG8_STAGE(PG8_SA(0, 0), a2, voffA);
;             PG8_WAIT_V(8); PG8_WAIT_L(0); PG8_BAR; PG8_MMA(1, 0, At, B0); PG8_MMA(1, 1, At, B1); PG8_BAR; PG8_SCHED;
.LBB0_2082:
	ds_read_b128 v[144:147], v151
	ds_read_b128 v[156:159], v151 offset:1024
	ds_read_b128 v[160:163], v151 offset:2048
	ds_read_b128 v[164:167], v151 offset:3072
	ds_read_b128 v[168:171], v152
	ds_read_b128 v[172:175], v152 offset:1024
	ds_read_b128 v[176:179], v152 offset:2048
	ds_read_b128 v[180:183], v152 offset:3072
	s_add_u32 s40, s38, 0xfff80080
	s_addc_u32 s41, s39, -1
	s_cmp_eq_u32 s58, 28
	s_cselect_b32 s43, s19, s41
	s_cselect_b32 s42, s25, s40
	s_cselect_b32 s41, s17, s57
	s_cselect_b32 s40, s55, s56
	v_lshl_add_u64 v[216:217], s[38:39], 0, v[136:137]
	s_add_i32 m0, s33, 0xc000
	ds_read_b128 v[184:187], v153
	ds_read_b128 v[188:191], v153 offset:1024
	ds_read_b128 v[192:195], v153 offset:2048
	ds_read_b128 v[196:199], v153 offset:3072
	ds_read_b128 v[200:203], v153 offset:4096
	ds_read_b128 v[204:207], v153 offset:5120
	ds_read_b128 v[208:211], v153 offset:6144
	ds_read_b128 v[212:215], v153 offset:7168
	global_load_lds_dwordx4 v[216:217], off
	v_lshl_add_u64 v[216:217], s[38:39], 0, v[138:139]
	s_add_i32 m0, s33, 0xe000
	s_nop 0
	global_load_lds_dwordx4 v[216:217], off
	s_waitcnt vmcnt(8)
	s_waitcnt lgkmcnt(0)
	s_barrier
	s_setprio 1
	v_mfma_f32_16x16x32_bf16 v[124:127], v[144:147], v[184:187], v[124:127]
	v_mfma_f32_16x16x32_bf16 v[120:123], v[160:163], v[184:187], v[120:123]
	v_mfma_f32_16x16x32_bf16 v[108:111], v[144:147], v[192:195], v[108:111]
	v_mfma_f32_16x16x32_bf16 v[104:107], v[160:163], v[192:195], v[104:107]
	v_mfma_f32_16x16x32_bf16 v[92:95], v[144:147], v[200:203], v[92:95]
	v_mfma_f32_16x16x32_bf16 v[88:91], v[160:163], v[200:203], v[88:91]
	v_mfma_f32_16x16x32_bf16 v[76:79], v[144:147], v[208:211], v[76:79]
	v_mfma_f32_16x16x32_bf16 v[72:75], v[160:163], v[208:211], v[72:75]
	v_mfma_f32_16x16x32_bf16 v[124:127], v[156:159], v[188:191], v[124:127]
	v_mfma_f32_16x16x32_bf16 v[120:123], v[164:167], v[188:191], v[120:123]
	v_mfma_f32_16x16x32_bf16 v[108:111], v[156:159], v[196:199], v[108:111]
	v_mfma_f32_16x16x32_bf16 v[104:107], v[164:167], v[196:199], v[104:107]
	v_mfma_f32_16x16x32_bf16 v[92:95], v[156:159], v[204:207], v[92:95]
	v_mfma_f32_16x16x32_bf16 v[88:91], v[164:167], v[204:207], v[88:91]
	v_mfma_f32_16x16x32_bf16 v[76:79], v[156:159], v[212:215], v[76:79]
	v_mfma_f32_16x16x32_bf16 v[72:75], v[164:167], v[212:215], v[72:75]
	v_mfma_f32_16x16x32_bf16 v[116:119], v[168:171], v[184:187], v[116:119]
	v_mfma_f32_16x16x32_bf16 v[112:115], v[176:179], v[184:187], v[112:115]
	v_mfma_f32_16x16x32_bf16 v[100:103], v[168:171], v[192:195], v[100:103]
	v_mfma_f32_16x16x32_bf16 v[96:99], v[176:179], v[192:195], v[96:99]
	v_mfma_f32_16x16x32_bf16 v[84:87], v[168:171], v[200:203], v[84:87]
	v_mfma_f32_16x16x32_bf16 v[80:83], v[176:179], v[200:203], v[80:83]
	v_mfma_f32_16x16x32_bf16 v[68:71], v[168:171], v[208:211], v[68:71]
	v_mfma_f32_16x16x32_bf16 v[64:67], v[176:179], v[208:211], v[64:67]
	v_mfma_f32_16x16x32_bf16 v[116:119], v[172:175], v[188:191], v[116:119]
	v_mfma_f32_16x16x32_bf16 v[112:115], v[180:183], v[188:191], v[112:115]
	v_mfma_f32_16x16x32_bf16 v[100:103], v[172:175], v[196:199], v[100:103]
	v_mfma_f32_16x16x32_bf16 v[96:99], v[180:183], v[196:199], v[96:99]
	v_mfma_f32_16x16x32_bf16 v[84:87], v[172:175], v[204:207], v[84:87]
	v_mfma_f32_16x16x32_bf16 v[80:83], v[180:183], v[204:207], v[80:83]
	v_mfma_f32_16x16x32_bf16 v[68:71], v[172:175], v[212:215], v[68:71]
	v_mfma_f32_16x16x32_bf16 v[64:67], v[180:183], v[212:215], v[64:67]
	s_setprio 0
	s_barrier
	s_add_i32 s59, s53, s11
	v_lshl_add_u64 v[216:217], s[40:41], 0, v[130:131]
	s_mov_b32 m0, s59
	ds_read_b128 v[184:187], v153 offset:16384
	ds_read_b128 v[188:191], v153 offset:17408
	ds_read_b128 v[192:195], v153 offset:18432
	ds_read_b128 v[196:199], v153 offset:19456
	ds_read_b128 v[200:203], v153 offset:20480
	ds_read_b128 v[204:207], v153 offset:21504
	ds_read_b128 v[208:211], v153 offset:22528
	ds_read_b128 v[212:215], v153 offset:23552
	global_load_lds_dwordx4 v[216:217], off
	s_add_i32 m0, s59, 0x2000
	s_add_u32 s60, s40, 0x80000
	v_lshl_add_u64 v[218:219], s[40:41], 0, v[134:135]
	s_addc_u32 s61, s41, 0
	s_add_i32 s59, s54, s11
	global_load_lds_dwordx4 v[218:219], off
	v_lshl_add_u64 v[220:221], s[60:61], 0, v[130:131]
	s_mov_b32 m0, s59
	v_lshl_add_u64 v[222:223], s[42:43], 0, v[132:133]
	global_load_lds_dwordx4 v[220:221], off
	v_lshl_add_u64 v[220:221], s[60:61], 0, v[134:135]
	s_add_i32 m0, s59, 0x2000
	s_nop 0
	global_load_lds_dwordx4 v[220:221], off
	v_lshl_add_u64 v[220:221], s[42:43], 0, v[128:129]
	s_mov_b32 m0, s33
	s_nop 0
	global_load_lds_dwordx4 v[220:221], off
	s_mov_b32 m0, s35
	s_nop 0
	global_load_lds_dwordx4 v[222:223], off
	s_waitcnt vmcnt(8)
	s_waitcnt lgkmcnt(0)
	s_barrier
; #define PG8_STAGE(bufoff, gbase, voff) do { _Pragma("unroll") for (int _i = 0; _i < 2; ++_i) \
;         __builtin_amdgcn_global_load_lds((const unsigned*)((const char*)(gbase) + (voff)[_i]), (PG8_LAS unsigned*)(lds + (bufoff) + ldsw + _i * 8192), 16, 0, 0); } while (0)
; #define PG8_LDA(dst, b, h) do { _Pragma("unroll") for (int m = 0; m < 4; ++m) _Pragma("unroll") for (int k = 0; k < 2; ++k) dst[m][k] = *(const PG8_LAS bf16x8*)(lds + PG8_SA(b, h) + aoff + m * 2048 + k * 1024); } while (0)
; #define PG8_LDB(dst, b, h) do { _Pragma("unroll") for (int n = 0; n < 2; ++n) _Pragma("unroll") for (int k = 0; k < 2; ++k) dst[n][k] = *(const PG8_LAS bf16x8*)(lds + PG8_SB(b, h) + boff + n * 2048 + k * 1024); } while (0)
; #define PG8_MMA(ai, bj, At, Bt) do { __builtin_amdgcn_s_setprio(1); _Pragma("unroll") for (int m = 0; m < 4; ++m) _Pragma("unroll") for (int n = 0; n < 2; ++n) _Pragma("unroll") for (int k = 0; k < 2; ++k) \
;         acc[ai][bj][m][n] = __builtin_amdgcn_mfma_f32_16x16x32_bf16(Bt[n][k], At[m][k], acc[ai][bj][m][n], 0, 0, 0); __builtin_amdgcn_s_setprio(0); } while (0)
; #define PG8_WAIT_V(n) asm volatile("s_waitcnt vmcnt(" #n ")" ::: "memory")
; #define PG8_WAIT_L(n) asm volatile("s_waitcnt lgkmcnt(" #n ")" ::: "memory")
; #define PG8_BAR __builtin_amdgcn_s_barrier()
; #define PG8_SCHED __builtin_amdgcn_sched_barrier(0)
; template <class Epi, class Sched, bool ALIGN_EPI = false, bool SP2 = false>
; __device__ __forceinline__ void gemm_phase(PG8_LAS unsigned char* lds, const Gemm g, const Sched& S, const Epi& E, const int wave_in) {
;     ...
;             PG8_WAIT_V(8); PG8_WAIT_L(0); PG8_BAR; PG8_MMA(1, 0, At, B0); PG8_MMA(1, 1, At, B1); PG8_BAR; PG8_SCHED;
;             PG8_LDB(B0, 1, 0); PG8_LDB(B1, 1, 1); PG8_SCHED; PG8_LDA(At, 1, 0); PG8_STAGE(PG8_SA(0, 1), a2 + hstepA, voffA);
;             PG8_WAIT_V(8); PG8_WAIT_L(0); PG8_BAR; PG8_MMA(0, 0, At, B0); PG8_MMA(0, 1, At, B1); PG8_BAR; PG8_SCHED;
	s_setprio 1
	v_mfma_f32_16x16x32_bf16 v[60:63], v[144:147], v[184:187], v[60:63]
	v_mfma_f32_16x16x32_bf16 v[56:59], v[160:163], v[184:187], v[56:59]
	v_mfma_f32_16x16x32_bf16 v[44:47], v[144:147], v[192:195], v[44:47]
	v_mfma_f32_16x16x32_bf16 v[40:43], v[160:163], v[192:195], v[40:43]
	v_mfma_f32_16x16x32_bf16 v[28:31], v[144:147], v[200:203], v[28:31]
	v_mfma_f32_16x16x32_bf16 v[24:27], v[160:163], v[200:203], v[24:27]
	v_mfma_f32_16x16x32_bf16 v[12:15], v[144:147], v[208:211], v[12:15]
	v_mfma_f32_16x16x32_bf16 v[8:11], v[160:163], v[208:211], v[8:11]
	v_mfma_f32_16x16x32_bf16 v[60:63], v[156:159], v[188:191], v[60:63]
	v_mfma_f32_16x16x32_bf16 v[56:59], v[164:167], v[188:191], v[56:59]
	v_mfma_f32_16x16x32_bf16 v[44:47], v[156:159], v[196:199], v[44:47]
	v_mfma_f32_16x16x32_bf16 v[40:43], v[164:167], v[196:199], v[40:43]
	v_mfma_f32_16x16x32_bf16 v[28:31], v[156:159], v[204:207], v[28:31]
	v_mfma_f32_16x16x32_bf16 v[24:27], v[164:167], v[204:207], v[24:27]
	v_mfma_f32_16x16x32_bf16 v[12:15], v[156:159], v[212:215], v[12:15]
	v_mfma_f32_16x16x32_bf16 v[8:11], v[164:167], v[212:215], v[8:11]
	v_mfma_f32_16x16x32_bf16 v[52:55], v[168:171], v[184:187], v[52:55]
	v_mfma_f32_16x16x32_bf16 v[48:51], v[176:179], v[184:187], v[48:51]
	v_mfma_f32_16x16x32_bf16 v[36:39], v[168:171], v[192:195], v[36:39]
	v_mfma_f32_16x16x32_bf16 v[32:35], v[176:179], v[192:195], v[32:35]
	v_mfma_f32_16x16x32_bf16 v[20:23], v[168:171], v[200:203], v[20:23]
	v_mfma_f32_16x16x32_bf16 v[16:19], v[176:179], v[200:203], v[16:19]
	v_mfma_f32_16x16x32_bf16 v[4:7], v[168:171], v[208:211], v[4:7]
	v_mfma_f32_16x16x32_bf16 v[0:3], v[176:179], v[208:211], v[0:3]
	v_mfma_f32_16x16x32_bf16 v[52:55], v[172:175], v[188:191], v[52:55]
	v_mfma_f32_16x16x32_bf16 v[48:51], v[180:183], v[188:191], v[48:51]
	v_mfma_f32_16x16x32_bf16 v[36:39], v[172:175], v[196:199], v[36:39]
	v_mfma_f32_16x16x32_bf16 v[32:35], v[180:183], v[196:199], v[32:35]
	v_mfma_f32_16x16x32_bf16 v[20:23], v[172:175], v[204:207], v[20:23]
	v_mfma_f32_16x16x32_bf16 v[16:19], v[180:183], v[204:207], v[16:19]
	v_mfma_f32_16x16x32_bf16 v[4:7], v[172:175], v[212:215], v[4:7]
	v_mfma_f32_16x16x32_bf16 v[0:3], v[180:183], v[212:215], v[0:3]
	s_setprio 0
	s_barrier
	s_add_i32 s59, 0, 0x18000
	v_add_u32_e32 v155, s59, v149
	s_add_i32 s60, 0, 0x1c000
	ds_read_b128 v[144:147], v155
	ds_read_b128 v[156:159], v155 offset:1024
	ds_read_b128 v[160:163], v155 offset:2048
	ds_read_b128 v[164:167], v155 offset:3072
	v_add_u32_e32 v155, s60, v149
	ds_read_b128 v[168:171], v155
	ds_read_b128 v[172:175], v155 offset:1024
	ds_read_b128 v[176:179], v155 offset:2048
	ds_read_b128 v[180:183], v155 offset:3072
	s_add_u32 s42, s42, 0x80000
	s_addc_u32 s43, s43, 0
	s_mov_b32 m0, s37
	v_lshl_add_u64 v[224:225], s[42:43], 0, v[128:129]
	ds_read_b128 v[184:187], v153 offset:32768
	ds_read_b128 v[188:191], v153 offset:33792
	ds_read_b128 v[192:195], v153 offset:34816
	ds_read_b128 v[196:199], v153 offset:35840
	ds_read_b128 v[200:203], v153 offset:36864
	ds_read_b128 v[204:207], v153 offset:37888
	ds_read_b128 v[208:211], v153 offset:38912
	ds_read_b128 v[212:215], v153 offset:39936
	global_load_lds_dwordx4 v[224:225], off
	v_lshl_add_u64 v[224:225], s[42:43], 0, v[132:133]
	s_mov_b32 m0, s48
	s_nop 0
	global_load_lds_dwordx4 v[224:225], off
	s_waitcnt vmcnt(8)
	s_waitcnt lgkmcnt(0)
	s_barrier
	s_setprio 1
	v_mfma_f32_16x16x32_bf16 v[124:127], v[144:147], v[184:187], v[124:127]
	v_mfma_f32_16x16x32_bf16 v[120:123], v[160:163], v[184:187], v[120:123]
	v_mfma_f32_16x16x32_bf16 v[108:111], v[144:147], v[192:195], v[108:111]
	v_mfma_f32_16x16x32_bf16 v[104:107], v[160:163], v[192:195], v[104:107]
	v_mfma_f32_16x16x32_bf16 v[92:95], v[144:147], v[200:203], v[92:95]
	v_mfma_f32_16x16x32_bf16 v[88:91], v[160:163], v[200:203], v[88:91]
	v_mfma_f32_16x16x32_bf16 v[76:79], v[144:147], v[208:211], v[76:79]
	v_mfma_f32_16x16x32_bf16 v[72:75], v[160:163], v[208:211], v[72:75]
	v_mfma_f32_16x16x32_bf16 v[124:127], v[156:159], v[188:191], v[124:127]
	v_mfma_f32_16x16x32_bf16 v[120:123], v[164:167], v[188:191], v[120:123]
	v_mfma_f32_16x16x32_bf16 v[108:111], v[156:159], v[196:199], v[108:111]
	v_mfma_f32_16x16x32_bf16 v[104:107], v[164:167], v[196:199], v[104:107]
	v_mfma_f32_16x16x32_bf16 v[92:95], v[156:159], v[204:207], v[92:95]
	v_mfma_f32_16x16x32_bf16 v[88:91], v[164:167], v[204:207], v[88:91]
	v_mfma_f32_16x16x32_bf16 v[76:79], v[156:159], v[212:215], v[76:79]
	v_mfma_f32_16x16x32_bf16 v[72:75], v[164:167], v[212:215], v[72:75]
	v_mfma_f32_16x16x32_bf16 v[116:119], v[168:171], v[184:187], v[116:119]
	v_mfma_f32_16x16x32_bf16 v[112:115], v[176:179], v[184:187], v[112:115]
	v_mfma_f32_16x16x32_bf16 v[100:103], v[168:171], v[192:195], v[100:103]
	v_mfma_f32_16x16x32_bf16 v[96:99], v[176:179], v[192:195], v[96:99]
	v_mfma_f32_16x16x32_bf16 v[84:87], v[168:171], v[200:203], v[84:87]
	v_mfma_f32_16x16x32_bf16 v[80:83], v[176:179], v[200:203], v[80:83]
	v_mfma_f32_16x16x32_bf16 v[68:71], v[168:171], v[208:211], v[68:71]
	v_mfma_f32_16x16x32_bf16 v[64:67], v[176:179], v[208:211], v[64:67]
	v_mfma_f32_16x16x32_bf16 v[116:119], v[172:175], v[188:191], v[116:119]
	v_mfma_f32_16x16x32_bf16 v[112:115], v[180:183], v[188:191], v[112:115]
	v_mfma_f32_16x16x32_bf16 v[100:103], v[172:175], v[196:199], v[100:103]
	v_mfma_f32_16x16x32_bf16 v[96:99], v[180:183], v[196:199], v[96:99]
	v_mfma_f32_16x16x32_bf16 v[84:87], v[172:175], v[204:207], v[84:87]
	v_mfma_f32_16x16x32_bf16 v[80:83], v[180:183], v[204:207], v[80:83]
	v_mfma_f32_16x16x32_bf16 v[68:71], v[172:175], v[212:215], v[68:71]
	v_mfma_f32_16x16x32_bf16 v[64:67], v[180:183], v[212:215], v[64:67]
	s_setprio 0
	s_barrier
; #define PG8_STAGE(bufoff, gbase, voff) do { _Pragma("unroll") for (int _i = 0; _i < 2; ++_i) \
;         __builtin_amdgcn_global_load_lds((const unsigned*)((const char*)(gbase) + (voff)[_i]), (PG8_LAS unsigned*)(lds + (bufoff) + ldsw + _i * 8192), 16, 0, 0); } while (0)
; #define PG8_LDA(dst, b, h) do { _Pragma("unroll") for (int m = 0; m < 4; ++m) _Pragma("unroll") for (int k = 0; k < 2; ++k) dst[m][k] = *(const PG8_LAS bf16x8*)(lds + PG8_SA(b, h) + aoff + m * 2048 + k * 1024); } while (0)
; #define PG8_MMA(ai, bj, At, Bt) do { __builtin_amdgcn_s_setprio(1); _Pragma("unroll") for (int m = 0; m < 4; ++m) _Pragma("unroll") for (int n = 0; n < 2; ++n) _Pragma("unroll") for (int k = 0; k < 2; ++k) \
;         acc[ai][bj][m][n] = __builtin_amdgcn_mfma_f32_16x16x32_bf16(Bt[n][k], At[m][k], acc[ai][bj][m][n], 0, 0, 0); __builtin_amdgcn_s_setprio(0); } while (0)
; #define PG8_WAIT_V(n) asm volatile("s_waitcnt vmcnt(" #n ")" ::: "memory")
; #define PG8_WAIT_L(n) asm volatile("s_waitcnt lgkmcnt(" #n ")" ::: "memory")
; #define PG8_BAR __builtin_amdgcn_s_barrier()
; #define PG8_SCHED __builtin_amdgcn_sched_barrier(0)
; template <class Epi, class Sched, bool ALIGN_EPI = false, bool SP2 = false>
; __device__ __forceinline__ void gemm_phase(PG8_LAS unsigned char* lds, const Gemm g, const Sched& S, const Epi& E, const int wave_in) {
;     ...
;         for (int t = 0; t < nt; t += 2) {
;             const bool last = (t == nt - 2);
;             const char* a1 = cA + (size_t)(t + 1) * kstep;
;             const char* a2 = last ? nA : cA + (size_t)(t + 2) * kstep; const char* b2 = last ? nB : cB + (size_t)(t + 2) * kstep;
;             const char* a3 = a2 + kstep; const char* b3 = b2 + kstep;
;             if (last && has_next) S.a_ready(nxt);
;     ...
;             PG8_LDA(At, 1, 1); PG8_STAGE(PG8_SB(1, 0), b3, voffB); PG8_STAGE(PG8_SB(1, 1), b3 + hstep, voffB); PG8_STAGE(PG8_SA(1, 0), a3, voffA);
;             PG8_WAIT_V(8); PG8_WAIT_L(0); PG8_BAR; PG8_MMA(1, 0, At, B0); PG8_MMA(1, 1, At, B1); PG8_BAR; PG8_SCHED;
	s_add_i32 s42, s59, s11
	v_lshl_add_u64 v[216:217], v[216:217], 0, s[12:13]
	s_mov_b32 m0, s42
	ds_read_b128 v[184:187], v153 offset:49152
	ds_read_b128 v[188:191], v153 offset:50176
	ds_read_b128 v[192:195], v153 offset:51200
	ds_read_b128 v[196:199], v153 offset:52224
	ds_read_b128 v[200:203], v153 offset:53248
	ds_read_b128 v[204:207], v153 offset:54272
	ds_read_b128 v[208:211], v153 offset:55296
	ds_read_b128 v[212:215], v153 offset:56320
	global_load_lds_dwordx4 v[216:217], off
	s_add_i32 m0, s42, 0x2000
	s_add_u32 s40, s40, 0x80080
	v_lshl_add_u64 v[216:217], v[218:219], 0, s[12:13]
	s_addc_u32 s41, s41, 0
	s_add_i32 s42, s60, s11
	global_load_lds_dwordx4 v[216:217], off
	v_lshl_add_u64 v[216:217], s[40:41], 0, v[130:131]
	s_mov_b32 m0, s42
	s_nop 0
	global_load_lds_dwordx4 v[216:217], off
	v_lshl_add_u64 v[216:217], s[40:41], 0, v[134:135]
	s_add_i32 m0, s42, 0x2000
	s_nop 0
	global_load_lds_dwordx4 v[216:217], off
	v_lshl_add_u64 v[216:217], v[220:221], 0, s[12:13]
	s_mov_b32 m0, s50
	s_nop 0
	global_load_lds_dwordx4 v[216:217], off
	v_lshl_add_u64 v[216:217], v[222:223], 0, s[12:13]
	s_mov_b32 m0, s51
	s_nop 0
	global_load_lds_dwordx4 v[216:217], off
	s_waitcnt vmcnt(8)
	s_waitcnt lgkmcnt(0)
	s_barrier
	s_setprio 1
	v_mfma_f32_16x16x32_bf16 v[60:63], v[144:147], v[184:187], v[60:63]
	v_mfma_f32_16x16x32_bf16 v[56:59], v[160:163], v[184:187], v[56:59]
	v_mfma_f32_16x16x32_bf16 v[44:47], v[144:147], v[192:195], v[44:47]
	v_mfma_f32_16x16x32_bf16 v[40:43], v[160:163], v[192:195], v[40:43]
	v_mfma_f32_16x16x32_bf16 v[28:31], v[144:147], v[200:203], v[28:31]
	v_mfma_f32_16x16x32_bf16 v[24:27], v[160:163], v[200:203], v[24:27]
	v_mfma_f32_16x16x32_bf16 v[12:15], v[144:147], v[208:211], v[12:15]
	v_mfma_f32_16x16x32_bf16 v[8:11], v[160:163], v[208:211], v[8:11]
	v_mfma_f32_16x16x32_bf16 v[60:63], v[156:159], v[188:191], v[60:63]
	v_mfma_f32_16x16x32_bf16 v[56:59], v[164:167], v[188:191], v[56:59]
	v_mfma_f32_16x16x32_bf16 v[44:47], v[156:159], v[196:199], v[44:47]
	v_mfma_f32_16x16x32_bf16 v[40:43], v[164:167], v[196:199], v[40:43]
	v_mfma_f32_16x16x32_bf16 v[28:31], v[156:159], v[204:207], v[28:31]
	v_mfma_f32_16x16x32_bf16 v[24:27], v[164:167], v[204:207], v[24:27]
	v_mfma_f32_16x16x32_bf16 v[12:15], v[156:159], v[212:215], v[12:15]
	v_mfma_f32_16x16x32_bf16 v[8:11], v[164:167], v[212:215], v[8:11]
	v_mfma_f32_16x16x32_bf16 v[52:55], v[168:171], v[184:187], v[52:55]
	v_mfma_f32_16x16x32_bf16 v[48:51], v[176:179], v[184:187], v[48:51]
	v_mfma_f32_16x16x32_bf16 v[36:39], v[168:171], v[192:195], v[36:39]
	v_mfma_f32_16x16x32_bf16 v[32:35], v[176:179], v[192:195], v[32:35]
	v_mfma_f32_16x16x32_bf16 v[20:23], v[168:171], v[200:203], v[20:23]
	v_mfma_f32_16x16x32_bf16 v[16:19], v[176:179], v[200:203], v[16:19]
	v_mfma_f32_16x16x32_bf16 v[4:7], v[168:171], v[208:211], v[4:7]
	v_mfma_f32_16x16x32_bf16 v[0:3], v[176:179], v[208:211], v[0:3]
	v_mfma_f32_16x16x32_bf16 v[52:55], v[172:175], v[188:191], v[52:55]
	v_mfma_f32_16x16x32_bf16 v[48:51], v[180:183], v[188:191], v[48:51]
	v_mfma_f32_16x16x32_bf16 v[36:39], v[172:175], v[196:199], v[36:39]
	v_mfma_f32_16x16x32_bf16 v[32:35], v[180:183], v[196:199], v[32:35]
	v_mfma_f32_16x16x32_bf16 v[20:23], v[172:175], v[204:207], v[20:23]
	v_mfma_f32_16x16x32_bf16 v[16:19], v[180:183], v[204:207], v[16:19]
	v_mfma_f32_16x16x32_bf16 v[4:7], v[172:175], v[212:215], v[4:7]
	v_mfma_f32_16x16x32_bf16 v[0:3], v[180:183], v[212:215], v[0:3]
	s_setprio 0
	s_barrier
	s_add_i32 s58, s58, 2
	s_add_u32 s38, s38, 0x100
	s_addc_u32 s39, s39, 0
	s_add_u32 s56, s56, 0x100
	s_addc_u32 s57, s57, 0
	s_cmp_gt_u32 s58, 29
	s_cbranch_scc0 .LBB0_2082
	s_and_b64 vcc, exec, s[14:15]
	s_cbranch_vccz .LBB0_2085
	s_barrier

; #define PG8_STAGE(bufoff, gbase, voff) do { _Pragma("unroll") for (int _i = 0; _i < 2; ++_i) \
;         __builtin_amdgcn_global_load_lds((const unsigned*)((const char*)(gbase) + (voff)[_i]), (PG8_LAS unsigned*)(lds + (bufoff) + ldsw + _i * 8192), 16, 0, 0); } while (0)
; #define PG8_LDA(dst, b, h) do { _Pragma("unroll") for (int m = 0; m < 4; ++m) _Pragma("unroll") for (int k = 0; k < 2; ++k) dst[m][k] = *(const PG8_LAS bf16x8*)(lds + PG8_SA(b, h) + aoff + m * 2048 + k * 1024); } while (0)
; #define PG8_LDB(dst, b, h) do { _Pragma("unroll") for (int n = 0; n < 2; ++n) _Pragma("unroll") for (int k = 0; k < 2; ++k) dst[n][k] = *(const PG8_LAS bf16x8*)(lds + PG8_SB(b, h) + boff + n * 2048 + k * 1024); } while (0)
; #define PG8_MMA(ai, bj, At, Bt) do { __builtin_amdgcn_s_setprio(1); _Pragma("unroll") for (int m = 0; m < 4; ++m) _Pragma("unroll") for (int n = 0; n < 2; ++n) _Pragma("unroll") for (int k = 0; k < 2; ++k) \
;         acc[ai][bj][m][n] = __builtin_amdgcn_mfma_f32_16x16x32_bf16(Bt[n][k], At[m][k], acc[ai][bj][m][n], 0, 0, 0); __builtin_amdgcn_s_setprio(0); } while (0)
; #define PG8_WAIT_V(n) asm volatile("s_waitcnt vmcnt(" #n ")" ::: "memory")
; #define PG8_WAIT_L(n) asm volatile("s_waitcnt lgkmcnt(" #n ")" ::: "memory")
; #define PG8_BAR __builtin_amdgcn_s_barrier()
; #define PG8_SCHED __builtin_amdgcn_sched_barrier(0)
; template <class Epi, class Sched, bool ALIGN_EPI = false, bool SP2 = false>
; __device__ __forceinline__ void gemm_phase(PG8_LAS unsigned char* lds, const Gemm g, const Sched& S, const Epi& E, const int wave_in) {
;     ...
;             const char* a2 = last ? nA : cA + (size_t)(t + 2) * kstep; const char* b2 = last ? nB : cB + (size_t)(t + 2) * kstep;
;     ...
;             PG8_LDB(B0, 0, 0); PG8_LDB(B1, 0, 1); PG8_SCHED; PG8_LDA(At, 0, 0); PG8_STAGE(PG8_SA(1, 1), a1 + hstepA, voffA);
;             PG8_WAIT_V(8); PG8_WAIT_L(0); PG8_BAR; PG8_MMA(0, 0, At, B0); PG8_MMA(0, 1, At, B1); PG8_BAR; PG8_SCHED;
;             PG8_LDA(At, 0, 1); PG8_STAGE(PG8_SB(0, 0), b2, voffB); PG8_STAGE(PG8_SB(0, 1), b2 + hstep, voffB); PG8_STAGE(PG8_SA(0, 0), a2, voffA);
;             PG8_WAIT_V(8); PG8_WAIT_L(0); PG8_BAR; PG8_MMA(1, 0, At, B0); PG8_MMA(1, 1, At, B1); PG8_BAR; PG8_SCHED;
.LBB0_2169:
	ds_read_b128 v[144:147], v151
	ds_read_b128 v[156:159], v151 offset:1024
	ds_read_b128 v[160:163], v151 offset:2048
	ds_read_b128 v[164:167], v151 offset:3072
	ds_read_b128 v[168:171], v152
	ds_read_b128 v[172:175], v152 offset:1024
	ds_read_b128 v[176:179], v152 offset:2048
	ds_read_b128 v[180:183], v152 offset:3072
	s_add_u32 s36, s24, 0xfff80080
	s_addc_u32 s37, s25, -1
	s_cmp_eq_u32 s58, 28
	s_cselect_b32 s39, s17, s37
	s_cselect_b32 s38, s54, s36
	s_cselect_b32 s37, s15, s57
	s_cselect_b32 s36, s55, s56
	v_lshl_add_u64 v[216:217], s[24:25], 0, v[136:137]
	s_add_i32 m0, s23, 0xc000
	ds_read_b128 v[184:187], v153
	ds_read_b128 v[188:191], v153 offset:1024
	ds_read_b128 v[192:195], v153 offset:2048
	ds_read_b128 v[196:199], v153 offset:3072
	ds_read_b128 v[200:203], v153 offset:4096
	ds_read_b128 v[204:207], v153 offset:5120
	ds_read_b128 v[208:211], v153 offset:6144
	ds_read_b128 v[212:215], v153 offset:7168
	global_load_lds_dwordx4 v[216:217], off
	v_lshl_add_u64 v[216:217], s[24:25], 0, v[138:139]
	s_add_i32 m0, s23, 0xe000
	s_nop 0
	global_load_lds_dwordx4 v[216:217], off
	s_waitcnt vmcnt(8)
	s_waitcnt lgkmcnt(0)
	s_barrier
	s_setprio 1
	v_mfma_f32_16x16x32_bf16 v[116:119], v[144:147], v[184:187], v[116:119]
	v_mfma_f32_16x16x32_bf16 v[112:115], v[160:163], v[184:187], v[112:115]
	v_mfma_f32_16x16x32_bf16 v[100:103], v[144:147], v[192:195], v[100:103]
	v_mfma_f32_16x16x32_bf16 v[96:99], v[160:163], v[192:195], v[96:99]
	v_mfma_f32_16x16x32_bf16 v[84:87], v[144:147], v[200:203], v[84:87]
	v_mfma_f32_16x16x32_bf16 v[80:83], v[160:163], v[200:203], v[80:83]
	v_mfma_f32_16x16x32_bf16 v[68:71], v[144:147], v[208:211], v[68:71]
	v_mfma_f32_16x16x32_bf16 v[64:67], v[160:163], v[208:211], v[64:67]
	v_mfma_f32_16x16x32_bf16 v[116:119], v[156:159], v[188:191], v[116:119]
	v_mfma_f32_16x16x32_bf16 v[112:115], v[164:167], v[188:191], v[112:115]
	v_mfma_f32_16x16x32_bf16 v[100:103], v[156:159], v[196:199], v[100:103]
	v_mfma_f32_16x16x32_bf16 v[96:99], v[164:167], v[196:199], v[96:99]
	v_mfma_f32_16x16x32_bf16 v[84:87], v[156:159], v[204:207], v[84:87]
	v_mfma_f32_16x16x32_bf16 v[80:83], v[164:167], v[204:207], v[80:83]
	v_mfma_f32_16x16x32_bf16 v[68:71], v[156:159], v[212:215], v[68:71]
	v_mfma_f32_16x16x32_bf16 v[64:67], v[164:167], v[212:215], v[64:67]
	v_mfma_f32_16x16x32_bf16 v[124:127], v[168:171], v[184:187], v[124:127]
	v_mfma_f32_16x16x32_bf16 v[120:123], v[176:179], v[184:187], v[120:123]
	v_mfma_f32_16x16x32_bf16 v[108:111], v[168:171], v[192:195], v[108:111]
	v_mfma_f32_16x16x32_bf16 v[104:107], v[176:179], v[192:195], v[104:107]
	v_mfma_f32_16x16x32_bf16 v[92:95], v[168:171], v[200:203], v[92:95]
	v_mfma_f32_16x16x32_bf16 v[88:91], v[176:179], v[200:203], v[88:91]
	v_mfma_f32_16x16x32_bf16 v[76:79], v[168:171], v[208:211], v[76:79]
	v_mfma_f32_16x16x32_bf16 v[72:75], v[176:179], v[208:211], v[72:75]
	v_mfma_f32_16x16x32_bf16 v[124:127], v[172:175], v[188:191], v[124:127]
	v_mfma_f32_16x16x32_bf16 v[120:123], v[180:183], v[188:191], v[120:123]
	v_mfma_f32_16x16x32_bf16 v[108:111], v[172:175], v[196:199], v[108:111]
	v_mfma_f32_16x16x32_bf16 v[104:107], v[180:183], v[196:199], v[104:107]
	v_mfma_f32_16x16x32_bf16 v[92:95], v[172:175], v[204:207], v[92:95]
	v_mfma_f32_16x16x32_bf16 v[88:91], v[180:183], v[204:207], v[88:91]
	v_mfma_f32_16x16x32_bf16 v[76:79], v[172:175], v[212:215], v[76:79]
	v_mfma_f32_16x16x32_bf16 v[72:75], v[180:183], v[212:215], v[72:75]
	s_setprio 0
	s_barrier
	s_add_i32 s59, s50, s11
	v_lshl_add_u64 v[216:217], s[36:37], 0, v[132:133]
	s_mov_b32 m0, s59
	ds_read_b128 v[184:187], v153 offset:16384
	ds_read_b128 v[188:191], v153 offset:17408
	ds_read_b128 v[192:195], v153 offset:18432
	ds_read_b128 v[196:199], v153 offset:19456
	ds_read_b128 v[200:203], v153 offset:20480
	ds_read_b128 v[204:207], v153 offset:21504
	ds_read_b128 v[208:211], v153 offset:22528
	ds_read_b128 v[212:215], v153 offset:23552
	global_load_lds_dwordx4 v[216:217], off
	s_add_i32 m0, s59, 0x2000
	s_add_u32 s60, s36, 0x80000
	v_lshl_add_u64 v[218:219], s[36:37], 0, v[128:129]
	s_addc_u32 s61, s37, 0
	s_add_i32 s59, s51, s11
	global_load_lds_dwordx4 v[218:219], off
	v_lshl_add_u64 v[220:221], s[60:61], 0, v[132:133]
	s_mov_b32 m0, s59
	v_lshl_add_u64 v[222:223], s[38:39], 0, v[130:131]
	global_load_lds_dwordx4 v[220:221], off
	v_lshl_add_u64 v[220:221], s[60:61], 0, v[128:129]
	s_add_i32 m0, s59, 0x2000
	s_nop 0
	global_load_lds_dwordx4 v[220:221], off
	v_lshl_add_u64 v[220:221], s[38:39], 0, v[134:135]
	s_mov_b32 m0, s23
	s_nop 0
	global_load_lds_dwordx4 v[220:221], off
	s_mov_b32 m0, s40
	s_nop 0
	global_load_lds_dwordx4 v[222:223], off
	s_waitcnt vmcnt(8)
	s_waitcnt lgkmcnt(0)
	s_barrier
; #define PG8_STAGE(bufoff, gbase, voff) do { _Pragma("unroll") for (int _i = 0; _i < 2; ++_i) \
;         __builtin_amdgcn_global_load_lds((const unsigned*)((const char*)(gbase) + (voff)[_i]), (PG8_LAS unsigned*)(lds + (bufoff) + ldsw + _i * 8192), 16, 0, 0); } while (0)
; #define PG8_LDA(dst, b, h) do { _Pragma("unroll") for (int m = 0; m < 4; ++m) _Pragma("unroll") for (int k = 0; k < 2; ++k) dst[m][k] = *(const PG8_LAS bf16x8*)(lds + PG8_SA(b, h) + aoff + m * 2048 + k * 1024); } while (0)
; #define PG8_LDB(dst, b, h) do { _Pragma("unroll") for (int n = 0; n < 2; ++n) _Pragma("unroll") for (int k = 0; k < 2; ++k) dst[n][k] = *(const PG8_LAS bf16x8*)(lds + PG8_SB(b, h) + boff + n * 2048 + k * 1024); } while (0)
; #define PG8_MMA(ai, bj, At, Bt) do { __builtin_amdgcn_s_setprio(1); _Pragma("unroll") for (int m = 0; m < 4; ++m) _Pragma("unroll") for (int n = 0; n < 2; ++n) _Pragma("unroll") for (int k = 0; k < 2; ++k) \
;         acc[ai][bj][m][n] = __builtin_amdgcn_mfma_f32_16x16x32_bf16(Bt[n][k], At[m][k], acc[ai][bj][m][n], 0, 0, 0); __builtin_amdgcn_s_setprio(0); } while (0)
; #define PG8_WAIT_V(n) asm volatile("s_waitcnt vmcnt(" #n ")" ::: "memory")
; #define PG8_WAIT_L(n) asm volatile("s_waitcnt lgkmcnt(" #n ")" ::: "memory")
; #define PG8_BAR __builtin_amdgcn_s_barrier()
; #define PG8_SCHED __builtin_amdgcn_sched_barrier(0)
; template <class Epi, class Sched, bool ALIGN_EPI = false, bool SP2 = false>
; __device__ __forceinline__ void gemm_phase(PG8_LAS unsigned char* lds, const Gemm g, const Sched& S, const Epi& E, const int wave_in) {
;     ...
;             PG8_WAIT_V(8); PG8_WAIT_L(0); PG8_BAR; PG8_MMA(1, 0, At, B0); PG8_MMA(1, 1, At, B1); PG8_BAR; PG8_SCHED;
;             PG8_LDB(B0, 1, 0); PG8_LDB(B1, 1, 1); PG8_SCHED; PG8_LDA(At, 1, 0); PG8_STAGE(PG8_SA(0, 1), a2 + hstepA, voffA);
;             PG8_WAIT_V(8); PG8_WAIT_L(0); PG8_BAR; PG8_MMA(0, 0, At, B0); PG8_MMA(0, 1, At, B1); PG8_BAR; PG8_SCHED;
	s_setprio 1
	v_mfma_f32_16x16x32_bf16 v[52:55], v[144:147], v[184:187], v[52:55]
	v_mfma_f32_16x16x32_bf16 v[48:51], v[160:163], v[184:187], v[48:51]
	v_mfma_f32_16x16x32_bf16 v[36:39], v[144:147], v[192:195], v[36:39]
	v_mfma_f32_16x16x32_bf16 v[32:35], v[160:163], v[192:195], v[32:35]
	v_mfma_f32_16x16x32_bf16 v[20:23], v[144:147], v[200:203], v[20:23]
	v_mfma_f32_16x16x32_bf16 v[16:19], v[160:163], v[200:203], v[16:19]
	v_mfma_f32_16x16x32_bf16 v[4:7], v[144:147], v[208:211], v[4:7]
	v_mfma_f32_16x16x32_bf16 v[0:3], v[160:163], v[208:211], v[0:3]
	v_mfma_f32_16x16x32_bf16 v[52:55], v[156:159], v[188:191], v[52:55]
	v_mfma_f32_16x16x32_bf16 v[48:51], v[164:167], v[188:191], v[48:51]
	v_mfma_f32_16x16x32_bf16 v[36:39], v[156:159], v[196:199], v[36:39]
	v_mfma_f32_16x16x32_bf16 v[32:35], v[164:167], v[196:199], v[32:35]
	v_mfma_f32_16x16x32_bf16 v[20:23], v[156:159], v[204:207], v[20:23]
	v_mfma_f32_16x16x32_bf16 v[16:19], v[164:167], v[204:207], v[16:19]
	v_mfma_f32_16x16x32_bf16 v[4:7], v[156:159], v[212:215], v[4:7]
	v_mfma_f32_16x16x32_bf16 v[0:3], v[164:167], v[212:215], v[0:3]
	v_mfma_f32_16x16x32_bf16 v[60:63], v[168:171], v[184:187], v[60:63]
	v_mfma_f32_16x16x32_bf16 v[56:59], v[176:179], v[184:187], v[56:59]
	v_mfma_f32_16x16x32_bf16 v[44:47], v[168:171], v[192:195], v[44:47]
	v_mfma_f32_16x16x32_bf16 v[40:43], v[176:179], v[192:195], v[40:43]
	v_mfma_f32_16x16x32_bf16 v[28:31], v[168:171], v[200:203], v[28:31]
	v_mfma_f32_16x16x32_bf16 v[24:27], v[176:179], v[200:203], v[24:27]
	v_mfma_f32_16x16x32_bf16 v[12:15], v[168:171], v[208:211], v[12:15]
	v_mfma_f32_16x16x32_bf16 v[8:11], v[176:179], v[208:211], v[8:11]
	v_mfma_f32_16x16x32_bf16 v[60:63], v[172:175], v[188:191], v[60:63]
	v_mfma_f32_16x16x32_bf16 v[56:59], v[180:183], v[188:191], v[56:59]
	v_mfma_f32_16x16x32_bf16 v[44:47], v[172:175], v[196:199], v[44:47]
	v_mfma_f32_16x16x32_bf16 v[40:43], v[180:183], v[196:199], v[40:43]
	v_mfma_f32_16x16x32_bf16 v[28:31], v[172:175], v[204:207], v[28:31]
	v_mfma_f32_16x16x32_bf16 v[24:27], v[180:183], v[204:207], v[24:27]
	v_mfma_f32_16x16x32_bf16 v[12:15], v[172:175], v[212:215], v[12:15]
	v_mfma_f32_16x16x32_bf16 v[8:11], v[180:183], v[212:215], v[8:11]
	s_setprio 0
	s_barrier
	s_add_i32 s59, 0, 0x18000
	v_add_u32_e32 v155, s59, v149
	s_add_i32 s60, 0, 0x1c000
	ds_read_b128 v[144:147], v155
	ds_read_b128 v[156:159], v155 offset:1024
	ds_read_b128 v[160:163], v155 offset:2048
	ds_read_b128 v[164:167], v155 offset:3072
	v_add_u32_e32 v155, s60, v149
	ds_read_b128 v[168:171], v155
	ds_read_b128 v[172:175], v155 offset:1024
	ds_read_b128 v[176:179], v155 offset:2048
	ds_read_b128 v[180:183], v155 offset:3072
	s_add_u32 s38, s38, 0x80000
	s_addc_u32 s39, s39, 0
	s_mov_b32 m0, s41
	v_lshl_add_u64 v[224:225], s[38:39], 0, v[134:135]
	ds_read_b128 v[184:187], v153 offset:32768
	ds_read_b128 v[188:191], v153 offset:33792
	ds_read_b128 v[192:195], v153 offset:34816
	ds_read_b128 v[196:199], v153 offset:35840
	ds_read_b128 v[200:203], v153 offset:36864
	ds_read_b128 v[204:207], v153 offset:37888
	ds_read_b128 v[208:211], v153 offset:38912
	ds_read_b128 v[212:215], v153 offset:39936
	global_load_lds_dwordx4 v[224:225], off
	v_lshl_add_u64 v[224:225], s[38:39], 0, v[130:131]
	s_mov_b32 m0, s42
	s_nop 0
	global_load_lds_dwordx4 v[224:225], off
	s_waitcnt vmcnt(8)
	s_waitcnt lgkmcnt(0)
	s_barrier
	s_setprio 1
	v_mfma_f32_16x16x32_bf16 v[116:119], v[144:147], v[184:187], v[116:119]
	v_mfma_f32_16x16x32_bf16 v[112:115], v[160:163], v[184:187], v[112:115]
	v_mfma_f32_16x16x32_bf16 v[100:103], v[144:147], v[192:195], v[100:103]
	v_mfma_f32_16x16x32_bf16 v[96:99], v[160:163], v[192:195], v[96:99]
	v_mfma_f32_16x16x32_bf16 v[84:87], v[144:147], v[200:203], v[84:87]
	v_mfma_f32_16x16x32_bf16 v[80:83], v[160:163], v[200:203], v[80:83]
	v_mfma_f32_16x16x32_bf16 v[68:71], v[144:147], v[208:211], v[68:71]
	v_mfma_f32_16x16x32_bf16 v[64:67], v[160:163], v[208:211], v[64:67]
	v_mfma_f32_16x16x32_bf16 v[116:119], v[156:159], v[188:191], v[116:119]
	v_mfma_f32_16x16x32_bf16 v[112:115], v[164:167], v[188:191], v[112:115]
	v_mfma_f32_16x16x32_bf16 v[100:103], v[156:159], v[196:199], v[100:103]
	v_mfma_f32_16x16x32_bf16 v[96:99], v[164:167], v[196:199], v[96:99]
	v_mfma_f32_16x16x32_bf16 v[84:87], v[156:159], v[204:207], v[84:87]
	v_mfma_f32_16x16x32_bf16 v[80:83], v[164:167], v[204:207], v[80:83]
	v_mfma_f32_16x16x32_bf16 v[68:71], v[156:159], v[212:215], v[68:71]
	v_mfma_f32_16x16x32_bf16 v[64:67], v[164:167], v[212:215], v[64:67]
	v_mfma_f32_16x16x32_bf16 v[124:127], v[168:171], v[184:187], v[124:127]
	v_mfma_f32_16x16x32_bf16 v[120:123], v[176:179], v[184:187], v[120:123]
	v_mfma_f32_16x16x32_bf16 v[108:111], v[168:171], v[192:195], v[108:111]
	v_mfma_f32_16x16x32_bf16 v[104:107], v[176:179], v[192:195], v[104:107]
	v_mfma_f32_16x16x32_bf16 v[92:95], v[168:171], v[200:203], v[92:95]
	v_mfma_f32_16x16x32_bf16 v[88:91], v[176:179], v[200:203], v[88:91]
	v_mfma_f32_16x16x32_bf16 v[76:79], v[168:171], v[208:211], v[76:79]
	v_mfma_f32_16x16x32_bf16 v[72:75], v[176:179], v[208:211], v[72:75]
	v_mfma_f32_16x16x32_bf16 v[124:127], v[172:175], v[188:191], v[124:127]
	v_mfma_f32_16x16x32_bf16 v[120:123], v[180:183], v[188:191], v[120:123]
	v_mfma_f32_16x16x32_bf16 v[108:111], v[172:175], v[196:199], v[108:111]
	v_mfma_f32_16x16x32_bf16 v[104:107], v[180:183], v[196:199], v[104:107]
	v_mfma_f32_16x16x32_bf16 v[92:95], v[172:175], v[204:207], v[92:95]
	v_mfma_f32_16x16x32_bf16 v[88:91], v[180:183], v[204:207], v[88:91]
	v_mfma_f32_16x16x32_bf16 v[76:79], v[172:175], v[212:215], v[76:79]
	v_mfma_f32_16x16x32_bf16 v[72:75], v[180:183], v[212:215], v[72:75]
	s_setprio 0
	s_barrier
; #define PG8_STAGE(bufoff, gbase, voff) do { _Pragma("unroll") for (int _i = 0; _i < 2; ++_i) \
;         __builtin_amdgcn_global_load_lds((const unsigned*)((const char*)(gbase) + (voff)[_i]), (PG8_LAS unsigned*)(lds + (bufoff) + ldsw + _i * 8192), 16, 0, 0); } while (0)
; #define PG8_LDA(dst, b, h) do { _Pragma("unroll") for (int m = 0; m < 4; ++m) _Pragma("unroll") for (int k = 0; k < 2; ++k) dst[m][k] = *(const PG8_LAS bf16x8*)(lds + PG8_SA(b, h) + aoff + m * 2048 + k * 1024); } while (0)
; #define PG8_MMA(ai, bj, At, Bt) do { __builtin_amdgcn_s_setprio(1); _Pragma("unroll") for (int m = 0; m < 4; ++m) _Pragma("unroll") for (int n = 0; n < 2; ++n) _Pragma("unroll") for (int k = 0; k < 2; ++k) \
;         acc[ai][bj][m][n] = __builtin_amdgcn_mfma_f32_16x16x32_bf16(Bt[n][k], At[m][k], acc[ai][bj][m][n], 0, 0, 0); __builtin_amdgcn_s_setprio(0); } while (0)
; #define PG8_WAIT_V(n) asm volatile("s_waitcnt vmcnt(" #n ")" ::: "memory")
; #define PG8_WAIT_L(n) asm volatile("s_waitcnt lgkmcnt(" #n ")" ::: "memory")
; #define PG8_BAR __builtin_amdgcn_s_barrier()
; #define PG8_SCHED __builtin_amdgcn_sched_barrier(0)
; template <class Epi, class Sched, bool ALIGN_EPI = false, bool SP2 = false>
; __device__ __forceinline__ void gemm_phase(PG8_LAS unsigned char* lds, const Gemm g, const Sched& S, const Epi& E, const int wave_in) {
;     ...
;         for (int t = 0; t < nt; t += 2) {
;             const bool last = (t == nt - 2);
;             const char* a1 = cA + (size_t)(t + 1) * kstep;
;             const char* a2 = last ? nA : cA + (size_t)(t + 2) * kstep; const char* b2 = last ? nB : cB + (size_t)(t + 2) * kstep;
;             const char* a3 = a2 + kstep; const char* b3 = b2 + kstep;
;             if (last && has_next) S.a_ready(nxt);
;     ...
;             PG8_LDA(At, 1, 1); PG8_STAGE(PG8_SB(1, 0), b3, voffB); PG8_STAGE(PG8_SB(1, 1), b3 + hstep, voffB); PG8_STAGE(PG8_SA(1, 0), a3, voffA);
;             PG8_WAIT_V(8); PG8_WAIT_L(0); PG8_BAR; PG8_MMA(1, 0, At, B0); PG8_MMA(1, 1, At, B1); PG8_BAR; PG8_SCHED;
	s_add_i32 s38, s59, s11
	v_lshl_add_u64 v[216:217], v[216:217], 0, s[6:7]
	s_mov_b32 m0, s38
	ds_read_b128 v[184:187], v153 offset:49152
	ds_read_b128 v[188:191], v153 offset:50176
	ds_read_b128 v[192:195], v153 offset:51200
	ds_read_b128 v[196:199], v153 offset:52224
	ds_read_b128 v[200:203], v153 offset:53248
	ds_read_b128 v[204:207], v153 offset:54272
	ds_read_b128 v[208:211], v153 offset:55296
	ds_read_b128 v[212:215], v153 offset:56320
	global_load_lds_dwordx4 v[216:217], off
	s_add_i32 m0, s38, 0x2000
	s_add_u32 s36, s36, 0x80080
	v_lshl_add_u64 v[216:217], v[218:219], 0, s[6:7]
	s_addc_u32 s37, s37, 0
	s_add_i32 s38, s60, s11
	global_load_lds_dwordx4 v[216:217], off
	v_lshl_add_u64 v[216:217], s[36:37], 0, v[132:133]
	s_mov_b32 m0, s38
	s_nop 0
	global_load_lds_dwordx4 v[216:217], off
	v_lshl_add_u64 v[216:217], s[36:37], 0, v[128:129]
	s_add_i32 m0, s38, 0x2000
	s_nop 0
	global_load_lds_dwordx4 v[216:217], off
	v_lshl_add_u64 v[216:217], v[220:221], 0, s[6:7]
	s_mov_b32 m0, s48
	s_nop 0
	global_load_lds_dwordx4 v[216:217], off
	v_lshl_add_u64 v[216:217], v[222:223], 0, s[6:7]
	s_mov_b32 m0, s49
	s_nop 0
	global_load_lds_dwordx4 v[216:217], off
	s_waitcnt vmcnt(8)
	s_waitcnt lgkmcnt(0)
	s_barrier
	s_setprio 1
	v_mfma_f32_16x16x32_bf16 v[52:55], v[144:147], v[184:187], v[52:55]
	v_mfma_f32_16x16x32_bf16 v[48:51], v[160:163], v[184:187], v[48:51]
	v_mfma_f32_16x16x32_bf16 v[36:39], v[144:147], v[192:195], v[36:39]
	v_mfma_f32_16x16x32_bf16 v[32:35], v[160:163], v[192:195], v[32:35]
	v_mfma_f32_16x16x32_bf16 v[20:23], v[144:147], v[200:203], v[20:23]
	v_mfma_f32_16x16x32_bf16 v[16:19], v[160:163], v[200:203], v[16:19]
	v_mfma_f32_16x16x32_bf16 v[4:7], v[144:147], v[208:211], v[4:7]
	v_mfma_f32_16x16x32_bf16 v[0:3], v[160:163], v[208:211], v[0:3]
	v_mfma_f32_16x16x32_bf16 v[52:55], v[156:159], v[188:191], v[52:55]
	v_mfma_f32_16x16x32_bf16 v[48:51], v[164:167], v[188:191], v[48:51]
	v_mfma_f32_16x16x32_bf16 v[36:39], v[156:159], v[196:199], v[36:39]
	v_mfma_f32_16x16x32_bf16 v[32:35], v[164:167], v[196:199], v[32:35]
	v_mfma_f32_16x16x32_bf16 v[20:23], v[156:159], v[204:207], v[20:23]
	v_mfma_f32_16x16x32_bf16 v[16:19], v[164:167], v[204:207], v[16:19]
	v_mfma_f32_16x16x32_bf16 v[4:7], v[156:159], v[212:215], v[4:7]
	v_mfma_f32_16x16x32_bf16 v[0:3], v[164:167], v[212:215], v[0:3]
	v_mfma_f32_16x16x32_bf16 v[60:63], v[168:171], v[184:187], v[60:63]
	v_mfma_f32_16x16x32_bf16 v[56:59], v[176:179], v[184:187], v[56:59]
	v_mfma_f32_16x16x32_bf16 v[44:47], v[168:171], v[192:195], v[44:47]
	v_mfma_f32_16x16x32_bf16 v[40:43], v[176:179], v[192:195], v[40:43]
	v_mfma_f32_16x16x32_bf16 v[28:31], v[168:171], v[200:203], v[28:31]
	v_mfma_f32_16x16x32_bf16 v[24:27], v[176:179], v[200:203], v[24:27]
	v_mfma_f32_16x16x32_bf16 v[12:15], v[168:171], v[208:211], v[12:15]
	v_mfma_f32_16x16x32_bf16 v[8:11], v[176:179], v[208:211], v[8:11]
	v_mfma_f32_16x16x32_bf16 v[60:63], v[172:175], v[188:191], v[60:63]
	v_mfma_f32_16x16x32_bf16 v[56:59], v[180:183], v[188:191], v[56:59]
	v_mfma_f32_16x16x32_bf16 v[44:47], v[172:175], v[196:199], v[44:47]
	v_mfma_f32_16x16x32_bf16 v[40:43], v[180:183], v[196:199], v[40:43]
	v_mfma_f32_16x16x32_bf16 v[28:31], v[172:175], v[204:207], v[28:31]
	v_mfma_f32_16x16x32_bf16 v[24:27], v[180:183], v[204:207], v[24:27]
	v_mfma_f32_16x16x32_bf16 v[12:15], v[172:175], v[212:215], v[12:15]
	v_mfma_f32_16x16x32_bf16 v[8:11], v[180:183], v[212:215], v[8:11]
	s_setprio 0
	s_barrier
	s_add_i32 s58, s58, 2
	s_add_u32 s24, s24, 0x100
	s_addc_u32 s25, s25, 0
	s_add_u32 s56, s56, 0x100
	s_addc_u32 s57, s57, 0
	s_cmp_gt_u32 s58, 29
	s_cbranch_scc0 .LBB0_2169
	s_and_b64 vcc, exec, s[12:13]
	s_cbranch_vccz .LBB0_2172
	s_barrier

; #define PG8_STAGE(bufoff, gbase, voff) do { _Pragma("unroll") for (int _i = 0; _i < 2; ++_i) \
;         __builtin_amdgcn_global_load_lds((const unsigned*)((const char*)(gbase) + (voff)[_i]), (PG8_LAS unsigned*)(lds + (bufoff) + ldsw + _i * 8192), 16, 0, 0); } while (0)
; #define PG8_LDA(dst, b, h) do { _Pragma("unroll") for (int m = 0; m < 4; ++m) _Pragma("unroll") for (int k = 0; k < 2; ++k) dst[m][k] = *(const PG8_LAS bf16x8*)(lds + PG8_SA(b, h) + aoff + m * 2048 + k * 1024); } while (0)
; #define PG8_LDB(dst, b, h) do { _Pragma("unroll") for (int n = 0; n < 2; ++n) _Pragma("unroll") for (int k = 0; k < 2; ++k) dst[n][k] = *(const PG8_LAS bf16x8*)(lds + PG8_SB(b, h) + boff + n * 2048 + k * 1024); } while (0)
; #define PG8_MMA(ai, bj, At, Bt) do { __builtin_amdgcn_s_setprio(1); _Pragma("unroll") for (int m = 0; m < 4; ++m) _Pragma("unroll") for (int n = 0; n < 2; ++n) _Pragma("unroll") for (int k = 0; k < 2; ++k) \
;         acc[ai][bj][m][n] = __builtin_amdgcn_mfma_f32_16x16x32_bf16(Bt[n][k], At[m][k], acc[ai][bj][m][n], 0, 0, 0); __builtin_amdgcn_s_setprio(0); } while (0)
; #define PG8_WAIT_V(n) asm volatile("s_waitcnt vmcnt(" #n ")" ::: "memory")
; #define PG8_WAIT_L(n) asm volatile("s_waitcnt lgkmcnt(" #n ")" ::: "memory")
; #define PG8_BAR __builtin_amdgcn_s_barrier()
; #define PG8_SCHED __builtin_amdgcn_sched_barrier(0)
; template <class Epi, class Sched, bool ALIGN_EPI = false, bool SP2 = false>
; __device__ __forceinline__ void gemm_phase(PG8_LAS unsigned char* lds, const Gemm g, const Sched& S, const Epi& E, const int wave_in) {
;     ...
;             const char* a2 = last ? nA : cA + (size_t)(t + 2) * kstep; const char* b2 = last ? nB : cB + (size_t)(t + 2) * kstep;
;     ...
;             PG8_LDB(B0, 0, 0); PG8_LDB(B1, 0, 1); PG8_SCHED; PG8_LDA(At, 0, 0); PG8_STAGE(PG8_SA(1, 1), a1 + hstepA, voffA);
;             PG8_WAIT_V(8); PG8_WAIT_L(0); PG8_BAR; PG8_MMA(0, 0, At, B0); PG8_MMA(0, 1, At, B1); PG8_BAR; PG8_SCHED;
;             PG8_LDA(At, 0, 1); PG8_STAGE(PG8_SB(0, 0), b2, voffB); PG8_STAGE(PG8_SB(0, 1), b2 + hstep, voffB); PG8_STAGE(PG8_SA(0, 0), a2, voffA);
;             PG8_WAIT_V(8); PG8_WAIT_L(0); PG8_BAR; PG8_MMA(1, 0, At, B0); PG8_MMA(1, 1, At, B1); PG8_BAR; PG8_SCHED;
.LBB0_2254:
	ds_read_b128 v[144:147], v151
	ds_read_b128 v[156:159], v151 offset:1024
	ds_read_b128 v[160:163], v151 offset:2048
	ds_read_b128 v[164:167], v151 offset:3072
	ds_read_b128 v[168:171], v152
	ds_read_b128 v[172:175], v152 offset:1024
	ds_read_b128 v[176:179], v152 offset:2048
	ds_read_b128 v[180:183], v152 offset:3072
	s_add_u32 s22, s20, 0x100
	s_addc_u32 s23, s21, 0
	s_cmpk_eq_i32 s53, 0x54
	s_cselect_b32 s37, s7, s23
	s_cselect_b32 s36, s6, s22
	s_cselect_b32 s25, s19, s52
	s_cselect_b32 s24, s18, s51
	v_lshl_add_u64 v[216:217], s[20:21], 0, v[136:137]
	s_add_i32 m0, s33, 0xc000
	ds_read_b128 v[184:187], v153
	ds_read_b128 v[188:191], v153 offset:1024
	ds_read_b128 v[192:195], v153 offset:2048
	ds_read_b128 v[196:199], v153 offset:3072
	ds_read_b128 v[200:203], v153 offset:4096
	ds_read_b128 v[204:207], v153 offset:5120
	ds_read_b128 v[208:211], v153 offset:6144
	ds_read_b128 v[212:215], v153 offset:7168
	global_load_lds_dwordx4 v[216:217], off
	v_lshl_add_u64 v[216:217], s[20:21], 0, v[138:139]
	s_add_i32 m0, s33, 0xe000
	s_nop 0
	global_load_lds_dwordx4 v[216:217], off
	s_waitcnt vmcnt(8)
	s_waitcnt lgkmcnt(0)
	s_barrier
	s_setprio 1
	v_mfma_f32_16x16x32_bf16 v[124:127], v[144:147], v[184:187], v[124:127]
	v_mfma_f32_16x16x32_bf16 v[120:123], v[160:163], v[184:187], v[120:123]
	v_mfma_f32_16x16x32_bf16 v[108:111], v[144:147], v[192:195], v[108:111]
	v_mfma_f32_16x16x32_bf16 v[104:107], v[160:163], v[192:195], v[104:107]
	v_mfma_f32_16x16x32_bf16 v[92:95], v[144:147], v[200:203], v[92:95]
	v_mfma_f32_16x16x32_bf16 v[88:91], v[160:163], v[200:203], v[88:91]
	v_mfma_f32_16x16x32_bf16 v[76:79], v[144:147], v[208:211], v[76:79]
	v_mfma_f32_16x16x32_bf16 v[72:75], v[160:163], v[208:211], v[72:75]
	v_mfma_f32_16x16x32_bf16 v[124:127], v[156:159], v[188:191], v[124:127]
	v_mfma_f32_16x16x32_bf16 v[120:123], v[164:167], v[188:191], v[120:123]
	v_mfma_f32_16x16x32_bf16 v[108:111], v[156:159], v[196:199], v[108:111]
	v_mfma_f32_16x16x32_bf16 v[104:107], v[164:167], v[196:199], v[104:107]
	v_mfma_f32_16x16x32_bf16 v[92:95], v[156:159], v[204:207], v[92:95]
	v_mfma_f32_16x16x32_bf16 v[88:91], v[164:167], v[204:207], v[88:91]
	v_mfma_f32_16x16x32_bf16 v[76:79], v[156:159], v[212:215], v[76:79]
	v_mfma_f32_16x16x32_bf16 v[72:75], v[164:167], v[212:215], v[72:75]
	v_mfma_f32_16x16x32_bf16 v[116:119], v[168:171], v[184:187], v[116:119]
	v_mfma_f32_16x16x32_bf16 v[112:115], v[176:179], v[184:187], v[112:115]
	v_mfma_f32_16x16x32_bf16 v[100:103], v[168:171], v[192:195], v[100:103]
	v_mfma_f32_16x16x32_bf16 v[96:99], v[176:179], v[192:195], v[96:99]
	v_mfma_f32_16x16x32_bf16 v[84:87], v[168:171], v[200:203], v[84:87]
	v_mfma_f32_16x16x32_bf16 v[80:83], v[176:179], v[200:203], v[80:83]
	v_mfma_f32_16x16x32_bf16 v[68:71], v[168:171], v[208:211], v[68:71]
	v_mfma_f32_16x16x32_bf16 v[64:67], v[176:179], v[208:211], v[64:67]
	v_mfma_f32_16x16x32_bf16 v[116:119], v[172:175], v[188:191], v[116:119]
	v_mfma_f32_16x16x32_bf16 v[112:115], v[180:183], v[188:191], v[112:115]
	v_mfma_f32_16x16x32_bf16 v[100:103], v[172:175], v[196:199], v[100:103]
	v_mfma_f32_16x16x32_bf16 v[96:99], v[180:183], v[196:199], v[96:99]
	v_mfma_f32_16x16x32_bf16 v[84:87], v[172:175], v[204:207], v[84:87]
	v_mfma_f32_16x16x32_bf16 v[80:83], v[180:183], v[204:207], v[80:83]
	v_mfma_f32_16x16x32_bf16 v[68:71], v[172:175], v[212:215], v[68:71]
	v_mfma_f32_16x16x32_bf16 v[64:67], v[180:183], v[212:215], v[64:67]
	s_setprio 0
	s_barrier
	s_add_i32 s20, s43, s11
	v_lshl_add_u64 v[216:217], s[24:25], 0, v[130:131]
	s_mov_b32 m0, s20
	ds_read_b128 v[184:187], v153 offset:16384
	ds_read_b128 v[188:191], v153 offset:17408
	ds_read_b128 v[192:195], v153 offset:18432
	ds_read_b128 v[196:199], v153 offset:19456
	ds_read_b128 v[200:203], v153 offset:20480
	ds_read_b128 v[204:207], v153 offset:21504
	ds_read_b128 v[208:211], v153 offset:22528
	ds_read_b128 v[212:215], v153 offset:23552
	global_load_lds_dwordx4 v[216:217], off
	s_add_i32 m0, s20, 0x2000
	s_add_u32 s20, s24, 0x160000
	v_lshl_add_u64 v[218:219], s[24:25], 0, v[134:135]
	s_addc_u32 s21, s25, 0
	s_add_i32 s54, s46, s11
	global_load_lds_dwordx4 v[218:219], off
	v_lshl_add_u64 v[220:221], s[20:21], 0, v[130:131]
	s_mov_b32 m0, s54
	v_lshl_add_u64 v[222:223], s[36:37], 0, v[132:133]
	global_load_lds_dwordx4 v[220:221], off
	v_lshl_add_u64 v[220:221], s[20:21], 0, v[134:135]
	s_add_i32 m0, s54, 0x2000
	s_nop 0
	global_load_lds_dwordx4 v[220:221], off
	v_lshl_add_u64 v[220:221], s[36:37], 0, v[128:129]
	s_mov_b32 m0, s33
	s_nop 0
	global_load_lds_dwordx4 v[220:221], off
	s_mov_b32 m0, s35
	s_nop 0
	global_load_lds_dwordx4 v[222:223], off
	s_waitcnt vmcnt(8)
	s_waitcnt lgkmcnt(0)
	s_barrier
; #define PG8_STAGE(bufoff, gbase, voff) do { _Pragma("unroll") for (int _i = 0; _i < 2; ++_i) \
;         __builtin_amdgcn_global_load_lds((const unsigned*)((const char*)(gbase) + (voff)[_i]), (PG8_LAS unsigned*)(lds + (bufoff) + ldsw + _i * 8192), 16, 0, 0); } while (0)
; #define PG8_LDA(dst, b, h) do { _Pragma("unroll") for (int m = 0; m < 4; ++m) _Pragma("unroll") for (int k = 0; k < 2; ++k) dst[m][k] = *(const PG8_LAS bf16x8*)(lds + PG8_SA(b, h) + aoff + m * 2048 + k * 1024); } while (0)
; #define PG8_LDB(dst, b, h) do { _Pragma("unroll") for (int n = 0; n < 2; ++n) _Pragma("unroll") for (int k = 0; k < 2; ++k) dst[n][k] = *(const PG8_LAS bf16x8*)(lds + PG8_SB(b, h) + boff + n * 2048 + k * 1024); } while (0)
; #define PG8_MMA(ai, bj, At, Bt) do { __builtin_amdgcn_s_setprio(1); _Pragma("unroll") for (int m = 0; m < 4; ++m) _Pragma("unroll") for (int n = 0; n < 2; ++n) _Pragma("unroll") for (int k = 0; k < 2; ++k) \
;         acc[ai][bj][m][n] = __builtin_amdgcn_mfma_f32_16x16x32_bf16(Bt[n][k], At[m][k], acc[ai][bj][m][n], 0, 0, 0); __builtin_amdgcn_s_setprio(0); } while (0)
; #define PG8_WAIT_V(n) asm volatile("s_waitcnt vmcnt(" #n ")" ::: "memory")
; #define PG8_WAIT_L(n) asm volatile("s_waitcnt lgkmcnt(" #n ")" ::: "memory")
; #define PG8_BAR __builtin_amdgcn_s_barrier()
; #define PG8_SCHED __builtin_amdgcn_sched_barrier(0)
; template <class Epi, class Sched, bool ALIGN_EPI = false, bool SP2 = false>
; __device__ __forceinline__ void gemm_phase(PG8_LAS unsigned char* lds, const Gemm g, const Sched& S, const Epi& E, const int wave_in) {
;     ...
;             PG8_WAIT_V(8); PG8_WAIT_L(0); PG8_BAR; PG8_MMA(1, 0, At, B0); PG8_MMA(1, 1, At, B1); PG8_BAR; PG8_SCHED;
;             PG8_LDB(B0, 1, 0); PG8_LDB(B1, 1, 1); PG8_SCHED; PG8_LDA(At, 1, 0); PG8_STAGE(PG8_SA(0, 1), a2 + hstepA, voffA);
;             PG8_WAIT_V(8); PG8_WAIT_L(0); PG8_BAR; PG8_MMA(0, 0, At, B0); PG8_MMA(0, 1, At, B1); PG8_BAR; PG8_SCHED;
	s_setprio 1
	v_mfma_f32_16x16x32_bf16 v[60:63], v[144:147], v[184:187], v[60:63]
	v_mfma_f32_16x16x32_bf16 v[56:59], v[160:163], v[184:187], v[56:59]
	v_mfma_f32_16x16x32_bf16 v[44:47], v[144:147], v[192:195], v[44:47]
	v_mfma_f32_16x16x32_bf16 v[40:43], v[160:163], v[192:195], v[40:43]
	v_mfma_f32_16x16x32_bf16 v[28:31], v[144:147], v[200:203], v[28:31]
	v_mfma_f32_16x16x32_bf16 v[24:27], v[160:163], v[200:203], v[24:27]
	v_mfma_f32_16x16x32_bf16 v[12:15], v[144:147], v[208:211], v[12:15]
	v_mfma_f32_16x16x32_bf16 v[8:11], v[160:163], v[208:211], v[8:11]
	v_mfma_f32_16x16x32_bf16 v[60:63], v[156:159], v[188:191], v[60:63]
	v_mfma_f32_16x16x32_bf16 v[56:59], v[164:167], v[188:191], v[56:59]
	v_mfma_f32_16x16x32_bf16 v[44:47], v[156:159], v[196:199], v[44:47]
	v_mfma_f32_16x16x32_bf16 v[40:43], v[164:167], v[196:199], v[40:43]
	v_mfma_f32_16x16x32_bf16 v[28:31], v[156:159], v[204:207], v[28:31]
	v_mfma_f32_16x16x32_bf16 v[24:27], v[164:167], v[204:207], v[24:27]
	v_mfma_f32_16x16x32_bf16 v[12:15], v[156:159], v[212:215], v[12:15]
	v_mfma_f32_16x16x32_bf16 v[8:11], v[164:167], v[212:215], v[8:11]
	v_mfma_f32_16x16x32_bf16 v[52:55], v[168:171], v[184:187], v[52:55]
	v_mfma_f32_16x16x32_bf16 v[48:51], v[176:179], v[184:187], v[48:51]
	v_mfma_f32_16x16x32_bf16 v[36:39], v[168:171], v[192:195], v[36:39]
	v_mfma_f32_16x16x32_bf16 v[32:35], v[176:179], v[192:195], v[32:35]
	v_mfma_f32_16x16x32_bf16 v[20:23], v[168:171], v[200:203], v[20:23]
	v_mfma_f32_16x16x32_bf16 v[16:19], v[176:179], v[200:203], v[16:19]
	v_mfma_f32_16x16x32_bf16 v[4:7], v[168:171], v[208:211], v[4:7]
	v_mfma_f32_16x16x32_bf16 v[0:3], v[176:179], v[208:211], v[0:3]
	v_mfma_f32_16x16x32_bf16 v[52:55], v[172:175], v[188:191], v[52:55]
	v_mfma_f32_16x16x32_bf16 v[48:51], v[180:183], v[188:191], v[48:51]
	v_mfma_f32_16x16x32_bf16 v[36:39], v[172:175], v[196:199], v[36:39]
	v_mfma_f32_16x16x32_bf16 v[32:35], v[180:183], v[196:199], v[32:35]
	v_mfma_f32_16x16x32_bf16 v[20:23], v[172:175], v[204:207], v[20:23]
	v_mfma_f32_16x16x32_bf16 v[16:19], v[180:183], v[204:207], v[16:19]
	v_mfma_f32_16x16x32_bf16 v[4:7], v[172:175], v[212:215], v[4:7]
	v_mfma_f32_16x16x32_bf16 v[0:3], v[180:183], v[212:215], v[0:3]
	s_setprio 0
	s_barrier
	s_add_i32 s54, 0, 0x18000
	v_add_u32_e32 v155, s54, v149
	s_add_i32 s55, 0, 0x1c000
	ds_read_b128 v[144:147], v155
	ds_read_b128 v[156:159], v155 offset:1024
	ds_read_b128 v[160:163], v155 offset:2048
	ds_read_b128 v[164:167], v155 offset:3072
	v_add_u32_e32 v155, s55, v149
	ds_read_b128 v[168:171], v155
	ds_read_b128 v[172:175], v155 offset:1024
	ds_read_b128 v[176:179], v155 offset:2048
	ds_read_b128 v[180:183], v155 offset:3072
	s_add_u32 s20, s36, 0x160000
	s_addc_u32 s21, s37, 0
	s_mov_b32 m0, s38
	v_lshl_add_u64 v[224:225], s[20:21], 0, v[128:129]
	ds_read_b128 v[184:187], v153 offset:32768
	ds_read_b128 v[188:191], v153 offset:33792
	ds_read_b128 v[192:195], v153 offset:34816
	ds_read_b128 v[196:199], v153 offset:35840
	ds_read_b128 v[200:203], v153 offset:36864
	ds_read_b128 v[204:207], v153 offset:37888
	ds_read_b128 v[208:211], v153 offset:38912
	ds_read_b128 v[212:215], v153 offset:39936
	global_load_lds_dwordx4 v[224:225], off
	v_lshl_add_u64 v[224:225], s[20:21], 0, v[132:133]
	s_mov_b32 m0, s39
	s_nop 0
	global_load_lds_dwordx4 v[224:225], off
	s_waitcnt vmcnt(8)
	s_waitcnt lgkmcnt(0)
	s_barrier
	s_setprio 1
	v_mfma_f32_16x16x32_bf16 v[124:127], v[144:147], v[184:187], v[124:127]
	v_mfma_f32_16x16x32_bf16 v[120:123], v[160:163], v[184:187], v[120:123]
	v_mfma_f32_16x16x32_bf16 v[108:111], v[144:147], v[192:195], v[108:111]
	v_mfma_f32_16x16x32_bf16 v[104:107], v[160:163], v[192:195], v[104:107]
	v_mfma_f32_16x16x32_bf16 v[92:95], v[144:147], v[200:203], v[92:95]
	v_mfma_f32_16x16x32_bf16 v[88:91], v[160:163], v[200:203], v[88:91]
	v_mfma_f32_16x16x32_bf16 v[76:79], v[144:147], v[208:211], v[76:79]
	v_mfma_f32_16x16x32_bf16 v[72:75], v[160:163], v[208:211], v[72:75]
	v_mfma_f32_16x16x32_bf16 v[124:127], v[156:159], v[188:191], v[124:127]
	v_mfma_f32_16x16x32_bf16 v[120:123], v[164:167], v[188:191], v[120:123]
	v_mfma_f32_16x16x32_bf16 v[108:111], v[156:159], v[196:199], v[108:111]
	v_mfma_f32_16x16x32_bf16 v[104:107], v[164:167], v[196:199], v[104:107]
	v_mfma_f32_16x16x32_bf16 v[92:95], v[156:159], v[204:207], v[92:95]
	v_mfma_f32_16x16x32_bf16 v[88:91], v[164:167], v[204:207], v[88:91]
	v_mfma_f32_16x16x32_bf16 v[76:79], v[156:159], v[212:215], v[76:79]
	v_mfma_f32_16x16x32_bf16 v[72:75], v[164:167], v[212:215], v[72:75]
	v_mfma_f32_16x16x32_bf16 v[116:119], v[168:171], v[184:187], v[116:119]
	v_mfma_f32_16x16x32_bf16 v[112:115], v[176:179], v[184:187], v[112:115]
	v_mfma_f32_16x16x32_bf16 v[100:103], v[168:171], v[192:195], v[100:103]
	v_mfma_f32_16x16x32_bf16 v[96:99], v[176:179], v[192:195], v[96:99]
	v_mfma_f32_16x16x32_bf16 v[84:87], v[168:171], v[200:203], v[84:87]
	v_mfma_f32_16x16x32_bf16 v[80:83], v[176:179], v[200:203], v[80:83]
	v_mfma_f32_16x16x32_bf16 v[68:71], v[168:171], v[208:211], v[68:71]
	v_mfma_f32_16x16x32_bf16 v[64:67], v[176:179], v[208:211], v[64:67]
	v_mfma_f32_16x16x32_bf16 v[116:119], v[172:175], v[188:191], v[116:119]
	v_mfma_f32_16x16x32_bf16 v[112:115], v[180:183], v[188:191], v[112:115]
	v_mfma_f32_16x16x32_bf16 v[100:103], v[172:175], v[196:199], v[100:103]
	v_mfma_f32_16x16x32_bf16 v[96:99], v[180:183], v[196:199], v[96:99]
	v_mfma_f32_16x16x32_bf16 v[84:87], v[172:175], v[204:207], v[84:87]
	v_mfma_f32_16x16x32_bf16 v[80:83], v[180:183], v[204:207], v[80:83]
	v_mfma_f32_16x16x32_bf16 v[68:71], v[172:175], v[212:215], v[68:71]
	v_mfma_f32_16x16x32_bf16 v[64:67], v[180:183], v[212:215], v[64:67]
	s_setprio 0
	s_barrier
; #define PG8_STAGE(bufoff, gbase, voff) do { _Pragma("unroll") for (int _i = 0; _i < 2; ++_i) \
;         __builtin_amdgcn_global_load_lds((const unsigned*)((const char*)(gbase) + (voff)[_i]), (PG8_LAS unsigned*)(lds + (bufoff) + ldsw + _i * 8192), 16, 0, 0); } while (0)
; #define PG8_LDA(dst, b, h) do { _Pragma("unroll") for (int m = 0; m < 4; ++m) _Pragma("unroll") for (int k = 0; k < 2; ++k) dst[m][k] = *(const PG8_LAS bf16x8*)(lds + PG8_SA(b, h) + aoff + m * 2048 + k * 1024); } while (0)
; #define PG8_MMA(ai, bj, At, Bt) do { __builtin_amdgcn_s_setprio(1); _Pragma("unroll") for (int m = 0; m < 4; ++m) _Pragma("unroll") for (int n = 0; n < 2; ++n) _Pragma("unroll") for (int k = 0; k < 2; ++k) \
;         acc[ai][bj][m][n] = __builtin_amdgcn_mfma_f32_16x16x32_bf16(Bt[n][k], At[m][k], acc[ai][bj][m][n], 0, 0, 0); __builtin_amdgcn_s_setprio(0); } while (0)
; #define PG8_WAIT_V(n) asm volatile("s_waitcnt vmcnt(" #n ")" ::: "memory")
; #define PG8_WAIT_L(n) asm volatile("s_waitcnt lgkmcnt(" #n ")" ::: "memory")
; #define PG8_BAR __builtin_amdgcn_s_barrier()
; #define PG8_SCHED __builtin_amdgcn_sched_barrier(0)
; template <class Epi, class Sched, bool ALIGN_EPI = false, bool SP2 = false>
; __device__ __forceinline__ void gemm_phase(PG8_LAS unsigned char* lds, const Gemm g, const Sched& S, const Epi& E, const int wave_in) {
;     ...
;         for (int t = 0; t < nt; t += 2) {
;     ...
;             PG8_LDA(At, 1, 1); PG8_STAGE(PG8_SB(1, 0), b3, voffB); PG8_STAGE(PG8_SB(1, 1), b3 + hstep, voffB); PG8_STAGE(PG8_SA(1, 0), a3, voffA);
;             PG8_WAIT_V(8); PG8_WAIT_L(0); PG8_BAR; PG8_MMA(1, 0, At, B0); PG8_MMA(1, 1, At, B1); PG8_BAR; PG8_SCHED;
	s_add_i32 s20, s54, s11
	v_lshl_add_u64 v[216:217], v[216:217], 0, s[14:15]
	s_mov_b32 m0, s20
	ds_read_b128 v[184:187], v153 offset:49152
	ds_read_b128 v[188:191], v153 offset:50176
	ds_read_b128 v[192:195], v153 offset:51200
	ds_read_b128 v[196:199], v153 offset:52224
	ds_read_b128 v[200:203], v153 offset:53248
	ds_read_b128 v[204:207], v153 offset:54272
	ds_read_b128 v[208:211], v153 offset:55296
	ds_read_b128 v[212:215], v153 offset:56320
	global_load_lds_dwordx4 v[216:217], off
	s_add_i32 m0, s20, 0x2000
	s_add_u32 s20, s24, 0x160080
	v_lshl_add_u64 v[216:217], v[218:219], 0, s[14:15]
	s_addc_u32 s21, s25, 0
	s_add_i32 s24, s55, s11
	global_load_lds_dwordx4 v[216:217], off
	v_lshl_add_u64 v[216:217], s[20:21], 0, v[130:131]
	s_mov_b32 m0, s24
	s_nop 0
	global_load_lds_dwordx4 v[216:217], off
	v_lshl_add_u64 v[216:217], s[20:21], 0, v[134:135]
	s_add_i32 m0, s24, 0x2000
	s_nop 0
	global_load_lds_dwordx4 v[216:217], off
	v_lshl_add_u64 v[216:217], v[220:221], 0, s[14:15]
	s_mov_b32 m0, s41
	s_nop 0
	global_load_lds_dwordx4 v[216:217], off
	v_lshl_add_u64 v[216:217], v[222:223], 0, s[14:15]
	s_mov_b32 m0, s42
	s_nop 0
	global_load_lds_dwordx4 v[216:217], off
	s_waitcnt vmcnt(8)
	s_waitcnt lgkmcnt(0)
	s_barrier
	s_setprio 1
	v_mfma_f32_16x16x32_bf16 v[60:63], v[144:147], v[184:187], v[60:63]
	v_mfma_f32_16x16x32_bf16 v[56:59], v[160:163], v[184:187], v[56:59]
	v_mfma_f32_16x16x32_bf16 v[44:47], v[144:147], v[192:195], v[44:47]
	v_mfma_f32_16x16x32_bf16 v[40:43], v[160:163], v[192:195], v[40:43]
	v_mfma_f32_16x16x32_bf16 v[28:31], v[144:147], v[200:203], v[28:31]
	v_mfma_f32_16x16x32_bf16 v[24:27], v[160:163], v[200:203], v[24:27]
	v_mfma_f32_16x16x32_bf16 v[12:15], v[144:147], v[208:211], v[12:15]
	v_mfma_f32_16x16x32_bf16 v[8:11], v[160:163], v[208:211], v[8:11]
	v_mfma_f32_16x16x32_bf16 v[60:63], v[156:159], v[188:191], v[60:63]
	v_mfma_f32_16x16x32_bf16 v[56:59], v[164:167], v[188:191], v[56:59]
	v_mfma_f32_16x16x32_bf16 v[44:47], v[156:159], v[196:199], v[44:47]
	v_mfma_f32_16x16x32_bf16 v[40:43], v[164:167], v[196:199], v[40:43]
	v_mfma_f32_16x16x32_bf16 v[28:31], v[156:159], v[204:207], v[28:31]
	v_mfma_f32_16x16x32_bf16 v[24:27], v[164:167], v[204:207], v[24:27]
	v_mfma_f32_16x16x32_bf16 v[12:15], v[156:159], v[212:215], v[12:15]
	v_mfma_f32_16x16x32_bf16 v[8:11], v[164:167], v[212:215], v[8:11]
	v_mfma_f32_16x16x32_bf16 v[52:55], v[168:171], v[184:187], v[52:55]
	v_mfma_f32_16x16x32_bf16 v[48:51], v[176:179], v[184:187], v[48:51]
	v_mfma_f32_16x16x32_bf16 v[36:39], v[168:171], v[192:195], v[36:39]
	v_mfma_f32_16x16x32_bf16 v[32:35], v[176:179], v[192:195], v[32:35]
	v_mfma_f32_16x16x32_bf16 v[20:23], v[168:171], v[200:203], v[20:23]
	v_mfma_f32_16x16x32_bf16 v[16:19], v[176:179], v[200:203], v[16:19]
	v_mfma_f32_16x16x32_bf16 v[4:7], v[168:171], v[208:211], v[4:7]
	v_mfma_f32_16x16x32_bf16 v[0:3], v[176:179], v[208:211], v[0:3]
	v_mfma_f32_16x16x32_bf16 v[52:55], v[172:175], v[188:191], v[52:55]
	v_mfma_f32_16x16x32_bf16 v[48:51], v[180:183], v[188:191], v[48:51]
	v_mfma_f32_16x16x32_bf16 v[36:39], v[172:175], v[196:199], v[36:39]
	v_mfma_f32_16x16x32_bf16 v[32:35], v[180:183], v[196:199], v[32:35]
	v_mfma_f32_16x16x32_bf16 v[20:23], v[172:175], v[204:207], v[20:23]
	v_mfma_f32_16x16x32_bf16 v[16:19], v[180:183], v[204:207], v[16:19]
	v_mfma_f32_16x16x32_bf16 v[4:7], v[172:175], v[212:215], v[4:7]
	v_mfma_f32_16x16x32_bf16 v[0:3], v[180:183], v[212:215], v[0:3]
	s_setprio 0
	s_barrier
	s_add_i32 s53, s53, 2
	s_add_u32 s51, s51, 0x100
	s_addc_u32 s52, s52, 0
	s_cmpk_gt_u32 s53, 0x55
	s_mov_b64 s[20:21], s[22:23]
	s_cbranch_scc0 .LBB0_2254
	s_and_b64 vcc, exec, s[16:17]
	s_cbranch_vccz .LBB0_2257
	s_barrier
